# GEMM K-loops unrolled by two with static LDS stage address sets: no per-step address toggles left
# speedup vs baseline: 1.0032x; 1.0032x over previous
.LBB0_303:
	s_mul_hi_i32 s5, s68, 0x2aaaaaab
	s_lshr_b32 s2, s5, 31
	s_add_i32 s5, s5, s2
	s_lshl_b32 s69, s5, 8
	s_waitcnt lgkmcnt(0)
	v_add_u32_e32 v0, s69, v189
	v_min_i32_e32 v0, 0x7fff, v0
	v_ashrrev_i32_e32 v1, 31, v0
	v_lshlrev_b64 v[0:1], 11, v[0:1]
	s_mul_i32 s2, s5, 0x600
	v_lshl_add_u64 v[172:173], v[168:169], 0, v[0:1]
	v_subrev_u32_e32 v0, s2, v200
	v_ashrrev_i32_e32 v1, 31, v0
	v_lshlrev_b64 v[0:1], 11, v[0:1]
	v_lshl_add_u64 v[180:181], v[170:171], 0, v[0:1]
	v_subrev_u32_e32 v0, s2, v201
	v_ashrrev_i32_e32 v1, 31, v0
	v_lshlrev_b64 v[0:1], 11, v[0:1]
	v_lshl_add_u64 v[182:183], v[170:171], 0, v[0:1]
	v_subrev_u32_e32 v0, s2, v202
	v_ashrrev_i32_e32 v1, 31, v0
	v_add_u32_e32 v2, s69, v190
	v_add_u32_e32 v4, s69, v163
	v_add_u32_e32 v6, s69, v192
	v_lshlrev_b64 v[0:1], 11, v[0:1]
	v_min_i32_e32 v2, 0x7fff, v2
	v_min_i32_e32 v4, 0x7fff, v4
	v_min_i32_e32 v6, 0x7fff, v6
	v_lshl_add_u64 v[184:185], v[170:171], 0, v[0:1]
	v_subrev_u32_e32 v0, s2, v203
	v_ashrrev_i32_e32 v3, 31, v2
	v_ashrrev_i32_e32 v5, 31, v4
	v_ashrrev_i32_e32 v7, 31, v6
	v_ashrrev_i32_e32 v1, 31, v0
	v_lshlrev_b64 v[2:3], 11, v[2:3]
	v_lshlrev_b64 v[4:5], 11, v[4:5]
	v_lshlrev_b64 v[6:7], 11, v[6:7]
	v_lshlrev_b64 v[0:1], 11, v[0:1]
	s_mov_b32 s4, s68
	v_lshl_add_u64 v[174:175], v[168:169], 0, v[2:3]
	v_lshl_add_u64 v[176:177], v[168:169], 0, v[4:5]
	v_lshl_add_u64 v[178:179], v[168:169], 0, v[6:7]
	v_lshl_add_u64 v[186:187], v[170:171], 0, v[0:1]
	s_mov_b64 s[2:3], 0
	s_mov_b32 s6, s25
	v_mov_b32_e32 v0, v161
	v_mov_b32_e32 v1, v161
	v_mov_b32_e32 v2, v161
	v_mov_b32_e32 v3, v161
	v_mov_b32_e32 v4, v161
	v_mov_b32_e32 v5, v161
	v_mov_b32_e32 v6, v161
	v_mov_b32_e32 v7, v161
	v_mov_b32_e32 v8, v161
	v_mov_b32_e32 v9, v161
	v_mov_b32_e32 v10, v161
	v_mov_b32_e32 v11, v161
	v_mov_b32_e32 v12, v161
	v_mov_b32_e32 v13, v161
	v_mov_b32_e32 v14, v161
	v_mov_b32_e32 v15, v161
	v_mov_b32_e32 v16, v161
	v_mov_b32_e32 v17, v161
	v_mov_b32_e32 v18, v161
	v_mov_b32_e32 v19, v161
	v_mov_b32_e32 v20, v161
	v_mov_b32_e32 v21, v161
	v_mov_b32_e32 v22, v161
	v_mov_b32_e32 v23, v161
	v_mov_b32_e32 v24, v161
	v_mov_b32_e32 v25, v161
	v_mov_b32_e32 v26, v161
	v_mov_b32_e32 v27, v161
	v_mov_b32_e32 v28, v161
	v_mov_b32_e32 v29, v161
	v_mov_b32_e32 v30, v161
	v_mov_b32_e32 v31, v161
	v_mov_b32_e32 v32, v161
	v_mov_b32_e32 v33, v161
	v_mov_b32_e32 v34, v161
	v_mov_b32_e32 v35, v161
	v_mov_b32_e32 v36, v161
	v_mov_b32_e32 v37, v161
	v_mov_b32_e32 v38, v161
	v_mov_b32_e32 v39, v161
	v_mov_b32_e32 v40, v161
	v_mov_b32_e32 v41, v161
	v_mov_b32_e32 v42, v161
	v_mov_b32_e32 v43, v161
	v_mov_b32_e32 v44, v161
	v_mov_b32_e32 v45, v161
	v_mov_b32_e32 v46, v161
	v_mov_b32_e32 v47, v161
	v_mov_b32_e32 v48, v161
	v_mov_b32_e32 v49, v161
	v_mov_b32_e32 v50, v161
	v_mov_b32_e32 v51, v161
	v_mov_b32_e32 v52, v161
	v_mov_b32_e32 v53, v161
	v_mov_b32_e32 v54, v161
	v_mov_b32_e32 v55, v161
	v_mov_b32_e32 v56, v161
	v_mov_b32_e32 v57, v161
	v_mov_b32_e32 v58, v161
	v_mov_b32_e32 v59, v161
	v_mov_b32_e32 v60, v161
	v_mov_b32_e32 v61, v161
	v_mov_b32_e32 v62, v161
	v_mov_b32_e32 v63, v161
	v_mov_b32_e32 v64, v161
	v_mov_b32_e32 v65, v161
	v_mov_b32_e32 v66, v161
	v_mov_b32_e32 v67, v161
	v_mov_b32_e32 v68, v161
	v_mov_b32_e32 v69, v161
	v_mov_b32_e32 v70, v161
	v_mov_b32_e32 v71, v161
	v_mov_b32_e32 v72, v161
	v_mov_b32_e32 v73, v161
	v_mov_b32_e32 v74, v161
	v_mov_b32_e32 v75, v161
	v_mov_b32_e32 v76, v161
	v_mov_b32_e32 v77, v161
	v_mov_b32_e32 v78, v161
	v_mov_b32_e32 v79, v161
	v_mov_b32_e32 v80, v161
	v_mov_b32_e32 v81, v161
	v_mov_b32_e32 v82, v161
	v_mov_b32_e32 v83, v161
	v_mov_b32_e32 v84, v161
	v_mov_b32_e32 v85, v161
	v_mov_b32_e32 v86, v161
	v_mov_b32_e32 v87, v161
	v_mov_b32_e32 v88, v161
	v_mov_b32_e32 v89, v161
	v_mov_b32_e32 v90, v161
	v_mov_b32_e32 v91, v161
	v_mov_b32_e32 v92, v161
	v_mov_b32_e32 v93, v161
	v_mov_b32_e32 v94, v161
	v_mov_b32_e32 v95, v161
	v_mov_b32_e32 v96, v161
	v_mov_b32_e32 v97, v161
	v_mov_b32_e32 v98, v161
	v_mov_b32_e32 v99, v161
	v_mov_b32_e32 v100, v161
	v_mov_b32_e32 v101, v161
	v_mov_b32_e32 v102, v161
	v_mov_b32_e32 v103, v161
	v_mov_b32_e32 v104, v161
	v_mov_b32_e32 v105, v161
	v_mov_b32_e32 v106, v161
	v_mov_b32_e32 v107, v161
	v_mov_b32_e32 v108, v161
	v_mov_b32_e32 v109, v161
	v_mov_b32_e32 v110, v161
	v_mov_b32_e32 v111, v161
	v_mov_b32_e32 v112, v161
	v_mov_b32_e32 v113, v161
	v_mov_b32_e32 v114, v161
	v_mov_b32_e32 v115, v161
	v_mov_b32_e32 v116, v161
	v_mov_b32_e32 v117, v161
	v_mov_b32_e32 v118, v161
	v_mov_b32_e32 v119, v161
	v_mov_b32_e32 v120, v161
	v_mov_b32_e32 v121, v161
	v_mov_b32_e32 v122, v161
	v_mov_b32_e32 v123, v161
	v_mov_b32_e32 v124, v161
	v_mov_b32_e32 v125, v161
	v_mov_b32_e32 v126, v161
	v_mov_b32_e32 v127, v161
	v_mbcnt_hi_u32_b32 v128, -1, v210
	s_and_b32 s90, s70, 0x40
	v_and_b32_e32 v159, 48, v128
	v_or_b32_e32 v159, s90, v159
	v_and_b32_e32 v129, 31, v128
	v_lshrrev_b32_e32 v130, 5, v128
	v_bfe_u32 v131, v128, 1, 3
	v_lshlrev_b32_e32 v132, 7, v129
	s_lshr_b32 s91, s70, 7
	s_lshl_b32 s91, s91, 13
	s_lshl_b32 s90, s90, 8
	s_add_u32 s90, s90, 0x8000
	s_lshl_b32 s88, s70, 4
	s_mov_b32 s89, 0x10000
	s_lshl_b32 s92, s22, 4
	s_and_b32 s92, s92, 0x780
	s_mov_b32 s93, 0
	s_load_dwordx2 s[96:97], s[0:1], 0x158
	s_load_dwordx2 s[98:99], s[0:1], 0xc0
	s_waitcnt lgkmcnt(0)
	v_subrev_u32_e32 v152, s96, v172
	v_xor_b32_e32 v152, v159, v152
	v_subrev_u32_e32 v153, s98, v180
	v_xor_b32_e32 v153, v159, v153
	v_subrev_u32_e32 v154, s96, v174
	v_xor_b32_e32 v154, v159, v154
	v_subrev_u32_e32 v155, s98, v182
	v_xor_b32_e32 v155, v159, v155
	v_subrev_u32_e32 v156, s96, v176
	v_xor_b32_e32 v156, v159, v156
	v_subrev_u32_e32 v157, s98, v184
	v_xor_b32_e32 v157, v159, v157
	v_subrev_u32_e32 v158, s96, v178
	v_xor_b32_e32 v158, v159, v158
	v_subrev_u32_e32 v160, s98, v186
	v_xor_b32_e32 v160, v159, v160
	v_xor_b32_e32 v133, v130, v131
	v_lshl_add_u32 v133, v133, 4, v132
	v_add_u32_e32 v232, s91, v133
	v_add_u32_e32 v236, s90, v133
	v_add_u32_e32 v205, 0x10000, v232
	v_add_u32_e32 v243, 0x10000, v236
	v_or_b32_e32 v133, 2, v130
	v_xor_b32_e32 v133, v133, v131
	v_lshl_add_u32 v133, v133, 4, v132
	v_add_u32_e32 v233, s91, v133
	v_add_u32_e32 v237, s90, v133
	v_add_u32_e32 v240, 0x10000, v233
	v_add_u32_e32 v253, 0x10000, v237
	v_or_b32_e32 v133, 4, v130
	v_xor_b32_e32 v133, v133, v131
	v_lshl_add_u32 v133, v133, 4, v132
	v_add_u32_e32 v234, s91, v133
	v_add_u32_e32 v238, s90, v133
	v_add_u32_e32 v241, 0x10000, v234
	v_add_u32_e32 v254, 0x10000, v238
	v_or_b32_e32 v133, 6, v130
	v_xor_b32_e32 v133, v133, v131
	v_lshl_add_u32 v133, v133, 4, v132
	v_add_u32_e32 v235, s91, v133
	v_add_u32_e32 v239, s90, v133
	v_add_u32_e32 v242, 0x10000, v235
	v_add_u32_e32 v255, 0x10000, v239
	s_barrier
	ds_read_b128 v[206:209], v232
	ds_read_b128 v[216:219], v236
	ds_read_b128 v[212:215], v232 offset:4096
	ds_read_b128 v[220:223], v236 offset:4096
	ds_read_b128 v[224:227], v236 offset:8192
	ds_read_b128 v[228:231], v236 offset:12288
	s_add_u32 s94, s2, s92
	s_add_u32 s94, s94, 0x80
	s_and_b32 s94, s94, 0x780
	s_sub_u32 s94, s94, 0x80
	s_subb_u32 s95, 0, 0
	s_add_u32 s100, s96, s94
	s_addc_u32 s101, s97, s95
	s_add_u32 s94, s98, s94
	s_addc_u32 s95, s99, s95
	s_add_u32 s90, s88, s89
	s_add_u32 m0, s90, 0
	s_nop 0
	global_load_lds_dwordx4 v152, s[100:101]
	s_add_u32 m0, s90, 32768
	s_nop 0
	global_load_lds_dwordx4 v153, s[94:95]
	s_add_u32 m0, s90, 8192
	s_nop 0
	global_load_lds_dwordx4 v154, s[100:101]
	s_add_u32 m0, s90, 40960
	s_nop 0
	global_load_lds_dwordx4 v155, s[94:95]
	s_add_u32 m0, s90, 16384
	s_nop 0
	global_load_lds_dwordx4 v156, s[100:101]
	s_add_u32 m0, s90, 49152
	s_nop 0
	global_load_lds_dwordx4 v157, s[94:95]
	s_add_u32 m0, s90, 24576
	s_nop 0
	global_load_lds_dwordx4 v158, s[100:101]
	s_add_u32 m0, s90, 57344
	s_nop 0
	global_load_lds_dwordx4 v160, s[94:95]
	s_xor_b32 s89, s89, 0x10000
.Lgk0_loop:
	ds_read_b128 v[128:131], v233
	ds_read_b128 v[136:139], v237
	ds_read_b128 v[132:135], v233 offset:4096
	ds_read_b128 v[140:143], v237 offset:4096
	ds_read_b128 v[144:147], v237 offset:8192
	ds_read_b128 v[148:151], v237 offset:12288
	s_waitcnt lgkmcnt(6)
	v_mfma_f32_32x32x16_bf16 v[112:127], v[206:209], v[216:219], v[112:127]
	v_mfma_f32_32x32x16_bf16 v[48:63], v[212:215], v[216:219], v[48:63]
	v_mfma_f32_32x32x16_bf16 v[96:111], v[206:209], v[220:223], v[96:111]
	v_mfma_f32_32x32x16_bf16 v[32:47], v[212:215], v[220:223], v[32:47]
	v_mfma_f32_32x32x16_bf16 v[80:95], v[206:209], v[224:227], v[80:95]
	v_mfma_f32_32x32x16_bf16 v[16:31], v[212:215], v[224:227], v[16:31]
	v_mfma_f32_32x32x16_bf16 v[64:79], v[206:209], v[228:231], v[64:79]
	v_mfma_f32_32x32x16_bf16 v[0:15], v[212:215], v[228:231], v[0:15]
	ds_read_b128 v[206:209], v234
	ds_read_b128 v[216:219], v238
	ds_read_b128 v[212:215], v234 offset:4096
	ds_read_b128 v[220:223], v238 offset:4096
	ds_read_b128 v[224:227], v238 offset:8192
	ds_read_b128 v[228:231], v238 offset:12288
	s_waitcnt lgkmcnt(6)
	v_mfma_f32_32x32x16_bf16 v[112:127], v[128:131], v[136:139], v[112:127]
	v_mfma_f32_32x32x16_bf16 v[48:63], v[132:135], v[136:139], v[48:63]
	v_mfma_f32_32x32x16_bf16 v[96:111], v[128:131], v[140:143], v[96:111]
	v_mfma_f32_32x32x16_bf16 v[32:47], v[132:135], v[140:143], v[32:47]
	v_mfma_f32_32x32x16_bf16 v[80:95], v[128:131], v[144:147], v[80:95]
	v_mfma_f32_32x32x16_bf16 v[16:31], v[132:135], v[144:147], v[16:31]
	v_mfma_f32_32x32x16_bf16 v[64:79], v[128:131], v[148:151], v[64:79]
	v_mfma_f32_32x32x16_bf16 v[0:15], v[132:135], v[148:151], v[0:15]
	ds_read_b128 v[128:131], v235
	ds_read_b128 v[136:139], v239
	ds_read_b128 v[132:135], v235 offset:4096
	ds_read_b128 v[140:143], v239 offset:4096
	ds_read_b128 v[144:147], v239 offset:8192
	ds_read_b128 v[148:151], v239 offset:12288
	s_waitcnt lgkmcnt(6)
	v_mfma_f32_32x32x16_bf16 v[112:127], v[206:209], v[216:219], v[112:127]
	v_mfma_f32_32x32x16_bf16 v[48:63], v[212:215], v[216:219], v[48:63]
	v_mfma_f32_32x32x16_bf16 v[96:111], v[206:209], v[220:223], v[96:111]
	v_mfma_f32_32x32x16_bf16 v[32:47], v[212:215], v[220:223], v[32:47]
	v_mfma_f32_32x32x16_bf16 v[80:95], v[206:209], v[224:227], v[80:95]
	v_mfma_f32_32x32x16_bf16 v[16:31], v[212:215], v[224:227], v[16:31]
	v_mfma_f32_32x32x16_bf16 v[64:79], v[206:209], v[228:231], v[64:79]
	v_mfma_f32_32x32x16_bf16 v[0:15], v[212:215], v[228:231], v[0:15]
	s_waitcnt vmcnt(0) lgkmcnt(0)
	s_barrier
	ds_read_b128 v[206:209], v205
	ds_read_b128 v[216:219], v243
	ds_read_b128 v[212:215], v205 offset:4096
	ds_read_b128 v[220:223], v243 offset:4096
	ds_read_b128 v[224:227], v243 offset:8192
	ds_read_b128 v[228:231], v243 offset:12288
	s_add_u32 s94, s2, s92
	s_add_u32 s94, s94, 0x100
	s_and_b32 s94, s94, 0x780
	s_sub_u32 s94, s94, 0x80
	s_subb_u32 s95, 0, 0
	s_add_u32 s100, s96, s94
	s_addc_u32 s101, s97, s95
	s_add_u32 s94, s98, s94
	s_addc_u32 s95, s99, s95
	s_add_u32 s90, s88, s89
	s_add_u32 m0, s90, 0
	v_mfma_f32_32x32x16_bf16 v[112:127], v[128:131], v[136:139], v[112:127]
	global_load_lds_dwordx4 v152, s[100:101]
	s_add_u32 m0, s90, 32768
	v_mfma_f32_32x32x16_bf16 v[48:63], v[132:135], v[136:139], v[48:63]
	global_load_lds_dwordx4 v153, s[94:95]
	s_add_u32 m0, s90, 8192
	v_mfma_f32_32x32x16_bf16 v[96:111], v[128:131], v[140:143], v[96:111]
	global_load_lds_dwordx4 v154, s[100:101]
	s_add_u32 m0, s90, 40960
	v_mfma_f32_32x32x16_bf16 v[32:47], v[132:135], v[140:143], v[32:47]
	global_load_lds_dwordx4 v155, s[94:95]
	s_add_u32 m0, s90, 16384
	v_mfma_f32_32x32x16_bf16 v[80:95], v[128:131], v[144:147], v[80:95]
	global_load_lds_dwordx4 v156, s[100:101]
	s_add_u32 m0, s90, 49152
	v_mfma_f32_32x32x16_bf16 v[16:31], v[132:135], v[144:147], v[16:31]
	global_load_lds_dwordx4 v157, s[94:95]
	s_add_u32 m0, s90, 24576
	v_mfma_f32_32x32x16_bf16 v[64:79], v[128:131], v[148:151], v[64:79]
	global_load_lds_dwordx4 v158, s[100:101]
	s_add_u32 m0, s90, 57344
	v_mfma_f32_32x32x16_bf16 v[0:15], v[132:135], v[148:151], v[0:15]
	global_load_lds_dwordx4 v160, s[94:95]
	s_xor_b32 s89, s89, 0x10000
	s_add_i32 s6, s6, 1
	s_add_u32 s2, s2, 0x80
	s_addc_u32 s3, s3, 0
	ds_read_b128 v[128:131], v240
	ds_read_b128 v[136:139], v253
	ds_read_b128 v[132:135], v240 offset:4096
	ds_read_b128 v[140:143], v253 offset:4096
	ds_read_b128 v[144:147], v253 offset:8192
	ds_read_b128 v[148:151], v253 offset:12288
	s_waitcnt lgkmcnt(6)
	v_mfma_f32_32x32x16_bf16 v[112:127], v[206:209], v[216:219], v[112:127]
	v_mfma_f32_32x32x16_bf16 v[48:63], v[212:215], v[216:219], v[48:63]
	v_mfma_f32_32x32x16_bf16 v[96:111], v[206:209], v[220:223], v[96:111]
	v_mfma_f32_32x32x16_bf16 v[32:47], v[212:215], v[220:223], v[32:47]
	v_mfma_f32_32x32x16_bf16 v[80:95], v[206:209], v[224:227], v[80:95]
	v_mfma_f32_32x32x16_bf16 v[16:31], v[212:215], v[224:227], v[16:31]
	v_mfma_f32_32x32x16_bf16 v[64:79], v[206:209], v[228:231], v[64:79]
	v_mfma_f32_32x32x16_bf16 v[0:15], v[212:215], v[228:231], v[0:15]
	ds_read_b128 v[206:209], v241
	ds_read_b128 v[216:219], v254
	ds_read_b128 v[212:215], v241 offset:4096
	ds_read_b128 v[220:223], v254 offset:4096
	ds_read_b128 v[224:227], v254 offset:8192
	ds_read_b128 v[228:231], v254 offset:12288
	s_waitcnt lgkmcnt(6)
	v_mfma_f32_32x32x16_bf16 v[112:127], v[128:131], v[136:139], v[112:127]
	v_mfma_f32_32x32x16_bf16 v[48:63], v[132:135], v[136:139], v[48:63]
	v_mfma_f32_32x32x16_bf16 v[96:111], v[128:131], v[140:143], v[96:111]
	v_mfma_f32_32x32x16_bf16 v[32:47], v[132:135], v[140:143], v[32:47]
	v_mfma_f32_32x32x16_bf16 v[80:95], v[128:131], v[144:147], v[80:95]
	v_mfma_f32_32x32x16_bf16 v[16:31], v[132:135], v[144:147], v[16:31]
	v_mfma_f32_32x32x16_bf16 v[64:79], v[128:131], v[148:151], v[64:79]
	v_mfma_f32_32x32x16_bf16 v[0:15], v[132:135], v[148:151], v[0:15]
	ds_read_b128 v[128:131], v242
	ds_read_b128 v[136:139], v255
	ds_read_b128 v[132:135], v242 offset:4096
	ds_read_b128 v[140:143], v255 offset:4096
	ds_read_b128 v[144:147], v255 offset:8192
	ds_read_b128 v[148:151], v255 offset:12288
	s_waitcnt lgkmcnt(6)
	v_mfma_f32_32x32x16_bf16 v[112:127], v[206:209], v[216:219], v[112:127]
	v_mfma_f32_32x32x16_bf16 v[48:63], v[212:215], v[216:219], v[48:63]
	v_mfma_f32_32x32x16_bf16 v[96:111], v[206:209], v[220:223], v[96:111]
	v_mfma_f32_32x32x16_bf16 v[32:47], v[212:215], v[220:223], v[32:47]
	v_mfma_f32_32x32x16_bf16 v[80:95], v[206:209], v[224:227], v[80:95]
	v_mfma_f32_32x32x16_bf16 v[16:31], v[212:215], v[224:227], v[16:31]
	v_mfma_f32_32x32x16_bf16 v[64:79], v[206:209], v[228:231], v[64:79]
	v_mfma_f32_32x32x16_bf16 v[0:15], v[212:215], v[228:231], v[0:15]
	s_waitcnt vmcnt(0) lgkmcnt(0)
	s_barrier
	ds_read_b128 v[206:209], v232
	ds_read_b128 v[216:219], v236
	ds_read_b128 v[212:215], v232 offset:4096
	ds_read_b128 v[220:223], v236 offset:4096
	ds_read_b128 v[224:227], v236 offset:8192
	ds_read_b128 v[228:231], v236 offset:12288
	s_add_u32 s94, s2, s92
	s_add_u32 s94, s94, 0x100
	s_and_b32 s94, s94, 0x780
	s_sub_u32 s94, s94, 0x80
	s_subb_u32 s95, 0, 0
	s_add_u32 s100, s96, s94
	s_addc_u32 s101, s97, s95
	s_add_u32 s94, s98, s94
	s_addc_u32 s95, s99, s95
	s_add_u32 s90, s88, s89
	s_add_u32 m0, s90, 0
	v_mfma_f32_32x32x16_bf16 v[112:127], v[128:131], v[136:139], v[112:127]
	global_load_lds_dwordx4 v152, s[100:101]
	s_add_u32 m0, s90, 32768
	v_mfma_f32_32x32x16_bf16 v[48:63], v[132:135], v[136:139], v[48:63]
	global_load_lds_dwordx4 v153, s[94:95]
	s_add_u32 m0, s90, 8192
	v_mfma_f32_32x32x16_bf16 v[96:111], v[128:131], v[140:143], v[96:111]
	global_load_lds_dwordx4 v154, s[100:101]
	s_add_u32 m0, s90, 40960
	v_mfma_f32_32x32x16_bf16 v[32:47], v[132:135], v[140:143], v[32:47]
	global_load_lds_dwordx4 v155, s[94:95]
	s_add_u32 m0, s90, 16384
	v_mfma_f32_32x32x16_bf16 v[80:95], v[128:131], v[144:147], v[80:95]
	global_load_lds_dwordx4 v156, s[100:101]
	s_add_u32 m0, s90, 49152
	v_mfma_f32_32x32x16_bf16 v[16:31], v[132:135], v[144:147], v[16:31]
	global_load_lds_dwordx4 v157, s[94:95]
	s_add_u32 m0, s90, 24576
	v_mfma_f32_32x32x16_bf16 v[64:79], v[128:131], v[148:151], v[64:79]
	global_load_lds_dwordx4 v158, s[100:101]
	s_add_u32 m0, s90, 57344
	v_mfma_f32_32x32x16_bf16 v[0:15], v[132:135], v[148:151], v[0:15]
	global_load_lds_dwordx4 v160, s[94:95]
	s_xor_b32 s89, s89, 0x10000
	s_add_i32 s6, s6, 1
	s_add_u32 s2, s2, 0x80
	s_addc_u32 s3, s3, 0
	s_cmpk_eq_i32 s2, 0x700
	s_cbranch_scc0 .Lgk0_loop
	ds_read_b128 v[128:131], v233
	ds_read_b128 v[136:139], v237
	ds_read_b128 v[132:135], v233 offset:4096
	ds_read_b128 v[140:143], v237 offset:4096
	ds_read_b128 v[144:147], v237 offset:8192
	ds_read_b128 v[148:151], v237 offset:12288
	s_waitcnt lgkmcnt(6)
	v_mfma_f32_32x32x16_bf16 v[112:127], v[206:209], v[216:219], v[112:127]
	v_mfma_f32_32x32x16_bf16 v[48:63], v[212:215], v[216:219], v[48:63]
	v_mfma_f32_32x32x16_bf16 v[96:111], v[206:209], v[220:223], v[96:111]
	v_mfma_f32_32x32x16_bf16 v[32:47], v[212:215], v[220:223], v[32:47]
	v_mfma_f32_32x32x16_bf16 v[80:95], v[206:209], v[224:227], v[80:95]
	v_mfma_f32_32x32x16_bf16 v[16:31], v[212:215], v[224:227], v[16:31]
	v_mfma_f32_32x32x16_bf16 v[64:79], v[206:209], v[228:231], v[64:79]
	v_mfma_f32_32x32x16_bf16 v[0:15], v[212:215], v[228:231], v[0:15]
	ds_read_b128 v[206:209], v234
	ds_read_b128 v[216:219], v238
	ds_read_b128 v[212:215], v234 offset:4096
	ds_read_b128 v[220:223], v238 offset:4096
	ds_read_b128 v[224:227], v238 offset:8192
	ds_read_b128 v[228:231], v238 offset:12288
	s_waitcnt lgkmcnt(6)
	v_mfma_f32_32x32x16_bf16 v[112:127], v[128:131], v[136:139], v[112:127]
	v_mfma_f32_32x32x16_bf16 v[48:63], v[132:135], v[136:139], v[48:63]
	v_mfma_f32_32x32x16_bf16 v[96:111], v[128:131], v[140:143], v[96:111]
	v_mfma_f32_32x32x16_bf16 v[32:47], v[132:135], v[140:143], v[32:47]
	v_mfma_f32_32x32x16_bf16 v[80:95], v[128:131], v[144:147], v[80:95]
	v_mfma_f32_32x32x16_bf16 v[16:31], v[132:135], v[144:147], v[16:31]
	v_mfma_f32_32x32x16_bf16 v[64:79], v[128:131], v[148:151], v[64:79]
	v_mfma_f32_32x32x16_bf16 v[0:15], v[132:135], v[148:151], v[0:15]
	ds_read_b128 v[128:131], v235
	ds_read_b128 v[136:139], v239
	ds_read_b128 v[132:135], v235 offset:4096
	ds_read_b128 v[140:143], v239 offset:4096
	ds_read_b128 v[144:147], v239 offset:8192
	ds_read_b128 v[148:151], v239 offset:12288
	s_waitcnt lgkmcnt(6)
	v_mfma_f32_32x32x16_bf16 v[112:127], v[206:209], v[216:219], v[112:127]
	v_mfma_f32_32x32x16_bf16 v[48:63], v[212:215], v[216:219], v[48:63]
	v_mfma_f32_32x32x16_bf16 v[96:111], v[206:209], v[220:223], v[96:111]
	v_mfma_f32_32x32x16_bf16 v[32:47], v[212:215], v[220:223], v[32:47]
	v_mfma_f32_32x32x16_bf16 v[80:95], v[206:209], v[224:227], v[80:95]
	v_mfma_f32_32x32x16_bf16 v[16:31], v[212:215], v[224:227], v[16:31]
	v_mfma_f32_32x32x16_bf16 v[64:79], v[206:209], v[228:231], v[64:79]
	v_mfma_f32_32x32x16_bf16 v[0:15], v[212:215], v[228:231], v[0:15]
	s_waitcnt vmcnt(0) lgkmcnt(0)
	s_barrier
	ds_read_b128 v[206:209], v205
	ds_read_b128 v[216:219], v243
	ds_read_b128 v[212:215], v205 offset:4096
	ds_read_b128 v[220:223], v243 offset:4096
	ds_read_b128 v[224:227], v243 offset:8192
	ds_read_b128 v[228:231], v243 offset:12288
	v_mfma_f32_32x32x16_bf16 v[112:127], v[128:131], v[136:139], v[112:127]
	v_mfma_f32_32x32x16_bf16 v[48:63], v[132:135], v[136:139], v[48:63]
	v_mfma_f32_32x32x16_bf16 v[96:111], v[128:131], v[140:143], v[96:111]
	v_mfma_f32_32x32x16_bf16 v[32:47], v[132:135], v[140:143], v[32:47]
	v_mfma_f32_32x32x16_bf16 v[80:95], v[128:131], v[144:147], v[80:95]
	v_mfma_f32_32x32x16_bf16 v[16:31], v[132:135], v[144:147], v[16:31]
	v_mfma_f32_32x32x16_bf16 v[64:79], v[128:131], v[148:151], v[64:79]
	v_mfma_f32_32x32x16_bf16 v[0:15], v[132:135], v[148:151], v[0:15]
	s_xor_b32 s89, s89, 0x10000
	s_add_i32 s6, s6, 1
	s_add_u32 s2, s2, 0x80
	s_addc_u32 s3, s3, 0
	s_add_i32 s68, s4, s42
	s_cmpk_gt_i32 s68, 0x2ff
	s_cselect_b64 s[28:29], -1, 0
	s_and_b64 vcc, exec, s[28:29]
	s_cbranch_vccnz .LBB0_307
	s_mul_hi_i32 s2, s68, 0x2aaaaaab
	s_lshr_b32 s3, s2, 31
	s_add_i32 s2, s2, s3
	s_mul_i32 s3, s2, -6
	s_lshl_b32 s2, s2, 8
	v_add_u32_e32 v129, s2, v190
	s_add_i32 s3, s3, s68
	v_min_i32_e32 v132, 0x7fff, v129
	v_add_u32_e32 v129, s2, v163
	s_lshl_b32 s3, s3, 8
	v_add_u32_e32 v128, s2, v189
	v_min_i32_e32 v136, 0x7fff, v129
	v_add_u32_e32 v129, s2, v192
	v_min_i32_e32 v128, 0x7fff, v128
	v_add_u32_e32 v130, s3, v189
	v_add_u32_e32 v134, s3, v190
	v_add_u32_e32 v138, s3, v163
	v_min_i32_e32 v140, 0x7fff, v129
	v_add_u32_e32 v142, s3, v192
	v_ashrrev_i32_e32 v143, 31, v142
	v_ashrrev_i32_e32 v141, 31, v140
	v_ashrrev_i32_e32 v139, 31, v138
	v_ashrrev_i32_e32 v137, 31, v136
	v_ashrrev_i32_e32 v135, 31, v134
	v_ashrrev_i32_e32 v133, 31, v132
	v_ashrrev_i32_e32 v131, 31, v130
	v_ashrrev_i32_e32 v129, 31, v128
	v_lshlrev_b64 v[142:143], 11, v[142:143]
	v_lshlrev_b64 v[140:141], 11, v[140:141]
	v_lshlrev_b64 v[138:139], 11, v[138:139]
	v_lshlrev_b64 v[136:137], 11, v[136:137]
	v_lshlrev_b64 v[134:135], 11, v[134:135]
	v_lshlrev_b64 v[132:133], 11, v[132:133]
	v_lshlrev_b64 v[130:131], 11, v[130:131]
	v_lshlrev_b64 v[128:129], 11, v[128:129]
	v_lshl_add_u64 v[156:157], v[164:165], 0, v[142:143]
	v_lshl_add_u64 v[152:153], v[166:167], 0, v[140:141]
	v_lshl_add_u64 v[148:149], v[164:165], 0, v[138:139]
	v_lshl_add_u64 v[144:145], v[166:167], 0, v[136:137]
	v_lshl_add_u64 v[140:141], v[164:165], 0, v[134:135]
	v_lshl_add_u64 v[136:137], v[166:167], 0, v[132:133]
	v_lshl_add_u64 v[132:133], v[164:165], 0, v[130:131]
	v_lshl_add_u64 v[128:129], v[166:167], 0, v[128:129]
	s_add_u32 m0, s88, 0
	v_lshl_add_u64 v[128:129], v[128:129], 0, s[92:93]
	v_xor_b32_e32 v128, v159, v128
	global_load_lds_dwordx4 v[128:129], off
	s_add_u32 m0, s88, 32768
	v_lshl_add_u64 v[132:133], v[132:133], 0, s[92:93]
	v_xor_b32_e32 v132, v159, v132
	global_load_lds_dwordx4 v[132:133], off
	s_add_u32 m0, s88, 8192
	v_lshl_add_u64 v[136:137], v[136:137], 0, s[92:93]
	v_xor_b32_e32 v136, v159, v136
	global_load_lds_dwordx4 v[136:137], off
	s_add_u32 m0, s88, 40960
	v_lshl_add_u64 v[140:141], v[140:141], 0, s[92:93]
	v_xor_b32_e32 v140, v159, v140
	global_load_lds_dwordx4 v[140:141], off
	s_add_u32 m0, s88, 16384
	v_lshl_add_u64 v[144:145], v[144:145], 0, s[92:93]
	v_xor_b32_e32 v144, v159, v144
	global_load_lds_dwordx4 v[144:145], off
	s_add_u32 m0, s88, 49152
	v_lshl_add_u64 v[148:149], v[148:149], 0, s[92:93]
	v_xor_b32_e32 v148, v159, v148
	global_load_lds_dwordx4 v[148:149], off
	s_add_u32 m0, s88, 24576
	v_lshl_add_u64 v[152:153], v[152:153], 0, s[92:93]
	v_xor_b32_e32 v152, v159, v152
	global_load_lds_dwordx4 v[152:153], off
	s_add_u32 m0, s88, 57344
	v_lshl_add_u64 v[156:157], v[156:157], 0, s[92:93]
	v_xor_b32_e32 v156, v159, v156
	global_load_lds_dwordx4 v[156:157], off
.LBB0_307:
	ds_read_b128 v[128:131], v240
	ds_read_b128 v[136:139], v253
	ds_read_b128 v[132:135], v240 offset:4096
	ds_read_b128 v[140:143], v253 offset:4096
	ds_read_b128 v[144:147], v253 offset:8192
	ds_read_b128 v[148:151], v253 offset:12288
	s_waitcnt lgkmcnt(6)
	v_mfma_f32_32x32x16_bf16 v[112:127], v[206:209], v[216:219], v[112:127]
	v_mfma_f32_32x32x16_bf16 v[48:63], v[212:215], v[216:219], v[48:63]
	v_mfma_f32_32x32x16_bf16 v[96:111], v[206:209], v[220:223], v[96:111]
	v_mfma_f32_32x32x16_bf16 v[32:47], v[212:215], v[220:223], v[32:47]
	v_mfma_f32_32x32x16_bf16 v[80:95], v[206:209], v[224:227], v[80:95]
	v_mfma_f32_32x32x16_bf16 v[16:31], v[212:215], v[224:227], v[16:31]
	v_mfma_f32_32x32x16_bf16 v[64:79], v[206:209], v[228:231], v[64:79]
	v_mfma_f32_32x32x16_bf16 v[0:15], v[212:215], v[228:231], v[0:15]
	ds_read_b128 v[206:209], v241
	ds_read_b128 v[216:219], v254
	ds_read_b128 v[212:215], v241 offset:4096
	ds_read_b128 v[220:223], v254 offset:4096
	ds_read_b128 v[224:227], v254 offset:8192
	ds_read_b128 v[228:231], v254 offset:12288
	s_waitcnt lgkmcnt(6)
	v_mfma_f32_32x32x16_bf16 v[112:127], v[128:131], v[136:139], v[112:127]
	v_mfma_f32_32x32x16_bf16 v[48:63], v[132:135], v[136:139], v[48:63]
	v_mfma_f32_32x32x16_bf16 v[96:111], v[128:131], v[140:143], v[96:111]
	v_mfma_f32_32x32x16_bf16 v[32:47], v[132:135], v[140:143], v[32:47]
	v_mfma_f32_32x32x16_bf16 v[80:95], v[128:131], v[144:147], v[80:95]
	v_mfma_f32_32x32x16_bf16 v[16:31], v[132:135], v[144:147], v[16:31]
	v_mfma_f32_32x32x16_bf16 v[64:79], v[128:131], v[148:151], v[64:79]
	v_mfma_f32_32x32x16_bf16 v[0:15], v[132:135], v[148:151], v[0:15]
	ds_read_b128 v[128:131], v242
	ds_read_b128 v[136:139], v255
	ds_read_b128 v[132:135], v242 offset:4096
	ds_read_b128 v[140:143], v255 offset:4096
	ds_read_b128 v[144:147], v255 offset:8192
	ds_read_b128 v[148:151], v255 offset:12288
	s_waitcnt lgkmcnt(6)
	v_mfma_f32_32x32x16_bf16 v[112:127], v[206:209], v[216:219], v[112:127]
	v_mfma_f32_32x32x16_bf16 v[48:63], v[212:215], v[216:219], v[48:63]
	v_mfma_f32_32x32x16_bf16 v[96:111], v[206:209], v[220:223], v[96:111]
	v_mfma_f32_32x32x16_bf16 v[32:47], v[212:215], v[220:223], v[32:47]
	v_mfma_f32_32x32x16_bf16 v[80:95], v[206:209], v[224:227], v[80:95]
	v_mfma_f32_32x32x16_bf16 v[16:31], v[212:215], v[224:227], v[16:31]
	v_mfma_f32_32x32x16_bf16 v[64:79], v[206:209], v[228:231], v[64:79]
	v_mfma_f32_32x32x16_bf16 v[0:15], v[212:215], v[228:231], v[0:15]
	s_waitcnt vmcnt(0) lgkmcnt(0)
	s_barrier
	v_mfma_f32_32x32x16_bf16 v[112:127], v[128:131], v[136:139], v[112:127]
	v_mfma_f32_32x32x16_bf16 v[48:63], v[132:135], v[136:139], v[48:63]
	v_mfma_f32_32x32x16_bf16 v[96:111], v[128:131], v[140:143], v[96:111]
	v_mfma_f32_32x32x16_bf16 v[32:47], v[132:135], v[140:143], v[32:47]
	v_mfma_f32_32x32x16_bf16 v[80:95], v[128:131], v[144:147], v[80:95]
	v_mfma_f32_32x32x16_bf16 v[16:31], v[132:135], v[144:147], v[16:31]
	v_mfma_f32_32x32x16_bf16 v[64:79], v[128:131], v[148:151], v[64:79]
	v_mfma_f32_32x32x16_bf16 v[0:15], v[132:135], v[148:151], v[0:15]
	v_mbcnt_hi_u32_b32 v228, -1, v210
	v_and_b32_e32 v229, 31, v228
	v_lshrrev_b32_e32 v230, 5, v228
	v_lshlrev_b32_e32 v160, 3, v229
	v_lshlrev_b32_e32 v225, 2, v230
	s_lshr_b32 s90, s70, 6
	s_mul_i32 s91, s90, 0x1200
	s_add_u32 s91, s91, 0x12000
	v_mul_u32_u24_e32 v231, 0x240, v230
	v_lshl_add_u32 v231, v229, 1, v231
	v_add_u32_e32 v205, s91, v231
	v_lshrrev_b32_e32 v226, 3, v228
	v_and_b32_e32 v232, 7, v228
	v_lshlrev_b32_e32 v227, 4, v232
	v_mul_u32_u24_e32 v231, 0x90, v226
	v_add3_u32 v224, v231, v227, s91
	s_mul_i32 s92, s5, 6
	s_sub_u32 s93, s4, s92
	s_lshl_b32 s93, s93, 8
	s_lshl_b32 s92, s5, 8
	s_lshr_b32 s94, s90, 1
	s_lshl_b32 s94, s94, 6
	s_add_u32 s92, s92, s94
	s_and_b32 s94, s90, 1
	s_lshl_b32 s94, s94, 7
	s_add_u32 s93, s93, s94

.Lep0_00_mP:
	v_cvt_pk_bf16_f32 v228, v112, v96
	ds_write_b16 v205, v228
	ds_write_b16_d16_hi v205, v228 offset:64
	v_cvt_pk_bf16_f32 v229, v113, v97
	ds_write_b16 v205, v229 offset:144
	ds_write_b16_d16_hi v205, v229 offset:208
	v_cvt_pk_bf16_f32 v230, v114, v98
	ds_write_b16 v205, v230 offset:288
	ds_write_b16_d16_hi v205, v230 offset:352
	v_cvt_pk_bf16_f32 v231, v115, v99
	ds_write_b16 v205, v231 offset:432
	ds_write_b16_d16_hi v205, v231 offset:496
	v_cvt_pk_bf16_f32 v228, v116, v100
	ds_write_b16 v205, v228 offset:1152
	ds_write_b16_d16_hi v205, v228 offset:1216
	v_cvt_pk_bf16_f32 v229, v117, v101
	ds_write_b16 v205, v229 offset:1296
	ds_write_b16_d16_hi v205, v229 offset:1360
	v_cvt_pk_bf16_f32 v230, v118, v102
	ds_write_b16 v205, v230 offset:1440
	ds_write_b16_d16_hi v205, v230 offset:1504
	v_cvt_pk_bf16_f32 v231, v119, v103
	ds_write_b16 v205, v231 offset:1584
	ds_write_b16_d16_hi v205, v231 offset:1648
	v_cvt_pk_bf16_f32 v228, v120, v104
	ds_write_b16 v205, v228 offset:2304
	ds_write_b16_d16_hi v205, v228 offset:2368
	v_cvt_pk_bf16_f32 v229, v121, v105
	ds_write_b16 v205, v229 offset:2448
	ds_write_b16_d16_hi v205, v229 offset:2512
	v_cvt_pk_bf16_f32 v230, v122, v106
	ds_write_b16 v205, v230 offset:2592
	ds_write_b16_d16_hi v205, v230 offset:2656
	v_cvt_pk_bf16_f32 v231, v123, v107
	ds_write_b16 v205, v231 offset:2736
	ds_write_b16_d16_hi v205, v231 offset:2800
	v_cvt_pk_bf16_f32 v228, v124, v108
	ds_write_b16 v205, v228 offset:3456
	ds_write_b16_d16_hi v205, v228 offset:3520
	v_cvt_pk_bf16_f32 v229, v125, v109
	ds_write_b16 v205, v229 offset:3600
	ds_write_b16_d16_hi v205, v229 offset:3664
	v_cvt_pk_bf16_f32 v230, v126, v110
	ds_write_b16 v205, v230 offset:3744
	ds_write_b16_d16_hi v205, v230 offset:3808
	v_cvt_pk_bf16_f32 v231, v127, v111
	ds_write_b16 v205, v231 offset:3888
	ds_write_b16_d16_hi v205, v231 offset:3952
	s_branch .Lep0_00_stq
.Lep0_00_mR:
	s_load_dwordx2 s[98:99], s[0:1], 0x148
	v_add_u32_e32 v228, s94, v225
	v_lshlrev_b32_e32 v228, 8, v228
	v_add_u32_e32 v234, v228, v160
	v_mov_b32_e32 v235, 0
	s_waitcnt lgkmcnt(0)
	v_lshl_add_u64 v[234:235], s[98:99], 0, v[234:235]
	global_load_dwordx2 v[128:129], v[234:235], off
	global_load_dwordx2 v[130:131], v[234:235], off offset:256
	global_load_dwordx2 v[132:133], v[234:235], off offset:512
	global_load_dwordx2 v[134:135], v[234:235], off offset:768
	global_load_dwordx2 v[136:137], v[234:235], off offset:2048
	global_load_dwordx2 v[138:139], v[234:235], off offset:2304
	global_load_dwordx2 v[140:141], v[234:235], off offset:2560
	global_load_dwordx2 v[142:143], v[234:235], off offset:2816
	v_add_co_u32_e32 v236, vcc, 0x1000, v234
	s_nop 1
	v_addc_co_u32_e32 v237, vcc, 0, v235, vcc
	global_load_dwordx2 v[144:145], v[236:237], off
	global_load_dwordx2 v[146:147], v[236:237], off offset:256
	global_load_dwordx2 v[148:149], v[236:237], off offset:512
	global_load_dwordx2 v[150:151], v[236:237], off offset:768
	global_load_dwordx2 v[152:153], v[236:237], off offset:2048
	global_load_dwordx2 v[154:155], v[236:237], off offset:2304
	global_load_dwordx2 v[156:157], v[236:237], off offset:2560
	global_load_dwordx2 v[158:159], v[236:237], off offset:2816
	s_waitcnt vmcnt(15)
	v_mul_f32_e32 v228, v96, v129
	v_mul_f32_e32 v229, v112, v129
	v_fma_f32 v228, v112, v128, -v228
	v_fma_f32 v229, v96, v128, v229
	v_mul_f32_e32 v228, s88, v228
	v_mul_f32_e32 v229, s88, v229
	v_cvt_pk_bf16_f32 v228, v228, v229
	ds_write_b16 v205, v228
	ds_write_b16_d16_hi v205, v228 offset:64
	s_waitcnt vmcnt(14)
	v_mul_f32_e32 v228, v97, v131
	v_mul_f32_e32 v229, v113, v131
	v_fma_f32 v228, v113, v130, -v228
	v_fma_f32 v229, v97, v130, v229
	v_mul_f32_e32 v228, s88, v228
	v_mul_f32_e32 v229, s88, v229
	v_cvt_pk_bf16_f32 v228, v228, v229
	ds_write_b16 v205, v228 offset:144
	ds_write_b16_d16_hi v205, v228 offset:208
	s_waitcnt vmcnt(13)
	v_mul_f32_e32 v228, v98, v133
	v_mul_f32_e32 v229, v114, v133
	v_fma_f32 v228, v114, v132, -v228
	v_fma_f32 v229, v98, v132, v229
	v_mul_f32_e32 v228, s88, v228
	v_mul_f32_e32 v229, s88, v229
	v_cvt_pk_bf16_f32 v228, v228, v229
	ds_write_b16 v205, v228 offset:288
	ds_write_b16_d16_hi v205, v228 offset:352
	s_waitcnt vmcnt(12)
	v_mul_f32_e32 v228, v99, v135
	v_mul_f32_e32 v229, v115, v135
	v_fma_f32 v228, v115, v134, -v228
	v_fma_f32 v229, v99, v134, v229
	v_mul_f32_e32 v228, s88, v228
	v_mul_f32_e32 v229, s88, v229
	v_cvt_pk_bf16_f32 v228, v228, v229
	ds_write_b16 v205, v228 offset:432
	ds_write_b16_d16_hi v205, v228 offset:496
	s_waitcnt vmcnt(11)
	v_mul_f32_e32 v228, v100, v137
	v_mul_f32_e32 v229, v116, v137
	v_fma_f32 v228, v116, v136, -v228
	v_fma_f32 v229, v100, v136, v229
	v_mul_f32_e32 v228, s88, v228
	v_mul_f32_e32 v229, s88, v229
	v_cvt_pk_bf16_f32 v228, v228, v229
	ds_write_b16 v205, v228 offset:1152
	ds_write_b16_d16_hi v205, v228 offset:1216
	s_waitcnt vmcnt(10)
	v_mul_f32_e32 v228, v101, v139
	v_mul_f32_e32 v229, v117, v139
	v_fma_f32 v228, v117, v138, -v228
	v_fma_f32 v229, v101, v138, v229
	v_mul_f32_e32 v228, s88, v228
	v_mul_f32_e32 v229, s88, v229
	v_cvt_pk_bf16_f32 v228, v228, v229
	ds_write_b16 v205, v228 offset:1296
	ds_write_b16_d16_hi v205, v228 offset:1360
	s_waitcnt vmcnt(9)
	v_mul_f32_e32 v228, v102, v141
	v_mul_f32_e32 v229, v118, v141
	v_fma_f32 v228, v118, v140, -v228
	v_fma_f32 v229, v102, v140, v229
	v_mul_f32_e32 v228, s88, v228
	v_mul_f32_e32 v229, s88, v229
	v_cvt_pk_bf16_f32 v228, v228, v229
	ds_write_b16 v205, v228 offset:1440
	ds_write_b16_d16_hi v205, v228 offset:1504
	s_waitcnt vmcnt(8)
	v_mul_f32_e32 v228, v103, v143
	v_mul_f32_e32 v229, v119, v143
	v_fma_f32 v228, v119, v142, -v228
	v_fma_f32 v229, v103, v142, v229
	v_mul_f32_e32 v228, s88, v228
	v_mul_f32_e32 v229, s88, v229
	v_cvt_pk_bf16_f32 v228, v228, v229
	ds_write_b16 v205, v228 offset:1584
	ds_write_b16_d16_hi v205, v228 offset:1648
	s_waitcnt vmcnt(7)
	v_mul_f32_e32 v228, v104, v145
	v_mul_f32_e32 v229, v120, v145
	v_fma_f32 v228, v120, v144, -v228
	v_fma_f32 v229, v104, v144, v229
	v_mul_f32_e32 v228, s88, v228
	v_mul_f32_e32 v229, s88, v229
	v_cvt_pk_bf16_f32 v228, v228, v229
	ds_write_b16 v205, v228 offset:2304
	ds_write_b16_d16_hi v205, v228 offset:2368
	s_waitcnt vmcnt(6)
	v_mul_f32_e32 v228, v105, v147
	v_mul_f32_e32 v229, v121, v147
	v_fma_f32 v228, v121, v146, -v228
	v_fma_f32 v229, v105, v146, v229
	v_mul_f32_e32 v228, s88, v228
	v_mul_f32_e32 v229, s88, v229
	v_cvt_pk_bf16_f32 v228, v228, v229
	ds_write_b16 v205, v228 offset:2448
	ds_write_b16_d16_hi v205, v228 offset:2512
	s_waitcnt vmcnt(5)
	v_mul_f32_e32 v228, v106, v149
	v_mul_f32_e32 v229, v122, v149
	v_fma_f32 v228, v122, v148, -v228
	v_fma_f32 v229, v106, v148, v229
	v_mul_f32_e32 v228, s88, v228
	v_mul_f32_e32 v229, s88, v229
	v_cvt_pk_bf16_f32 v228, v228, v229
	ds_write_b16 v205, v228 offset:2592
	ds_write_b16_d16_hi v205, v228 offset:2656
	s_waitcnt vmcnt(4)
	v_mul_f32_e32 v228, v107, v151
	v_mul_f32_e32 v229, v123, v151
	v_fma_f32 v228, v123, v150, -v228
	v_fma_f32 v229, v107, v150, v229
	v_mul_f32_e32 v228, s88, v228
	v_mul_f32_e32 v229, s88, v229
	v_cvt_pk_bf16_f32 v228, v228, v229
	ds_write_b16 v205, v228 offset:2736
	ds_write_b16_d16_hi v205, v228 offset:2800
	s_waitcnt vmcnt(3)
	v_mul_f32_e32 v228, v108, v153
	v_mul_f32_e32 v229, v124, v153
	v_fma_f32 v228, v124, v152, -v228
	v_fma_f32 v229, v108, v152, v229
	v_mul_f32_e32 v228, s88, v228
	v_mul_f32_e32 v229, s88, v229
	v_cvt_pk_bf16_f32 v228, v228, v229
	ds_write_b16 v205, v228 offset:3456
	ds_write_b16_d16_hi v205, v228 offset:3520
	s_waitcnt vmcnt(2)
	v_mul_f32_e32 v228, v109, v155
	v_mul_f32_e32 v229, v125, v155
	v_fma_f32 v228, v125, v154, -v228
	v_fma_f32 v229, v109, v154, v229
	v_mul_f32_e32 v228, s88, v228
	v_mul_f32_e32 v229, s88, v229
	v_cvt_pk_bf16_f32 v228, v228, v229
	ds_write_b16 v205, v228 offset:3600
	ds_write_b16_d16_hi v205, v228 offset:3664
	s_waitcnt vmcnt(1)
	v_mul_f32_e32 v228, v110, v157
	v_mul_f32_e32 v229, v126, v157
	v_fma_f32 v228, v126, v156, -v228
	v_fma_f32 v229, v110, v156, v229
	v_mul_f32_e32 v228, s88, v228
	v_mul_f32_e32 v229, s88, v229
	v_cvt_pk_bf16_f32 v228, v228, v229
	ds_write_b16 v205, v228 offset:3744
	ds_write_b16_d16_hi v205, v228 offset:3808
	s_waitcnt vmcnt(0)
	v_mul_f32_e32 v228, v111, v159
	v_mul_f32_e32 v229, v127, v159
	v_fma_f32 v228, v127, v158, -v228
	v_fma_f32 v229, v111, v158, v229
	v_mul_f32_e32 v228, s88, v228
	v_mul_f32_e32 v229, s88, v229
	v_cvt_pk_bf16_f32 v228, v228, v229
	ds_write_b16 v205, v228 offset:3888
	ds_write_b16_d16_hi v205, v228 offset:3952
	s_branch .Lep0_00_stb
.Lep0_00_mS:
	v_mul_f32_e32 v228, 0xbfb8aa3b, v112
	v_mul_f32_e32 v229, 0xbfb8aa3b, v96
	v_exp_f32_e32 v228, v228
	v_exp_f32_e32 v229, v229
	v_add_f32_e32 v228, 1.0, v228
	v_add_f32_e32 v229, 1.0, v229
	v_rcp_f32_e32 v228, v228
	v_rcp_f32_e32 v229, v229
	v_mul_f32_e32 v228, v112, v228
	v_mul_f32_e32 v229, v96, v229
	v_cvt_pk_bf16_f32 v228, v228, v229
	ds_write_b16 v205, v228
	ds_write_b16_d16_hi v205, v228 offset:64
	v_mul_f32_e32 v230, 0xbfb8aa3b, v113
	v_mul_f32_e32 v231, 0xbfb8aa3b, v97
	v_exp_f32_e32 v230, v230
	v_exp_f32_e32 v231, v231
	v_add_f32_e32 v230, 1.0, v230
	v_add_f32_e32 v231, 1.0, v231
	v_rcp_f32_e32 v230, v230
	v_rcp_f32_e32 v231, v231
	v_mul_f32_e32 v230, v113, v230
	v_mul_f32_e32 v231, v97, v231
	v_cvt_pk_bf16_f32 v230, v230, v231
	ds_write_b16 v205, v230 offset:144
	ds_write_b16_d16_hi v205, v230 offset:208
	v_mul_f32_e32 v228, 0xbfb8aa3b, v114
	v_mul_f32_e32 v229, 0xbfb8aa3b, v98
	v_exp_f32_e32 v228, v228
	v_exp_f32_e32 v229, v229
	v_add_f32_e32 v228, 1.0, v228
	v_add_f32_e32 v229, 1.0, v229
	v_rcp_f32_e32 v228, v228
	v_rcp_f32_e32 v229, v229
	v_mul_f32_e32 v228, v114, v228
	v_mul_f32_e32 v229, v98, v229
	v_cvt_pk_bf16_f32 v228, v228, v229
	ds_write_b16 v205, v228 offset:288
	ds_write_b16_d16_hi v205, v228 offset:352
	v_mul_f32_e32 v230, 0xbfb8aa3b, v115
	v_mul_f32_e32 v231, 0xbfb8aa3b, v99
	v_exp_f32_e32 v230, v230
	v_exp_f32_e32 v231, v231
	v_add_f32_e32 v230, 1.0, v230
	v_add_f32_e32 v231, 1.0, v231
	v_rcp_f32_e32 v230, v230
	v_rcp_f32_e32 v231, v231
	v_mul_f32_e32 v230, v115, v230
	v_mul_f32_e32 v231, v99, v231
	v_cvt_pk_bf16_f32 v230, v230, v231
	ds_write_b16 v205, v230 offset:432
	ds_write_b16_d16_hi v205, v230 offset:496
	v_mul_f32_e32 v228, 0xbfb8aa3b, v116
	v_mul_f32_e32 v229, 0xbfb8aa3b, v100
	v_exp_f32_e32 v228, v228
	v_exp_f32_e32 v229, v229
	v_add_f32_e32 v228, 1.0, v228
	v_add_f32_e32 v229, 1.0, v229
	v_rcp_f32_e32 v228, v228
	v_rcp_f32_e32 v229, v229
	v_mul_f32_e32 v228, v116, v228
	v_mul_f32_e32 v229, v100, v229
	v_cvt_pk_bf16_f32 v228, v228, v229
	ds_write_b16 v205, v228 offset:1152
	ds_write_b16_d16_hi v205, v228 offset:1216
	v_mul_f32_e32 v230, 0xbfb8aa3b, v117
	v_mul_f32_e32 v231, 0xbfb8aa3b, v101
	v_exp_f32_e32 v230, v230
	v_exp_f32_e32 v231, v231
	v_add_f32_e32 v230, 1.0, v230
	v_add_f32_e32 v231, 1.0, v231
	v_rcp_f32_e32 v230, v230
	v_rcp_f32_e32 v231, v231
	v_mul_f32_e32 v230, v117, v230
	v_mul_f32_e32 v231, v101, v231
	v_cvt_pk_bf16_f32 v230, v230, v231
	ds_write_b16 v205, v230 offset:1296
	ds_write_b16_d16_hi v205, v230 offset:1360
	v_mul_f32_e32 v228, 0xbfb8aa3b, v118
	v_mul_f32_e32 v229, 0xbfb8aa3b, v102
	v_exp_f32_e32 v228, v228
	v_exp_f32_e32 v229, v229
	v_add_f32_e32 v228, 1.0, v228
	v_add_f32_e32 v229, 1.0, v229
	v_rcp_f32_e32 v228, v228
	v_rcp_f32_e32 v229, v229
	v_mul_f32_e32 v228, v118, v228
	v_mul_f32_e32 v229, v102, v229
	v_cvt_pk_bf16_f32 v228, v228, v229
	ds_write_b16 v205, v228 offset:1440
	ds_write_b16_d16_hi v205, v228 offset:1504
	v_mul_f32_e32 v230, 0xbfb8aa3b, v119
	v_mul_f32_e32 v231, 0xbfb8aa3b, v103
	v_exp_f32_e32 v230, v230
	v_exp_f32_e32 v231, v231
	v_add_f32_e32 v230, 1.0, v230
	v_add_f32_e32 v231, 1.0, v231
	v_rcp_f32_e32 v230, v230
	v_rcp_f32_e32 v231, v231
	v_mul_f32_e32 v230, v119, v230
	v_mul_f32_e32 v231, v103, v231
	v_cvt_pk_bf16_f32 v230, v230, v231
	ds_write_b16 v205, v230 offset:1584
	ds_write_b16_d16_hi v205, v230 offset:1648
	v_mul_f32_e32 v228, 0xbfb8aa3b, v120
	v_mul_f32_e32 v229, 0xbfb8aa3b, v104
	v_exp_f32_e32 v228, v228
	v_exp_f32_e32 v229, v229
	v_add_f32_e32 v228, 1.0, v228
	v_add_f32_e32 v229, 1.0, v229
	v_rcp_f32_e32 v228, v228
	v_rcp_f32_e32 v229, v229
	v_mul_f32_e32 v228, v120, v228
	v_mul_f32_e32 v229, v104, v229
	v_cvt_pk_bf16_f32 v228, v228, v229
	ds_write_b16 v205, v228 offset:2304
	ds_write_b16_d16_hi v205, v228 offset:2368
	v_mul_f32_e32 v230, 0xbfb8aa3b, v121
	v_mul_f32_e32 v231, 0xbfb8aa3b, v105
	v_exp_f32_e32 v230, v230
	v_exp_f32_e32 v231, v231
	v_add_f32_e32 v230, 1.0, v230
	v_add_f32_e32 v231, 1.0, v231
	v_rcp_f32_e32 v230, v230
	v_rcp_f32_e32 v231, v231
	v_mul_f32_e32 v230, v121, v230
	v_mul_f32_e32 v231, v105, v231
	v_cvt_pk_bf16_f32 v230, v230, v231
	ds_write_b16 v205, v230 offset:2448
	ds_write_b16_d16_hi v205, v230 offset:2512
	v_mul_f32_e32 v228, 0xbfb8aa3b, v122
	v_mul_f32_e32 v229, 0xbfb8aa3b, v106
	v_exp_f32_e32 v228, v228
	v_exp_f32_e32 v229, v229
	v_add_f32_e32 v228, 1.0, v228
	v_add_f32_e32 v229, 1.0, v229
	v_rcp_f32_e32 v228, v228
	v_rcp_f32_e32 v229, v229
	v_mul_f32_e32 v228, v122, v228
	v_mul_f32_e32 v229, v106, v229
	v_cvt_pk_bf16_f32 v228, v228, v229
	ds_write_b16 v205, v228 offset:2592
	ds_write_b16_d16_hi v205, v228 offset:2656
	v_mul_f32_e32 v230, 0xbfb8aa3b, v123
	v_mul_f32_e32 v231, 0xbfb8aa3b, v107
	v_exp_f32_e32 v230, v230
	v_exp_f32_e32 v231, v231
	v_add_f32_e32 v230, 1.0, v230
	v_add_f32_e32 v231, 1.0, v231
	v_rcp_f32_e32 v230, v230
	v_rcp_f32_e32 v231, v231
	v_mul_f32_e32 v230, v123, v230
	v_mul_f32_e32 v231, v107, v231
	v_cvt_pk_bf16_f32 v230, v230, v231
	ds_write_b16 v205, v230 offset:2736
	ds_write_b16_d16_hi v205, v230 offset:2800
	v_mul_f32_e32 v228, 0xbfb8aa3b, v124
	v_mul_f32_e32 v229, 0xbfb8aa3b, v108
	v_exp_f32_e32 v228, v228
	v_exp_f32_e32 v229, v229
	v_add_f32_e32 v228, 1.0, v228
	v_add_f32_e32 v229, 1.0, v229
	v_rcp_f32_e32 v228, v228
	v_rcp_f32_e32 v229, v229
	v_mul_f32_e32 v228, v124, v228
	v_mul_f32_e32 v229, v108, v229
	v_cvt_pk_bf16_f32 v228, v228, v229
	ds_write_b16 v205, v228 offset:3456
	ds_write_b16_d16_hi v205, v228 offset:3520
	v_mul_f32_e32 v230, 0xbfb8aa3b, v125
	v_mul_f32_e32 v231, 0xbfb8aa3b, v109
	v_exp_f32_e32 v230, v230
	v_exp_f32_e32 v231, v231
	v_add_f32_e32 v230, 1.0, v230
	v_add_f32_e32 v231, 1.0, v231
	v_rcp_f32_e32 v230, v230
	v_rcp_f32_e32 v231, v231
	v_mul_f32_e32 v230, v125, v230
	v_mul_f32_e32 v231, v109, v231
	v_cvt_pk_bf16_f32 v230, v230, v231
	ds_write_b16 v205, v230 offset:3600
	ds_write_b16_d16_hi v205, v230 offset:3664
	v_mul_f32_e32 v228, 0xbfb8aa3b, v126
	v_mul_f32_e32 v229, 0xbfb8aa3b, v110
	v_exp_f32_e32 v228, v228
	v_exp_f32_e32 v229, v229
	v_add_f32_e32 v228, 1.0, v228
	v_add_f32_e32 v229, 1.0, v229
	v_rcp_f32_e32 v228, v228
	v_rcp_f32_e32 v229, v229
	v_mul_f32_e32 v228, v126, v228
	v_mul_f32_e32 v229, v110, v229
	v_cvt_pk_bf16_f32 v228, v228, v229
	ds_write_b16 v205, v228 offset:3744
	ds_write_b16_d16_hi v205, v228 offset:3808
	v_mul_f32_e32 v230, 0xbfb8aa3b, v127
	v_mul_f32_e32 v231, 0xbfb8aa3b, v111
	v_exp_f32_e32 v230, v230
	v_exp_f32_e32 v231, v231
	v_add_f32_e32 v230, 1.0, v230
	v_add_f32_e32 v231, 1.0, v231
	v_rcp_f32_e32 v230, v230
	v_rcp_f32_e32 v231, v231
	v_mul_f32_e32 v230, v127, v230
	v_mul_f32_e32 v231, v111, v231
	v_cvt_pk_bf16_f32 v230, v230, v231
	ds_write_b16 v205, v230 offset:3888
	ds_write_b16_d16_hi v205, v230 offset:3952
	s_branch .Lep0_00_st
.Lep0_00_stq:
	v_add_u32_e32 v232, s94, v226
	s_waitcnt lgkmcnt(0)
	ds_read_b128 v[206:209], v224
	ds_read_b128 v[212:215], v224 offset:1152
	ds_read_b128 v[216:219], v224 offset:2304
	ds_read_b128 v[220:223], v224 offset:3456
	v_add_u32_e32 v228, 0, v232
	v_mul_lo_u32 v228, v228, s89
	v_add3_u32 v228, v228, v227, s91
	v_add_u32_e32 v229, 8, v232
	v_mul_lo_u32 v229, v229, s89
	v_add3_u32 v229, v229, v227, s91
	v_add_u32_e32 v230, 16, v232
	v_mul_lo_u32 v230, v230, s89
	v_add3_u32 v230, v230, v227, s91
	v_add_u32_e32 v231, 24, v232
	v_mul_lo_u32 v231, v231, s89
	v_add3_u32 v231, v231, v227, s91
	s_waitcnt lgkmcnt(3)
	global_store_dwordx4 v228, v[206:209], s[96:97]
	s_waitcnt lgkmcnt(2)
	global_store_dwordx4 v229, v[212:215], s[96:97]
	s_waitcnt lgkmcnt(1)
	global_store_dwordx4 v230, v[216:219], s[96:97]
	s_waitcnt lgkmcnt(0)
	global_store_dwordx4 v231, v[220:223], s[96:97]
	v_lshlrev_b32_e32 v132, 16, v206
	v_and_b32_e32 v133, 0xffff0000, v206
	v_mul_f32_e32 v128, v132, v132
	v_fma_f32 v128, v133, v133, v128
	v_lshlrev_b32_e32 v132, 16, v207
	v_and_b32_e32 v133, 0xffff0000, v207
	v_fma_f32 v128, v132, v132, v128
	v_fma_f32 v128, v133, v133, v128
	v_lshlrev_b32_e32 v132, 16, v208
	v_and_b32_e32 v133, 0xffff0000, v208
	v_fma_f32 v128, v132, v132, v128
	v_fma_f32 v128, v133, v133, v128
	v_lshlrev_b32_e32 v132, 16, v209
	v_and_b32_e32 v133, 0xffff0000, v209
	v_fma_f32 v128, v132, v132, v128
	v_fma_f32 v128, v133, v133, v128
	v_lshlrev_b32_e32 v132, 16, v212
	v_and_b32_e32 v133, 0xffff0000, v212
	v_mul_f32_e32 v129, v132, v132
	v_fma_f32 v129, v133, v133, v129
	v_lshlrev_b32_e32 v132, 16, v213
	v_and_b32_e32 v133, 0xffff0000, v213
	v_fma_f32 v129, v132, v132, v129
	v_fma_f32 v129, v133, v133, v129
	v_lshlrev_b32_e32 v132, 16, v214
	v_and_b32_e32 v133, 0xffff0000, v214
	v_fma_f32 v129, v132, v132, v129
	v_fma_f32 v129, v133, v133, v129
	v_lshlrev_b32_e32 v132, 16, v215
	v_and_b32_e32 v133, 0xffff0000, v215
	v_fma_f32 v129, v132, v132, v129
	v_fma_f32 v129, v133, v133, v129
	v_lshlrev_b32_e32 v132, 16, v216
	v_and_b32_e32 v133, 0xffff0000, v216
	v_mul_f32_e32 v130, v132, v132
	v_fma_f32 v130, v133, v133, v130
	v_lshlrev_b32_e32 v132, 16, v217
	v_and_b32_e32 v133, 0xffff0000, v217
	v_fma_f32 v130, v132, v132, v130
	v_fma_f32 v130, v133, v133, v130
	v_lshlrev_b32_e32 v132, 16, v218
	v_and_b32_e32 v133, 0xffff0000, v218
	v_fma_f32 v130, v132, v132, v130
	v_fma_f32 v130, v133, v133, v130
	v_lshlrev_b32_e32 v132, 16, v219
	v_and_b32_e32 v133, 0xffff0000, v219
	v_fma_f32 v130, v132, v132, v130
	v_fma_f32 v130, v133, v133, v130
	v_lshlrev_b32_e32 v132, 16, v220
	v_and_b32_e32 v133, 0xffff0000, v220
	v_mul_f32_e32 v131, v132, v132
	v_fma_f32 v131, v133, v133, v131
	v_lshlrev_b32_e32 v132, 16, v221
	v_and_b32_e32 v133, 0xffff0000, v221
	v_fma_f32 v131, v132, v132, v131
	v_fma_f32 v131, v133, v133, v131
	v_lshlrev_b32_e32 v132, 16, v222
	v_and_b32_e32 v133, 0xffff0000, v222
	v_fma_f32 v131, v132, v132, v131
	v_fma_f32 v131, v133, v133, v131
	v_lshlrev_b32_e32 v132, 16, v223
	v_and_b32_e32 v133, 0xffff0000, v223
	v_fma_f32 v131, v132, v132, v131
	v_fma_f32 v131, v133, v133, v131
	s_nop 1
	v_add_f32_dpp v136, v128, v128 quad_perm:[1,0,3,2] row_mask:0xf bank_mask:0xf
	v_add_f32_dpp v137, v129, v129 quad_perm:[1,0,3,2] row_mask:0xf bank_mask:0xf
	v_add_f32_dpp v138, v130, v130 quad_perm:[1,0,3,2] row_mask:0xf bank_mask:0xf
	v_add_f32_dpp v139, v131, v131 quad_perm:[1,0,3,2] row_mask:0xf bank_mask:0xf
	v_add_f32_dpp v128, v136, v136 quad_perm:[2,3,0,1] row_mask:0xf bank_mask:0xf
	v_add_f32_dpp v129, v137, v137 quad_perm:[2,3,0,1] row_mask:0xf bank_mask:0xf
	v_add_f32_dpp v130, v138, v138 quad_perm:[2,3,0,1] row_mask:0xf bank_mask:0xf
	v_add_f32_dpp v131, v139, v139 quad_perm:[2,3,0,1] row_mask:0xf bank_mask:0xf
	v_add_f32_dpp v234, v128, v128 row_half_mirror row_mask:0xf bank_mask:0xf
	v_add_f32_dpp v235, v129, v129 row_half_mirror row_mask:0xf bank_mask:0xf
	v_add_f32_dpp v236, v130, v130 row_half_mirror row_mask:0xf bank_mask:0xf
	v_add_f32_dpp v237, v131, v131 row_half_mirror row_mask:0xf bank_mask:0xf
	s_branch .Lep0_00_end
.Lep0_00_stb:
	v_add_u32_e32 v232, s94, v226
	s_waitcnt lgkmcnt(0)
	ds_read_b128 v[206:209], v224
	ds_read_b128 v[212:215], v224 offset:1152
	ds_read_b128 v[216:219], v224 offset:2304
	ds_read_b128 v[220:223], v224 offset:3456
	s_mov_b32 s88, 0xc00000
	s_mov_b32 s89, 0x180
	v_add_u32_e32 v228, 0, v232
	v_lshrrev_b32_e32 v128, 12, v228
	v_and_b32_e32 v228, 0xfff, v228
	v_mul_lo_u32 v128, v128, s88
	v_mul_lo_u32 v228, v228, s89
	v_add3_u32 v228, v228, v128, v227
	v_add_u32_e32 v229, 8, v232
	v_lshrrev_b32_e32 v129, 12, v229
	v_and_b32_e32 v229, 0xfff, v229
	v_mul_lo_u32 v129, v129, s88
	v_mul_lo_u32 v229, v229, s89
	v_add3_u32 v229, v229, v129, v227
	v_add_u32_e32 v230, 16, v232
	v_lshrrev_b32_e32 v130, 12, v230
	v_and_b32_e32 v230, 0xfff, v230
	v_mul_lo_u32 v130, v130, s88
	v_mul_lo_u32 v230, v230, s89
	v_add3_u32 v230, v230, v130, v227
	v_add_u32_e32 v231, 24, v232
	v_lshrrev_b32_e32 v131, 12, v231
	v_and_b32_e32 v231, 0xfff, v231
	v_mul_lo_u32 v131, v131, s88
	v_mul_lo_u32 v231, v231, s89
	v_add3_u32 v231, v231, v131, v227
	s_waitcnt lgkmcnt(3)
	global_store_dwordx4 v228, v[206:209], s[96:97] offset:256
	v_add_u32_e32 v228, 0x180000, v228
	s_waitcnt lgkmcnt(2)
	global_store_dwordx4 v229, v[212:215], s[96:97] offset:256
	v_add_u32_e32 v229, 0x180000, v229
	s_waitcnt lgkmcnt(1)
	global_store_dwordx4 v230, v[216:219], s[96:97] offset:256
	v_add_u32_e32 v230, 0x180000, v230
	s_waitcnt lgkmcnt(0)
	global_store_dwordx4 v231, v[220:223], s[96:97] offset:256
	v_add_u32_e32 v231, 0x180000, v231
	global_store_dwordx4 v228, v[206:209], s[96:97] offset:256
	v_add_u32_e32 v228, 0x180000, v228
	global_store_dwordx4 v229, v[212:215], s[96:97] offset:256
	v_add_u32_e32 v229, 0x180000, v229
	global_store_dwordx4 v230, v[216:219], s[96:97] offset:256
	v_add_u32_e32 v230, 0x180000, v230
	global_store_dwordx4 v231, v[220:223], s[96:97] offset:256
	v_add_u32_e32 v231, 0x180000, v231
	global_store_dwordx4 v228, v[206:209], s[96:97] offset:256
	v_add_u32_e32 v228, 0x180000, v228
	global_store_dwordx4 v229, v[212:215], s[96:97] offset:256
	v_add_u32_e32 v229, 0x180000, v229
	global_store_dwordx4 v230, v[216:219], s[96:97] offset:256
	v_add_u32_e32 v230, 0x180000, v230
	global_store_dwordx4 v231, v[220:223], s[96:97] offset:256
	v_add_u32_e32 v231, 0x180000, v231
	global_store_dwordx4 v228, v[206:209], s[96:97] offset:256
	v_add_u32_e32 v228, 0x180000, v228
	global_store_dwordx4 v229, v[212:215], s[96:97] offset:256
	v_add_u32_e32 v229, 0x180000, v229
	global_store_dwordx4 v230, v[216:219], s[96:97] offset:256
	v_add_u32_e32 v230, 0x180000, v230
	global_store_dwordx4 v231, v[220:223], s[96:97] offset:256
	v_add_u32_e32 v231, 0x180000, v231
	global_store_dwordx4 v228, v[206:209], s[96:97] offset:256
	v_add_u32_e32 v228, 0x180000, v228
	global_store_dwordx4 v229, v[212:215], s[96:97] offset:256
	v_add_u32_e32 v229, 0x180000, v229
	global_store_dwordx4 v230, v[216:219], s[96:97] offset:256
	v_add_u32_e32 v230, 0x180000, v230
	global_store_dwordx4 v231, v[220:223], s[96:97] offset:256
	v_add_u32_e32 v231, 0x180000, v231
	global_store_dwordx4 v228, v[206:209], s[96:97] offset:256
	v_add_u32_e32 v228, 0x180000, v228
	global_store_dwordx4 v229, v[212:215], s[96:97] offset:256
	v_add_u32_e32 v229, 0x180000, v229
	global_store_dwordx4 v230, v[216:219], s[96:97] offset:256
	v_add_u32_e32 v230, 0x180000, v230
	global_store_dwordx4 v231, v[220:223], s[96:97] offset:256
	v_add_u32_e32 v231, 0x180000, v231
	global_store_dwordx4 v228, v[206:209], s[96:97] offset:256
	v_add_u32_e32 v228, 0x180000, v228
	global_store_dwordx4 v229, v[212:215], s[96:97] offset:256
	v_add_u32_e32 v229, 0x180000, v229
	global_store_dwordx4 v230, v[216:219], s[96:97] offset:256
	v_add_u32_e32 v230, 0x180000, v230
	global_store_dwordx4 v231, v[220:223], s[96:97] offset:256
	v_add_u32_e32 v231, 0x180000, v231
	global_store_dwordx4 v228, v[206:209], s[96:97] offset:256
	global_store_dwordx4 v229, v[212:215], s[96:97] offset:256
	global_store_dwordx4 v230, v[216:219], s[96:97] offset:256
	global_store_dwordx4 v231, v[220:223], s[96:97] offset:256
	s_branch .Lep0_00_end
.Lep0_00_st:
	v_add_u32_e32 v232, s94, v226
	s_waitcnt lgkmcnt(0)
	ds_read_b128 v[206:209], v224
	ds_read_b128 v[212:215], v224 offset:1152
	ds_read_b128 v[216:219], v224 offset:2304
	ds_read_b128 v[220:223], v224 offset:3456
	v_add_u32_e32 v228, 0, v232
	v_mul_lo_u32 v228, v228, s89
	v_add3_u32 v228, v228, v227, s91
	v_add_u32_e32 v229, 8, v232
	v_mul_lo_u32 v229, v229, s89
	v_add3_u32 v229, v229, v227, s91
	v_add_u32_e32 v230, 16, v232
	v_mul_lo_u32 v230, v230, s89
	v_add3_u32 v230, v230, v227, s91
	v_add_u32_e32 v231, 24, v232
	v_mul_lo_u32 v231, v231, s89
	v_add3_u32 v231, v231, v227, s91
	s_waitcnt lgkmcnt(3)
	global_store_dwordx4 v228, v[206:209], s[96:97]
	s_waitcnt lgkmcnt(2)
	global_store_dwordx4 v229, v[212:215], s[96:97]
	s_waitcnt lgkmcnt(1)
	global_store_dwordx4 v230, v[216:219], s[96:97]
	s_waitcnt lgkmcnt(0)
	global_store_dwordx4 v231, v[220:223], s[96:97]

.Lep0_01_mP:
	v_cvt_pk_bf16_f32 v228, v80, v64
	ds_write_b16 v205, v228
	ds_write_b16_d16_hi v205, v228 offset:64
	v_cvt_pk_bf16_f32 v229, v81, v65
	ds_write_b16 v205, v229 offset:144
	ds_write_b16_d16_hi v205, v229 offset:208
	v_cvt_pk_bf16_f32 v230, v82, v66
	ds_write_b16 v205, v230 offset:288
	ds_write_b16_d16_hi v205, v230 offset:352
	v_cvt_pk_bf16_f32 v231, v83, v67
	ds_write_b16 v205, v231 offset:432
	ds_write_b16_d16_hi v205, v231 offset:496
	v_cvt_pk_bf16_f32 v228, v84, v68
	ds_write_b16 v205, v228 offset:1152
	ds_write_b16_d16_hi v205, v228 offset:1216
	v_cvt_pk_bf16_f32 v229, v85, v69
	ds_write_b16 v205, v229 offset:1296
	ds_write_b16_d16_hi v205, v229 offset:1360
	v_cvt_pk_bf16_f32 v230, v86, v70
	ds_write_b16 v205, v230 offset:1440
	ds_write_b16_d16_hi v205, v230 offset:1504
	v_cvt_pk_bf16_f32 v231, v87, v71
	ds_write_b16 v205, v231 offset:1584
	ds_write_b16_d16_hi v205, v231 offset:1648
	v_cvt_pk_bf16_f32 v228, v88, v72
	ds_write_b16 v205, v228 offset:2304
	ds_write_b16_d16_hi v205, v228 offset:2368
	v_cvt_pk_bf16_f32 v229, v89, v73
	ds_write_b16 v205, v229 offset:2448
	ds_write_b16_d16_hi v205, v229 offset:2512
	v_cvt_pk_bf16_f32 v230, v90, v74
	ds_write_b16 v205, v230 offset:2592
	ds_write_b16_d16_hi v205, v230 offset:2656
	v_cvt_pk_bf16_f32 v231, v91, v75
	ds_write_b16 v205, v231 offset:2736
	ds_write_b16_d16_hi v205, v231 offset:2800
	v_cvt_pk_bf16_f32 v228, v92, v76
	ds_write_b16 v205, v228 offset:3456
	ds_write_b16_d16_hi v205, v228 offset:3520
	v_cvt_pk_bf16_f32 v229, v93, v77
	ds_write_b16 v205, v229 offset:3600
	ds_write_b16_d16_hi v205, v229 offset:3664
	v_cvt_pk_bf16_f32 v230, v94, v78
	ds_write_b16 v205, v230 offset:3744
	ds_write_b16_d16_hi v205, v230 offset:3808
	v_cvt_pk_bf16_f32 v231, v95, v79
	ds_write_b16 v205, v231 offset:3888
	ds_write_b16_d16_hi v205, v231 offset:3952
	s_branch .Lep0_01_stq
.Lep0_01_mR:
	s_load_dwordx2 s[98:99], s[0:1], 0x148
	v_add_u32_e32 v228, s94, v225
	v_lshlrev_b32_e32 v228, 8, v228
	v_add_u32_e32 v234, v228, v160
	v_mov_b32_e32 v235, 0
	s_waitcnt lgkmcnt(0)
	v_lshl_add_u64 v[234:235], s[98:99], 0, v[234:235]
	global_load_dwordx2 v[128:129], v[234:235], off
	global_load_dwordx2 v[130:131], v[234:235], off offset:256
	global_load_dwordx2 v[132:133], v[234:235], off offset:512
	global_load_dwordx2 v[134:135], v[234:235], off offset:768
	global_load_dwordx2 v[136:137], v[234:235], off offset:2048
	global_load_dwordx2 v[138:139], v[234:235], off offset:2304
	global_load_dwordx2 v[140:141], v[234:235], off offset:2560
	global_load_dwordx2 v[142:143], v[234:235], off offset:2816
	v_add_co_u32_e32 v236, vcc, 0x1000, v234
	s_nop 1
	v_addc_co_u32_e32 v237, vcc, 0, v235, vcc
	global_load_dwordx2 v[144:145], v[236:237], off
	global_load_dwordx2 v[146:147], v[236:237], off offset:256
	global_load_dwordx2 v[148:149], v[236:237], off offset:512
	global_load_dwordx2 v[150:151], v[236:237], off offset:768
	global_load_dwordx2 v[152:153], v[236:237], off offset:2048
	global_load_dwordx2 v[154:155], v[236:237], off offset:2304
	global_load_dwordx2 v[156:157], v[236:237], off offset:2560
	global_load_dwordx2 v[158:159], v[236:237], off offset:2816
	s_waitcnt vmcnt(15)
	v_mul_f32_e32 v228, v64, v129
	v_mul_f32_e32 v229, v80, v129
	v_fma_f32 v228, v80, v128, -v228
	v_fma_f32 v229, v64, v128, v229
	v_mul_f32_e32 v228, s88, v228
	v_mul_f32_e32 v229, s88, v229
	v_cvt_pk_bf16_f32 v228, v228, v229
	ds_write_b16 v205, v228
	ds_write_b16_d16_hi v205, v228 offset:64
	s_waitcnt vmcnt(14)
	v_mul_f32_e32 v228, v65, v131
	v_mul_f32_e32 v229, v81, v131
	v_fma_f32 v228, v81, v130, -v228
	v_fma_f32 v229, v65, v130, v229
	v_mul_f32_e32 v228, s88, v228
	v_mul_f32_e32 v229, s88, v229
	v_cvt_pk_bf16_f32 v228, v228, v229
	ds_write_b16 v205, v228 offset:144
	ds_write_b16_d16_hi v205, v228 offset:208
	s_waitcnt vmcnt(13)
	v_mul_f32_e32 v228, v66, v133
	v_mul_f32_e32 v229, v82, v133
	v_fma_f32 v228, v82, v132, -v228
	v_fma_f32 v229, v66, v132, v229
	v_mul_f32_e32 v228, s88, v228
	v_mul_f32_e32 v229, s88, v229
	v_cvt_pk_bf16_f32 v228, v228, v229
	ds_write_b16 v205, v228 offset:288
	ds_write_b16_d16_hi v205, v228 offset:352
	s_waitcnt vmcnt(12)
	v_mul_f32_e32 v228, v67, v135
	v_mul_f32_e32 v229, v83, v135
	v_fma_f32 v228, v83, v134, -v228
	v_fma_f32 v229, v67, v134, v229
	v_mul_f32_e32 v228, s88, v228
	v_mul_f32_e32 v229, s88, v229
	v_cvt_pk_bf16_f32 v228, v228, v229
	ds_write_b16 v205, v228 offset:432
	ds_write_b16_d16_hi v205, v228 offset:496
	s_waitcnt vmcnt(11)
	v_mul_f32_e32 v228, v68, v137
	v_mul_f32_e32 v229, v84, v137
	v_fma_f32 v228, v84, v136, -v228
	v_fma_f32 v229, v68, v136, v229
	v_mul_f32_e32 v228, s88, v228
	v_mul_f32_e32 v229, s88, v229
	v_cvt_pk_bf16_f32 v228, v228, v229
	ds_write_b16 v205, v228 offset:1152
	ds_write_b16_d16_hi v205, v228 offset:1216
	s_waitcnt vmcnt(10)
	v_mul_f32_e32 v228, v69, v139
	v_mul_f32_e32 v229, v85, v139
	v_fma_f32 v228, v85, v138, -v228
	v_fma_f32 v229, v69, v138, v229
	v_mul_f32_e32 v228, s88, v228
	v_mul_f32_e32 v229, s88, v229
	v_cvt_pk_bf16_f32 v228, v228, v229
	ds_write_b16 v205, v228 offset:1296
	ds_write_b16_d16_hi v205, v228 offset:1360
	s_waitcnt vmcnt(9)
	v_mul_f32_e32 v228, v70, v141
	v_mul_f32_e32 v229, v86, v141
	v_fma_f32 v228, v86, v140, -v228
	v_fma_f32 v229, v70, v140, v229
	v_mul_f32_e32 v228, s88, v228
	v_mul_f32_e32 v229, s88, v229
	v_cvt_pk_bf16_f32 v228, v228, v229
	ds_write_b16 v205, v228 offset:1440
	ds_write_b16_d16_hi v205, v228 offset:1504
	s_waitcnt vmcnt(8)
	v_mul_f32_e32 v228, v71, v143
	v_mul_f32_e32 v229, v87, v143
	v_fma_f32 v228, v87, v142, -v228
	v_fma_f32 v229, v71, v142, v229
	v_mul_f32_e32 v228, s88, v228
	v_mul_f32_e32 v229, s88, v229
	v_cvt_pk_bf16_f32 v228, v228, v229
	ds_write_b16 v205, v228 offset:1584
	ds_write_b16_d16_hi v205, v228 offset:1648
	s_waitcnt vmcnt(7)
	v_mul_f32_e32 v228, v72, v145
	v_mul_f32_e32 v229, v88, v145
	v_fma_f32 v228, v88, v144, -v228
	v_fma_f32 v229, v72, v144, v229
	v_mul_f32_e32 v228, s88, v228
	v_mul_f32_e32 v229, s88, v229
	v_cvt_pk_bf16_f32 v228, v228, v229
	ds_write_b16 v205, v228 offset:2304
	ds_write_b16_d16_hi v205, v228 offset:2368
	s_waitcnt vmcnt(6)
	v_mul_f32_e32 v228, v73, v147
	v_mul_f32_e32 v229, v89, v147
	v_fma_f32 v228, v89, v146, -v228
	v_fma_f32 v229, v73, v146, v229
	v_mul_f32_e32 v228, s88, v228
	v_mul_f32_e32 v229, s88, v229
	v_cvt_pk_bf16_f32 v228, v228, v229
	ds_write_b16 v205, v228 offset:2448
	ds_write_b16_d16_hi v205, v228 offset:2512
	s_waitcnt vmcnt(5)
	v_mul_f32_e32 v228, v74, v149
	v_mul_f32_e32 v229, v90, v149
	v_fma_f32 v228, v90, v148, -v228
	v_fma_f32 v229, v74, v148, v229
	v_mul_f32_e32 v228, s88, v228
	v_mul_f32_e32 v229, s88, v229
	v_cvt_pk_bf16_f32 v228, v228, v229
	ds_write_b16 v205, v228 offset:2592
	ds_write_b16_d16_hi v205, v228 offset:2656
	s_waitcnt vmcnt(4)
	v_mul_f32_e32 v228, v75, v151
	v_mul_f32_e32 v229, v91, v151
	v_fma_f32 v228, v91, v150, -v228
	v_fma_f32 v229, v75, v150, v229
	v_mul_f32_e32 v228, s88, v228
	v_mul_f32_e32 v229, s88, v229
	v_cvt_pk_bf16_f32 v228, v228, v229
	ds_write_b16 v205, v228 offset:2736
	ds_write_b16_d16_hi v205, v228 offset:2800
	s_waitcnt vmcnt(3)
	v_mul_f32_e32 v228, v76, v153
	v_mul_f32_e32 v229, v92, v153
	v_fma_f32 v228, v92, v152, -v228
	v_fma_f32 v229, v76, v152, v229
	v_mul_f32_e32 v228, s88, v228
	v_mul_f32_e32 v229, s88, v229
	v_cvt_pk_bf16_f32 v228, v228, v229
	ds_write_b16 v205, v228 offset:3456
	ds_write_b16_d16_hi v205, v228 offset:3520
	s_waitcnt vmcnt(2)
	v_mul_f32_e32 v228, v77, v155
	v_mul_f32_e32 v229, v93, v155
	v_fma_f32 v228, v93, v154, -v228
	v_fma_f32 v229, v77, v154, v229
	v_mul_f32_e32 v228, s88, v228
	v_mul_f32_e32 v229, s88, v229
	v_cvt_pk_bf16_f32 v228, v228, v229
	ds_write_b16 v205, v228 offset:3600
	ds_write_b16_d16_hi v205, v228 offset:3664
	s_waitcnt vmcnt(1)
	v_mul_f32_e32 v228, v78, v157
	v_mul_f32_e32 v229, v94, v157
	v_fma_f32 v228, v94, v156, -v228
	v_fma_f32 v229, v78, v156, v229
	v_mul_f32_e32 v228, s88, v228
	v_mul_f32_e32 v229, s88, v229
	v_cvt_pk_bf16_f32 v228, v228, v229
	ds_write_b16 v205, v228 offset:3744
	ds_write_b16_d16_hi v205, v228 offset:3808
	s_waitcnt vmcnt(0)
	v_mul_f32_e32 v228, v79, v159
	v_mul_f32_e32 v229, v95, v159
	v_fma_f32 v228, v95, v158, -v228
	v_fma_f32 v229, v79, v158, v229
	v_mul_f32_e32 v228, s88, v228
	v_mul_f32_e32 v229, s88, v229
	v_cvt_pk_bf16_f32 v228, v228, v229
	ds_write_b16 v205, v228 offset:3888
	ds_write_b16_d16_hi v205, v228 offset:3952
	s_branch .Lep0_01_stb
.Lep0_01_mS:
	v_mul_f32_e32 v228, 0xbfb8aa3b, v80
	v_mul_f32_e32 v229, 0xbfb8aa3b, v64
	v_exp_f32_e32 v228, v228
	v_exp_f32_e32 v229, v229
	v_add_f32_e32 v228, 1.0, v228
	v_add_f32_e32 v229, 1.0, v229
	v_rcp_f32_e32 v228, v228
	v_rcp_f32_e32 v229, v229
	v_mul_f32_e32 v228, v80, v228
	v_mul_f32_e32 v229, v64, v229
	v_cvt_pk_bf16_f32 v228, v228, v229
	ds_write_b16 v205, v228
	ds_write_b16_d16_hi v205, v228 offset:64
	v_mul_f32_e32 v230, 0xbfb8aa3b, v81
	v_mul_f32_e32 v231, 0xbfb8aa3b, v65
	v_exp_f32_e32 v230, v230
	v_exp_f32_e32 v231, v231
	v_add_f32_e32 v230, 1.0, v230
	v_add_f32_e32 v231, 1.0, v231
	v_rcp_f32_e32 v230, v230
	v_rcp_f32_e32 v231, v231
	v_mul_f32_e32 v230, v81, v230
	v_mul_f32_e32 v231, v65, v231
	v_cvt_pk_bf16_f32 v230, v230, v231
	ds_write_b16 v205, v230 offset:144
	ds_write_b16_d16_hi v205, v230 offset:208
	v_mul_f32_e32 v228, 0xbfb8aa3b, v82
	v_mul_f32_e32 v229, 0xbfb8aa3b, v66
	v_exp_f32_e32 v228, v228
	v_exp_f32_e32 v229, v229
	v_add_f32_e32 v228, 1.0, v228
	v_add_f32_e32 v229, 1.0, v229
	v_rcp_f32_e32 v228, v228
	v_rcp_f32_e32 v229, v229
	v_mul_f32_e32 v228, v82, v228
	v_mul_f32_e32 v229, v66, v229
	v_cvt_pk_bf16_f32 v228, v228, v229
	ds_write_b16 v205, v228 offset:288
	ds_write_b16_d16_hi v205, v228 offset:352
	v_mul_f32_e32 v230, 0xbfb8aa3b, v83
	v_mul_f32_e32 v231, 0xbfb8aa3b, v67
	v_exp_f32_e32 v230, v230
	v_exp_f32_e32 v231, v231
	v_add_f32_e32 v230, 1.0, v230
	v_add_f32_e32 v231, 1.0, v231
	v_rcp_f32_e32 v230, v230
	v_rcp_f32_e32 v231, v231
	v_mul_f32_e32 v230, v83, v230
	v_mul_f32_e32 v231, v67, v231
	v_cvt_pk_bf16_f32 v230, v230, v231
	ds_write_b16 v205, v230 offset:432
	ds_write_b16_d16_hi v205, v230 offset:496
	v_mul_f32_e32 v228, 0xbfb8aa3b, v84
	v_mul_f32_e32 v229, 0xbfb8aa3b, v68
	v_exp_f32_e32 v228, v228
	v_exp_f32_e32 v229, v229
	v_add_f32_e32 v228, 1.0, v228
	v_add_f32_e32 v229, 1.0, v229
	v_rcp_f32_e32 v228, v228
	v_rcp_f32_e32 v229, v229
	v_mul_f32_e32 v228, v84, v228
	v_mul_f32_e32 v229, v68, v229
	v_cvt_pk_bf16_f32 v228, v228, v229
	ds_write_b16 v205, v228 offset:1152
	ds_write_b16_d16_hi v205, v228 offset:1216
	v_mul_f32_e32 v230, 0xbfb8aa3b, v85
	v_mul_f32_e32 v231, 0xbfb8aa3b, v69
	v_exp_f32_e32 v230, v230
	v_exp_f32_e32 v231, v231
	v_add_f32_e32 v230, 1.0, v230
	v_add_f32_e32 v231, 1.0, v231
	v_rcp_f32_e32 v230, v230
	v_rcp_f32_e32 v231, v231
	v_mul_f32_e32 v230, v85, v230
	v_mul_f32_e32 v231, v69, v231
	v_cvt_pk_bf16_f32 v230, v230, v231
	ds_write_b16 v205, v230 offset:1296
	ds_write_b16_d16_hi v205, v230 offset:1360
	v_mul_f32_e32 v228, 0xbfb8aa3b, v86
	v_mul_f32_e32 v229, 0xbfb8aa3b, v70
	v_exp_f32_e32 v228, v228
	v_exp_f32_e32 v229, v229
	v_add_f32_e32 v228, 1.0, v228
	v_add_f32_e32 v229, 1.0, v229
	v_rcp_f32_e32 v228, v228
	v_rcp_f32_e32 v229, v229
	v_mul_f32_e32 v228, v86, v228
	v_mul_f32_e32 v229, v70, v229
	v_cvt_pk_bf16_f32 v228, v228, v229
	ds_write_b16 v205, v228 offset:1440
	ds_write_b16_d16_hi v205, v228 offset:1504
	v_mul_f32_e32 v230, 0xbfb8aa3b, v87
	v_mul_f32_e32 v231, 0xbfb8aa3b, v71
	v_exp_f32_e32 v230, v230
	v_exp_f32_e32 v231, v231
	v_add_f32_e32 v230, 1.0, v230
	v_add_f32_e32 v231, 1.0, v231
	v_rcp_f32_e32 v230, v230
	v_rcp_f32_e32 v231, v231
	v_mul_f32_e32 v230, v87, v230
	v_mul_f32_e32 v231, v71, v231
	v_cvt_pk_bf16_f32 v230, v230, v231
	ds_write_b16 v205, v230 offset:1584
	ds_write_b16_d16_hi v205, v230 offset:1648
	v_mul_f32_e32 v228, 0xbfb8aa3b, v88
	v_mul_f32_e32 v229, 0xbfb8aa3b, v72
	v_exp_f32_e32 v228, v228
	v_exp_f32_e32 v229, v229
	v_add_f32_e32 v228, 1.0, v228
	v_add_f32_e32 v229, 1.0, v229
	v_rcp_f32_e32 v228, v228
	v_rcp_f32_e32 v229, v229
	v_mul_f32_e32 v228, v88, v228
	v_mul_f32_e32 v229, v72, v229
	v_cvt_pk_bf16_f32 v228, v228, v229
	ds_write_b16 v205, v228 offset:2304
	ds_write_b16_d16_hi v205, v228 offset:2368
	v_mul_f32_e32 v230, 0xbfb8aa3b, v89
	v_mul_f32_e32 v231, 0xbfb8aa3b, v73
	v_exp_f32_e32 v230, v230
	v_exp_f32_e32 v231, v231
	v_add_f32_e32 v230, 1.0, v230
	v_add_f32_e32 v231, 1.0, v231
	v_rcp_f32_e32 v230, v230
	v_rcp_f32_e32 v231, v231
	v_mul_f32_e32 v230, v89, v230
	v_mul_f32_e32 v231, v73, v231
	v_cvt_pk_bf16_f32 v230, v230, v231
	ds_write_b16 v205, v230 offset:2448
	ds_write_b16_d16_hi v205, v230 offset:2512
	v_mul_f32_e32 v228, 0xbfb8aa3b, v90
	v_mul_f32_e32 v229, 0xbfb8aa3b, v74
	v_exp_f32_e32 v228, v228
	v_exp_f32_e32 v229, v229
	v_add_f32_e32 v228, 1.0, v228
	v_add_f32_e32 v229, 1.0, v229
	v_rcp_f32_e32 v228, v228
	v_rcp_f32_e32 v229, v229
	v_mul_f32_e32 v228, v90, v228
	v_mul_f32_e32 v229, v74, v229
	v_cvt_pk_bf16_f32 v228, v228, v229
	ds_write_b16 v205, v228 offset:2592
	ds_write_b16_d16_hi v205, v228 offset:2656
	v_mul_f32_e32 v230, 0xbfb8aa3b, v91
	v_mul_f32_e32 v231, 0xbfb8aa3b, v75
	v_exp_f32_e32 v230, v230
	v_exp_f32_e32 v231, v231
	v_add_f32_e32 v230, 1.0, v230
	v_add_f32_e32 v231, 1.0, v231
	v_rcp_f32_e32 v230, v230
	v_rcp_f32_e32 v231, v231
	v_mul_f32_e32 v230, v91, v230
	v_mul_f32_e32 v231, v75, v231
	v_cvt_pk_bf16_f32 v230, v230, v231
	ds_write_b16 v205, v230 offset:2736
	ds_write_b16_d16_hi v205, v230 offset:2800
	v_mul_f32_e32 v228, 0xbfb8aa3b, v92
	v_mul_f32_e32 v229, 0xbfb8aa3b, v76
	v_exp_f32_e32 v228, v228
	v_exp_f32_e32 v229, v229
	v_add_f32_e32 v228, 1.0, v228
	v_add_f32_e32 v229, 1.0, v229
	v_rcp_f32_e32 v228, v228
	v_rcp_f32_e32 v229, v229
	v_mul_f32_e32 v228, v92, v228
	v_mul_f32_e32 v229, v76, v229
	v_cvt_pk_bf16_f32 v228, v228, v229
	ds_write_b16 v205, v228 offset:3456
	ds_write_b16_d16_hi v205, v228 offset:3520
	v_mul_f32_e32 v230, 0xbfb8aa3b, v93
	v_mul_f32_e32 v231, 0xbfb8aa3b, v77
	v_exp_f32_e32 v230, v230
	v_exp_f32_e32 v231, v231
	v_add_f32_e32 v230, 1.0, v230
	v_add_f32_e32 v231, 1.0, v231
	v_rcp_f32_e32 v230, v230
	v_rcp_f32_e32 v231, v231
	v_mul_f32_e32 v230, v93, v230
	v_mul_f32_e32 v231, v77, v231
	v_cvt_pk_bf16_f32 v230, v230, v231
	ds_write_b16 v205, v230 offset:3600
	ds_write_b16_d16_hi v205, v230 offset:3664
	v_mul_f32_e32 v228, 0xbfb8aa3b, v94
	v_mul_f32_e32 v229, 0xbfb8aa3b, v78
	v_exp_f32_e32 v228, v228
	v_exp_f32_e32 v229, v229
	v_add_f32_e32 v228, 1.0, v228
	v_add_f32_e32 v229, 1.0, v229
	v_rcp_f32_e32 v228, v228
	v_rcp_f32_e32 v229, v229
	v_mul_f32_e32 v228, v94, v228
	v_mul_f32_e32 v229, v78, v229
	v_cvt_pk_bf16_f32 v228, v228, v229
	ds_write_b16 v205, v228 offset:3744
	ds_write_b16_d16_hi v205, v228 offset:3808
	v_mul_f32_e32 v230, 0xbfb8aa3b, v95
	v_mul_f32_e32 v231, 0xbfb8aa3b, v79
	v_exp_f32_e32 v230, v230
	v_exp_f32_e32 v231, v231
	v_add_f32_e32 v230, 1.0, v230
	v_add_f32_e32 v231, 1.0, v231
	v_rcp_f32_e32 v230, v230
	v_rcp_f32_e32 v231, v231
	v_mul_f32_e32 v230, v95, v230
	v_mul_f32_e32 v231, v79, v231
	v_cvt_pk_bf16_f32 v230, v230, v231
	ds_write_b16 v205, v230 offset:3888
	ds_write_b16_d16_hi v205, v230 offset:3952
	s_branch .Lep0_01_st
.Lep0_01_stq:
	v_add_u32_e32 v232, s94, v226
	s_waitcnt lgkmcnt(0)
	ds_read_b128 v[206:209], v224
	ds_read_b128 v[212:215], v224 offset:1152
	ds_read_b128 v[216:219], v224 offset:2304
	ds_read_b128 v[220:223], v224 offset:3456
	v_add_u32_e32 v228, 0, v232
	v_mul_lo_u32 v228, v228, s89
	v_add3_u32 v228, v228, v227, s91
	v_add_u32_e32 v229, 8, v232
	v_mul_lo_u32 v229, v229, s89
	v_add3_u32 v229, v229, v227, s91
	v_add_u32_e32 v230, 16, v232
	v_mul_lo_u32 v230, v230, s89
	v_add3_u32 v230, v230, v227, s91
	v_add_u32_e32 v231, 24, v232
	v_mul_lo_u32 v231, v231, s89
	v_add3_u32 v231, v231, v227, s91
	s_waitcnt lgkmcnt(3)
	global_store_dwordx4 v228, v[206:209], s[96:97]
	s_waitcnt lgkmcnt(2)
	global_store_dwordx4 v229, v[212:215], s[96:97]
	s_waitcnt lgkmcnt(1)
	global_store_dwordx4 v230, v[216:219], s[96:97]
	s_waitcnt lgkmcnt(0)
	global_store_dwordx4 v231, v[220:223], s[96:97]
	v_lshlrev_b32_e32 v132, 16, v206
	v_and_b32_e32 v133, 0xffff0000, v206
	v_mul_f32_e32 v128, v132, v132
	v_fma_f32 v128, v133, v133, v128
	v_lshlrev_b32_e32 v132, 16, v207
	v_and_b32_e32 v133, 0xffff0000, v207
	v_fma_f32 v128, v132, v132, v128
	v_fma_f32 v128, v133, v133, v128
	v_lshlrev_b32_e32 v132, 16, v208
	v_and_b32_e32 v133, 0xffff0000, v208
	v_fma_f32 v128, v132, v132, v128
	v_fma_f32 v128, v133, v133, v128
	v_lshlrev_b32_e32 v132, 16, v209
	v_and_b32_e32 v133, 0xffff0000, v209
	v_fma_f32 v128, v132, v132, v128
	v_fma_f32 v128, v133, v133, v128
	v_lshlrev_b32_e32 v132, 16, v212
	v_and_b32_e32 v133, 0xffff0000, v212
	v_mul_f32_e32 v129, v132, v132
	v_fma_f32 v129, v133, v133, v129
	v_lshlrev_b32_e32 v132, 16, v213
	v_and_b32_e32 v133, 0xffff0000, v213
	v_fma_f32 v129, v132, v132, v129
	v_fma_f32 v129, v133, v133, v129
	v_lshlrev_b32_e32 v132, 16, v214
	v_and_b32_e32 v133, 0xffff0000, v214
	v_fma_f32 v129, v132, v132, v129
	v_fma_f32 v129, v133, v133, v129
	v_lshlrev_b32_e32 v132, 16, v215
	v_and_b32_e32 v133, 0xffff0000, v215
	v_fma_f32 v129, v132, v132, v129
	v_fma_f32 v129, v133, v133, v129
	v_lshlrev_b32_e32 v132, 16, v216
	v_and_b32_e32 v133, 0xffff0000, v216
	v_mul_f32_e32 v130, v132, v132
	v_fma_f32 v130, v133, v133, v130
	v_lshlrev_b32_e32 v132, 16, v217
	v_and_b32_e32 v133, 0xffff0000, v217
	v_fma_f32 v130, v132, v132, v130
	v_fma_f32 v130, v133, v133, v130
	v_lshlrev_b32_e32 v132, 16, v218
	v_and_b32_e32 v133, 0xffff0000, v218
	v_fma_f32 v130, v132, v132, v130
	v_fma_f32 v130, v133, v133, v130
	v_lshlrev_b32_e32 v132, 16, v219
	v_and_b32_e32 v133, 0xffff0000, v219
	v_fma_f32 v130, v132, v132, v130
	v_fma_f32 v130, v133, v133, v130
	v_lshlrev_b32_e32 v132, 16, v220
	v_and_b32_e32 v133, 0xffff0000, v220
	v_mul_f32_e32 v131, v132, v132
	v_fma_f32 v131, v133, v133, v131
	v_lshlrev_b32_e32 v132, 16, v221
	v_and_b32_e32 v133, 0xffff0000, v221
	v_fma_f32 v131, v132, v132, v131
	v_fma_f32 v131, v133, v133, v131
	v_lshlrev_b32_e32 v132, 16, v222
	v_and_b32_e32 v133, 0xffff0000, v222
	v_fma_f32 v131, v132, v132, v131
	v_fma_f32 v131, v133, v133, v131
	v_lshlrev_b32_e32 v132, 16, v223
	v_and_b32_e32 v133, 0xffff0000, v223
	v_fma_f32 v131, v132, v132, v131
	v_fma_f32 v131, v133, v133, v131
	s_nop 1
	v_add_f32_dpp v136, v128, v128 quad_perm:[1,0,3,2] row_mask:0xf bank_mask:0xf
	v_add_f32_dpp v137, v129, v129 quad_perm:[1,0,3,2] row_mask:0xf bank_mask:0xf
	v_add_f32_dpp v138, v130, v130 quad_perm:[1,0,3,2] row_mask:0xf bank_mask:0xf
	v_add_f32_dpp v139, v131, v131 quad_perm:[1,0,3,2] row_mask:0xf bank_mask:0xf
	v_add_f32_dpp v128, v136, v136 quad_perm:[2,3,0,1] row_mask:0xf bank_mask:0xf
	v_add_f32_dpp v129, v137, v137 quad_perm:[2,3,0,1] row_mask:0xf bank_mask:0xf
	v_add_f32_dpp v130, v138, v138 quad_perm:[2,3,0,1] row_mask:0xf bank_mask:0xf
	v_add_f32_dpp v131, v139, v139 quad_perm:[2,3,0,1] row_mask:0xf bank_mask:0xf
	v_add_f32_dpp v136, v128, v128 row_half_mirror row_mask:0xf bank_mask:0xf
	v_add_f32_dpp v137, v129, v129 row_half_mirror row_mask:0xf bank_mask:0xf
	v_add_f32_dpp v138, v130, v130 row_half_mirror row_mask:0xf bank_mask:0xf
	v_add_f32_dpp v139, v131, v131 row_half_mirror row_mask:0xf bank_mask:0xf
	v_add_f32_e32 v136, v234, v136
	v_add_f32_e32 v137, v235, v137
	v_add_f32_e32 v138, v236, v138
	v_add_f32_e32 v139, v237, v139
	v_cmp_eq_u32_e32 vcc, 0, v227
	v_add_u32_e32 v228, 0, v232
	v_lshlrev_b32_e32 v228, 2, v228
	v_add_u32_e32 v229, 8, v232
	v_lshlrev_b32_e32 v229, 2, v229
	v_add_u32_e32 v230, 16, v232
	v_lshlrev_b32_e32 v230, 2, v230
	v_add_u32_e32 v231, 24, v232
	v_lshlrev_b32_e32 v231, 2, v231
	s_and_b64 exec, exec, vcc
	global_atomic_add_f32 v228, v136, s[98:99]
	global_atomic_add_f32 v229, v137, s[98:99]
	global_atomic_add_f32 v230, v138, s[98:99]
	global_atomic_add_f32 v231, v139, s[98:99]
	s_mov_b64 exec, -1
	s_branch .Lep0_01_end

.Lep0_10_mP:
	v_cvt_pk_bf16_f32 v228, v48, v32
	ds_write_b16 v205, v228
	ds_write_b16_d16_hi v205, v228 offset:64
	v_cvt_pk_bf16_f32 v229, v49, v33
	ds_write_b16 v205, v229 offset:144
	ds_write_b16_d16_hi v205, v229 offset:208
	v_cvt_pk_bf16_f32 v230, v50, v34
	ds_write_b16 v205, v230 offset:288
	ds_write_b16_d16_hi v205, v230 offset:352
	v_cvt_pk_bf16_f32 v231, v51, v35
	ds_write_b16 v205, v231 offset:432
	ds_write_b16_d16_hi v205, v231 offset:496
	v_cvt_pk_bf16_f32 v228, v52, v36
	ds_write_b16 v205, v228 offset:1152
	ds_write_b16_d16_hi v205, v228 offset:1216
	v_cvt_pk_bf16_f32 v229, v53, v37
	ds_write_b16 v205, v229 offset:1296
	ds_write_b16_d16_hi v205, v229 offset:1360
	v_cvt_pk_bf16_f32 v230, v54, v38
	ds_write_b16 v205, v230 offset:1440
	ds_write_b16_d16_hi v205, v230 offset:1504
	v_cvt_pk_bf16_f32 v231, v55, v39
	ds_write_b16 v205, v231 offset:1584
	ds_write_b16_d16_hi v205, v231 offset:1648
	v_cvt_pk_bf16_f32 v228, v56, v40
	ds_write_b16 v205, v228 offset:2304
	ds_write_b16_d16_hi v205, v228 offset:2368
	v_cvt_pk_bf16_f32 v229, v57, v41
	ds_write_b16 v205, v229 offset:2448
	ds_write_b16_d16_hi v205, v229 offset:2512
	v_cvt_pk_bf16_f32 v230, v58, v42
	ds_write_b16 v205, v230 offset:2592
	ds_write_b16_d16_hi v205, v230 offset:2656
	v_cvt_pk_bf16_f32 v231, v59, v43
	ds_write_b16 v205, v231 offset:2736
	ds_write_b16_d16_hi v205, v231 offset:2800
	v_cvt_pk_bf16_f32 v228, v60, v44
	ds_write_b16 v205, v228 offset:3456
	ds_write_b16_d16_hi v205, v228 offset:3520
	v_cvt_pk_bf16_f32 v229, v61, v45
	ds_write_b16 v205, v229 offset:3600
	ds_write_b16_d16_hi v205, v229 offset:3664
	v_cvt_pk_bf16_f32 v230, v62, v46
	ds_write_b16 v205, v230 offset:3744
	ds_write_b16_d16_hi v205, v230 offset:3808
	v_cvt_pk_bf16_f32 v231, v63, v47
	ds_write_b16 v205, v231 offset:3888
	ds_write_b16_d16_hi v205, v231 offset:3952
	s_branch .Lep0_10_stq
.Lep0_10_mR:
	s_load_dwordx2 s[98:99], s[0:1], 0x148
	v_add_u32_e32 v228, s94, v225
	v_lshlrev_b32_e32 v228, 8, v228
	v_add_u32_e32 v234, v228, v160
	v_mov_b32_e32 v235, 0
	s_waitcnt lgkmcnt(0)
	v_lshl_add_u64 v[234:235], s[98:99], 0, v[234:235]
	global_load_dwordx2 v[128:129], v[234:235], off
	global_load_dwordx2 v[130:131], v[234:235], off offset:256
	global_load_dwordx2 v[132:133], v[234:235], off offset:512
	global_load_dwordx2 v[134:135], v[234:235], off offset:768
	global_load_dwordx2 v[136:137], v[234:235], off offset:2048
	global_load_dwordx2 v[138:139], v[234:235], off offset:2304
	global_load_dwordx2 v[140:141], v[234:235], off offset:2560
	global_load_dwordx2 v[142:143], v[234:235], off offset:2816
	v_add_co_u32_e32 v236, vcc, 0x1000, v234
	s_nop 1
	v_addc_co_u32_e32 v237, vcc, 0, v235, vcc
	global_load_dwordx2 v[144:145], v[236:237], off
	global_load_dwordx2 v[146:147], v[236:237], off offset:256
	global_load_dwordx2 v[148:149], v[236:237], off offset:512
	global_load_dwordx2 v[150:151], v[236:237], off offset:768
	global_load_dwordx2 v[152:153], v[236:237], off offset:2048
	global_load_dwordx2 v[154:155], v[236:237], off offset:2304
	global_load_dwordx2 v[156:157], v[236:237], off offset:2560
	global_load_dwordx2 v[158:159], v[236:237], off offset:2816
	s_waitcnt vmcnt(15)
	v_mul_f32_e32 v228, v32, v129
	v_mul_f32_e32 v229, v48, v129
	v_fma_f32 v228, v48, v128, -v228
	v_fma_f32 v229, v32, v128, v229
	v_mul_f32_e32 v228, s88, v228
	v_mul_f32_e32 v229, s88, v229
	v_cvt_pk_bf16_f32 v228, v228, v229
	ds_write_b16 v205, v228
	ds_write_b16_d16_hi v205, v228 offset:64
	s_waitcnt vmcnt(14)
	v_mul_f32_e32 v228, v33, v131
	v_mul_f32_e32 v229, v49, v131
	v_fma_f32 v228, v49, v130, -v228
	v_fma_f32 v229, v33, v130, v229
	v_mul_f32_e32 v228, s88, v228
	v_mul_f32_e32 v229, s88, v229
	v_cvt_pk_bf16_f32 v228, v228, v229
	ds_write_b16 v205, v228 offset:144
	ds_write_b16_d16_hi v205, v228 offset:208
	s_waitcnt vmcnt(13)
	v_mul_f32_e32 v228, v34, v133
	v_mul_f32_e32 v229, v50, v133
	v_fma_f32 v228, v50, v132, -v228
	v_fma_f32 v229, v34, v132, v229
	v_mul_f32_e32 v228, s88, v228
	v_mul_f32_e32 v229, s88, v229
	v_cvt_pk_bf16_f32 v228, v228, v229
	ds_write_b16 v205, v228 offset:288
	ds_write_b16_d16_hi v205, v228 offset:352
	s_waitcnt vmcnt(12)
	v_mul_f32_e32 v228, v35, v135
	v_mul_f32_e32 v229, v51, v135
	v_fma_f32 v228, v51, v134, -v228
	v_fma_f32 v229, v35, v134, v229
	v_mul_f32_e32 v228, s88, v228
	v_mul_f32_e32 v229, s88, v229
	v_cvt_pk_bf16_f32 v228, v228, v229
	ds_write_b16 v205, v228 offset:432
	ds_write_b16_d16_hi v205, v228 offset:496
	s_waitcnt vmcnt(11)
	v_mul_f32_e32 v228, v36, v137
	v_mul_f32_e32 v229, v52, v137
	v_fma_f32 v228, v52, v136, -v228
	v_fma_f32 v229, v36, v136, v229
	v_mul_f32_e32 v228, s88, v228
	v_mul_f32_e32 v229, s88, v229
	v_cvt_pk_bf16_f32 v228, v228, v229
	ds_write_b16 v205, v228 offset:1152
	ds_write_b16_d16_hi v205, v228 offset:1216
	s_waitcnt vmcnt(10)
	v_mul_f32_e32 v228, v37, v139
	v_mul_f32_e32 v229, v53, v139
	v_fma_f32 v228, v53, v138, -v228
	v_fma_f32 v229, v37, v138, v229
	v_mul_f32_e32 v228, s88, v228
	v_mul_f32_e32 v229, s88, v229
	v_cvt_pk_bf16_f32 v228, v228, v229
	ds_write_b16 v205, v228 offset:1296
	ds_write_b16_d16_hi v205, v228 offset:1360
	s_waitcnt vmcnt(9)
	v_mul_f32_e32 v228, v38, v141
	v_mul_f32_e32 v229, v54, v141
	v_fma_f32 v228, v54, v140, -v228
	v_fma_f32 v229, v38, v140, v229
	v_mul_f32_e32 v228, s88, v228
	v_mul_f32_e32 v229, s88, v229
	v_cvt_pk_bf16_f32 v228, v228, v229
	ds_write_b16 v205, v228 offset:1440
	ds_write_b16_d16_hi v205, v228 offset:1504
	s_waitcnt vmcnt(8)
	v_mul_f32_e32 v228, v39, v143
	v_mul_f32_e32 v229, v55, v143
	v_fma_f32 v228, v55, v142, -v228
	v_fma_f32 v229, v39, v142, v229
	v_mul_f32_e32 v228, s88, v228
	v_mul_f32_e32 v229, s88, v229
	v_cvt_pk_bf16_f32 v228, v228, v229
	ds_write_b16 v205, v228 offset:1584
	ds_write_b16_d16_hi v205, v228 offset:1648
	s_waitcnt vmcnt(7)
	v_mul_f32_e32 v228, v40, v145
	v_mul_f32_e32 v229, v56, v145
	v_fma_f32 v228, v56, v144, -v228
	v_fma_f32 v229, v40, v144, v229
	v_mul_f32_e32 v228, s88, v228
	v_mul_f32_e32 v229, s88, v229
	v_cvt_pk_bf16_f32 v228, v228, v229
	ds_write_b16 v205, v228 offset:2304
	ds_write_b16_d16_hi v205, v228 offset:2368
	s_waitcnt vmcnt(6)
	v_mul_f32_e32 v228, v41, v147
	v_mul_f32_e32 v229, v57, v147
	v_fma_f32 v228, v57, v146, -v228
	v_fma_f32 v229, v41, v146, v229
	v_mul_f32_e32 v228, s88, v228
	v_mul_f32_e32 v229, s88, v229
	v_cvt_pk_bf16_f32 v228, v228, v229
	ds_write_b16 v205, v228 offset:2448
	ds_write_b16_d16_hi v205, v228 offset:2512
	s_waitcnt vmcnt(5)
	v_mul_f32_e32 v228, v42, v149
	v_mul_f32_e32 v229, v58, v149
	v_fma_f32 v228, v58, v148, -v228
	v_fma_f32 v229, v42, v148, v229
	v_mul_f32_e32 v228, s88, v228
	v_mul_f32_e32 v229, s88, v229
	v_cvt_pk_bf16_f32 v228, v228, v229
	ds_write_b16 v205, v228 offset:2592
	ds_write_b16_d16_hi v205, v228 offset:2656
	s_waitcnt vmcnt(4)
	v_mul_f32_e32 v228, v43, v151
	v_mul_f32_e32 v229, v59, v151
	v_fma_f32 v228, v59, v150, -v228
	v_fma_f32 v229, v43, v150, v229
	v_mul_f32_e32 v228, s88, v228
	v_mul_f32_e32 v229, s88, v229
	v_cvt_pk_bf16_f32 v228, v228, v229
	ds_write_b16 v205, v228 offset:2736
	ds_write_b16_d16_hi v205, v228 offset:2800
	s_waitcnt vmcnt(3)
	v_mul_f32_e32 v228, v44, v153
	v_mul_f32_e32 v229, v60, v153
	v_fma_f32 v228, v60, v152, -v228
	v_fma_f32 v229, v44, v152, v229
	v_mul_f32_e32 v228, s88, v228
	v_mul_f32_e32 v229, s88, v229
	v_cvt_pk_bf16_f32 v228, v228, v229
	ds_write_b16 v205, v228 offset:3456
	ds_write_b16_d16_hi v205, v228 offset:3520
	s_waitcnt vmcnt(2)
	v_mul_f32_e32 v228, v45, v155
	v_mul_f32_e32 v229, v61, v155
	v_fma_f32 v228, v61, v154, -v228
	v_fma_f32 v229, v45, v154, v229
	v_mul_f32_e32 v228, s88, v228
	v_mul_f32_e32 v229, s88, v229
	v_cvt_pk_bf16_f32 v228, v228, v229
	ds_write_b16 v205, v228 offset:3600
	ds_write_b16_d16_hi v205, v228 offset:3664
	s_waitcnt vmcnt(1)
	v_mul_f32_e32 v228, v46, v157
	v_mul_f32_e32 v229, v62, v157
	v_fma_f32 v228, v62, v156, -v228
	v_fma_f32 v229, v46, v156, v229
	v_mul_f32_e32 v228, s88, v228
	v_mul_f32_e32 v229, s88, v229
	v_cvt_pk_bf16_f32 v228, v228, v229
	ds_write_b16 v205, v228 offset:3744
	ds_write_b16_d16_hi v205, v228 offset:3808
	s_waitcnt vmcnt(0)
	v_mul_f32_e32 v228, v47, v159
	v_mul_f32_e32 v229, v63, v159
	v_fma_f32 v228, v63, v158, -v228
	v_fma_f32 v229, v47, v158, v229
	v_mul_f32_e32 v228, s88, v228
	v_mul_f32_e32 v229, s88, v229
	v_cvt_pk_bf16_f32 v228, v228, v229
	ds_write_b16 v205, v228 offset:3888
	ds_write_b16_d16_hi v205, v228 offset:3952
	s_branch .Lep0_10_stb
.Lep0_10_mS:
	v_mul_f32_e32 v228, 0xbfb8aa3b, v48
	v_mul_f32_e32 v229, 0xbfb8aa3b, v32
	v_exp_f32_e32 v228, v228
	v_exp_f32_e32 v229, v229
	v_add_f32_e32 v228, 1.0, v228
	v_add_f32_e32 v229, 1.0, v229
	v_rcp_f32_e32 v228, v228
	v_rcp_f32_e32 v229, v229
	v_mul_f32_e32 v228, v48, v228
	v_mul_f32_e32 v229, v32, v229
	v_cvt_pk_bf16_f32 v228, v228, v229
	ds_write_b16 v205, v228
	ds_write_b16_d16_hi v205, v228 offset:64
	v_mul_f32_e32 v230, 0xbfb8aa3b, v49
	v_mul_f32_e32 v231, 0xbfb8aa3b, v33
	v_exp_f32_e32 v230, v230
	v_exp_f32_e32 v231, v231
	v_add_f32_e32 v230, 1.0, v230
	v_add_f32_e32 v231, 1.0, v231
	v_rcp_f32_e32 v230, v230
	v_rcp_f32_e32 v231, v231
	v_mul_f32_e32 v230, v49, v230
	v_mul_f32_e32 v231, v33, v231
	v_cvt_pk_bf16_f32 v230, v230, v231
	ds_write_b16 v205, v230 offset:144
	ds_write_b16_d16_hi v205, v230 offset:208
	v_mul_f32_e32 v228, 0xbfb8aa3b, v50
	v_mul_f32_e32 v229, 0xbfb8aa3b, v34
	v_exp_f32_e32 v228, v228
	v_exp_f32_e32 v229, v229
	v_add_f32_e32 v228, 1.0, v228
	v_add_f32_e32 v229, 1.0, v229
	v_rcp_f32_e32 v228, v228
	v_rcp_f32_e32 v229, v229
	v_mul_f32_e32 v228, v50, v228
	v_mul_f32_e32 v229, v34, v229
	v_cvt_pk_bf16_f32 v228, v228, v229
	ds_write_b16 v205, v228 offset:288
	ds_write_b16_d16_hi v205, v228 offset:352
	v_mul_f32_e32 v230, 0xbfb8aa3b, v51
	v_mul_f32_e32 v231, 0xbfb8aa3b, v35
	v_exp_f32_e32 v230, v230
	v_exp_f32_e32 v231, v231
	v_add_f32_e32 v230, 1.0, v230
	v_add_f32_e32 v231, 1.0, v231
	v_rcp_f32_e32 v230, v230
	v_rcp_f32_e32 v231, v231
	v_mul_f32_e32 v230, v51, v230
	v_mul_f32_e32 v231, v35, v231
	v_cvt_pk_bf16_f32 v230, v230, v231
	ds_write_b16 v205, v230 offset:432
	ds_write_b16_d16_hi v205, v230 offset:496
	v_mul_f32_e32 v228, 0xbfb8aa3b, v52
	v_mul_f32_e32 v229, 0xbfb8aa3b, v36
	v_exp_f32_e32 v228, v228
	v_exp_f32_e32 v229, v229
	v_add_f32_e32 v228, 1.0, v228
	v_add_f32_e32 v229, 1.0, v229
	v_rcp_f32_e32 v228, v228
	v_rcp_f32_e32 v229, v229
	v_mul_f32_e32 v228, v52, v228
	v_mul_f32_e32 v229, v36, v229
	v_cvt_pk_bf16_f32 v228, v228, v229
	ds_write_b16 v205, v228 offset:1152
	ds_write_b16_d16_hi v205, v228 offset:1216
	v_mul_f32_e32 v230, 0xbfb8aa3b, v53
	v_mul_f32_e32 v231, 0xbfb8aa3b, v37
	v_exp_f32_e32 v230, v230
	v_exp_f32_e32 v231, v231
	v_add_f32_e32 v230, 1.0, v230
	v_add_f32_e32 v231, 1.0, v231
	v_rcp_f32_e32 v230, v230
	v_rcp_f32_e32 v231, v231
	v_mul_f32_e32 v230, v53, v230
	v_mul_f32_e32 v231, v37, v231
	v_cvt_pk_bf16_f32 v230, v230, v231
	ds_write_b16 v205, v230 offset:1296
	ds_write_b16_d16_hi v205, v230 offset:1360
	v_mul_f32_e32 v228, 0xbfb8aa3b, v54
	v_mul_f32_e32 v229, 0xbfb8aa3b, v38
	v_exp_f32_e32 v228, v228
	v_exp_f32_e32 v229, v229
	v_add_f32_e32 v228, 1.0, v228
	v_add_f32_e32 v229, 1.0, v229
	v_rcp_f32_e32 v228, v228
	v_rcp_f32_e32 v229, v229
	v_mul_f32_e32 v228, v54, v228
	v_mul_f32_e32 v229, v38, v229
	v_cvt_pk_bf16_f32 v228, v228, v229
	ds_write_b16 v205, v228 offset:1440
	ds_write_b16_d16_hi v205, v228 offset:1504
	v_mul_f32_e32 v230, 0xbfb8aa3b, v55
	v_mul_f32_e32 v231, 0xbfb8aa3b, v39
	v_exp_f32_e32 v230, v230
	v_exp_f32_e32 v231, v231
	v_add_f32_e32 v230, 1.0, v230
	v_add_f32_e32 v231, 1.0, v231
	v_rcp_f32_e32 v230, v230
	v_rcp_f32_e32 v231, v231
	v_mul_f32_e32 v230, v55, v230
	v_mul_f32_e32 v231, v39, v231
	v_cvt_pk_bf16_f32 v230, v230, v231
	ds_write_b16 v205, v230 offset:1584
	ds_write_b16_d16_hi v205, v230 offset:1648
	v_mul_f32_e32 v228, 0xbfb8aa3b, v56
	v_mul_f32_e32 v229, 0xbfb8aa3b, v40
	v_exp_f32_e32 v228, v228
	v_exp_f32_e32 v229, v229
	v_add_f32_e32 v228, 1.0, v228
	v_add_f32_e32 v229, 1.0, v229
	v_rcp_f32_e32 v228, v228
	v_rcp_f32_e32 v229, v229
	v_mul_f32_e32 v228, v56, v228
	v_mul_f32_e32 v229, v40, v229
	v_cvt_pk_bf16_f32 v228, v228, v229
	ds_write_b16 v205, v228 offset:2304
	ds_write_b16_d16_hi v205, v228 offset:2368
	v_mul_f32_e32 v230, 0xbfb8aa3b, v57
	v_mul_f32_e32 v231, 0xbfb8aa3b, v41
	v_exp_f32_e32 v230, v230
	v_exp_f32_e32 v231, v231
	v_add_f32_e32 v230, 1.0, v230
	v_add_f32_e32 v231, 1.0, v231
	v_rcp_f32_e32 v230, v230
	v_rcp_f32_e32 v231, v231
	v_mul_f32_e32 v230, v57, v230
	v_mul_f32_e32 v231, v41, v231
	v_cvt_pk_bf16_f32 v230, v230, v231
	ds_write_b16 v205, v230 offset:2448
	ds_write_b16_d16_hi v205, v230 offset:2512
	v_mul_f32_e32 v228, 0xbfb8aa3b, v58
	v_mul_f32_e32 v229, 0xbfb8aa3b, v42
	v_exp_f32_e32 v228, v228
	v_exp_f32_e32 v229, v229
	v_add_f32_e32 v228, 1.0, v228
	v_add_f32_e32 v229, 1.0, v229
	v_rcp_f32_e32 v228, v228
	v_rcp_f32_e32 v229, v229
	v_mul_f32_e32 v228, v58, v228
	v_mul_f32_e32 v229, v42, v229
	v_cvt_pk_bf16_f32 v228, v228, v229
	ds_write_b16 v205, v228 offset:2592
	ds_write_b16_d16_hi v205, v228 offset:2656
	v_mul_f32_e32 v230, 0xbfb8aa3b, v59
	v_mul_f32_e32 v231, 0xbfb8aa3b, v43
	v_exp_f32_e32 v230, v230
	v_exp_f32_e32 v231, v231
	v_add_f32_e32 v230, 1.0, v230
	v_add_f32_e32 v231, 1.0, v231
	v_rcp_f32_e32 v230, v230
	v_rcp_f32_e32 v231, v231
	v_mul_f32_e32 v230, v59, v230
	v_mul_f32_e32 v231, v43, v231
	v_cvt_pk_bf16_f32 v230, v230, v231
	ds_write_b16 v205, v230 offset:2736
	ds_write_b16_d16_hi v205, v230 offset:2800
	v_mul_f32_e32 v228, 0xbfb8aa3b, v60
	v_mul_f32_e32 v229, 0xbfb8aa3b, v44
	v_exp_f32_e32 v228, v228
	v_exp_f32_e32 v229, v229
	v_add_f32_e32 v228, 1.0, v228
	v_add_f32_e32 v229, 1.0, v229
	v_rcp_f32_e32 v228, v228
	v_rcp_f32_e32 v229, v229
	v_mul_f32_e32 v228, v60, v228
	v_mul_f32_e32 v229, v44, v229
	v_cvt_pk_bf16_f32 v228, v228, v229
	ds_write_b16 v205, v228 offset:3456
	ds_write_b16_d16_hi v205, v228 offset:3520
	v_mul_f32_e32 v230, 0xbfb8aa3b, v61
	v_mul_f32_e32 v231, 0xbfb8aa3b, v45
	v_exp_f32_e32 v230, v230
	v_exp_f32_e32 v231, v231
	v_add_f32_e32 v230, 1.0, v230
	v_add_f32_e32 v231, 1.0, v231
	v_rcp_f32_e32 v230, v230
	v_rcp_f32_e32 v231, v231
	v_mul_f32_e32 v230, v61, v230
	v_mul_f32_e32 v231, v45, v231
	v_cvt_pk_bf16_f32 v230, v230, v231
	ds_write_b16 v205, v230 offset:3600
	ds_write_b16_d16_hi v205, v230 offset:3664
	v_mul_f32_e32 v228, 0xbfb8aa3b, v62
	v_mul_f32_e32 v229, 0xbfb8aa3b, v46
	v_exp_f32_e32 v228, v228
	v_exp_f32_e32 v229, v229
	v_add_f32_e32 v228, 1.0, v228
	v_add_f32_e32 v229, 1.0, v229
	v_rcp_f32_e32 v228, v228
	v_rcp_f32_e32 v229, v229
	v_mul_f32_e32 v228, v62, v228
	v_mul_f32_e32 v229, v46, v229
	v_cvt_pk_bf16_f32 v228, v228, v229
	ds_write_b16 v205, v228 offset:3744
	ds_write_b16_d16_hi v205, v228 offset:3808
	v_mul_f32_e32 v230, 0xbfb8aa3b, v63
	v_mul_f32_e32 v231, 0xbfb8aa3b, v47
	v_exp_f32_e32 v230, v230
	v_exp_f32_e32 v231, v231
	v_add_f32_e32 v230, 1.0, v230
	v_add_f32_e32 v231, 1.0, v231
	v_rcp_f32_e32 v230, v230
	v_rcp_f32_e32 v231, v231
	v_mul_f32_e32 v230, v63, v230
	v_mul_f32_e32 v231, v47, v231
	v_cvt_pk_bf16_f32 v230, v230, v231
	ds_write_b16 v205, v230 offset:3888
	ds_write_b16_d16_hi v205, v230 offset:3952
	s_branch .Lep0_10_st

.Lep0_11_mP:
	v_cvt_pk_bf16_f32 v228, v16, v0
	ds_write_b16 v205, v228
	ds_write_b16_d16_hi v205, v228 offset:64
	v_cvt_pk_bf16_f32 v229, v17, v1
	ds_write_b16 v205, v229 offset:144
	ds_write_b16_d16_hi v205, v229 offset:208
	v_cvt_pk_bf16_f32 v230, v18, v2
	ds_write_b16 v205, v230 offset:288
	ds_write_b16_d16_hi v205, v230 offset:352
	v_cvt_pk_bf16_f32 v231, v19, v3
	ds_write_b16 v205, v231 offset:432
	ds_write_b16_d16_hi v205, v231 offset:496
	v_cvt_pk_bf16_f32 v228, v20, v4
	ds_write_b16 v205, v228 offset:1152
	ds_write_b16_d16_hi v205, v228 offset:1216
	v_cvt_pk_bf16_f32 v229, v21, v5
	ds_write_b16 v205, v229 offset:1296
	ds_write_b16_d16_hi v205, v229 offset:1360
	v_cvt_pk_bf16_f32 v230, v22, v6
	ds_write_b16 v205, v230 offset:1440
	ds_write_b16_d16_hi v205, v230 offset:1504
	v_cvt_pk_bf16_f32 v231, v23, v7
	ds_write_b16 v205, v231 offset:1584
	ds_write_b16_d16_hi v205, v231 offset:1648
	v_cvt_pk_bf16_f32 v228, v24, v8
	ds_write_b16 v205, v228 offset:2304
	ds_write_b16_d16_hi v205, v228 offset:2368
	v_cvt_pk_bf16_f32 v229, v25, v9
	ds_write_b16 v205, v229 offset:2448
	ds_write_b16_d16_hi v205, v229 offset:2512
	v_cvt_pk_bf16_f32 v230, v26, v10
	ds_write_b16 v205, v230 offset:2592
	ds_write_b16_d16_hi v205, v230 offset:2656
	v_cvt_pk_bf16_f32 v231, v27, v11
	ds_write_b16 v205, v231 offset:2736
	ds_write_b16_d16_hi v205, v231 offset:2800
	v_cvt_pk_bf16_f32 v228, v28, v12
	ds_write_b16 v205, v228 offset:3456
	ds_write_b16_d16_hi v205, v228 offset:3520
	v_cvt_pk_bf16_f32 v229, v29, v13
	ds_write_b16 v205, v229 offset:3600
	ds_write_b16_d16_hi v205, v229 offset:3664
	v_cvt_pk_bf16_f32 v230, v30, v14
	ds_write_b16 v205, v230 offset:3744
	ds_write_b16_d16_hi v205, v230 offset:3808
	v_cvt_pk_bf16_f32 v231, v31, v15
	ds_write_b16 v205, v231 offset:3888
	ds_write_b16_d16_hi v205, v231 offset:3952
	s_branch .Lep0_11_stq
.Lep0_11_mR:
	s_load_dwordx2 s[98:99], s[0:1], 0x148
	v_add_u32_e32 v228, s94, v225
	v_lshlrev_b32_e32 v228, 8, v228
	v_add_u32_e32 v234, v228, v160
	v_mov_b32_e32 v235, 0
	s_waitcnt lgkmcnt(0)
	v_lshl_add_u64 v[234:235], s[98:99], 0, v[234:235]
	global_load_dwordx2 v[128:129], v[234:235], off
	global_load_dwordx2 v[130:131], v[234:235], off offset:256
	global_load_dwordx2 v[132:133], v[234:235], off offset:512
	global_load_dwordx2 v[134:135], v[234:235], off offset:768
	global_load_dwordx2 v[136:137], v[234:235], off offset:2048
	global_load_dwordx2 v[138:139], v[234:235], off offset:2304
	global_load_dwordx2 v[140:141], v[234:235], off offset:2560
	global_load_dwordx2 v[142:143], v[234:235], off offset:2816
	v_add_co_u32_e32 v236, vcc, 0x1000, v234
	s_nop 1
	v_addc_co_u32_e32 v237, vcc, 0, v235, vcc
	global_load_dwordx2 v[144:145], v[236:237], off
	global_load_dwordx2 v[146:147], v[236:237], off offset:256
	global_load_dwordx2 v[148:149], v[236:237], off offset:512
	global_load_dwordx2 v[150:151], v[236:237], off offset:768
	global_load_dwordx2 v[152:153], v[236:237], off offset:2048
	global_load_dwordx2 v[154:155], v[236:237], off offset:2304
	global_load_dwordx2 v[156:157], v[236:237], off offset:2560
	global_load_dwordx2 v[158:159], v[236:237], off offset:2816
	s_waitcnt vmcnt(15)
	v_mul_f32_e32 v228, v0, v129
	v_mul_f32_e32 v229, v16, v129
	v_fma_f32 v228, v16, v128, -v228
	v_fma_f32 v229, v0, v128, v229
	v_mul_f32_e32 v228, s88, v228
	v_mul_f32_e32 v229, s88, v229
	v_cvt_pk_bf16_f32 v228, v228, v229
	ds_write_b16 v205, v228
	ds_write_b16_d16_hi v205, v228 offset:64
	s_waitcnt vmcnt(14)
	v_mul_f32_e32 v228, v1, v131
	v_mul_f32_e32 v229, v17, v131
	v_fma_f32 v228, v17, v130, -v228
	v_fma_f32 v229, v1, v130, v229
	v_mul_f32_e32 v228, s88, v228
	v_mul_f32_e32 v229, s88, v229
	v_cvt_pk_bf16_f32 v228, v228, v229
	ds_write_b16 v205, v228 offset:144
	ds_write_b16_d16_hi v205, v228 offset:208
	s_waitcnt vmcnt(13)
	v_mul_f32_e32 v228, v2, v133
	v_mul_f32_e32 v229, v18, v133
	v_fma_f32 v228, v18, v132, -v228
	v_fma_f32 v229, v2, v132, v229
	v_mul_f32_e32 v228, s88, v228
	v_mul_f32_e32 v229, s88, v229
	v_cvt_pk_bf16_f32 v228, v228, v229
	ds_write_b16 v205, v228 offset:288
	ds_write_b16_d16_hi v205, v228 offset:352
	s_waitcnt vmcnt(12)
	v_mul_f32_e32 v228, v3, v135
	v_mul_f32_e32 v229, v19, v135
	v_fma_f32 v228, v19, v134, -v228
	v_fma_f32 v229, v3, v134, v229
	v_mul_f32_e32 v228, s88, v228
	v_mul_f32_e32 v229, s88, v229
	v_cvt_pk_bf16_f32 v228, v228, v229
	ds_write_b16 v205, v228 offset:432
	ds_write_b16_d16_hi v205, v228 offset:496
	s_waitcnt vmcnt(11)
	v_mul_f32_e32 v228, v4, v137
	v_mul_f32_e32 v229, v20, v137
	v_fma_f32 v228, v20, v136, -v228
	v_fma_f32 v229, v4, v136, v229
	v_mul_f32_e32 v228, s88, v228
	v_mul_f32_e32 v229, s88, v229
	v_cvt_pk_bf16_f32 v228, v228, v229
	ds_write_b16 v205, v228 offset:1152
	ds_write_b16_d16_hi v205, v228 offset:1216
	s_waitcnt vmcnt(10)
	v_mul_f32_e32 v228, v5, v139
	v_mul_f32_e32 v229, v21, v139
	v_fma_f32 v228, v21, v138, -v228
	v_fma_f32 v229, v5, v138, v229
	v_mul_f32_e32 v228, s88, v228
	v_mul_f32_e32 v229, s88, v229
	v_cvt_pk_bf16_f32 v228, v228, v229
	ds_write_b16 v205, v228 offset:1296
	ds_write_b16_d16_hi v205, v228 offset:1360
	s_waitcnt vmcnt(9)
	v_mul_f32_e32 v228, v6, v141
	v_mul_f32_e32 v229, v22, v141
	v_fma_f32 v228, v22, v140, -v228
	v_fma_f32 v229, v6, v140, v229
	v_mul_f32_e32 v228, s88, v228
	v_mul_f32_e32 v229, s88, v229
	v_cvt_pk_bf16_f32 v228, v228, v229
	ds_write_b16 v205, v228 offset:1440
	ds_write_b16_d16_hi v205, v228 offset:1504
	s_waitcnt vmcnt(8)
	v_mul_f32_e32 v228, v7, v143
	v_mul_f32_e32 v229, v23, v143
	v_fma_f32 v228, v23, v142, -v228
	v_fma_f32 v229, v7, v142, v229
	v_mul_f32_e32 v228, s88, v228
	v_mul_f32_e32 v229, s88, v229
	v_cvt_pk_bf16_f32 v228, v228, v229
	ds_write_b16 v205, v228 offset:1584
	ds_write_b16_d16_hi v205, v228 offset:1648
	s_waitcnt vmcnt(7)
	v_mul_f32_e32 v228, v8, v145
	v_mul_f32_e32 v229, v24, v145
	v_fma_f32 v228, v24, v144, -v228
	v_fma_f32 v229, v8, v144, v229
	v_mul_f32_e32 v228, s88, v228
	v_mul_f32_e32 v229, s88, v229
	v_cvt_pk_bf16_f32 v228, v228, v229
	ds_write_b16 v205, v228 offset:2304
	ds_write_b16_d16_hi v205, v228 offset:2368
	s_waitcnt vmcnt(6)
	v_mul_f32_e32 v228, v9, v147
	v_mul_f32_e32 v229, v25, v147
	v_fma_f32 v228, v25, v146, -v228
	v_fma_f32 v229, v9, v146, v229
	v_mul_f32_e32 v228, s88, v228
	v_mul_f32_e32 v229, s88, v229
	v_cvt_pk_bf16_f32 v228, v228, v229
	ds_write_b16 v205, v228 offset:2448
	ds_write_b16_d16_hi v205, v228 offset:2512
	s_waitcnt vmcnt(5)
	v_mul_f32_e32 v228, v10, v149
	v_mul_f32_e32 v229, v26, v149
	v_fma_f32 v228, v26, v148, -v228
	v_fma_f32 v229, v10, v148, v229
	v_mul_f32_e32 v228, s88, v228
	v_mul_f32_e32 v229, s88, v229
	v_cvt_pk_bf16_f32 v228, v228, v229
	ds_write_b16 v205, v228 offset:2592
	ds_write_b16_d16_hi v205, v228 offset:2656
	s_waitcnt vmcnt(4)
	v_mul_f32_e32 v228, v11, v151
	v_mul_f32_e32 v229, v27, v151
	v_fma_f32 v228, v27, v150, -v228
	v_fma_f32 v229, v11, v150, v229
	v_mul_f32_e32 v228, s88, v228
	v_mul_f32_e32 v229, s88, v229
	v_cvt_pk_bf16_f32 v228, v228, v229
	ds_write_b16 v205, v228 offset:2736
	ds_write_b16_d16_hi v205, v228 offset:2800
	s_waitcnt vmcnt(3)
	v_mul_f32_e32 v228, v12, v153
	v_mul_f32_e32 v229, v28, v153
	v_fma_f32 v228, v28, v152, -v228
	v_fma_f32 v229, v12, v152, v229
	v_mul_f32_e32 v228, s88, v228
	v_mul_f32_e32 v229, s88, v229
	v_cvt_pk_bf16_f32 v228, v228, v229
	ds_write_b16 v205, v228 offset:3456
	ds_write_b16_d16_hi v205, v228 offset:3520
	s_waitcnt vmcnt(2)
	v_mul_f32_e32 v228, v13, v155
	v_mul_f32_e32 v229, v29, v155
	v_fma_f32 v228, v29, v154, -v228
	v_fma_f32 v229, v13, v154, v229
	v_mul_f32_e32 v228, s88, v228
	v_mul_f32_e32 v229, s88, v229
	v_cvt_pk_bf16_f32 v228, v228, v229
	ds_write_b16 v205, v228 offset:3600
	ds_write_b16_d16_hi v205, v228 offset:3664
	s_waitcnt vmcnt(1)
	v_mul_f32_e32 v228, v14, v157
	v_mul_f32_e32 v229, v30, v157
	v_fma_f32 v228, v30, v156, -v228
	v_fma_f32 v229, v14, v156, v229
	v_mul_f32_e32 v228, s88, v228
	v_mul_f32_e32 v229, s88, v229
	v_cvt_pk_bf16_f32 v228, v228, v229
	ds_write_b16 v205, v228 offset:3744
	ds_write_b16_d16_hi v205, v228 offset:3808
	s_waitcnt vmcnt(0)
	v_mul_f32_e32 v228, v15, v159
	v_mul_f32_e32 v229, v31, v159
	v_fma_f32 v228, v31, v158, -v228
	v_fma_f32 v229, v15, v158, v229
	v_mul_f32_e32 v228, s88, v228
	v_mul_f32_e32 v229, s88, v229
	v_cvt_pk_bf16_f32 v228, v228, v229
	ds_write_b16 v205, v228 offset:3888
	ds_write_b16_d16_hi v205, v228 offset:3952
	s_branch .Lep0_11_stb
.Lep0_11_mS:
	v_mul_f32_e32 v228, 0xbfb8aa3b, v16
	v_mul_f32_e32 v229, 0xbfb8aa3b, v0
	v_exp_f32_e32 v228, v228
	v_exp_f32_e32 v229, v229
	v_add_f32_e32 v228, 1.0, v228
	v_add_f32_e32 v229, 1.0, v229
	v_rcp_f32_e32 v228, v228
	v_rcp_f32_e32 v229, v229
	v_mul_f32_e32 v228, v16, v228
	v_mul_f32_e32 v229, v0, v229
	v_cvt_pk_bf16_f32 v228, v228, v229
	ds_write_b16 v205, v228
	ds_write_b16_d16_hi v205, v228 offset:64
	v_mul_f32_e32 v230, 0xbfb8aa3b, v17
	v_mul_f32_e32 v231, 0xbfb8aa3b, v1
	v_exp_f32_e32 v230, v230
	v_exp_f32_e32 v231, v231
	v_add_f32_e32 v230, 1.0, v230
	v_add_f32_e32 v231, 1.0, v231
	v_rcp_f32_e32 v230, v230
	v_rcp_f32_e32 v231, v231
	v_mul_f32_e32 v230, v17, v230
	v_mul_f32_e32 v231, v1, v231
	v_cvt_pk_bf16_f32 v230, v230, v231
	ds_write_b16 v205, v230 offset:144
	ds_write_b16_d16_hi v205, v230 offset:208
	v_mul_f32_e32 v228, 0xbfb8aa3b, v18
	v_mul_f32_e32 v229, 0xbfb8aa3b, v2
	v_exp_f32_e32 v228, v228
	v_exp_f32_e32 v229, v229
	v_add_f32_e32 v228, 1.0, v228
	v_add_f32_e32 v229, 1.0, v229
	v_rcp_f32_e32 v228, v228
	v_rcp_f32_e32 v229, v229
	v_mul_f32_e32 v228, v18, v228
	v_mul_f32_e32 v229, v2, v229
	v_cvt_pk_bf16_f32 v228, v228, v229
	ds_write_b16 v205, v228 offset:288
	ds_write_b16_d16_hi v205, v228 offset:352
	v_mul_f32_e32 v230, 0xbfb8aa3b, v19
	v_mul_f32_e32 v231, 0xbfb8aa3b, v3
	v_exp_f32_e32 v230, v230
	v_exp_f32_e32 v231, v231
	v_add_f32_e32 v230, 1.0, v230
	v_add_f32_e32 v231, 1.0, v231
	v_rcp_f32_e32 v230, v230
	v_rcp_f32_e32 v231, v231
	v_mul_f32_e32 v230, v19, v230
	v_mul_f32_e32 v231, v3, v231
	v_cvt_pk_bf16_f32 v230, v230, v231
	ds_write_b16 v205, v230 offset:432
	ds_write_b16_d16_hi v205, v230 offset:496
	v_mul_f32_e32 v228, 0xbfb8aa3b, v20
	v_mul_f32_e32 v229, 0xbfb8aa3b, v4
	v_exp_f32_e32 v228, v228
	v_exp_f32_e32 v229, v229
	v_add_f32_e32 v228, 1.0, v228
	v_add_f32_e32 v229, 1.0, v229
	v_rcp_f32_e32 v228, v228
	v_rcp_f32_e32 v229, v229
	v_mul_f32_e32 v228, v20, v228
	v_mul_f32_e32 v229, v4, v229
	v_cvt_pk_bf16_f32 v228, v228, v229
	ds_write_b16 v205, v228 offset:1152
	ds_write_b16_d16_hi v205, v228 offset:1216
	v_mul_f32_e32 v230, 0xbfb8aa3b, v21
	v_mul_f32_e32 v231, 0xbfb8aa3b, v5
	v_exp_f32_e32 v230, v230
	v_exp_f32_e32 v231, v231
	v_add_f32_e32 v230, 1.0, v230
	v_add_f32_e32 v231, 1.0, v231
	v_rcp_f32_e32 v230, v230
	v_rcp_f32_e32 v231, v231
	v_mul_f32_e32 v230, v21, v230
	v_mul_f32_e32 v231, v5, v231
	v_cvt_pk_bf16_f32 v230, v230, v231
	ds_write_b16 v205, v230 offset:1296
	ds_write_b16_d16_hi v205, v230 offset:1360
	v_mul_f32_e32 v228, 0xbfb8aa3b, v22
	v_mul_f32_e32 v229, 0xbfb8aa3b, v6
	v_exp_f32_e32 v228, v228
	v_exp_f32_e32 v229, v229
	v_add_f32_e32 v228, 1.0, v228
	v_add_f32_e32 v229, 1.0, v229
	v_rcp_f32_e32 v228, v228
	v_rcp_f32_e32 v229, v229
	v_mul_f32_e32 v228, v22, v228
	v_mul_f32_e32 v229, v6, v229
	v_cvt_pk_bf16_f32 v228, v228, v229
	ds_write_b16 v205, v228 offset:1440
	ds_write_b16_d16_hi v205, v228 offset:1504
	v_mul_f32_e32 v230, 0xbfb8aa3b, v23
	v_mul_f32_e32 v231, 0xbfb8aa3b, v7
	v_exp_f32_e32 v230, v230
	v_exp_f32_e32 v231, v231
	v_add_f32_e32 v230, 1.0, v230
	v_add_f32_e32 v231, 1.0, v231
	v_rcp_f32_e32 v230, v230
	v_rcp_f32_e32 v231, v231
	v_mul_f32_e32 v230, v23, v230
	v_mul_f32_e32 v231, v7, v231
	v_cvt_pk_bf16_f32 v230, v230, v231
	ds_write_b16 v205, v230 offset:1584
	ds_write_b16_d16_hi v205, v230 offset:1648
	v_mul_f32_e32 v228, 0xbfb8aa3b, v24
	v_mul_f32_e32 v229, 0xbfb8aa3b, v8
	v_exp_f32_e32 v228, v228
	v_exp_f32_e32 v229, v229
	v_add_f32_e32 v228, 1.0, v228
	v_add_f32_e32 v229, 1.0, v229
	v_rcp_f32_e32 v228, v228
	v_rcp_f32_e32 v229, v229
	v_mul_f32_e32 v228, v24, v228
	v_mul_f32_e32 v229, v8, v229
	v_cvt_pk_bf16_f32 v228, v228, v229
	ds_write_b16 v205, v228 offset:2304
	ds_write_b16_d16_hi v205, v228 offset:2368
	v_mul_f32_e32 v230, 0xbfb8aa3b, v25
	v_mul_f32_e32 v231, 0xbfb8aa3b, v9
	v_exp_f32_e32 v230, v230
	v_exp_f32_e32 v231, v231
	v_add_f32_e32 v230, 1.0, v230
	v_add_f32_e32 v231, 1.0, v231
	v_rcp_f32_e32 v230, v230
	v_rcp_f32_e32 v231, v231
	v_mul_f32_e32 v230, v25, v230
	v_mul_f32_e32 v231, v9, v231
	v_cvt_pk_bf16_f32 v230, v230, v231
	ds_write_b16 v205, v230 offset:2448
	ds_write_b16_d16_hi v205, v230 offset:2512
	v_mul_f32_e32 v228, 0xbfb8aa3b, v26
	v_mul_f32_e32 v229, 0xbfb8aa3b, v10
	v_exp_f32_e32 v228, v228
	v_exp_f32_e32 v229, v229
	v_add_f32_e32 v228, 1.0, v228
	v_add_f32_e32 v229, 1.0, v229
	v_rcp_f32_e32 v228, v228
	v_rcp_f32_e32 v229, v229
	v_mul_f32_e32 v228, v26, v228
	v_mul_f32_e32 v229, v10, v229
	v_cvt_pk_bf16_f32 v228, v228, v229
	ds_write_b16 v205, v228 offset:2592
	ds_write_b16_d16_hi v205, v228 offset:2656
	v_mul_f32_e32 v230, 0xbfb8aa3b, v27
	v_mul_f32_e32 v231, 0xbfb8aa3b, v11
	v_exp_f32_e32 v230, v230
	v_exp_f32_e32 v231, v231
	v_add_f32_e32 v230, 1.0, v230
	v_add_f32_e32 v231, 1.0, v231
	v_rcp_f32_e32 v230, v230
	v_rcp_f32_e32 v231, v231
	v_mul_f32_e32 v230, v27, v230
	v_mul_f32_e32 v231, v11, v231
	v_cvt_pk_bf16_f32 v230, v230, v231
	ds_write_b16 v205, v230 offset:2736
	ds_write_b16_d16_hi v205, v230 offset:2800
	v_mul_f32_e32 v228, 0xbfb8aa3b, v28
	v_mul_f32_e32 v229, 0xbfb8aa3b, v12
	v_exp_f32_e32 v228, v228
	v_exp_f32_e32 v229, v229
	v_add_f32_e32 v228, 1.0, v228
	v_add_f32_e32 v229, 1.0, v229
	v_rcp_f32_e32 v228, v228
	v_rcp_f32_e32 v229, v229
	v_mul_f32_e32 v228, v28, v228
	v_mul_f32_e32 v229, v12, v229
	v_cvt_pk_bf16_f32 v228, v228, v229
	ds_write_b16 v205, v228 offset:3456
	ds_write_b16_d16_hi v205, v228 offset:3520
	v_mul_f32_e32 v230, 0xbfb8aa3b, v29
	v_mul_f32_e32 v231, 0xbfb8aa3b, v13
	v_exp_f32_e32 v230, v230
	v_exp_f32_e32 v231, v231
	v_add_f32_e32 v230, 1.0, v230
	v_add_f32_e32 v231, 1.0, v231
	v_rcp_f32_e32 v230, v230
	v_rcp_f32_e32 v231, v231
	v_mul_f32_e32 v230, v29, v230
	v_mul_f32_e32 v231, v13, v231
	v_cvt_pk_bf16_f32 v230, v230, v231
	ds_write_b16 v205, v230 offset:3600
	ds_write_b16_d16_hi v205, v230 offset:3664
	v_mul_f32_e32 v228, 0xbfb8aa3b, v30
	v_mul_f32_e32 v229, 0xbfb8aa3b, v14
	v_exp_f32_e32 v228, v228
	v_exp_f32_e32 v229, v229
	v_add_f32_e32 v228, 1.0, v228
	v_add_f32_e32 v229, 1.0, v229
	v_rcp_f32_e32 v228, v228
	v_rcp_f32_e32 v229, v229
	v_mul_f32_e32 v228, v30, v228
	v_mul_f32_e32 v229, v14, v229
	v_cvt_pk_bf16_f32 v228, v228, v229
	ds_write_b16 v205, v228 offset:3744
	ds_write_b16_d16_hi v205, v228 offset:3808
	v_mul_f32_e32 v230, 0xbfb8aa3b, v31
	v_mul_f32_e32 v231, 0xbfb8aa3b, v15
	v_exp_f32_e32 v230, v230
	v_exp_f32_e32 v231, v231
	v_add_f32_e32 v230, 1.0, v230
	v_add_f32_e32 v231, 1.0, v231
	v_rcp_f32_e32 v230, v230
	v_rcp_f32_e32 v231, v231
	v_mul_f32_e32 v230, v31, v230
	v_mul_f32_e32 v231, v15, v231
	v_cvt_pk_bf16_f32 v230, v230, v231
	ds_write_b16 v205, v230 offset:3888
	ds_write_b16_d16_hi v205, v230 offset:3952
	s_branch .Lep0_11_st

.LBB0_1275:
	s_ashr_i32 s2, s54, 31
	s_lshr_b32 s2, s2, 30
	s_add_i32 s2, s54, s2
	s_ashr_i32 s2, s2, 2
	s_lshl_b32 s4, s2, 8
	v_add_u32_e32 v0, s4, v212
	v_min_i32_e32 v0, 0x7fff, v0
	v_ashrrev_i32_e32 v1, 31, v0
	s_lshl_b32 s6, s2, 10
	v_lshlrev_b64 v[0:1], 11, v[0:1]
	v_lshl_add_u64 v[160:161], v[176:177], 0, v[0:1]
	v_subrev_u32_e32 v0, s6, v220
	v_ashrrev_i32_e32 v1, 31, v0
	v_lshlrev_b64 v[0:1], 11, v[0:1]
	v_lshl_add_u64 v[180:181], v[178:179], 0, v[0:1]
	v_subrev_u32_e32 v0, s6, v221
	v_ashrrev_i32_e32 v1, 31, v0
	v_lshlrev_b64 v[0:1], 11, v[0:1]
	v_lshl_add_u64 v[182:183], v[178:179], 0, v[0:1]
	v_subrev_u32_e32 v0, s6, v222
	v_ashrrev_i32_e32 v1, 31, v0
	v_add_u32_e32 v2, s4, v213
	v_add_u32_e32 v4, s4, v171
	v_add_u32_e32 v6, s4, v215
	v_lshlrev_b64 v[0:1], 11, v[0:1]
	v_min_i32_e32 v2, 0x7fff, v2
	v_min_i32_e32 v4, 0x7fff, v4
	v_min_i32_e32 v6, 0x7fff, v6
	v_lshl_add_u64 v[184:185], v[178:179], 0, v[0:1]
	v_subrev_u32_e32 v0, s6, v223
	v_ashrrev_i32_e32 v3, 31, v2
	v_ashrrev_i32_e32 v5, 31, v4
	v_ashrrev_i32_e32 v7, 31, v6
	v_ashrrev_i32_e32 v1, 31, v0
	v_lshlrev_b64 v[2:3], 11, v[2:3]
	v_lshlrev_b64 v[4:5], 11, v[4:5]
	v_lshlrev_b64 v[6:7], 11, v[6:7]
	v_lshlrev_b64 v[0:1], 11, v[0:1]
	s_mov_b32 s5, s54
	v_lshl_add_u64 v[162:163], v[176:177], 0, v[2:3]
	v_lshl_add_u64 v[164:165], v[176:177], 0, v[4:5]
	v_lshl_add_u64 v[166:167], v[176:177], 0, v[6:7]
	v_lshl_add_u64 v[186:187], v[178:179], 0, v[0:1]
	s_mov_b64 s[2:3], 0
	s_mov_b32 s7, 0
	v_mov_b32_e32 v0, 0
	v_mov_b32_e32 v1, v169
	v_mov_b32_e32 v2, v169
	v_mov_b32_e32 v3, v169
	v_mov_b32_e32 v4, v169
	v_mov_b32_e32 v5, v169
	v_mov_b32_e32 v6, v169
	v_mov_b32_e32 v7, v169
	v_mov_b32_e32 v8, v169
	v_mov_b32_e32 v9, v169
	v_mov_b32_e32 v10, v169
	v_mov_b32_e32 v11, v169
	v_mov_b32_e32 v12, v169
	v_mov_b32_e32 v13, v169
	v_mov_b32_e32 v14, v169
	v_mov_b32_e32 v15, v169
	v_mov_b32_e32 v16, 0
	v_mov_b32_e32 v17, v169
	v_mov_b32_e32 v18, v169
	v_mov_b32_e32 v19, v169
	v_mov_b32_e32 v20, v169
	v_mov_b32_e32 v21, v169
	v_mov_b32_e32 v22, v169
	v_mov_b32_e32 v23, v169
	v_mov_b32_e32 v24, v169
	v_mov_b32_e32 v25, v169
	v_mov_b32_e32 v26, v169
	v_mov_b32_e32 v27, v169
	v_mov_b32_e32 v28, v169
	v_mov_b32_e32 v29, v169
	v_mov_b32_e32 v30, v169
	v_mov_b32_e32 v31, v169
	v_mov_b32_e32 v32, 0
	v_mov_b32_e32 v33, v169
	v_mov_b32_e32 v34, v169
	v_mov_b32_e32 v35, v169
	v_mov_b32_e32 v36, v169
	v_mov_b32_e32 v37, v169
	v_mov_b32_e32 v38, v169
	v_mov_b32_e32 v39, v169
	v_mov_b32_e32 v40, v169
	v_mov_b32_e32 v41, v169
	v_mov_b32_e32 v42, v169
	v_mov_b32_e32 v43, v169
	v_mov_b32_e32 v44, v169
	v_mov_b32_e32 v45, v169
	v_mov_b32_e32 v46, v169
	v_mov_b32_e32 v47, v169
	v_mov_b32_e32 v48, 0
	v_mov_b32_e32 v49, v169
	v_mov_b32_e32 v50, v169
	v_mov_b32_e32 v51, v169
	v_mov_b32_e32 v52, v169
	v_mov_b32_e32 v53, v169
	v_mov_b32_e32 v54, v169
	v_mov_b32_e32 v55, v169
	v_mov_b32_e32 v56, v169
	v_mov_b32_e32 v57, v169
	v_mov_b32_e32 v58, v169
	v_mov_b32_e32 v59, v169
	v_mov_b32_e32 v60, v169
	v_mov_b32_e32 v61, v169
	v_mov_b32_e32 v62, v169
	v_mov_b32_e32 v63, v169
	v_mov_b32_e32 v64, 0
	v_mov_b32_e32 v65, v169
	v_mov_b32_e32 v66, v169
	v_mov_b32_e32 v67, v169
	v_mov_b32_e32 v68, v169
	v_mov_b32_e32 v69, v169
	v_mov_b32_e32 v70, v169
	v_mov_b32_e32 v71, v169
	v_mov_b32_e32 v72, v169
	v_mov_b32_e32 v73, v169
	v_mov_b32_e32 v74, v169
	v_mov_b32_e32 v75, v169
	v_mov_b32_e32 v76, v169
	v_mov_b32_e32 v77, v169
	v_mov_b32_e32 v78, v169
	v_mov_b32_e32 v79, v169
	v_mov_b32_e32 v80, 0
	v_mov_b32_e32 v81, v169
	v_mov_b32_e32 v82, v169
	v_mov_b32_e32 v83, v169
	v_mov_b32_e32 v84, v169
	v_mov_b32_e32 v85, v169
	v_mov_b32_e32 v86, v169
	v_mov_b32_e32 v87, v169
	v_mov_b32_e32 v88, v169
	v_mov_b32_e32 v89, v169
	v_mov_b32_e32 v90, v169
	v_mov_b32_e32 v91, v169
	v_mov_b32_e32 v92, v169
	v_mov_b32_e32 v93, v169
	v_mov_b32_e32 v94, v169
	v_mov_b32_e32 v95, v169
	v_mov_b32_e32 v96, 0
	v_mov_b32_e32 v97, v169
	v_mov_b32_e32 v98, v169
	v_mov_b32_e32 v99, v169
	v_mov_b32_e32 v100, v169
	v_mov_b32_e32 v101, v169
	v_mov_b32_e32 v102, v169
	v_mov_b32_e32 v103, v169
	v_mov_b32_e32 v104, v169
	v_mov_b32_e32 v105, v169
	v_mov_b32_e32 v106, v169
	v_mov_b32_e32 v107, v169
	v_mov_b32_e32 v108, v169
	v_mov_b32_e32 v109, v169
	v_mov_b32_e32 v110, v169
	v_mov_b32_e32 v111, v169
	v_mov_b32_e32 v112, 0
	v_mov_b32_e32 v113, v169
	v_mov_b32_e32 v114, v169
	v_mov_b32_e32 v115, v169
	v_mov_b32_e32 v116, v169
	v_mov_b32_e32 v117, v169
	v_mov_b32_e32 v118, v169
	v_mov_b32_e32 v119, v169
	v_mov_b32_e32 v120, v169
	v_mov_b32_e32 v121, v169
	v_mov_b32_e32 v122, v169
	v_mov_b32_e32 v123, v169
	v_mov_b32_e32 v124, v169
	v_mov_b32_e32 v125, v169
	v_mov_b32_e32 v126, v169
	v_mov_b32_e32 v127, v169
	v_mbcnt_hi_u32_b32 v128, -1, v210
	s_and_b32 s90, s70, 0x40
	v_and_b32_e32 v159, 48, v128
	v_or_b32_e32 v159, s90, v159
	v_and_b32_e32 v129, 31, v128
	v_lshrrev_b32_e32 v130, 5, v128
	v_bfe_u32 v131, v128, 1, 3
	v_lshlrev_b32_e32 v132, 7, v129
	s_lshr_b32 s91, s70, 7
	s_lshl_b32 s91, s91, 13
	s_lshl_b32 s90, s90, 8
	s_add_u32 s90, s90, 0x8000
	s_lshl_b32 s88, s70, 4
	s_mov_b32 s89, 0x10000
	s_lshl_b32 s92, s22, 4
	s_and_b32 s92, s92, 0x780
	s_mov_b32 s93, 0
	s_load_dwordx2 s[96:97], s[0:1], 0x158
	s_load_dwordx2 s[98:99], s[0:1], 0xf0
	s_waitcnt lgkmcnt(0)
	v_subrev_u32_e32 v152, s96, v160
	v_xor_b32_e32 v152, v159, v152
	v_subrev_u32_e32 v153, s98, v180
	v_xor_b32_e32 v153, v159, v153
	v_subrev_u32_e32 v154, s96, v162
	v_xor_b32_e32 v154, v159, v154
	v_subrev_u32_e32 v155, s98, v182
	v_xor_b32_e32 v155, v159, v155
	v_subrev_u32_e32 v156, s96, v164
	v_xor_b32_e32 v156, v159, v156
	v_subrev_u32_e32 v157, s98, v184
	v_xor_b32_e32 v157, v159, v157
	v_subrev_u32_e32 v158, s96, v166
	v_xor_b32_e32 v158, v159, v158
	v_subrev_u32_e32 v168, s98, v186
	v_xor_b32_e32 v168, v159, v168
	v_xor_b32_e32 v133, v130, v131
	v_lshl_add_u32 v133, v133, 4, v132
	v_add_u32_e32 v230, s91, v133
	v_add_u32_e32 v234, s90, v133
	v_add_u32_e32 v208, 0x10000, v230
	v_add_u32_e32 v241, 0x10000, v234
	v_or_b32_e32 v133, 2, v130
	v_xor_b32_e32 v133, v133, v131
	v_lshl_add_u32 v133, v133, 4, v132
	v_add_u32_e32 v231, s91, v133
	v_add_u32_e32 v235, s90, v133
	v_add_u32_e32 v238, 0x10000, v231
	v_add_u32_e32 v253, 0x10000, v235
	v_or_b32_e32 v133, 4, v130
	v_xor_b32_e32 v133, v133, v131
	v_lshl_add_u32 v133, v133, 4, v132
	v_add_u32_e32 v232, s91, v133
	v_add_u32_e32 v236, s90, v133
	v_add_u32_e32 v239, 0x10000, v232
	v_add_u32_e32 v254, 0x10000, v236
	v_or_b32_e32 v133, 6, v130
	v_xor_b32_e32 v133, v133, v131
	v_lshl_add_u32 v133, v133, 4, v132
	v_add_u32_e32 v233, s91, v133
	v_add_u32_e32 v237, s90, v133
	v_add_u32_e32 v240, 0x10000, v233
	v_add_u32_e32 v255, 0x10000, v237
	s_barrier
	ds_read_b128 v[188:191], v230
	ds_read_b128 v[196:199], v234
	ds_read_b128 v[192:195], v230 offset:4096
	ds_read_b128 v[200:203], v234 offset:4096
	ds_read_b128 v[204:207], v234 offset:8192
	ds_read_b128 v[226:229], v234 offset:12288
	s_add_u32 s94, s2, s92
	s_add_u32 s94, s94, 0x80
	s_and_b32 s94, s94, 0x780
	s_sub_u32 s94, s94, 0x80
	s_subb_u32 s95, 0, 0
	s_add_u32 s100, s96, s94
	s_addc_u32 s101, s97, s95
	s_add_u32 s94, s98, s94
	s_addc_u32 s95, s99, s95
	s_add_u32 s90, s88, s89
	s_add_u32 m0, s90, 0
	s_nop 0
	global_load_lds_dwordx4 v152, s[100:101]
	s_add_u32 m0, s90, 32768
	s_nop 0
	global_load_lds_dwordx4 v153, s[94:95]
	s_add_u32 m0, s90, 8192
	s_nop 0
	global_load_lds_dwordx4 v154, s[100:101]
	s_add_u32 m0, s90, 40960
	s_nop 0
	global_load_lds_dwordx4 v155, s[94:95]
	s_add_u32 m0, s90, 16384
	s_nop 0
	global_load_lds_dwordx4 v156, s[100:101]
	s_add_u32 m0, s90, 49152
	s_nop 0
	global_load_lds_dwordx4 v157, s[94:95]
	s_add_u32 m0, s90, 24576
	s_nop 0
	global_load_lds_dwordx4 v158, s[100:101]
	s_add_u32 m0, s90, 57344
	s_nop 0
	global_load_lds_dwordx4 v168, s[94:95]
	s_xor_b32 s89, s89, 0x10000
.Lgk1_loop:
	ds_read_b128 v[128:131], v231
	ds_read_b128 v[136:139], v235
	ds_read_b128 v[132:135], v231 offset:4096
	ds_read_b128 v[140:143], v235 offset:4096
	ds_read_b128 v[144:147], v235 offset:8192
	ds_read_b128 v[148:151], v235 offset:12288
	s_waitcnt lgkmcnt(6)
	v_mfma_f32_32x32x16_bf16 v[112:127], v[188:191], v[196:199], v[112:127]
	v_mfma_f32_32x32x16_bf16 v[48:63], v[192:195], v[196:199], v[48:63]
	v_mfma_f32_32x32x16_bf16 v[96:111], v[188:191], v[200:203], v[96:111]
	v_mfma_f32_32x32x16_bf16 v[32:47], v[192:195], v[200:203], v[32:47]
	v_mfma_f32_32x32x16_bf16 v[80:95], v[188:191], v[204:207], v[80:95]
	v_mfma_f32_32x32x16_bf16 v[16:31], v[192:195], v[204:207], v[16:31]
	v_mfma_f32_32x32x16_bf16 v[64:79], v[188:191], v[226:229], v[64:79]
	v_mfma_f32_32x32x16_bf16 v[0:15], v[192:195], v[226:229], v[0:15]
	ds_read_b128 v[188:191], v232
	ds_read_b128 v[196:199], v236
	ds_read_b128 v[192:195], v232 offset:4096
	ds_read_b128 v[200:203], v236 offset:4096
	ds_read_b128 v[204:207], v236 offset:8192
	ds_read_b128 v[226:229], v236 offset:12288
	s_waitcnt lgkmcnt(6)
	v_mfma_f32_32x32x16_bf16 v[112:127], v[128:131], v[136:139], v[112:127]
	v_mfma_f32_32x32x16_bf16 v[48:63], v[132:135], v[136:139], v[48:63]
	v_mfma_f32_32x32x16_bf16 v[96:111], v[128:131], v[140:143], v[96:111]
	v_mfma_f32_32x32x16_bf16 v[32:47], v[132:135], v[140:143], v[32:47]
	v_mfma_f32_32x32x16_bf16 v[80:95], v[128:131], v[144:147], v[80:95]
	v_mfma_f32_32x32x16_bf16 v[16:31], v[132:135], v[144:147], v[16:31]
	v_mfma_f32_32x32x16_bf16 v[64:79], v[128:131], v[148:151], v[64:79]
	v_mfma_f32_32x32x16_bf16 v[0:15], v[132:135], v[148:151], v[0:15]
	ds_read_b128 v[128:131], v233
	ds_read_b128 v[136:139], v237
	ds_read_b128 v[132:135], v233 offset:4096
	ds_read_b128 v[140:143], v237 offset:4096
	ds_read_b128 v[144:147], v237 offset:8192
	ds_read_b128 v[148:151], v237 offset:12288
	s_waitcnt lgkmcnt(6)
	v_mfma_f32_32x32x16_bf16 v[112:127], v[188:191], v[196:199], v[112:127]
	v_mfma_f32_32x32x16_bf16 v[48:63], v[192:195], v[196:199], v[48:63]
	v_mfma_f32_32x32x16_bf16 v[96:111], v[188:191], v[200:203], v[96:111]
	v_mfma_f32_32x32x16_bf16 v[32:47], v[192:195], v[200:203], v[32:47]
	v_mfma_f32_32x32x16_bf16 v[80:95], v[188:191], v[204:207], v[80:95]
	v_mfma_f32_32x32x16_bf16 v[16:31], v[192:195], v[204:207], v[16:31]
	v_mfma_f32_32x32x16_bf16 v[64:79], v[188:191], v[226:229], v[64:79]
	v_mfma_f32_32x32x16_bf16 v[0:15], v[192:195], v[226:229], v[0:15]
	s_waitcnt vmcnt(0) lgkmcnt(0)
	s_barrier
	ds_read_b128 v[188:191], v208
	ds_read_b128 v[196:199], v241
	ds_read_b128 v[192:195], v208 offset:4096
	ds_read_b128 v[200:203], v241 offset:4096
	ds_read_b128 v[204:207], v241 offset:8192
	ds_read_b128 v[226:229], v241 offset:12288
	s_add_u32 s94, s2, s92
	s_add_u32 s94, s94, 0x100
	s_and_b32 s94, s94, 0x780
	s_sub_u32 s94, s94, 0x80
	s_subb_u32 s95, 0, 0
	s_add_u32 s100, s96, s94
	s_addc_u32 s101, s97, s95
	s_add_u32 s94, s98, s94
	s_addc_u32 s95, s99, s95
	s_add_u32 s90, s88, s89
	s_add_u32 m0, s90, 0
	v_mfma_f32_32x32x16_bf16 v[112:127], v[128:131], v[136:139], v[112:127]
	global_load_lds_dwordx4 v152, s[100:101]
	s_add_u32 m0, s90, 32768
	v_mfma_f32_32x32x16_bf16 v[48:63], v[132:135], v[136:139], v[48:63]
	global_load_lds_dwordx4 v153, s[94:95]
	s_add_u32 m0, s90, 8192
	v_mfma_f32_32x32x16_bf16 v[96:111], v[128:131], v[140:143], v[96:111]
	global_load_lds_dwordx4 v154, s[100:101]
	s_add_u32 m0, s90, 40960
	v_mfma_f32_32x32x16_bf16 v[32:47], v[132:135], v[140:143], v[32:47]
	global_load_lds_dwordx4 v155, s[94:95]
	s_add_u32 m0, s90, 16384
	v_mfma_f32_32x32x16_bf16 v[80:95], v[128:131], v[144:147], v[80:95]
	global_load_lds_dwordx4 v156, s[100:101]
	s_add_u32 m0, s90, 49152
	v_mfma_f32_32x32x16_bf16 v[16:31], v[132:135], v[144:147], v[16:31]
	global_load_lds_dwordx4 v157, s[94:95]
	s_add_u32 m0, s90, 24576
	v_mfma_f32_32x32x16_bf16 v[64:79], v[128:131], v[148:151], v[64:79]
	global_load_lds_dwordx4 v158, s[100:101]
	s_add_u32 m0, s90, 57344
	v_mfma_f32_32x32x16_bf16 v[0:15], v[132:135], v[148:151], v[0:15]
	global_load_lds_dwordx4 v168, s[94:95]
	s_xor_b32 s89, s89, 0x10000
	s_add_i32 s7, s7, 1
	s_add_u32 s2, s2, 0x80
	s_addc_u32 s3, s3, 0
	ds_read_b128 v[128:131], v238
	ds_read_b128 v[136:139], v253
	ds_read_b128 v[132:135], v238 offset:4096
	ds_read_b128 v[140:143], v253 offset:4096
	ds_read_b128 v[144:147], v253 offset:8192
	ds_read_b128 v[148:151], v253 offset:12288
	s_waitcnt lgkmcnt(6)
	v_mfma_f32_32x32x16_bf16 v[112:127], v[188:191], v[196:199], v[112:127]
	v_mfma_f32_32x32x16_bf16 v[48:63], v[192:195], v[196:199], v[48:63]
	v_mfma_f32_32x32x16_bf16 v[96:111], v[188:191], v[200:203], v[96:111]
	v_mfma_f32_32x32x16_bf16 v[32:47], v[192:195], v[200:203], v[32:47]
	v_mfma_f32_32x32x16_bf16 v[80:95], v[188:191], v[204:207], v[80:95]
	v_mfma_f32_32x32x16_bf16 v[16:31], v[192:195], v[204:207], v[16:31]
	v_mfma_f32_32x32x16_bf16 v[64:79], v[188:191], v[226:229], v[64:79]
	v_mfma_f32_32x32x16_bf16 v[0:15], v[192:195], v[226:229], v[0:15]
	ds_read_b128 v[188:191], v239
	ds_read_b128 v[196:199], v254
	ds_read_b128 v[192:195], v239 offset:4096
	ds_read_b128 v[200:203], v254 offset:4096
	ds_read_b128 v[204:207], v254 offset:8192
	ds_read_b128 v[226:229], v254 offset:12288
	s_waitcnt lgkmcnt(6)
	v_mfma_f32_32x32x16_bf16 v[112:127], v[128:131], v[136:139], v[112:127]
	v_mfma_f32_32x32x16_bf16 v[48:63], v[132:135], v[136:139], v[48:63]
	v_mfma_f32_32x32x16_bf16 v[96:111], v[128:131], v[140:143], v[96:111]
	v_mfma_f32_32x32x16_bf16 v[32:47], v[132:135], v[140:143], v[32:47]
	v_mfma_f32_32x32x16_bf16 v[80:95], v[128:131], v[144:147], v[80:95]
	v_mfma_f32_32x32x16_bf16 v[16:31], v[132:135], v[144:147], v[16:31]
	v_mfma_f32_32x32x16_bf16 v[64:79], v[128:131], v[148:151], v[64:79]
	v_mfma_f32_32x32x16_bf16 v[0:15], v[132:135], v[148:151], v[0:15]
	ds_read_b128 v[128:131], v240
	ds_read_b128 v[136:139], v255
	ds_read_b128 v[132:135], v240 offset:4096
	ds_read_b128 v[140:143], v255 offset:4096
	ds_read_b128 v[144:147], v255 offset:8192
	ds_read_b128 v[148:151], v255 offset:12288
	s_waitcnt lgkmcnt(6)
	v_mfma_f32_32x32x16_bf16 v[112:127], v[188:191], v[196:199], v[112:127]
	v_mfma_f32_32x32x16_bf16 v[48:63], v[192:195], v[196:199], v[48:63]
	v_mfma_f32_32x32x16_bf16 v[96:111], v[188:191], v[200:203], v[96:111]
	v_mfma_f32_32x32x16_bf16 v[32:47], v[192:195], v[200:203], v[32:47]
	v_mfma_f32_32x32x16_bf16 v[80:95], v[188:191], v[204:207], v[80:95]
	v_mfma_f32_32x32x16_bf16 v[16:31], v[192:195], v[204:207], v[16:31]
	v_mfma_f32_32x32x16_bf16 v[64:79], v[188:191], v[226:229], v[64:79]
	v_mfma_f32_32x32x16_bf16 v[0:15], v[192:195], v[226:229], v[0:15]
	s_waitcnt vmcnt(0) lgkmcnt(0)
	s_barrier
	ds_read_b128 v[188:191], v230
	ds_read_b128 v[196:199], v234
	ds_read_b128 v[192:195], v230 offset:4096
	ds_read_b128 v[200:203], v234 offset:4096
	ds_read_b128 v[204:207], v234 offset:8192
	ds_read_b128 v[226:229], v234 offset:12288
	s_add_u32 s94, s2, s92
	s_add_u32 s94, s94, 0x100
	s_and_b32 s94, s94, 0x780
	s_sub_u32 s94, s94, 0x80
	s_subb_u32 s95, 0, 0
	s_add_u32 s100, s96, s94
	s_addc_u32 s101, s97, s95
	s_add_u32 s94, s98, s94
	s_addc_u32 s95, s99, s95
	s_add_u32 s90, s88, s89
	s_add_u32 m0, s90, 0
	v_mfma_f32_32x32x16_bf16 v[112:127], v[128:131], v[136:139], v[112:127]
	global_load_lds_dwordx4 v152, s[100:101]
	s_add_u32 m0, s90, 32768
	v_mfma_f32_32x32x16_bf16 v[48:63], v[132:135], v[136:139], v[48:63]
	global_load_lds_dwordx4 v153, s[94:95]
	s_add_u32 m0, s90, 8192
	v_mfma_f32_32x32x16_bf16 v[96:111], v[128:131], v[140:143], v[96:111]
	global_load_lds_dwordx4 v154, s[100:101]
	s_add_u32 m0, s90, 40960
	v_mfma_f32_32x32x16_bf16 v[32:47], v[132:135], v[140:143], v[32:47]
	global_load_lds_dwordx4 v155, s[94:95]
	s_add_u32 m0, s90, 16384
	v_mfma_f32_32x32x16_bf16 v[80:95], v[128:131], v[144:147], v[80:95]
	global_load_lds_dwordx4 v156, s[100:101]
	s_add_u32 m0, s90, 49152
	v_mfma_f32_32x32x16_bf16 v[16:31], v[132:135], v[144:147], v[16:31]
	global_load_lds_dwordx4 v157, s[94:95]
	s_add_u32 m0, s90, 24576
	v_mfma_f32_32x32x16_bf16 v[64:79], v[128:131], v[148:151], v[64:79]
	global_load_lds_dwordx4 v158, s[100:101]
	s_add_u32 m0, s90, 57344
	v_mfma_f32_32x32x16_bf16 v[0:15], v[132:135], v[148:151], v[0:15]
	global_load_lds_dwordx4 v168, s[94:95]
	s_xor_b32 s89, s89, 0x10000
	s_add_i32 s7, s7, 1
	s_add_u32 s2, s2, 0x80
	s_addc_u32 s3, s3, 0
	s_cmpk_eq_i32 s2, 0x700
	s_cbranch_scc0 .Lgk1_loop
	ds_read_b128 v[128:131], v231
	ds_read_b128 v[136:139], v235
	ds_read_b128 v[132:135], v231 offset:4096
	ds_read_b128 v[140:143], v235 offset:4096
	ds_read_b128 v[144:147], v235 offset:8192
	ds_read_b128 v[148:151], v235 offset:12288
	s_waitcnt lgkmcnt(6)
	v_mfma_f32_32x32x16_bf16 v[112:127], v[188:191], v[196:199], v[112:127]
	v_mfma_f32_32x32x16_bf16 v[48:63], v[192:195], v[196:199], v[48:63]
	v_mfma_f32_32x32x16_bf16 v[96:111], v[188:191], v[200:203], v[96:111]
	v_mfma_f32_32x32x16_bf16 v[32:47], v[192:195], v[200:203], v[32:47]
	v_mfma_f32_32x32x16_bf16 v[80:95], v[188:191], v[204:207], v[80:95]
	v_mfma_f32_32x32x16_bf16 v[16:31], v[192:195], v[204:207], v[16:31]
	v_mfma_f32_32x32x16_bf16 v[64:79], v[188:191], v[226:229], v[64:79]
	v_mfma_f32_32x32x16_bf16 v[0:15], v[192:195], v[226:229], v[0:15]
	ds_read_b128 v[188:191], v232
	ds_read_b128 v[196:199], v236
	ds_read_b128 v[192:195], v232 offset:4096
	ds_read_b128 v[200:203], v236 offset:4096
	ds_read_b128 v[204:207], v236 offset:8192
	ds_read_b128 v[226:229], v236 offset:12288
	s_waitcnt lgkmcnt(6)
	v_mfma_f32_32x32x16_bf16 v[112:127], v[128:131], v[136:139], v[112:127]
	v_mfma_f32_32x32x16_bf16 v[48:63], v[132:135], v[136:139], v[48:63]
	v_mfma_f32_32x32x16_bf16 v[96:111], v[128:131], v[140:143], v[96:111]
	v_mfma_f32_32x32x16_bf16 v[32:47], v[132:135], v[140:143], v[32:47]
	v_mfma_f32_32x32x16_bf16 v[80:95], v[128:131], v[144:147], v[80:95]
	v_mfma_f32_32x32x16_bf16 v[16:31], v[132:135], v[144:147], v[16:31]
	v_mfma_f32_32x32x16_bf16 v[64:79], v[128:131], v[148:151], v[64:79]
	v_mfma_f32_32x32x16_bf16 v[0:15], v[132:135], v[148:151], v[0:15]
	ds_read_b128 v[128:131], v233
	ds_read_b128 v[136:139], v237
	ds_read_b128 v[132:135], v233 offset:4096
	ds_read_b128 v[140:143], v237 offset:4096
	ds_read_b128 v[144:147], v237 offset:8192
	ds_read_b128 v[148:151], v237 offset:12288
	s_waitcnt lgkmcnt(6)
	v_mfma_f32_32x32x16_bf16 v[112:127], v[188:191], v[196:199], v[112:127]
	v_mfma_f32_32x32x16_bf16 v[48:63], v[192:195], v[196:199], v[48:63]
	v_mfma_f32_32x32x16_bf16 v[96:111], v[188:191], v[200:203], v[96:111]
	v_mfma_f32_32x32x16_bf16 v[32:47], v[192:195], v[200:203], v[32:47]
	v_mfma_f32_32x32x16_bf16 v[80:95], v[188:191], v[204:207], v[80:95]
	v_mfma_f32_32x32x16_bf16 v[16:31], v[192:195], v[204:207], v[16:31]
	v_mfma_f32_32x32x16_bf16 v[64:79], v[188:191], v[226:229], v[64:79]
	v_mfma_f32_32x32x16_bf16 v[0:15], v[192:195], v[226:229], v[0:15]
	s_waitcnt vmcnt(0) lgkmcnt(0)
	s_barrier
	ds_read_b128 v[188:191], v208
	ds_read_b128 v[196:199], v241
	ds_read_b128 v[192:195], v208 offset:4096
	ds_read_b128 v[200:203], v241 offset:4096
	ds_read_b128 v[204:207], v241 offset:8192
	ds_read_b128 v[226:229], v241 offset:12288
	v_mfma_f32_32x32x16_bf16 v[112:127], v[128:131], v[136:139], v[112:127]
	v_mfma_f32_32x32x16_bf16 v[48:63], v[132:135], v[136:139], v[48:63]
	v_mfma_f32_32x32x16_bf16 v[96:111], v[128:131], v[140:143], v[96:111]
	v_mfma_f32_32x32x16_bf16 v[32:47], v[132:135], v[140:143], v[32:47]
	v_mfma_f32_32x32x16_bf16 v[80:95], v[128:131], v[144:147], v[80:95]
	v_mfma_f32_32x32x16_bf16 v[16:31], v[132:135], v[144:147], v[16:31]
	v_mfma_f32_32x32x16_bf16 v[64:79], v[128:131], v[148:151], v[64:79]
	v_mfma_f32_32x32x16_bf16 v[0:15], v[132:135], v[148:151], v[0:15]
	s_xor_b32 s89, s89, 0x10000
	s_add_i32 s7, s7, 1
	s_add_u32 s2, s2, 0x80
	s_addc_u32 s3, s3, 0
	s_add_i32 s54, s5, s42
	s_cmpk_gt_i32 s54, 0x1ff
	s_cselect_b64 s[20:21], -1, 0
	s_and_b64 vcc, exec, s[20:21]
	s_cbranch_vccnz .LBB0_1279
	s_ashr_i32 s2, s54, 31
	s_lshr_b32 s2, s2, 30
	s_add_i32 s2, s54, s2
	s_ashr_i32 s2, s2, 2
	s_lshl_b32 s3, s2, 8
	v_add_u32_e32 v129, s3, v213
	s_lshl_b32 s2, s2, 10
	s_lshl_b32 s7, s54, 8
	v_min_i32_e32 v132, 0x7fff, v129
	v_add_u32_e32 v129, s3, v171
	s_sub_i32 s2, s7, s2
	v_add_u32_e32 v128, s3, v212
	v_min_i32_e32 v136, 0x7fff, v129
	v_add_u32_e32 v129, s3, v215
	v_min_i32_e32 v128, 0x7fff, v128
	v_add_u32_e32 v130, s2, v212
	v_add_u32_e32 v134, s2, v213
	v_add_u32_e32 v138, s2, v171
	v_min_i32_e32 v140, 0x7fff, v129
	v_add_u32_e32 v142, s2, v215
	v_ashrrev_i32_e32 v143, 31, v142
	v_ashrrev_i32_e32 v141, 31, v140
	v_ashrrev_i32_e32 v139, 31, v138
	v_ashrrev_i32_e32 v137, 31, v136
	v_ashrrev_i32_e32 v135, 31, v134
	v_ashrrev_i32_e32 v133, 31, v132
	v_ashrrev_i32_e32 v131, 31, v130
	v_ashrrev_i32_e32 v129, 31, v128
	v_lshlrev_b64 v[142:143], 11, v[142:143]
	v_lshlrev_b64 v[140:141], 11, v[140:141]
	v_lshlrev_b64 v[138:139], 11, v[138:139]
	v_lshlrev_b64 v[136:137], 11, v[136:137]
	v_lshlrev_b64 v[134:135], 11, v[134:135]
	v_lshlrev_b64 v[132:133], 11, v[132:133]
	v_lshlrev_b64 v[130:131], 11, v[130:131]
	v_lshlrev_b64 v[128:129], 11, v[128:129]
	v_lshl_add_u64 v[156:157], v[172:173], 0, v[142:143]
	v_lshl_add_u64 v[152:153], v[174:175], 0, v[140:141]
	v_lshl_add_u64 v[148:149], v[172:173], 0, v[138:139]
	v_lshl_add_u64 v[144:145], v[174:175], 0, v[136:137]
	v_lshl_add_u64 v[140:141], v[172:173], 0, v[134:135]
	v_lshl_add_u64 v[136:137], v[174:175], 0, v[132:133]
	v_lshl_add_u64 v[132:133], v[172:173], 0, v[130:131]
	v_lshl_add_u64 v[128:129], v[174:175], 0, v[128:129]
	s_add_u32 m0, s88, 0
	v_lshl_add_u64 v[128:129], v[128:129], 0, s[92:93]
	v_xor_b32_e32 v128, v159, v128
	global_load_lds_dwordx4 v[128:129], off
	s_add_u32 m0, s88, 32768
	v_lshl_add_u64 v[132:133], v[132:133], 0, s[92:93]
	v_xor_b32_e32 v132, v159, v132
	global_load_lds_dwordx4 v[132:133], off
	s_add_u32 m0, s88, 8192
	v_lshl_add_u64 v[136:137], v[136:137], 0, s[92:93]
	v_xor_b32_e32 v136, v159, v136
	global_load_lds_dwordx4 v[136:137], off
	s_add_u32 m0, s88, 40960
	v_lshl_add_u64 v[140:141], v[140:141], 0, s[92:93]
	v_xor_b32_e32 v140, v159, v140
	global_load_lds_dwordx4 v[140:141], off
	s_add_u32 m0, s88, 16384
	v_lshl_add_u64 v[144:145], v[144:145], 0, s[92:93]
	v_xor_b32_e32 v144, v159, v144
	global_load_lds_dwordx4 v[144:145], off
	s_add_u32 m0, s88, 49152
	v_lshl_add_u64 v[148:149], v[148:149], 0, s[92:93]
	v_xor_b32_e32 v148, v159, v148
	global_load_lds_dwordx4 v[148:149], off
	s_add_u32 m0, s88, 24576
	v_lshl_add_u64 v[152:153], v[152:153], 0, s[92:93]
	v_xor_b32_e32 v152, v159, v152
	global_load_lds_dwordx4 v[152:153], off
	s_add_u32 m0, s88, 57344
	v_lshl_add_u64 v[156:157], v[156:157], 0, s[92:93]
	v_xor_b32_e32 v156, v159, v156
	global_load_lds_dwordx4 v[156:157], off
.LBB0_1279:
	ds_read_b128 v[128:131], v238
	ds_read_b128 v[136:139], v253
	ds_read_b128 v[132:135], v238 offset:4096
	ds_read_b128 v[140:143], v253 offset:4096
	ds_read_b128 v[144:147], v253 offset:8192
	ds_read_b128 v[148:151], v253 offset:12288
	s_waitcnt lgkmcnt(6)
	v_mfma_f32_32x32x16_bf16 v[112:127], v[188:191], v[196:199], v[112:127]
	v_mfma_f32_32x32x16_bf16 v[48:63], v[192:195], v[196:199], v[48:63]
	v_mfma_f32_32x32x16_bf16 v[96:111], v[188:191], v[200:203], v[96:111]
	v_mfma_f32_32x32x16_bf16 v[32:47], v[192:195], v[200:203], v[32:47]
	v_mfma_f32_32x32x16_bf16 v[80:95], v[188:191], v[204:207], v[80:95]
	v_mfma_f32_32x32x16_bf16 v[16:31], v[192:195], v[204:207], v[16:31]
	v_mfma_f32_32x32x16_bf16 v[64:79], v[188:191], v[226:229], v[64:79]
	v_mfma_f32_32x32x16_bf16 v[0:15], v[192:195], v[226:229], v[0:15]
	ds_read_b128 v[188:191], v239
	ds_read_b128 v[196:199], v254
	ds_read_b128 v[192:195], v239 offset:4096
	ds_read_b128 v[200:203], v254 offset:4096
	ds_read_b128 v[204:207], v254 offset:8192
	ds_read_b128 v[226:229], v254 offset:12288
	s_waitcnt lgkmcnt(6)
	v_mfma_f32_32x32x16_bf16 v[112:127], v[128:131], v[136:139], v[112:127]
	v_mfma_f32_32x32x16_bf16 v[48:63], v[132:135], v[136:139], v[48:63]
	v_mfma_f32_32x32x16_bf16 v[96:111], v[128:131], v[140:143], v[96:111]
	v_mfma_f32_32x32x16_bf16 v[32:47], v[132:135], v[140:143], v[32:47]
	v_mfma_f32_32x32x16_bf16 v[80:95], v[128:131], v[144:147], v[80:95]
	v_mfma_f32_32x32x16_bf16 v[16:31], v[132:135], v[144:147], v[16:31]
	v_mfma_f32_32x32x16_bf16 v[64:79], v[128:131], v[148:151], v[64:79]
	v_mfma_f32_32x32x16_bf16 v[0:15], v[132:135], v[148:151], v[0:15]
	ds_read_b128 v[128:131], v240
	ds_read_b128 v[136:139], v255
	ds_read_b128 v[132:135], v240 offset:4096
	ds_read_b128 v[140:143], v255 offset:4096
	ds_read_b128 v[144:147], v255 offset:8192
	ds_read_b128 v[148:151], v255 offset:12288
	s_waitcnt lgkmcnt(6)
	v_mfma_f32_32x32x16_bf16 v[112:127], v[188:191], v[196:199], v[112:127]
	v_mfma_f32_32x32x16_bf16 v[48:63], v[192:195], v[196:199], v[48:63]
	v_mfma_f32_32x32x16_bf16 v[96:111], v[188:191], v[200:203], v[96:111]
	v_mfma_f32_32x32x16_bf16 v[32:47], v[192:195], v[200:203], v[32:47]
	v_mfma_f32_32x32x16_bf16 v[80:95], v[188:191], v[204:207], v[80:95]
	v_mfma_f32_32x32x16_bf16 v[16:31], v[192:195], v[204:207], v[16:31]
	v_mfma_f32_32x32x16_bf16 v[64:79], v[188:191], v[226:229], v[64:79]
	v_mfma_f32_32x32x16_bf16 v[0:15], v[192:195], v[226:229], v[0:15]
	s_waitcnt vmcnt(0) lgkmcnt(0)
	s_barrier
	v_mfma_f32_32x32x16_bf16 v[112:127], v[128:131], v[136:139], v[112:127]
	v_mfma_f32_32x32x16_bf16 v[48:63], v[132:135], v[136:139], v[48:63]
	v_mfma_f32_32x32x16_bf16 v[96:111], v[128:131], v[140:143], v[96:111]
	v_mfma_f32_32x32x16_bf16 v[32:47], v[132:135], v[140:143], v[32:47]
	v_mfma_f32_32x32x16_bf16 v[80:95], v[128:131], v[144:147], v[80:95]
	v_mfma_f32_32x32x16_bf16 v[16:31], v[132:135], v[144:147], v[16:31]
	v_mfma_f32_32x32x16_bf16 v[64:79], v[128:131], v[148:151], v[64:79]
	v_mfma_f32_32x32x16_bf16 v[0:15], v[132:135], v[148:151], v[0:15]
	s_lshl_b32 s2, s5, 8
	s_sub_i32 s2, s2, s6
	v_mov_b32_e32 v168, v214
	s_add_i32 s55, s4, s30
	s_or_b32 s26, s2, s31
	s_ashr_i32 s27, s26, 31
	s_load_dwordx2 s[24:25], s[0:1], 0x140
	v_ashrrev_i32_e32 v180, 3, v168
	v_and_b32_e32 v183, -4, v180
	v_add_u32_e32 v225, s55, v183
	v_add_u32_e32 v190, 8, v225
	v_min_i32_e32 v190, 0x7fff, v190
	v_ashrrev_i32_e32 v190, 12, v190
	v_min_i32_e32 v184, 0x7fff, v225
	v_and_b32_e32 v182, 31, v168
	v_ashrrev_i32_e32 v184, 12, v184
	v_or_b32_e32 v180, s26, v182
	v_mul_hi_i32_i24_e32 v185, 0x3000, v184
	v_mul_i32_i24_e32 v184, 0x3000, v184
	v_ashrrev_i32_e32 v181, 31, v180
	s_waitcnt lgkmcnt(0)
	v_lshl_add_u64 v[184:185], s[24:25], 0, v[184:185]
	v_add_u32_e32 v188, 9, v225
	v_mul_hi_i32_i24_e32 v187, 0x3000, v190
	v_mul_i32_i24_e32 v186, 0x3000, v190
	v_min_i32_e32 v188, 0x7fff, v188
	v_add_u32_e32 v190, 10, v225
	v_ashrrev_i32_e32 v188, 12, v188
	v_min_i32_e32 v190, 0x7fff, v190
	v_mul_hi_i32_i24_e32 v189, 0x3000, v188
	v_mul_i32_i24_e32 v188, 0x3000, v188
	v_ashrrev_i32_e32 v190, 12, v190
	v_lshl_add_u64 v[188:189], s[24:25], 0, v[188:189]
	v_mul_hi_i32_i24_e32 v191, 0x3000, v190
	v_mul_i32_i24_e32 v190, 0x3000, v190
	v_lshl_add_u64 v[184:185], v[184:185], 0, s[18:19]
	v_lshlrev_b64 v[180:181], 2, v[180:181]
	v_lshl_add_u64 v[186:187], s[24:25], 0, v[186:187]
	v_lshl_add_u64 v[188:189], v[188:189], 0, s[18:19]
	v_lshl_add_u64 v[190:191], s[24:25], 0, v[190:191]
	v_lshl_add_u64 v[208:209], v[184:185], 0, v[180:181]
	v_lshl_add_u64 v[186:187], v[186:187], 0, s[18:19]
	v_lshl_add_u64 v[190:191], v[190:191], 0, s[18:19]
	v_lshl_add_u64 v[230:231], v[186:187], 0, v[180:181]
	v_lshl_add_u64 v[196:197], v[188:189], 0, v[180:181]
	v_lshl_add_u64 v[198:199], v[190:191], 0, v[180:181]
	global_load_dword v232, v[208:209], off
	global_load_dword v233, v[208:209], off offset:128
	global_load_dword v238, v[230:231], off
	global_load_dword v239, v[230:231], off offset:128
	global_load_dword v240, v[196:197], off
	global_load_dword v241, v[196:197], off offset:128
	global_load_dword v242, v[198:199], off
	global_load_dword v243, v[198:199], off offset:128
	v_add_u32_e32 v196, 17, v225
	v_min_i32_e32 v196, 0x7fff, v196
	v_add_u32_e32 v198, 18, v225
	v_ashrrev_i32_e32 v196, 12, v196
	v_min_i32_e32 v198, 0x7fff, v198
	v_mul_hi_i32_i24_e32 v197, 0x3000, v196
	v_mul_i32_i24_e32 v196, 0x3000, v196
	v_ashrrev_i32_e32 v198, 12, v198
	v_lshl_add_u64 v[196:197], s[24:25], 0, v[196:197]
	v_mul_hi_i32_i24_e32 v199, 0x3000, v198
	v_mul_i32_i24_e32 v198, 0x3000, v198
	v_add_u32_e32 v192, 11, v225
	v_add_u32_e32 v194, 16, v225
	v_min_i32_e32 v192, 0x7fff, v192
	v_min_i32_e32 v194, 0x7fff, v194
	v_ashrrev_i32_e32 v192, 12, v192
	v_ashrrev_i32_e32 v194, 12, v194
	v_mul_hi_i32_i24_e32 v193, 0x3000, v192
	v_mul_i32_i24_e32 v192, 0x3000, v192
	v_mul_hi_i32_i24_e32 v195, 0x3000, v194
	v_mul_i32_i24_e32 v194, 0x3000, v194
	v_lshl_add_u64 v[192:193], s[24:25], 0, v[192:193]
	v_lshl_add_u64 v[194:195], s[24:25], 0, v[194:195]
	v_lshl_add_u64 v[192:193], v[192:193], 0, s[18:19]
	v_lshl_add_u64 v[194:195], v[194:195], 0, s[18:19]
	v_lshl_add_u64 v[196:197], v[196:197], 0, s[18:19]
	v_lshl_add_u64 v[198:199], s[24:25], 0, v[198:199]
	v_lshl_add_u64 v[208:209], v[192:193], 0, v[180:181]
	v_lshl_add_u64 v[198:199], v[198:199], 0, s[18:19]
	v_lshl_add_u64 v[226:227], v[198:199], 0, v[180:181]
	s_waitcnt vmcnt(7)
	v_mul_f32_e32 v112, v112, v232
	v_lshl_add_u64 v[204:205], v[194:195], 0, v[180:181]
	v_lshl_add_u64 v[206:207], v[196:197], 0, v[180:181]
	s_waitcnt vmcnt(6)
	s_nop 2
	v_mul_f32_e32 v96, v96, v233
	v_mul_f32_e32 v97, v97, v233
	global_load_dword v234, v[208:209], off
	global_load_dword v235, v[208:209], off offset:128
	global_load_dword v236, v[204:205], off
	global_load_dword v237, v[204:205], off offset:128
	global_load_dword v244, v[206:207], off
	global_load_dword v245, v[206:207], off offset:128
	global_load_dword v246, v[226:227], off
	global_load_dword v247, v[226:227], off offset:128
	v_add_u32_e32 v204, 25, v225
	v_add_u32_e32 v206, 26, v225
	v_min_i32_e32 v204, 0x7fff, v204
	v_min_i32_e32 v206, 0x7fff, v206
	v_ashrrev_i32_e32 v204, 12, v204
	v_ashrrev_i32_e32 v206, 12, v206
	v_add_u32_e32 v200, 19, v225
	v_min_i32_e32 v200, 0x7fff, v200
	v_add_u32_e32 v202, 24, v225
	v_ashrrev_i32_e32 v200, 12, v200
	v_min_i32_e32 v202, 0x7fff, v202
	v_mul_hi_i32_i24_e32 v201, 0x3000, v200
	v_mul_i32_i24_e32 v200, 0x3000, v200
	v_ashrrev_i32_e32 v202, 12, v202
	v_mul_hi_i32_i24_e32 v205, 0x3000, v204
	v_mul_i32_i24_e32 v204, 0x3000, v204
	v_mul_hi_i32_i24_e32 v207, 0x3000, v206
	v_mul_i32_i24_e32 v206, 0x3000, v206
	v_lshl_add_u64 v[200:201], s[24:25], 0, v[200:201]
	v_mul_hi_i32_i24_e32 v203, 0x3000, v202
	v_mul_i32_i24_e32 v202, 0x3000, v202
	v_lshl_add_u64 v[204:205], s[24:25], 0, v[204:205]
	v_lshl_add_u64 v[206:207], s[24:25], 0, v[206:207]
	v_lshl_add_u64 v[200:201], v[200:201], 0, s[18:19]
	v_lshl_add_u64 v[202:203], s[24:25], 0, v[202:203]
	v_lshl_add_u64 v[204:205], v[204:205], 0, s[18:19]
	v_lshl_add_u64 v[206:207], v[206:207], 0, s[18:19]
	v_lshl_add_u64 v[208:209], v[200:201], 0, v[180:181]
	v_lshl_add_u64 v[202:203], v[202:203], 0, s[18:19]
	v_lshl_add_u64 v[228:229], v[204:205], 0, v[180:181]
	v_lshl_add_u64 v[230:231], v[206:207], 0, v[180:181]
	v_lshl_add_u64 v[226:227], v[202:203], 0, v[180:181]
	global_load_dword v248, v[208:209], off
	global_load_dword v249, v[208:209], off offset:128
	global_load_dword v250, v[226:227], off
	global_load_dword v251, v[226:227], off offset:128
	global_load_dword v252, v[228:229], off
	s_nop 0
	global_load_dword v228, v[228:229], off offset:128
	s_nop 0
	global_load_dword v229, v[230:231], off
	s_nop 0
	global_load_dword v230, v[230:231], off offset:128
	v_add_u32_e32 v208, 27, v225
	v_min_i32_e32 v208, 0x7fff, v208
	v_ashrrev_i32_e32 v208, 12, v208
	v_mul_hi_i32_i24_e32 v209, 0x3000, v208
	v_mul_i32_i24_e32 v208, 0x3000, v208
	v_lshl_add_u64 v[208:209], s[24:25], 0, v[208:209]
	v_lshl_add_u64 v[208:209], v[208:209], 0, s[18:19]
	v_lshl_add_u64 v[226:227], v[208:209], 0, v[180:181]
	global_load_dword v225, v[226:227], off
	s_nop 0
	global_load_dword v226, v[226:227], off offset:128
	v_mad_u64_u32 v[160:161], s[2:3], v183, s36, v[182:183]
	v_lshl_add_u32 v162, v160, 2, s34
	ds_write2_b32 v162, v112, v96 offset1:32
	v_mul_f32_e32 v96, v113, v232
	ds_write2_b32 v162, v96, v97 offset0:68 offset1:100
	v_mul_f32_e32 v96, v114, v232
	v_mul_f32_e32 v97, v98, v233
	ds_write2_b32 v162, v96, v97 offset0:136 offset1:168
	v_mul_f32_e32 v96, v115, v232
	v_mul_f32_e32 v97, v99, v233
	ds_write2_b32 v162, v96, v97 offset0:204 offset1:236
	s_waitcnt vmcnt(23)
	v_mul_f32_e32 v96, v116, v238
	s_waitcnt vmcnt(22)
	v_mul_f32_e32 v97, v100, v239
	v_add_u32_e32 v115, 0x800, v162
	ds_write2_b32 v115, v96, v97 offset0:32 offset1:64
	s_waitcnt vmcnt(21)
	v_mul_f32_e32 v96, v117, v240
	s_waitcnt vmcnt(20)
	v_mul_f32_e32 v97, v101, v241
	ds_write2_b32 v115, v96, v97 offset0:100 offset1:132
	s_waitcnt vmcnt(19)
	v_mul_f32_e32 v96, v118, v242
	s_waitcnt vmcnt(18)
	v_mul_f32_e32 v97, v102, v243
	ds_write2_b32 v115, v96, v97 offset0:168 offset1:200
	v_add_u32_e32 v116, 0xa00, v162
	v_add_u32_e32 v117, 0x1000, v162
	v_add_u32_e32 v118, 0x1400, v162
	v_ashrrev_i32_e32 v163, 4, v168
	v_and_b32_e32 v160, 15, v168
	v_mul_lo_u32 v161, v163, s37
	s_waitcnt vmcnt(17)
	v_mul_f32_e32 v96, v119, v234
	s_waitcnt vmcnt(16)
	v_mul_f32_e32 v97, v103, v235
	ds_write2_b32 v116, v96, v97 offset0:108 offset1:140
	s_waitcnt vmcnt(15)
	v_mul_f32_e32 v96, v120, v236
	s_waitcnt vmcnt(14)
	v_mul_f32_e32 v97, v104, v237
	ds_write2_b32 v117, v96, v97 offset0:64 offset1:96
	s_waitcnt vmcnt(13)
	v_mul_f32_e32 v96, v121, v244
	s_waitcnt vmcnt(12)
	v_mul_f32_e32 v97, v105, v245
	ds_write2_b32 v117, v96, v97 offset0:132 offset1:164
	s_waitcnt vmcnt(11)
	v_mul_f32_e32 v96, v122, v246
	s_waitcnt vmcnt(10)
	v_mul_f32_e32 v97, v106, v247
	ds_write2_b32 v117, v96, v97 offset0:200 offset1:232
	v_add_u32_e32 v119, 0x1800, v162
	v_add_u32_e32 v120, 0x1a00, v162
	v_lshl_add_u32 v164, v160, 4, s34
	v_lshlrev_b32_e32 v168, 2, v160
	v_add_u32_e32 v160, s55, v163
	v_add_u32_e32 v121, 0x1c00, v162
	v_cmp_gt_i32_e32 vcc, s38, v160
	v_add_u32_e32 v114, v164, v161
	v_ashrrev_i32_e32 v161, 31, v160
	s_waitcnt vmcnt(9)
	v_mul_f32_e32 v96, v123, v248
	s_waitcnt vmcnt(8)
	v_mul_f32_e32 v97, v107, v249
	ds_write2_b32 v118, v96, v97 offset0:12 offset1:44
	s_waitcnt vmcnt(7)
	v_mul_f32_e32 v96, v124, v250
	s_waitcnt vmcnt(6)
	v_mul_f32_e32 v97, v108, v251
	ds_write2_b32 v119, v96, v97 offset0:96 offset1:128
	s_waitcnt vmcnt(5)
	v_mul_f32_e32 v96, v125, v252
	s_waitcnt vmcnt(4)
	v_mul_f32_e32 v97, v109, v228
	ds_write2_b32 v119, v96, v97 offset0:164 offset1:196
	s_waitcnt vmcnt(3)
	v_mul_f32_e32 v96, v126, v229
	s_waitcnt vmcnt(2)
	v_mul_f32_e32 v97, v110, v230
	ds_write2_b32 v120, v96, v97 offset0:104 offset1:136
	s_waitcnt vmcnt(1)
	v_mul_f32_e32 v96, v127, v225
	s_waitcnt vmcnt(0)
	v_mul_f32_e32 v97, v111, v226
	ds_write2_b32 v121, v96, v97 offset0:44 offset1:76
	v_or_b32_e32 v96, s26, v168
	v_mov_b32_e32 v97, s27
	v_add_u32_e32 v128, 0, v160
	v_ashrrev_i32_e32 v129, 31, v128
	v_lshlrev_b64 v[128:129], 10, v[128:129]
	v_lshl_add_u64 v[128:129], v[128:129], 0, v[96:97]
	v_lshlrev_b64 v[128:129], 2, v[128:129]
	v_lshl_add_u64 v[128:129], s[16:17], 0, v[128:129]
	global_load_dwordx4 v[128:131], v[128:129], off
	v_add_u32_e32 v132, 4, v160
	v_ashrrev_i32_e32 v133, 31, v132
	v_lshlrev_b64 v[132:133], 10, v[132:133]
	v_lshl_add_u64 v[132:133], v[132:133], 0, v[96:97]
	v_lshlrev_b64 v[132:133], 2, v[132:133]
	v_lshl_add_u64 v[132:133], s[16:17], 0, v[132:133]
	global_load_dwordx4 v[132:135], v[132:133], off
	v_add_u32_e32 v136, 8, v160
	v_ashrrev_i32_e32 v137, 31, v136
	v_lshlrev_b64 v[136:137], 10, v[136:137]
	v_lshl_add_u64 v[136:137], v[136:137], 0, v[96:97]
	v_lshlrev_b64 v[136:137], 2, v[136:137]
	v_lshl_add_u64 v[136:137], s[16:17], 0, v[136:137]
	global_load_dwordx4 v[136:139], v[136:137], off
	v_add_u32_e32 v140, 12, v160
	v_ashrrev_i32_e32 v141, 31, v140
	v_lshlrev_b64 v[140:141], 10, v[140:141]
	v_lshl_add_u64 v[140:141], v[140:141], 0, v[96:97]
	v_lshlrev_b64 v[140:141], 2, v[140:141]
	v_lshl_add_u64 v[140:141], s[16:17], 0, v[140:141]
	global_load_dwordx4 v[140:143], v[140:141], off
	v_add_u32_e32 v144, 16, v160
	v_ashrrev_i32_e32 v145, 31, v144
	v_lshlrev_b64 v[144:145], 10, v[144:145]
	v_lshl_add_u64 v[144:145], v[144:145], 0, v[96:97]
	v_lshlrev_b64 v[144:145], 2, v[144:145]
	v_lshl_add_u64 v[144:145], s[16:17], 0, v[144:145]
	global_load_dwordx4 v[144:147], v[144:145], off
	v_add_u32_e32 v148, 20, v160
	v_ashrrev_i32_e32 v149, 31, v148
	v_lshlrev_b64 v[148:149], 10, v[148:149]
	v_lshl_add_u64 v[148:149], v[148:149], 0, v[96:97]
	v_lshlrev_b64 v[148:149], 2, v[148:149]
	v_lshl_add_u64 v[148:149], s[16:17], 0, v[148:149]
	global_load_dwordx4 v[148:151], v[148:149], off
	v_add_u32_e32 v152, 24, v160
	v_ashrrev_i32_e32 v153, 31, v152
	v_lshlrev_b64 v[152:153], 10, v[152:153]
	v_lshl_add_u64 v[152:153], v[152:153], 0, v[96:97]
	v_lshlrev_b64 v[152:153], 2, v[152:153]
	v_lshl_add_u64 v[152:153], s[16:17], 0, v[152:153]
	global_load_dwordx4 v[152:155], v[152:153], off
	v_add_u32_e32 v156, 28, v160
	v_ashrrev_i32_e32 v157, 31, v156
	v_lshlrev_b64 v[156:157], 10, v[156:157]
	v_lshl_add_u64 v[156:157], v[156:157], 0, v[96:97]
	v_lshlrev_b64 v[156:157], 2, v[156:157]
	v_lshl_add_u64 v[156:157], s[16:17], 0, v[156:157]
	global_load_dwordx4 v[156:159], v[156:157], off
	s_and_saveexec_b64 s[2:3], vcc
	s_cbranch_execz .LBB0_1281
	v_lshlrev_b64 v[98:99], 10, v[160:161]
	v_lshl_add_u64 v[98:99], v[98:99], 0, v[96:97]
	v_lshlrev_b64 v[106:107], 2, v[98:99]
	v_lshl_add_u64 v[98:99], s[16:17], 0, v[106:107]
	ds_read_b128 v[102:105], v114
	s_load_dwordx2 s[4:5], s[0:1], 0xb8
	s_waitcnt vmcnt(7) lgkmcnt(0)
	v_pk_add_f32 v[100:101], v[104:105], v[130:131]
	v_pk_add_f32 v[98:99], v[102:103], v[128:129]
	v_lshl_add_u64 v[102:103], s[4:5], 0, v[106:107]
	global_store_dwordx4 v[102:103], v[98:101], off

.LBB0_1466:
	s_mul_hi_i32 s2, s8, 0x38e38e39
	s_lshr_b32 s3, s2, 31
	s_ashr_i32 s4, s2, 1
	s_add_i32 s4, s4, s3
	s_lshl_b32 s77, s4, 8
	v_add_u32_e32 v0, s77, v193
	v_min_i32_e32 v0, 0x7fff, v0
	v_ashrrev_i32_e32 v1, 31, v0
	v_lshlrev_b64 v[0:1], 11, v[0:1]
	s_mul_i32 s2, s4, 0x900
	v_lshl_add_u64 v[172:173], v[168:169], 0, v[0:1]
	v_subrev_u32_e32 v0, s2, v201
	v_ashrrev_i32_e32 v1, 31, v0
	v_lshlrev_b64 v[0:1], 11, v[0:1]
	v_lshl_add_u64 v[180:181], v[170:171], 0, v[0:1]
	v_subrev_u32_e32 v0, s2, v202
	v_ashrrev_i32_e32 v1, 31, v0
	v_lshlrev_b64 v[0:1], 11, v[0:1]
	v_lshl_add_u64 v[182:183], v[170:171], 0, v[0:1]
	v_subrev_u32_e32 v0, s2, v203
	v_ashrrev_i32_e32 v1, 31, v0
	v_add_u32_e32 v2, s77, v194
	v_add_u32_e32 v4, s77, v163
	v_add_u32_e32 v6, s77, v196
	v_lshlrev_b64 v[0:1], 11, v[0:1]
	v_min_i32_e32 v2, 0x7fff, v2
	v_min_i32_e32 v4, 0x7fff, v4
	v_min_i32_e32 v6, 0x7fff, v6
	v_lshl_add_u64 v[184:185], v[170:171], 0, v[0:1]
	v_subrev_u32_e32 v0, s2, v204
	v_ashrrev_i32_e32 v3, 31, v2
	v_ashrrev_i32_e32 v5, 31, v4
	v_ashrrev_i32_e32 v7, 31, v6
	v_ashrrev_i32_e32 v1, 31, v0
	v_lshlrev_b64 v[2:3], 11, v[2:3]
	v_lshlrev_b64 v[4:5], 11, v[4:5]
	v_lshlrev_b64 v[6:7], 11, v[6:7]
	v_lshlrev_b64 v[0:1], 11, v[0:1]
	v_lshl_add_u64 v[174:175], v[168:169], 0, v[2:3]
	v_lshl_add_u64 v[176:177], v[168:169], 0, v[4:5]
	v_lshl_add_u64 v[178:179], v[168:169], 0, v[6:7]
	v_lshl_add_u64 v[186:187], v[170:171], 0, v[0:1]
	s_mov_b64 s[2:3], 0
	s_mov_b32 s5, s25
	v_mov_b32_e32 v0, 0
	v_mov_b32_e32 v1, v161
	v_mov_b32_e32 v2, v161
	v_mov_b32_e32 v3, v161
	v_mov_b32_e32 v4, v161
	v_mov_b32_e32 v5, v161
	v_mov_b32_e32 v6, v161
	v_mov_b32_e32 v7, v161
	v_mov_b32_e32 v8, v161
	v_mov_b32_e32 v9, v161
	v_mov_b32_e32 v10, v161
	v_mov_b32_e32 v11, v161
	v_mov_b32_e32 v12, v161
	v_mov_b32_e32 v13, v161
	v_mov_b32_e32 v14, v161
	v_mov_b32_e32 v15, v161
	v_mov_b32_e32 v16, 0
	v_mov_b32_e32 v17, v161
	v_mov_b32_e32 v18, v161
	v_mov_b32_e32 v19, v161
	v_mov_b32_e32 v20, v161
	v_mov_b32_e32 v21, v161
	v_mov_b32_e32 v22, v161
	v_mov_b32_e32 v23, v161
	v_mov_b32_e32 v24, v161
	v_mov_b32_e32 v25, v161
	v_mov_b32_e32 v26, v161
	v_mov_b32_e32 v27, v161
	v_mov_b32_e32 v28, v161
	v_mov_b32_e32 v29, v161
	v_mov_b32_e32 v30, v161
	v_mov_b32_e32 v31, v161
	v_mov_b32_e32 v32, 0
	v_mov_b32_e32 v33, v161
	v_mov_b32_e32 v34, v161
	v_mov_b32_e32 v35, v161
	v_mov_b32_e32 v36, v161
	v_mov_b32_e32 v37, v161
	v_mov_b32_e32 v38, v161
	v_mov_b32_e32 v39, v161
	v_mov_b32_e32 v40, v161
	v_mov_b32_e32 v41, v161
	v_mov_b32_e32 v42, v161
	v_mov_b32_e32 v43, v161
	v_mov_b32_e32 v44, v161
	v_mov_b32_e32 v45, v161
	v_mov_b32_e32 v46, v161
	v_mov_b32_e32 v47, v161
	v_mov_b32_e32 v48, 0
	v_mov_b32_e32 v49, v161
	v_mov_b32_e32 v50, v161
	v_mov_b32_e32 v51, v161
	v_mov_b32_e32 v52, v161
	v_mov_b32_e32 v53, v161
	v_mov_b32_e32 v54, v161
	v_mov_b32_e32 v55, v161
	v_mov_b32_e32 v56, v161
	v_mov_b32_e32 v57, v161
	v_mov_b32_e32 v58, v161
	v_mov_b32_e32 v59, v161
	v_mov_b32_e32 v60, v161
	v_mov_b32_e32 v61, v161
	v_mov_b32_e32 v62, v161
	v_mov_b32_e32 v63, v161
	v_mov_b32_e32 v64, 0
	v_mov_b32_e32 v65, v161
	v_mov_b32_e32 v66, v161
	v_mov_b32_e32 v67, v161
	v_mov_b32_e32 v68, v161
	v_mov_b32_e32 v69, v161
	v_mov_b32_e32 v70, v161
	v_mov_b32_e32 v71, v161
	v_mov_b32_e32 v72, v161
	v_mov_b32_e32 v73, v161
	v_mov_b32_e32 v74, v161
	v_mov_b32_e32 v75, v161
	v_mov_b32_e32 v76, v161
	v_mov_b32_e32 v77, v161
	v_mov_b32_e32 v78, v161
	v_mov_b32_e32 v79, v161
	v_mov_b32_e32 v80, 0
	v_mov_b32_e32 v81, v161
	v_mov_b32_e32 v82, v161
	v_mov_b32_e32 v83, v161
	v_mov_b32_e32 v84, v161
	v_mov_b32_e32 v85, v161
	v_mov_b32_e32 v86, v161
	v_mov_b32_e32 v87, v161
	v_mov_b32_e32 v88, v161
	v_mov_b32_e32 v89, v161
	v_mov_b32_e32 v90, v161
	v_mov_b32_e32 v91, v161
	v_mov_b32_e32 v92, v161
	v_mov_b32_e32 v93, v161
	v_mov_b32_e32 v94, v161
	v_mov_b32_e32 v95, v161
	v_mov_b32_e32 v96, 0
	v_mov_b32_e32 v97, v161
	v_mov_b32_e32 v98, v161
	v_mov_b32_e32 v99, v161
	v_mov_b32_e32 v100, v161
	v_mov_b32_e32 v101, v161
	v_mov_b32_e32 v102, v161
	v_mov_b32_e32 v103, v161
	v_mov_b32_e32 v104, v161
	v_mov_b32_e32 v105, v161
	v_mov_b32_e32 v106, v161
	v_mov_b32_e32 v107, v161
	v_mov_b32_e32 v108, v161
	v_mov_b32_e32 v109, v161
	v_mov_b32_e32 v110, v161
	v_mov_b32_e32 v111, v161
	v_mov_b32_e32 v112, 0
	v_mov_b32_e32 v113, v161
	v_mov_b32_e32 v114, v161
	v_mov_b32_e32 v115, v161
	v_mov_b32_e32 v116, v161
	v_mov_b32_e32 v117, v161
	v_mov_b32_e32 v118, v161
	v_mov_b32_e32 v119, v161
	v_mov_b32_e32 v120, v161
	v_mov_b32_e32 v121, v161
	v_mov_b32_e32 v122, v161
	v_mov_b32_e32 v123, v161
	v_mov_b32_e32 v124, v161
	v_mov_b32_e32 v125, v161
	v_mov_b32_e32 v126, v161
	v_mov_b32_e32 v127, v161
	v_mbcnt_hi_u32_b32 v128, -1, v210
	s_and_b32 s90, s70, 0x40
	v_and_b32_e32 v159, 48, v128
	v_or_b32_e32 v159, s90, v159
	v_and_b32_e32 v129, 31, v128
	v_lshrrev_b32_e32 v130, 5, v128
	v_bfe_u32 v131, v128, 1, 3
	v_lshlrev_b32_e32 v132, 7, v129
	s_lshr_b32 s91, s70, 7
	s_lshl_b32 s91, s91, 13
	s_lshl_b32 s90, s90, 8
	s_add_u32 s90, s90, 0x8000
	s_lshl_b32 s88, s70, 4
	s_mov_b32 s89, 0x10000
	s_lshl_b32 s92, s22, 4
	s_and_b32 s92, s92, 0x780
	s_mov_b32 s93, 0
	s_load_dwordx2 s[96:97], s[0:1], 0x158
	s_load_dwordx2 s[98:99], s[0:1], 0x100
	s_waitcnt lgkmcnt(0)
	v_subrev_u32_e32 v152, s96, v172
	v_xor_b32_e32 v152, v159, v152
	v_subrev_u32_e32 v153, s98, v180
	v_xor_b32_e32 v153, v159, v153
	v_subrev_u32_e32 v154, s96, v174
	v_xor_b32_e32 v154, v159, v154
	v_subrev_u32_e32 v155, s98, v182
	v_xor_b32_e32 v155, v159, v155
	v_subrev_u32_e32 v156, s96, v176
	v_xor_b32_e32 v156, v159, v156
	v_subrev_u32_e32 v157, s98, v184
	v_xor_b32_e32 v157, v159, v157
	v_subrev_u32_e32 v158, s96, v178
	v_xor_b32_e32 v158, v159, v158
	v_subrev_u32_e32 v160, s98, v186
	v_xor_b32_e32 v160, v159, v160
	v_xor_b32_e32 v133, v130, v131
	v_lshl_add_u32 v133, v133, 4, v132
	v_add_u32_e32 v232, s91, v133
	v_add_u32_e32 v236, s90, v133
	v_add_u32_e32 v207, 0x10000, v232
	v_add_u32_e32 v241, 0x10000, v236
	v_or_b32_e32 v133, 2, v130
	v_xor_b32_e32 v133, v133, v131
	v_lshl_add_u32 v133, v133, 4, v132
	v_add_u32_e32 v233, s91, v133
	v_add_u32_e32 v237, s90, v133
	v_add_u32_e32 v208, 0x10000, v233
	v_add_u32_e32 v253, 0x10000, v237
	v_or_b32_e32 v133, 4, v130
	v_xor_b32_e32 v133, v133, v131
	v_lshl_add_u32 v133, v133, 4, v132
	v_add_u32_e32 v234, s91, v133
	v_add_u32_e32 v238, s90, v133
	v_add_u32_e32 v209, 0x10000, v234
	v_add_u32_e32 v254, 0x10000, v238
	v_or_b32_e32 v133, 6, v130
	v_xor_b32_e32 v133, v133, v131
	v_lshl_add_u32 v133, v133, 4, v132
	v_add_u32_e32 v235, s91, v133
	v_add_u32_e32 v239, s90, v133
	v_add_u32_e32 v240, 0x10000, v235
	v_add_u32_e32 v255, 0x10000, v239
	s_barrier
	ds_read_b128 v[188:191], v232
	ds_read_b128 v[216:219], v236
	ds_read_b128 v[212:215], v232 offset:4096
	ds_read_b128 v[220:223], v236 offset:4096
	ds_read_b128 v[224:227], v236 offset:8192
	ds_read_b128 v[228:231], v236 offset:12288
	s_add_u32 s94, s2, s92
	s_add_u32 s94, s94, 0x80
	s_and_b32 s94, s94, 0x780
	s_sub_u32 s94, s94, 0x80
	s_subb_u32 s95, 0, 0
	s_add_u32 s100, s96, s94
	s_addc_u32 s101, s97, s95
	s_add_u32 s94, s98, s94
	s_addc_u32 s95, s99, s95
	s_add_u32 s90, s88, s89
	s_add_u32 m0, s90, 0
	s_nop 0
	global_load_lds_dwordx4 v152, s[100:101]
	s_add_u32 m0, s90, 32768
	s_nop 0
	global_load_lds_dwordx4 v153, s[94:95]
	s_add_u32 m0, s90, 8192
	s_nop 0
	global_load_lds_dwordx4 v154, s[100:101]
	s_add_u32 m0, s90, 40960
	s_nop 0
	global_load_lds_dwordx4 v155, s[94:95]
	s_add_u32 m0, s90, 16384
	s_nop 0
	global_load_lds_dwordx4 v156, s[100:101]
	s_add_u32 m0, s90, 49152
	s_nop 0
	global_load_lds_dwordx4 v157, s[94:95]
	s_add_u32 m0, s90, 24576
	s_nop 0
	global_load_lds_dwordx4 v158, s[100:101]
	s_add_u32 m0, s90, 57344
	s_nop 0
	global_load_lds_dwordx4 v160, s[94:95]
	s_xor_b32 s89, s89, 0x10000
.Lgk2_loop:
	ds_read_b128 v[128:131], v233
	ds_read_b128 v[136:139], v237
	ds_read_b128 v[132:135], v233 offset:4096
	ds_read_b128 v[140:143], v237 offset:4096
	ds_read_b128 v[144:147], v237 offset:8192
	ds_read_b128 v[148:151], v237 offset:12288
	s_waitcnt lgkmcnt(6)
	v_mfma_f32_32x32x16_bf16 v[112:127], v[188:191], v[216:219], v[112:127]
	v_mfma_f32_32x32x16_bf16 v[48:63], v[212:215], v[216:219], v[48:63]
	v_mfma_f32_32x32x16_bf16 v[96:111], v[188:191], v[220:223], v[96:111]
	v_mfma_f32_32x32x16_bf16 v[32:47], v[212:215], v[220:223], v[32:47]
	v_mfma_f32_32x32x16_bf16 v[80:95], v[188:191], v[224:227], v[80:95]
	v_mfma_f32_32x32x16_bf16 v[16:31], v[212:215], v[224:227], v[16:31]
	v_mfma_f32_32x32x16_bf16 v[64:79], v[188:191], v[228:231], v[64:79]
	v_mfma_f32_32x32x16_bf16 v[0:15], v[212:215], v[228:231], v[0:15]
	ds_read_b128 v[188:191], v234
	ds_read_b128 v[216:219], v238
	ds_read_b128 v[212:215], v234 offset:4096
	ds_read_b128 v[220:223], v238 offset:4096
	ds_read_b128 v[224:227], v238 offset:8192
	ds_read_b128 v[228:231], v238 offset:12288
	s_waitcnt lgkmcnt(6)
	v_mfma_f32_32x32x16_bf16 v[112:127], v[128:131], v[136:139], v[112:127]
	v_mfma_f32_32x32x16_bf16 v[48:63], v[132:135], v[136:139], v[48:63]
	v_mfma_f32_32x32x16_bf16 v[96:111], v[128:131], v[140:143], v[96:111]
	v_mfma_f32_32x32x16_bf16 v[32:47], v[132:135], v[140:143], v[32:47]
	v_mfma_f32_32x32x16_bf16 v[80:95], v[128:131], v[144:147], v[80:95]
	v_mfma_f32_32x32x16_bf16 v[16:31], v[132:135], v[144:147], v[16:31]
	v_mfma_f32_32x32x16_bf16 v[64:79], v[128:131], v[148:151], v[64:79]
	v_mfma_f32_32x32x16_bf16 v[0:15], v[132:135], v[148:151], v[0:15]
	ds_read_b128 v[128:131], v235
	ds_read_b128 v[136:139], v239
	ds_read_b128 v[132:135], v235 offset:4096
	ds_read_b128 v[140:143], v239 offset:4096
	ds_read_b128 v[144:147], v239 offset:8192
	ds_read_b128 v[148:151], v239 offset:12288
	s_waitcnt lgkmcnt(6)
	v_mfma_f32_32x32x16_bf16 v[112:127], v[188:191], v[216:219], v[112:127]
	v_mfma_f32_32x32x16_bf16 v[48:63], v[212:215], v[216:219], v[48:63]
	v_mfma_f32_32x32x16_bf16 v[96:111], v[188:191], v[220:223], v[96:111]
	v_mfma_f32_32x32x16_bf16 v[32:47], v[212:215], v[220:223], v[32:47]
	v_mfma_f32_32x32x16_bf16 v[80:95], v[188:191], v[224:227], v[80:95]
	v_mfma_f32_32x32x16_bf16 v[16:31], v[212:215], v[224:227], v[16:31]
	v_mfma_f32_32x32x16_bf16 v[64:79], v[188:191], v[228:231], v[64:79]
	v_mfma_f32_32x32x16_bf16 v[0:15], v[212:215], v[228:231], v[0:15]
	s_waitcnt vmcnt(0) lgkmcnt(0)
	s_barrier
	ds_read_b128 v[188:191], v207
	ds_read_b128 v[216:219], v241
	ds_read_b128 v[212:215], v207 offset:4096
	ds_read_b128 v[220:223], v241 offset:4096
	ds_read_b128 v[224:227], v241 offset:8192
	ds_read_b128 v[228:231], v241 offset:12288
	s_add_u32 s94, s2, s92
	s_add_u32 s94, s94, 0x100
	s_and_b32 s94, s94, 0x780
	s_sub_u32 s94, s94, 0x80
	s_subb_u32 s95, 0, 0
	s_add_u32 s100, s96, s94
	s_addc_u32 s101, s97, s95
	s_add_u32 s94, s98, s94
	s_addc_u32 s95, s99, s95
	s_add_u32 s90, s88, s89
	s_add_u32 m0, s90, 0
	v_mfma_f32_32x32x16_bf16 v[112:127], v[128:131], v[136:139], v[112:127]
	global_load_lds_dwordx4 v152, s[100:101]
	s_add_u32 m0, s90, 32768
	v_mfma_f32_32x32x16_bf16 v[48:63], v[132:135], v[136:139], v[48:63]
	global_load_lds_dwordx4 v153, s[94:95]
	s_add_u32 m0, s90, 8192
	v_mfma_f32_32x32x16_bf16 v[96:111], v[128:131], v[140:143], v[96:111]
	global_load_lds_dwordx4 v154, s[100:101]
	s_add_u32 m0, s90, 40960
	v_mfma_f32_32x32x16_bf16 v[32:47], v[132:135], v[140:143], v[32:47]
	global_load_lds_dwordx4 v155, s[94:95]
	s_add_u32 m0, s90, 16384
	v_mfma_f32_32x32x16_bf16 v[80:95], v[128:131], v[144:147], v[80:95]
	global_load_lds_dwordx4 v156, s[100:101]
	s_add_u32 m0, s90, 49152
	v_mfma_f32_32x32x16_bf16 v[16:31], v[132:135], v[144:147], v[16:31]
	global_load_lds_dwordx4 v157, s[94:95]
	s_add_u32 m0, s90, 24576
	v_mfma_f32_32x32x16_bf16 v[64:79], v[128:131], v[148:151], v[64:79]
	global_load_lds_dwordx4 v158, s[100:101]
	s_add_u32 m0, s90, 57344
	v_mfma_f32_32x32x16_bf16 v[0:15], v[132:135], v[148:151], v[0:15]
	global_load_lds_dwordx4 v160, s[94:95]
	s_xor_b32 s89, s89, 0x10000
	s_add_i32 s5, s5, 1
	s_add_u32 s2, s2, 0x80
	s_addc_u32 s3, s3, 0
	ds_read_b128 v[128:131], v208
	ds_read_b128 v[136:139], v253
	ds_read_b128 v[132:135], v208 offset:4096
	ds_read_b128 v[140:143], v253 offset:4096
	ds_read_b128 v[144:147], v253 offset:8192
	ds_read_b128 v[148:151], v253 offset:12288
	s_waitcnt lgkmcnt(6)
	v_mfma_f32_32x32x16_bf16 v[112:127], v[188:191], v[216:219], v[112:127]
	v_mfma_f32_32x32x16_bf16 v[48:63], v[212:215], v[216:219], v[48:63]
	v_mfma_f32_32x32x16_bf16 v[96:111], v[188:191], v[220:223], v[96:111]
	v_mfma_f32_32x32x16_bf16 v[32:47], v[212:215], v[220:223], v[32:47]
	v_mfma_f32_32x32x16_bf16 v[80:95], v[188:191], v[224:227], v[80:95]
	v_mfma_f32_32x32x16_bf16 v[16:31], v[212:215], v[224:227], v[16:31]
	v_mfma_f32_32x32x16_bf16 v[64:79], v[188:191], v[228:231], v[64:79]
	v_mfma_f32_32x32x16_bf16 v[0:15], v[212:215], v[228:231], v[0:15]
	ds_read_b128 v[188:191], v209
	ds_read_b128 v[216:219], v254
	ds_read_b128 v[212:215], v209 offset:4096
	ds_read_b128 v[220:223], v254 offset:4096
	ds_read_b128 v[224:227], v254 offset:8192
	ds_read_b128 v[228:231], v254 offset:12288
	s_waitcnt lgkmcnt(6)
	v_mfma_f32_32x32x16_bf16 v[112:127], v[128:131], v[136:139], v[112:127]
	v_mfma_f32_32x32x16_bf16 v[48:63], v[132:135], v[136:139], v[48:63]
	v_mfma_f32_32x32x16_bf16 v[96:111], v[128:131], v[140:143], v[96:111]
	v_mfma_f32_32x32x16_bf16 v[32:47], v[132:135], v[140:143], v[32:47]
	v_mfma_f32_32x32x16_bf16 v[80:95], v[128:131], v[144:147], v[80:95]
	v_mfma_f32_32x32x16_bf16 v[16:31], v[132:135], v[144:147], v[16:31]
	v_mfma_f32_32x32x16_bf16 v[64:79], v[128:131], v[148:151], v[64:79]
	v_mfma_f32_32x32x16_bf16 v[0:15], v[132:135], v[148:151], v[0:15]
	ds_read_b128 v[128:131], v240
	ds_read_b128 v[136:139], v255
	ds_read_b128 v[132:135], v240 offset:4096
	ds_read_b128 v[140:143], v255 offset:4096
	ds_read_b128 v[144:147], v255 offset:8192
	ds_read_b128 v[148:151], v255 offset:12288
	s_waitcnt lgkmcnt(6)
	v_mfma_f32_32x32x16_bf16 v[112:127], v[188:191], v[216:219], v[112:127]
	v_mfma_f32_32x32x16_bf16 v[48:63], v[212:215], v[216:219], v[48:63]
	v_mfma_f32_32x32x16_bf16 v[96:111], v[188:191], v[220:223], v[96:111]
	v_mfma_f32_32x32x16_bf16 v[32:47], v[212:215], v[220:223], v[32:47]
	v_mfma_f32_32x32x16_bf16 v[80:95], v[188:191], v[224:227], v[80:95]
	v_mfma_f32_32x32x16_bf16 v[16:31], v[212:215], v[224:227], v[16:31]
	v_mfma_f32_32x32x16_bf16 v[64:79], v[188:191], v[228:231], v[64:79]
	v_mfma_f32_32x32x16_bf16 v[0:15], v[212:215], v[228:231], v[0:15]
	s_waitcnt vmcnt(0) lgkmcnt(0)
	s_barrier
	ds_read_b128 v[188:191], v232
	ds_read_b128 v[216:219], v236
	ds_read_b128 v[212:215], v232 offset:4096
	ds_read_b128 v[220:223], v236 offset:4096
	ds_read_b128 v[224:227], v236 offset:8192
	ds_read_b128 v[228:231], v236 offset:12288
	s_add_u32 s94, s2, s92
	s_add_u32 s94, s94, 0x100
	s_and_b32 s94, s94, 0x780
	s_sub_u32 s94, s94, 0x80
	s_subb_u32 s95, 0, 0
	s_add_u32 s100, s96, s94
	s_addc_u32 s101, s97, s95
	s_add_u32 s94, s98, s94
	s_addc_u32 s95, s99, s95
	s_add_u32 s90, s88, s89
	s_add_u32 m0, s90, 0
	v_mfma_f32_32x32x16_bf16 v[112:127], v[128:131], v[136:139], v[112:127]
	global_load_lds_dwordx4 v152, s[100:101]
	s_add_u32 m0, s90, 32768
	v_mfma_f32_32x32x16_bf16 v[48:63], v[132:135], v[136:139], v[48:63]
	global_load_lds_dwordx4 v153, s[94:95]
	s_add_u32 m0, s90, 8192
	v_mfma_f32_32x32x16_bf16 v[96:111], v[128:131], v[140:143], v[96:111]
	global_load_lds_dwordx4 v154, s[100:101]
	s_add_u32 m0, s90, 40960
	v_mfma_f32_32x32x16_bf16 v[32:47], v[132:135], v[140:143], v[32:47]
	global_load_lds_dwordx4 v155, s[94:95]
	s_add_u32 m0, s90, 16384
	v_mfma_f32_32x32x16_bf16 v[80:95], v[128:131], v[144:147], v[80:95]
	global_load_lds_dwordx4 v156, s[100:101]
	s_add_u32 m0, s90, 49152
	v_mfma_f32_32x32x16_bf16 v[16:31], v[132:135], v[144:147], v[16:31]
	global_load_lds_dwordx4 v157, s[94:95]
	s_add_u32 m0, s90, 24576
	v_mfma_f32_32x32x16_bf16 v[64:79], v[128:131], v[148:151], v[64:79]
	global_load_lds_dwordx4 v158, s[100:101]
	s_add_u32 m0, s90, 57344
	v_mfma_f32_32x32x16_bf16 v[0:15], v[132:135], v[148:151], v[0:15]
	global_load_lds_dwordx4 v160, s[94:95]
	s_xor_b32 s89, s89, 0x10000
	s_add_i32 s5, s5, 1
	s_add_u32 s2, s2, 0x80
	s_addc_u32 s3, s3, 0
	s_cmpk_eq_i32 s2, 0x700
	s_cbranch_scc0 .Lgk2_loop
	ds_read_b128 v[128:131], v233
	ds_read_b128 v[136:139], v237
	ds_read_b128 v[132:135], v233 offset:4096
	ds_read_b128 v[140:143], v237 offset:4096
	ds_read_b128 v[144:147], v237 offset:8192
	ds_read_b128 v[148:151], v237 offset:12288
	s_waitcnt lgkmcnt(6)
	v_mfma_f32_32x32x16_bf16 v[112:127], v[188:191], v[216:219], v[112:127]
	v_mfma_f32_32x32x16_bf16 v[48:63], v[212:215], v[216:219], v[48:63]
	v_mfma_f32_32x32x16_bf16 v[96:111], v[188:191], v[220:223], v[96:111]
	v_mfma_f32_32x32x16_bf16 v[32:47], v[212:215], v[220:223], v[32:47]
	v_mfma_f32_32x32x16_bf16 v[80:95], v[188:191], v[224:227], v[80:95]
	v_mfma_f32_32x32x16_bf16 v[16:31], v[212:215], v[224:227], v[16:31]
	v_mfma_f32_32x32x16_bf16 v[64:79], v[188:191], v[228:231], v[64:79]
	v_mfma_f32_32x32x16_bf16 v[0:15], v[212:215], v[228:231], v[0:15]
	ds_read_b128 v[188:191], v234
	ds_read_b128 v[216:219], v238
	ds_read_b128 v[212:215], v234 offset:4096
	ds_read_b128 v[220:223], v238 offset:4096
	ds_read_b128 v[224:227], v238 offset:8192
	ds_read_b128 v[228:231], v238 offset:12288
	s_waitcnt lgkmcnt(6)
	v_mfma_f32_32x32x16_bf16 v[112:127], v[128:131], v[136:139], v[112:127]
	v_mfma_f32_32x32x16_bf16 v[48:63], v[132:135], v[136:139], v[48:63]
	v_mfma_f32_32x32x16_bf16 v[96:111], v[128:131], v[140:143], v[96:111]
	v_mfma_f32_32x32x16_bf16 v[32:47], v[132:135], v[140:143], v[32:47]
	v_mfma_f32_32x32x16_bf16 v[80:95], v[128:131], v[144:147], v[80:95]
	v_mfma_f32_32x32x16_bf16 v[16:31], v[132:135], v[144:147], v[16:31]
	v_mfma_f32_32x32x16_bf16 v[64:79], v[128:131], v[148:151], v[64:79]
	v_mfma_f32_32x32x16_bf16 v[0:15], v[132:135], v[148:151], v[0:15]
	ds_read_b128 v[128:131], v235
	ds_read_b128 v[136:139], v239
	ds_read_b128 v[132:135], v235 offset:4096
	ds_read_b128 v[140:143], v239 offset:4096
	ds_read_b128 v[144:147], v239 offset:8192
	ds_read_b128 v[148:151], v239 offset:12288
	s_waitcnt lgkmcnt(6)
	v_mfma_f32_32x32x16_bf16 v[112:127], v[188:191], v[216:219], v[112:127]
	v_mfma_f32_32x32x16_bf16 v[48:63], v[212:215], v[216:219], v[48:63]
	v_mfma_f32_32x32x16_bf16 v[96:111], v[188:191], v[220:223], v[96:111]
	v_mfma_f32_32x32x16_bf16 v[32:47], v[212:215], v[220:223], v[32:47]
	v_mfma_f32_32x32x16_bf16 v[80:95], v[188:191], v[224:227], v[80:95]
	v_mfma_f32_32x32x16_bf16 v[16:31], v[212:215], v[224:227], v[16:31]
	v_mfma_f32_32x32x16_bf16 v[64:79], v[188:191], v[228:231], v[64:79]
	v_mfma_f32_32x32x16_bf16 v[0:15], v[212:215], v[228:231], v[0:15]
	s_waitcnt vmcnt(0) lgkmcnt(0)
	s_barrier
	ds_read_b128 v[188:191], v207
	ds_read_b128 v[216:219], v241
	ds_read_b128 v[212:215], v207 offset:4096
	ds_read_b128 v[220:223], v241 offset:4096
	ds_read_b128 v[224:227], v241 offset:8192
	ds_read_b128 v[228:231], v241 offset:12288
	v_mfma_f32_32x32x16_bf16 v[112:127], v[128:131], v[136:139], v[112:127]
	v_mfma_f32_32x32x16_bf16 v[48:63], v[132:135], v[136:139], v[48:63]
	v_mfma_f32_32x32x16_bf16 v[96:111], v[128:131], v[140:143], v[96:111]
	v_mfma_f32_32x32x16_bf16 v[32:47], v[132:135], v[140:143], v[32:47]
	v_mfma_f32_32x32x16_bf16 v[80:95], v[128:131], v[144:147], v[80:95]
	v_mfma_f32_32x32x16_bf16 v[16:31], v[132:135], v[144:147], v[16:31]
	v_mfma_f32_32x32x16_bf16 v[64:79], v[128:131], v[148:151], v[64:79]
	v_mfma_f32_32x32x16_bf16 v[0:15], v[132:135], v[148:151], v[0:15]
	s_xor_b32 s89, s89, 0x10000
	s_add_i32 s5, s5, 1
	s_add_u32 s2, s2, 0x80
	s_addc_u32 s3, s3, 0
	s_add_i32 s76, s8, s42
	s_cmpk_gt_i32 s76, 0x47f
	s_cselect_b64 s[50:51], -1, 0
	s_and_b64 vcc, exec, s[50:51]
	s_cbranch_vccnz .LBB0_1470
	s_mul_hi_i32 s2, s76, 0x38e38e39
	s_lshr_b32 s3, s2, 31
	s_ashr_i32 s2, s2, 1
	s_add_i32 s2, s2, s3
	s_mul_i32 s3, s2, -9
	s_lshl_b32 s2, s2, 8
	v_add_u32_e32 v129, s2, v194
	s_add_i32 s3, s3, s76
	v_min_i32_e32 v132, 0x7fff, v129
	v_add_u32_e32 v129, s2, v163
	s_lshl_b32 s3, s3, 8
	v_add_u32_e32 v128, s2, v193
	v_min_i32_e32 v136, 0x7fff, v129
	v_add_u32_e32 v129, s2, v196
	v_min_i32_e32 v128, 0x7fff, v128
	v_add_u32_e32 v130, s3, v193
	v_add_u32_e32 v134, s3, v194
	v_add_u32_e32 v138, s3, v163
	v_min_i32_e32 v140, 0x7fff, v129
	v_add_u32_e32 v142, s3, v196
	v_ashrrev_i32_e32 v143, 31, v142
	v_ashrrev_i32_e32 v141, 31, v140
	v_ashrrev_i32_e32 v139, 31, v138
	v_ashrrev_i32_e32 v137, 31, v136
	v_ashrrev_i32_e32 v135, 31, v134
	v_ashrrev_i32_e32 v133, 31, v132
	v_ashrrev_i32_e32 v131, 31, v130
	v_ashrrev_i32_e32 v129, 31, v128
	v_lshlrev_b64 v[142:143], 11, v[142:143]
	v_lshlrev_b64 v[140:141], 11, v[140:141]
	v_lshlrev_b64 v[138:139], 11, v[138:139]
	v_lshlrev_b64 v[136:137], 11, v[136:137]
	v_lshlrev_b64 v[134:135], 11, v[134:135]
	v_lshlrev_b64 v[132:133], 11, v[132:133]
	v_lshlrev_b64 v[130:131], 11, v[130:131]
	v_lshlrev_b64 v[128:129], 11, v[128:129]
	v_lshl_add_u64 v[156:157], v[164:165], 0, v[142:143]
	v_lshl_add_u64 v[152:153], v[166:167], 0, v[140:141]
	v_lshl_add_u64 v[148:149], v[164:165], 0, v[138:139]
	v_lshl_add_u64 v[144:145], v[166:167], 0, v[136:137]
	v_lshl_add_u64 v[140:141], v[164:165], 0, v[134:135]
	v_lshl_add_u64 v[136:137], v[166:167], 0, v[132:133]
	v_lshl_add_u64 v[132:133], v[164:165], 0, v[130:131]
	v_lshl_add_u64 v[128:129], v[166:167], 0, v[128:129]
	s_add_u32 m0, s88, 0
	v_lshl_add_u64 v[128:129], v[128:129], 0, s[92:93]
	v_xor_b32_e32 v128, v159, v128
	global_load_lds_dwordx4 v[128:129], off
	s_add_u32 m0, s88, 32768
	v_lshl_add_u64 v[132:133], v[132:133], 0, s[92:93]
	v_xor_b32_e32 v132, v159, v132
	global_load_lds_dwordx4 v[132:133], off
	s_add_u32 m0, s88, 8192
	v_lshl_add_u64 v[136:137], v[136:137], 0, s[92:93]
	v_xor_b32_e32 v136, v159, v136
	global_load_lds_dwordx4 v[136:137], off
	s_add_u32 m0, s88, 40960
	v_lshl_add_u64 v[140:141], v[140:141], 0, s[92:93]
	v_xor_b32_e32 v140, v159, v140
	global_load_lds_dwordx4 v[140:141], off
	s_add_u32 m0, s88, 16384
	v_lshl_add_u64 v[144:145], v[144:145], 0, s[92:93]
	v_xor_b32_e32 v144, v159, v144
	global_load_lds_dwordx4 v[144:145], off
	s_add_u32 m0, s88, 49152
	v_lshl_add_u64 v[148:149], v[148:149], 0, s[92:93]
	v_xor_b32_e32 v148, v159, v148
	global_load_lds_dwordx4 v[148:149], off
	s_add_u32 m0, s88, 24576
	v_lshl_add_u64 v[152:153], v[152:153], 0, s[92:93]
	v_xor_b32_e32 v152, v159, v152
	global_load_lds_dwordx4 v[152:153], off
	s_add_u32 m0, s88, 57344
	v_lshl_add_u64 v[156:157], v[156:157], 0, s[92:93]
	v_xor_b32_e32 v156, v159, v156
	global_load_lds_dwordx4 v[156:157], off
.LBB0_1470:
	ds_read_b128 v[128:131], v208
	ds_read_b128 v[136:139], v253
	ds_read_b128 v[132:135], v208 offset:4096
	ds_read_b128 v[140:143], v253 offset:4096
	ds_read_b128 v[144:147], v253 offset:8192
	ds_read_b128 v[148:151], v253 offset:12288
	s_waitcnt lgkmcnt(6)
	v_mfma_f32_32x32x16_bf16 v[112:127], v[188:191], v[216:219], v[112:127]
	v_mfma_f32_32x32x16_bf16 v[48:63], v[212:215], v[216:219], v[48:63]
	v_mfma_f32_32x32x16_bf16 v[96:111], v[188:191], v[220:223], v[96:111]
	v_mfma_f32_32x32x16_bf16 v[32:47], v[212:215], v[220:223], v[32:47]
	v_mfma_f32_32x32x16_bf16 v[80:95], v[188:191], v[224:227], v[80:95]
	v_mfma_f32_32x32x16_bf16 v[16:31], v[212:215], v[224:227], v[16:31]
	v_mfma_f32_32x32x16_bf16 v[64:79], v[188:191], v[228:231], v[64:79]
	v_mfma_f32_32x32x16_bf16 v[0:15], v[212:215], v[228:231], v[0:15]
	ds_read_b128 v[188:191], v209
	ds_read_b128 v[216:219], v254
	ds_read_b128 v[212:215], v209 offset:4096
	ds_read_b128 v[220:223], v254 offset:4096
	ds_read_b128 v[224:227], v254 offset:8192
	ds_read_b128 v[228:231], v254 offset:12288
	s_waitcnt lgkmcnt(6)
	v_mfma_f32_32x32x16_bf16 v[112:127], v[128:131], v[136:139], v[112:127]
	v_mfma_f32_32x32x16_bf16 v[48:63], v[132:135], v[136:139], v[48:63]
	v_mfma_f32_32x32x16_bf16 v[96:111], v[128:131], v[140:143], v[96:111]
	v_mfma_f32_32x32x16_bf16 v[32:47], v[132:135], v[140:143], v[32:47]
	v_mfma_f32_32x32x16_bf16 v[80:95], v[128:131], v[144:147], v[80:95]
	v_mfma_f32_32x32x16_bf16 v[16:31], v[132:135], v[144:147], v[16:31]
	v_mfma_f32_32x32x16_bf16 v[64:79], v[128:131], v[148:151], v[64:79]
	v_mfma_f32_32x32x16_bf16 v[0:15], v[132:135], v[148:151], v[0:15]
	ds_read_b128 v[128:131], v240
	ds_read_b128 v[136:139], v255
	ds_read_b128 v[132:135], v240 offset:4096
	ds_read_b128 v[140:143], v255 offset:4096
	ds_read_b128 v[144:147], v255 offset:8192
	ds_read_b128 v[148:151], v255 offset:12288
	s_waitcnt lgkmcnt(6)
	v_mfma_f32_32x32x16_bf16 v[112:127], v[188:191], v[216:219], v[112:127]
	v_mfma_f32_32x32x16_bf16 v[48:63], v[212:215], v[216:219], v[48:63]
	v_mfma_f32_32x32x16_bf16 v[96:111], v[188:191], v[220:223], v[96:111]
	v_mfma_f32_32x32x16_bf16 v[32:47], v[212:215], v[220:223], v[32:47]
	v_mfma_f32_32x32x16_bf16 v[80:95], v[188:191], v[224:227], v[80:95]
	v_mfma_f32_32x32x16_bf16 v[16:31], v[212:215], v[224:227], v[16:31]
	v_mfma_f32_32x32x16_bf16 v[64:79], v[188:191], v[228:231], v[64:79]
	v_mfma_f32_32x32x16_bf16 v[0:15], v[212:215], v[228:231], v[0:15]
	s_waitcnt vmcnt(0) lgkmcnt(0)
	s_barrier
	v_mfma_f32_32x32x16_bf16 v[112:127], v[128:131], v[136:139], v[112:127]
	v_mfma_f32_32x32x16_bf16 v[48:63], v[132:135], v[136:139], v[48:63]
	v_mfma_f32_32x32x16_bf16 v[96:111], v[128:131], v[140:143], v[96:111]
	v_mfma_f32_32x32x16_bf16 v[32:47], v[132:135], v[140:143], v[32:47]
	v_mfma_f32_32x32x16_bf16 v[80:95], v[128:131], v[144:147], v[80:95]
	v_mfma_f32_32x32x16_bf16 v[16:31], v[132:135], v[144:147], v[16:31]
	v_mfma_f32_32x32x16_bf16 v[64:79], v[128:131], v[148:151], v[64:79]
	v_mfma_f32_32x32x16_bf16 v[0:15], v[132:135], v[148:151], v[0:15]
	v_mbcnt_hi_u32_b32 v226, -1, v210
	v_and_b32_e32 v227, 31, v226
	v_lshrrev_b32_e32 v228, 5, v226
	v_lshlrev_b32_e32 v160, 3, v227
	v_lshlrev_b32_e32 v209, 2, v228
	s_lshr_b32 s90, s70, 6
	s_mul_i32 s91, s90, 0x1200
	s_add_u32 s91, s91, 0x12000
	v_mul_u32_u24_e32 v229, 0x240, v228
	v_lshl_add_u32 v229, v227, 1, v229
	v_add_u32_e32 v207, s91, v229
	v_lshrrev_b32_e32 v224, 3, v226
	v_and_b32_e32 v230, 7, v226
	v_lshlrev_b32_e32 v225, 4, v230
	v_mul_u32_u24_e32 v229, 0x90, v224
	v_add3_u32 v208, v229, v225, s91
	s_mul_i32 s92, s4, 9
	s_sub_u32 s93, s8, s92
	s_lshl_b32 s93, s93, 8
	s_lshl_b32 s92, s4, 8
	s_lshr_b32 s94, s90, 1
	s_lshl_b32 s94, s94, 6
	s_add_u32 s92, s92, s94
	s_and_b32 s94, s90, 1
	s_lshl_b32 s94, s94, 7
	s_add_u32 s93, s93, s94

.Lep2_00_mP:
	v_cvt_pk_bf16_f32 v226, v112, v96
	ds_write_b16 v207, v226
	ds_write_b16_d16_hi v207, v226 offset:64
	v_cvt_pk_bf16_f32 v227, v113, v97
	ds_write_b16 v207, v227 offset:144
	ds_write_b16_d16_hi v207, v227 offset:208
	v_cvt_pk_bf16_f32 v228, v114, v98
	ds_write_b16 v207, v228 offset:288
	ds_write_b16_d16_hi v207, v228 offset:352
	v_cvt_pk_bf16_f32 v229, v115, v99
	ds_write_b16 v207, v229 offset:432
	ds_write_b16_d16_hi v207, v229 offset:496
	v_cvt_pk_bf16_f32 v226, v116, v100
	ds_write_b16 v207, v226 offset:1152
	ds_write_b16_d16_hi v207, v226 offset:1216
	v_cvt_pk_bf16_f32 v227, v117, v101
	ds_write_b16 v207, v227 offset:1296
	ds_write_b16_d16_hi v207, v227 offset:1360
	v_cvt_pk_bf16_f32 v228, v118, v102
	ds_write_b16 v207, v228 offset:1440
	ds_write_b16_d16_hi v207, v228 offset:1504
	v_cvt_pk_bf16_f32 v229, v119, v103
	ds_write_b16 v207, v229 offset:1584
	ds_write_b16_d16_hi v207, v229 offset:1648
	v_cvt_pk_bf16_f32 v226, v120, v104
	ds_write_b16 v207, v226 offset:2304
	ds_write_b16_d16_hi v207, v226 offset:2368
	v_cvt_pk_bf16_f32 v227, v121, v105
	ds_write_b16 v207, v227 offset:2448
	ds_write_b16_d16_hi v207, v227 offset:2512
	v_cvt_pk_bf16_f32 v228, v122, v106
	ds_write_b16 v207, v228 offset:2592
	ds_write_b16_d16_hi v207, v228 offset:2656
	v_cvt_pk_bf16_f32 v229, v123, v107
	ds_write_b16 v207, v229 offset:2736
	ds_write_b16_d16_hi v207, v229 offset:2800
	v_cvt_pk_bf16_f32 v226, v124, v108
	ds_write_b16 v207, v226 offset:3456
	ds_write_b16_d16_hi v207, v226 offset:3520
	v_cvt_pk_bf16_f32 v227, v125, v109
	ds_write_b16 v207, v227 offset:3600
	ds_write_b16_d16_hi v207, v227 offset:3664
	v_cvt_pk_bf16_f32 v228, v126, v110
	ds_write_b16 v207, v228 offset:3744
	ds_write_b16_d16_hi v207, v228 offset:3808
	v_cvt_pk_bf16_f32 v229, v127, v111
	ds_write_b16 v207, v229 offset:3888
	ds_write_b16_d16_hi v207, v229 offset:3952
	s_branch .Lep2_00_st
.Lep2_00_mR:
	s_load_dwordx2 s[98:99], s[0:1], 0x148
	v_add_u32_e32 v226, s94, v209
	v_lshlrev_b32_e32 v226, 8, v226
	v_add_u32_e32 v232, v226, v160
	v_mov_b32_e32 v233, 0
	s_waitcnt lgkmcnt(0)
	v_lshl_add_u64 v[232:233], s[98:99], 0, v[232:233]
	global_load_dwordx2 v[128:129], v[232:233], off
	global_load_dwordx2 v[130:131], v[232:233], off offset:256
	global_load_dwordx2 v[132:133], v[232:233], off offset:512
	global_load_dwordx2 v[134:135], v[232:233], off offset:768
	global_load_dwordx2 v[136:137], v[232:233], off offset:2048
	global_load_dwordx2 v[138:139], v[232:233], off offset:2304
	global_load_dwordx2 v[140:141], v[232:233], off offset:2560
	global_load_dwordx2 v[142:143], v[232:233], off offset:2816
	v_add_co_u32_e32 v234, vcc, 0x1000, v232
	s_nop 1
	v_addc_co_u32_e32 v235, vcc, 0, v233, vcc
	global_load_dwordx2 v[144:145], v[234:235], off
	global_load_dwordx2 v[146:147], v[234:235], off offset:256
	global_load_dwordx2 v[148:149], v[234:235], off offset:512
	global_load_dwordx2 v[150:151], v[234:235], off offset:768
	global_load_dwordx2 v[152:153], v[234:235], off offset:2048
	global_load_dwordx2 v[154:155], v[234:235], off offset:2304
	global_load_dwordx2 v[156:157], v[234:235], off offset:2560
	global_load_dwordx2 v[158:159], v[234:235], off offset:2816
	s_waitcnt vmcnt(15)
	v_mul_f32_e32 v226, v96, v129
	v_mul_f32_e32 v227, v112, v129
	v_fma_f32 v226, v112, v128, -v226
	v_fma_f32 v227, v96, v128, v227
	v_mul_f32_e32 v226, s88, v226
	v_mul_f32_e32 v227, s88, v227
	v_cvt_pk_bf16_f32 v226, v226, v227
	ds_write_b16 v207, v226
	ds_write_b16_d16_hi v207, v226 offset:64
	s_waitcnt vmcnt(14)
	v_mul_f32_e32 v226, v97, v131
	v_mul_f32_e32 v227, v113, v131
	v_fma_f32 v226, v113, v130, -v226
	v_fma_f32 v227, v97, v130, v227
	v_mul_f32_e32 v226, s88, v226
	v_mul_f32_e32 v227, s88, v227
	v_cvt_pk_bf16_f32 v226, v226, v227
	ds_write_b16 v207, v226 offset:144
	ds_write_b16_d16_hi v207, v226 offset:208
	s_waitcnt vmcnt(13)
	v_mul_f32_e32 v226, v98, v133
	v_mul_f32_e32 v227, v114, v133
	v_fma_f32 v226, v114, v132, -v226
	v_fma_f32 v227, v98, v132, v227
	v_mul_f32_e32 v226, s88, v226
	v_mul_f32_e32 v227, s88, v227
	v_cvt_pk_bf16_f32 v226, v226, v227
	ds_write_b16 v207, v226 offset:288
	ds_write_b16_d16_hi v207, v226 offset:352
	s_waitcnt vmcnt(12)
	v_mul_f32_e32 v226, v99, v135
	v_mul_f32_e32 v227, v115, v135
	v_fma_f32 v226, v115, v134, -v226
	v_fma_f32 v227, v99, v134, v227
	v_mul_f32_e32 v226, s88, v226
	v_mul_f32_e32 v227, s88, v227
	v_cvt_pk_bf16_f32 v226, v226, v227
	ds_write_b16 v207, v226 offset:432
	ds_write_b16_d16_hi v207, v226 offset:496
	s_waitcnt vmcnt(11)
	v_mul_f32_e32 v226, v100, v137
	v_mul_f32_e32 v227, v116, v137
	v_fma_f32 v226, v116, v136, -v226
	v_fma_f32 v227, v100, v136, v227
	v_mul_f32_e32 v226, s88, v226
	v_mul_f32_e32 v227, s88, v227
	v_cvt_pk_bf16_f32 v226, v226, v227
	ds_write_b16 v207, v226 offset:1152
	ds_write_b16_d16_hi v207, v226 offset:1216
	s_waitcnt vmcnt(10)
	v_mul_f32_e32 v226, v101, v139
	v_mul_f32_e32 v227, v117, v139
	v_fma_f32 v226, v117, v138, -v226
	v_fma_f32 v227, v101, v138, v227
	v_mul_f32_e32 v226, s88, v226
	v_mul_f32_e32 v227, s88, v227
	v_cvt_pk_bf16_f32 v226, v226, v227
	ds_write_b16 v207, v226 offset:1296
	ds_write_b16_d16_hi v207, v226 offset:1360
	s_waitcnt vmcnt(9)
	v_mul_f32_e32 v226, v102, v141
	v_mul_f32_e32 v227, v118, v141
	v_fma_f32 v226, v118, v140, -v226
	v_fma_f32 v227, v102, v140, v227
	v_mul_f32_e32 v226, s88, v226
	v_mul_f32_e32 v227, s88, v227
	v_cvt_pk_bf16_f32 v226, v226, v227
	ds_write_b16 v207, v226 offset:1440
	ds_write_b16_d16_hi v207, v226 offset:1504
	s_waitcnt vmcnt(8)
	v_mul_f32_e32 v226, v103, v143
	v_mul_f32_e32 v227, v119, v143
	v_fma_f32 v226, v119, v142, -v226
	v_fma_f32 v227, v103, v142, v227
	v_mul_f32_e32 v226, s88, v226
	v_mul_f32_e32 v227, s88, v227
	v_cvt_pk_bf16_f32 v226, v226, v227
	ds_write_b16 v207, v226 offset:1584
	ds_write_b16_d16_hi v207, v226 offset:1648
	s_waitcnt vmcnt(7)
	v_mul_f32_e32 v226, v104, v145
	v_mul_f32_e32 v227, v120, v145
	v_fma_f32 v226, v120, v144, -v226
	v_fma_f32 v227, v104, v144, v227
	v_mul_f32_e32 v226, s88, v226
	v_mul_f32_e32 v227, s88, v227
	v_cvt_pk_bf16_f32 v226, v226, v227
	ds_write_b16 v207, v226 offset:2304
	ds_write_b16_d16_hi v207, v226 offset:2368
	s_waitcnt vmcnt(6)
	v_mul_f32_e32 v226, v105, v147
	v_mul_f32_e32 v227, v121, v147
	v_fma_f32 v226, v121, v146, -v226
	v_fma_f32 v227, v105, v146, v227
	v_mul_f32_e32 v226, s88, v226
	v_mul_f32_e32 v227, s88, v227
	v_cvt_pk_bf16_f32 v226, v226, v227
	ds_write_b16 v207, v226 offset:2448
	ds_write_b16_d16_hi v207, v226 offset:2512
	s_waitcnt vmcnt(5)
	v_mul_f32_e32 v226, v106, v149
	v_mul_f32_e32 v227, v122, v149
	v_fma_f32 v226, v122, v148, -v226
	v_fma_f32 v227, v106, v148, v227
	v_mul_f32_e32 v226, s88, v226
	v_mul_f32_e32 v227, s88, v227
	v_cvt_pk_bf16_f32 v226, v226, v227
	ds_write_b16 v207, v226 offset:2592
	ds_write_b16_d16_hi v207, v226 offset:2656
	s_waitcnt vmcnt(4)
	v_mul_f32_e32 v226, v107, v151
	v_mul_f32_e32 v227, v123, v151
	v_fma_f32 v226, v123, v150, -v226
	v_fma_f32 v227, v107, v150, v227
	v_mul_f32_e32 v226, s88, v226
	v_mul_f32_e32 v227, s88, v227
	v_cvt_pk_bf16_f32 v226, v226, v227
	ds_write_b16 v207, v226 offset:2736
	ds_write_b16_d16_hi v207, v226 offset:2800
	s_waitcnt vmcnt(3)
	v_mul_f32_e32 v226, v108, v153
	v_mul_f32_e32 v227, v124, v153
	v_fma_f32 v226, v124, v152, -v226
	v_fma_f32 v227, v108, v152, v227
	v_mul_f32_e32 v226, s88, v226
	v_mul_f32_e32 v227, s88, v227
	v_cvt_pk_bf16_f32 v226, v226, v227
	ds_write_b16 v207, v226 offset:3456
	ds_write_b16_d16_hi v207, v226 offset:3520
	s_waitcnt vmcnt(2)
	v_mul_f32_e32 v226, v109, v155
	v_mul_f32_e32 v227, v125, v155
	v_fma_f32 v226, v125, v154, -v226
	v_fma_f32 v227, v109, v154, v227
	v_mul_f32_e32 v226, s88, v226
	v_mul_f32_e32 v227, s88, v227
	v_cvt_pk_bf16_f32 v226, v226, v227
	ds_write_b16 v207, v226 offset:3600
	ds_write_b16_d16_hi v207, v226 offset:3664
	s_waitcnt vmcnt(1)
	v_mul_f32_e32 v226, v110, v157
	v_mul_f32_e32 v227, v126, v157
	v_fma_f32 v226, v126, v156, -v226
	v_fma_f32 v227, v110, v156, v227
	v_mul_f32_e32 v226, s88, v226
	v_mul_f32_e32 v227, s88, v227
	v_cvt_pk_bf16_f32 v226, v226, v227
	ds_write_b16 v207, v226 offset:3744
	ds_write_b16_d16_hi v207, v226 offset:3808
	s_waitcnt vmcnt(0)
	v_mul_f32_e32 v226, v111, v159
	v_mul_f32_e32 v227, v127, v159
	v_fma_f32 v226, v127, v158, -v226
	v_fma_f32 v227, v111, v158, v227
	v_mul_f32_e32 v226, s88, v226
	v_mul_f32_e32 v227, s88, v227
	v_cvt_pk_bf16_f32 v226, v226, v227
	ds_write_b16 v207, v226 offset:3888
	ds_write_b16_d16_hi v207, v226 offset:3952
	s_branch .Lep2_00_st
.Lep2_00_mS:
	v_mul_f32_e32 v226, 0xbfb8aa3b, v112
	v_mul_f32_e32 v227, 0xbfb8aa3b, v96
	v_exp_f32_e32 v226, v226
	v_exp_f32_e32 v227, v227
	v_add_f32_e32 v226, 1.0, v226
	v_add_f32_e32 v227, 1.0, v227
	v_rcp_f32_e32 v226, v226
	v_rcp_f32_e32 v227, v227
	v_mul_f32_e32 v226, v112, v226
	v_mul_f32_e32 v227, v96, v227
	v_cvt_pk_bf16_f32 v226, v226, v227
	ds_write_b16 v207, v226
	ds_write_b16_d16_hi v207, v226 offset:64
	v_mul_f32_e32 v228, 0xbfb8aa3b, v113
	v_mul_f32_e32 v229, 0xbfb8aa3b, v97
	v_exp_f32_e32 v228, v228
	v_exp_f32_e32 v229, v229
	v_add_f32_e32 v228, 1.0, v228
	v_add_f32_e32 v229, 1.0, v229
	v_rcp_f32_e32 v228, v228
	v_rcp_f32_e32 v229, v229
	v_mul_f32_e32 v228, v113, v228
	v_mul_f32_e32 v229, v97, v229
	v_cvt_pk_bf16_f32 v228, v228, v229
	ds_write_b16 v207, v228 offset:144
	ds_write_b16_d16_hi v207, v228 offset:208
	v_mul_f32_e32 v226, 0xbfb8aa3b, v114
	v_mul_f32_e32 v227, 0xbfb8aa3b, v98
	v_exp_f32_e32 v226, v226
	v_exp_f32_e32 v227, v227
	v_add_f32_e32 v226, 1.0, v226
	v_add_f32_e32 v227, 1.0, v227
	v_rcp_f32_e32 v226, v226
	v_rcp_f32_e32 v227, v227
	v_mul_f32_e32 v226, v114, v226
	v_mul_f32_e32 v227, v98, v227
	v_cvt_pk_bf16_f32 v226, v226, v227
	ds_write_b16 v207, v226 offset:288
	ds_write_b16_d16_hi v207, v226 offset:352
	v_mul_f32_e32 v228, 0xbfb8aa3b, v115
	v_mul_f32_e32 v229, 0xbfb8aa3b, v99
	v_exp_f32_e32 v228, v228
	v_exp_f32_e32 v229, v229
	v_add_f32_e32 v228, 1.0, v228
	v_add_f32_e32 v229, 1.0, v229
	v_rcp_f32_e32 v228, v228
	v_rcp_f32_e32 v229, v229
	v_mul_f32_e32 v228, v115, v228
	v_mul_f32_e32 v229, v99, v229
	v_cvt_pk_bf16_f32 v228, v228, v229
	ds_write_b16 v207, v228 offset:432
	ds_write_b16_d16_hi v207, v228 offset:496
	v_mul_f32_e32 v226, 0xbfb8aa3b, v116
	v_mul_f32_e32 v227, 0xbfb8aa3b, v100
	v_exp_f32_e32 v226, v226
	v_exp_f32_e32 v227, v227
	v_add_f32_e32 v226, 1.0, v226
	v_add_f32_e32 v227, 1.0, v227
	v_rcp_f32_e32 v226, v226
	v_rcp_f32_e32 v227, v227
	v_mul_f32_e32 v226, v116, v226
	v_mul_f32_e32 v227, v100, v227
	v_cvt_pk_bf16_f32 v226, v226, v227
	ds_write_b16 v207, v226 offset:1152
	ds_write_b16_d16_hi v207, v226 offset:1216
	v_mul_f32_e32 v228, 0xbfb8aa3b, v117
	v_mul_f32_e32 v229, 0xbfb8aa3b, v101
	v_exp_f32_e32 v228, v228
	v_exp_f32_e32 v229, v229
	v_add_f32_e32 v228, 1.0, v228
	v_add_f32_e32 v229, 1.0, v229
	v_rcp_f32_e32 v228, v228
	v_rcp_f32_e32 v229, v229
	v_mul_f32_e32 v228, v117, v228
	v_mul_f32_e32 v229, v101, v229
	v_cvt_pk_bf16_f32 v228, v228, v229
	ds_write_b16 v207, v228 offset:1296
	ds_write_b16_d16_hi v207, v228 offset:1360
	v_mul_f32_e32 v226, 0xbfb8aa3b, v118
	v_mul_f32_e32 v227, 0xbfb8aa3b, v102
	v_exp_f32_e32 v226, v226
	v_exp_f32_e32 v227, v227
	v_add_f32_e32 v226, 1.0, v226
	v_add_f32_e32 v227, 1.0, v227
	v_rcp_f32_e32 v226, v226
	v_rcp_f32_e32 v227, v227
	v_mul_f32_e32 v226, v118, v226
	v_mul_f32_e32 v227, v102, v227
	v_cvt_pk_bf16_f32 v226, v226, v227
	ds_write_b16 v207, v226 offset:1440
	ds_write_b16_d16_hi v207, v226 offset:1504
	v_mul_f32_e32 v228, 0xbfb8aa3b, v119
	v_mul_f32_e32 v229, 0xbfb8aa3b, v103
	v_exp_f32_e32 v228, v228
	v_exp_f32_e32 v229, v229
	v_add_f32_e32 v228, 1.0, v228
	v_add_f32_e32 v229, 1.0, v229
	v_rcp_f32_e32 v228, v228
	v_rcp_f32_e32 v229, v229
	v_mul_f32_e32 v228, v119, v228
	v_mul_f32_e32 v229, v103, v229
	v_cvt_pk_bf16_f32 v228, v228, v229
	ds_write_b16 v207, v228 offset:1584
	ds_write_b16_d16_hi v207, v228 offset:1648
	v_mul_f32_e32 v226, 0xbfb8aa3b, v120
	v_mul_f32_e32 v227, 0xbfb8aa3b, v104
	v_exp_f32_e32 v226, v226
	v_exp_f32_e32 v227, v227
	v_add_f32_e32 v226, 1.0, v226
	v_add_f32_e32 v227, 1.0, v227
	v_rcp_f32_e32 v226, v226
	v_rcp_f32_e32 v227, v227
	v_mul_f32_e32 v226, v120, v226
	v_mul_f32_e32 v227, v104, v227
	v_cvt_pk_bf16_f32 v226, v226, v227
	ds_write_b16 v207, v226 offset:2304
	ds_write_b16_d16_hi v207, v226 offset:2368
	v_mul_f32_e32 v228, 0xbfb8aa3b, v121
	v_mul_f32_e32 v229, 0xbfb8aa3b, v105
	v_exp_f32_e32 v228, v228
	v_exp_f32_e32 v229, v229
	v_add_f32_e32 v228, 1.0, v228
	v_add_f32_e32 v229, 1.0, v229
	v_rcp_f32_e32 v228, v228
	v_rcp_f32_e32 v229, v229
	v_mul_f32_e32 v228, v121, v228
	v_mul_f32_e32 v229, v105, v229
	v_cvt_pk_bf16_f32 v228, v228, v229
	ds_write_b16 v207, v228 offset:2448
	ds_write_b16_d16_hi v207, v228 offset:2512
	v_mul_f32_e32 v226, 0xbfb8aa3b, v122
	v_mul_f32_e32 v227, 0xbfb8aa3b, v106
	v_exp_f32_e32 v226, v226
	v_exp_f32_e32 v227, v227
	v_add_f32_e32 v226, 1.0, v226
	v_add_f32_e32 v227, 1.0, v227
	v_rcp_f32_e32 v226, v226
	v_rcp_f32_e32 v227, v227
	v_mul_f32_e32 v226, v122, v226
	v_mul_f32_e32 v227, v106, v227
	v_cvt_pk_bf16_f32 v226, v226, v227
	ds_write_b16 v207, v226 offset:2592
	ds_write_b16_d16_hi v207, v226 offset:2656
	v_mul_f32_e32 v228, 0xbfb8aa3b, v123
	v_mul_f32_e32 v229, 0xbfb8aa3b, v107
	v_exp_f32_e32 v228, v228
	v_exp_f32_e32 v229, v229
	v_add_f32_e32 v228, 1.0, v228
	v_add_f32_e32 v229, 1.0, v229
	v_rcp_f32_e32 v228, v228
	v_rcp_f32_e32 v229, v229
	v_mul_f32_e32 v228, v123, v228
	v_mul_f32_e32 v229, v107, v229
	v_cvt_pk_bf16_f32 v228, v228, v229
	ds_write_b16 v207, v228 offset:2736
	ds_write_b16_d16_hi v207, v228 offset:2800
	v_mul_f32_e32 v226, 0xbfb8aa3b, v124
	v_mul_f32_e32 v227, 0xbfb8aa3b, v108
	v_exp_f32_e32 v226, v226
	v_exp_f32_e32 v227, v227
	v_add_f32_e32 v226, 1.0, v226
	v_add_f32_e32 v227, 1.0, v227
	v_rcp_f32_e32 v226, v226
	v_rcp_f32_e32 v227, v227
	v_mul_f32_e32 v226, v124, v226
	v_mul_f32_e32 v227, v108, v227
	v_cvt_pk_bf16_f32 v226, v226, v227
	ds_write_b16 v207, v226 offset:3456
	ds_write_b16_d16_hi v207, v226 offset:3520
	v_mul_f32_e32 v228, 0xbfb8aa3b, v125
	v_mul_f32_e32 v229, 0xbfb8aa3b, v109
	v_exp_f32_e32 v228, v228
	v_exp_f32_e32 v229, v229
	v_add_f32_e32 v228, 1.0, v228
	v_add_f32_e32 v229, 1.0, v229
	v_rcp_f32_e32 v228, v228
	v_rcp_f32_e32 v229, v229
	v_mul_f32_e32 v228, v125, v228
	v_mul_f32_e32 v229, v109, v229
	v_cvt_pk_bf16_f32 v228, v228, v229
	ds_write_b16 v207, v228 offset:3600
	ds_write_b16_d16_hi v207, v228 offset:3664
	v_mul_f32_e32 v226, 0xbfb8aa3b, v126
	v_mul_f32_e32 v227, 0xbfb8aa3b, v110
	v_exp_f32_e32 v226, v226
	v_exp_f32_e32 v227, v227
	v_add_f32_e32 v226, 1.0, v226
	v_add_f32_e32 v227, 1.0, v227
	v_rcp_f32_e32 v226, v226
	v_rcp_f32_e32 v227, v227
	v_mul_f32_e32 v226, v126, v226
	v_mul_f32_e32 v227, v110, v227
	v_cvt_pk_bf16_f32 v226, v226, v227
	ds_write_b16 v207, v226 offset:3744
	ds_write_b16_d16_hi v207, v226 offset:3808
	v_mul_f32_e32 v228, 0xbfb8aa3b, v127
	v_mul_f32_e32 v229, 0xbfb8aa3b, v111
	v_exp_f32_e32 v228, v228
	v_exp_f32_e32 v229, v229
	v_add_f32_e32 v228, 1.0, v228
	v_add_f32_e32 v229, 1.0, v229
	v_rcp_f32_e32 v228, v228
	v_rcp_f32_e32 v229, v229
	v_mul_f32_e32 v228, v127, v228
	v_mul_f32_e32 v229, v111, v229
	v_cvt_pk_bf16_f32 v228, v228, v229
	ds_write_b16 v207, v228 offset:3888
	ds_write_b16_d16_hi v207, v228 offset:3952
	s_branch .Lep2_00_st
.Lep2_00_st:
	v_add_u32_e32 v230, s94, v224
	s_waitcnt lgkmcnt(0)
	ds_read_b128 v[188:191], v208
	ds_read_b128 v[212:215], v208 offset:1152
	ds_read_b128 v[216:219], v208 offset:2304
	ds_read_b128 v[220:223], v208 offset:3456
	v_add_u32_e32 v226, 0, v230
	v_mul_lo_u32 v226, v226, s89
	v_add3_u32 v226, v226, v225, s91
	v_add_u32_e32 v227, 8, v230
	v_mul_lo_u32 v227, v227, s89
	v_add3_u32 v227, v227, v225, s91
	v_add_u32_e32 v228, 16, v230
	v_mul_lo_u32 v228, v228, s89
	v_add3_u32 v228, v228, v225, s91
	v_add_u32_e32 v229, 24, v230
	v_mul_lo_u32 v229, v229, s89
	v_add3_u32 v229, v229, v225, s91
	s_waitcnt lgkmcnt(3)
	global_store_dwordx4 v226, v[188:191], s[96:97]
	s_waitcnt lgkmcnt(2)
	global_store_dwordx4 v227, v[212:215], s[96:97]
	s_waitcnt lgkmcnt(1)
	global_store_dwordx4 v228, v[216:219], s[96:97]
	s_waitcnt lgkmcnt(0)
	global_store_dwordx4 v229, v[220:223], s[96:97]

.Lep2_01_mP:
	v_cvt_pk_bf16_f32 v226, v80, v64
	ds_write_b16 v207, v226
	ds_write_b16_d16_hi v207, v226 offset:64
	v_cvt_pk_bf16_f32 v227, v81, v65
	ds_write_b16 v207, v227 offset:144
	ds_write_b16_d16_hi v207, v227 offset:208
	v_cvt_pk_bf16_f32 v228, v82, v66
	ds_write_b16 v207, v228 offset:288
	ds_write_b16_d16_hi v207, v228 offset:352
	v_cvt_pk_bf16_f32 v229, v83, v67
	ds_write_b16 v207, v229 offset:432
	ds_write_b16_d16_hi v207, v229 offset:496
	v_cvt_pk_bf16_f32 v226, v84, v68
	ds_write_b16 v207, v226 offset:1152
	ds_write_b16_d16_hi v207, v226 offset:1216
	v_cvt_pk_bf16_f32 v227, v85, v69
	ds_write_b16 v207, v227 offset:1296
	ds_write_b16_d16_hi v207, v227 offset:1360
	v_cvt_pk_bf16_f32 v228, v86, v70
	ds_write_b16 v207, v228 offset:1440
	ds_write_b16_d16_hi v207, v228 offset:1504
	v_cvt_pk_bf16_f32 v229, v87, v71
	ds_write_b16 v207, v229 offset:1584
	ds_write_b16_d16_hi v207, v229 offset:1648
	v_cvt_pk_bf16_f32 v226, v88, v72
	ds_write_b16 v207, v226 offset:2304
	ds_write_b16_d16_hi v207, v226 offset:2368
	v_cvt_pk_bf16_f32 v227, v89, v73
	ds_write_b16 v207, v227 offset:2448
	ds_write_b16_d16_hi v207, v227 offset:2512
	v_cvt_pk_bf16_f32 v228, v90, v74
	ds_write_b16 v207, v228 offset:2592
	ds_write_b16_d16_hi v207, v228 offset:2656
	v_cvt_pk_bf16_f32 v229, v91, v75
	ds_write_b16 v207, v229 offset:2736
	ds_write_b16_d16_hi v207, v229 offset:2800
	v_cvt_pk_bf16_f32 v226, v92, v76
	ds_write_b16 v207, v226 offset:3456
	ds_write_b16_d16_hi v207, v226 offset:3520
	v_cvt_pk_bf16_f32 v227, v93, v77
	ds_write_b16 v207, v227 offset:3600
	ds_write_b16_d16_hi v207, v227 offset:3664
	v_cvt_pk_bf16_f32 v228, v94, v78
	ds_write_b16 v207, v228 offset:3744
	ds_write_b16_d16_hi v207, v228 offset:3808
	v_cvt_pk_bf16_f32 v229, v95, v79
	ds_write_b16 v207, v229 offset:3888
	ds_write_b16_d16_hi v207, v229 offset:3952
	s_branch .Lep2_01_st
.Lep2_01_mR:
	s_load_dwordx2 s[98:99], s[0:1], 0x148
	v_add_u32_e32 v226, s94, v209
	v_lshlrev_b32_e32 v226, 8, v226
	v_add_u32_e32 v232, v226, v160
	v_mov_b32_e32 v233, 0
	s_waitcnt lgkmcnt(0)
	v_lshl_add_u64 v[232:233], s[98:99], 0, v[232:233]
	global_load_dwordx2 v[128:129], v[232:233], off
	global_load_dwordx2 v[130:131], v[232:233], off offset:256
	global_load_dwordx2 v[132:133], v[232:233], off offset:512
	global_load_dwordx2 v[134:135], v[232:233], off offset:768
	global_load_dwordx2 v[136:137], v[232:233], off offset:2048
	global_load_dwordx2 v[138:139], v[232:233], off offset:2304
	global_load_dwordx2 v[140:141], v[232:233], off offset:2560
	global_load_dwordx2 v[142:143], v[232:233], off offset:2816
	v_add_co_u32_e32 v234, vcc, 0x1000, v232
	s_nop 1
	v_addc_co_u32_e32 v235, vcc, 0, v233, vcc
	global_load_dwordx2 v[144:145], v[234:235], off
	global_load_dwordx2 v[146:147], v[234:235], off offset:256
	global_load_dwordx2 v[148:149], v[234:235], off offset:512
	global_load_dwordx2 v[150:151], v[234:235], off offset:768
	global_load_dwordx2 v[152:153], v[234:235], off offset:2048
	global_load_dwordx2 v[154:155], v[234:235], off offset:2304
	global_load_dwordx2 v[156:157], v[234:235], off offset:2560
	global_load_dwordx2 v[158:159], v[234:235], off offset:2816
	s_waitcnt vmcnt(15)
	v_mul_f32_e32 v226, v64, v129
	v_mul_f32_e32 v227, v80, v129
	v_fma_f32 v226, v80, v128, -v226
	v_fma_f32 v227, v64, v128, v227
	v_mul_f32_e32 v226, s88, v226
	v_mul_f32_e32 v227, s88, v227
	v_cvt_pk_bf16_f32 v226, v226, v227
	ds_write_b16 v207, v226
	ds_write_b16_d16_hi v207, v226 offset:64
	s_waitcnt vmcnt(14)
	v_mul_f32_e32 v226, v65, v131
	v_mul_f32_e32 v227, v81, v131
	v_fma_f32 v226, v81, v130, -v226
	v_fma_f32 v227, v65, v130, v227
	v_mul_f32_e32 v226, s88, v226
	v_mul_f32_e32 v227, s88, v227
	v_cvt_pk_bf16_f32 v226, v226, v227
	ds_write_b16 v207, v226 offset:144
	ds_write_b16_d16_hi v207, v226 offset:208
	s_waitcnt vmcnt(13)
	v_mul_f32_e32 v226, v66, v133
	v_mul_f32_e32 v227, v82, v133
	v_fma_f32 v226, v82, v132, -v226
	v_fma_f32 v227, v66, v132, v227
	v_mul_f32_e32 v226, s88, v226
	v_mul_f32_e32 v227, s88, v227
	v_cvt_pk_bf16_f32 v226, v226, v227
	ds_write_b16 v207, v226 offset:288
	ds_write_b16_d16_hi v207, v226 offset:352
	s_waitcnt vmcnt(12)
	v_mul_f32_e32 v226, v67, v135
	v_mul_f32_e32 v227, v83, v135
	v_fma_f32 v226, v83, v134, -v226
	v_fma_f32 v227, v67, v134, v227
	v_mul_f32_e32 v226, s88, v226
	v_mul_f32_e32 v227, s88, v227
	v_cvt_pk_bf16_f32 v226, v226, v227
	ds_write_b16 v207, v226 offset:432
	ds_write_b16_d16_hi v207, v226 offset:496
	s_waitcnt vmcnt(11)
	v_mul_f32_e32 v226, v68, v137
	v_mul_f32_e32 v227, v84, v137
	v_fma_f32 v226, v84, v136, -v226
	v_fma_f32 v227, v68, v136, v227
	v_mul_f32_e32 v226, s88, v226
	v_mul_f32_e32 v227, s88, v227
	v_cvt_pk_bf16_f32 v226, v226, v227
	ds_write_b16 v207, v226 offset:1152
	ds_write_b16_d16_hi v207, v226 offset:1216
	s_waitcnt vmcnt(10)
	v_mul_f32_e32 v226, v69, v139
	v_mul_f32_e32 v227, v85, v139
	v_fma_f32 v226, v85, v138, -v226
	v_fma_f32 v227, v69, v138, v227
	v_mul_f32_e32 v226, s88, v226
	v_mul_f32_e32 v227, s88, v227
	v_cvt_pk_bf16_f32 v226, v226, v227
	ds_write_b16 v207, v226 offset:1296
	ds_write_b16_d16_hi v207, v226 offset:1360
	s_waitcnt vmcnt(9)
	v_mul_f32_e32 v226, v70, v141
	v_mul_f32_e32 v227, v86, v141
	v_fma_f32 v226, v86, v140, -v226
	v_fma_f32 v227, v70, v140, v227
	v_mul_f32_e32 v226, s88, v226
	v_mul_f32_e32 v227, s88, v227
	v_cvt_pk_bf16_f32 v226, v226, v227
	ds_write_b16 v207, v226 offset:1440
	ds_write_b16_d16_hi v207, v226 offset:1504
	s_waitcnt vmcnt(8)
	v_mul_f32_e32 v226, v71, v143
	v_mul_f32_e32 v227, v87, v143
	v_fma_f32 v226, v87, v142, -v226
	v_fma_f32 v227, v71, v142, v227
	v_mul_f32_e32 v226, s88, v226
	v_mul_f32_e32 v227, s88, v227
	v_cvt_pk_bf16_f32 v226, v226, v227
	ds_write_b16 v207, v226 offset:1584
	ds_write_b16_d16_hi v207, v226 offset:1648
	s_waitcnt vmcnt(7)
	v_mul_f32_e32 v226, v72, v145
	v_mul_f32_e32 v227, v88, v145
	v_fma_f32 v226, v88, v144, -v226
	v_fma_f32 v227, v72, v144, v227
	v_mul_f32_e32 v226, s88, v226
	v_mul_f32_e32 v227, s88, v227
	v_cvt_pk_bf16_f32 v226, v226, v227
	ds_write_b16 v207, v226 offset:2304
	ds_write_b16_d16_hi v207, v226 offset:2368
	s_waitcnt vmcnt(6)
	v_mul_f32_e32 v226, v73, v147
	v_mul_f32_e32 v227, v89, v147
	v_fma_f32 v226, v89, v146, -v226
	v_fma_f32 v227, v73, v146, v227
	v_mul_f32_e32 v226, s88, v226
	v_mul_f32_e32 v227, s88, v227
	v_cvt_pk_bf16_f32 v226, v226, v227
	ds_write_b16 v207, v226 offset:2448
	ds_write_b16_d16_hi v207, v226 offset:2512
	s_waitcnt vmcnt(5)
	v_mul_f32_e32 v226, v74, v149
	v_mul_f32_e32 v227, v90, v149
	v_fma_f32 v226, v90, v148, -v226
	v_fma_f32 v227, v74, v148, v227
	v_mul_f32_e32 v226, s88, v226
	v_mul_f32_e32 v227, s88, v227
	v_cvt_pk_bf16_f32 v226, v226, v227
	ds_write_b16 v207, v226 offset:2592
	ds_write_b16_d16_hi v207, v226 offset:2656
	s_waitcnt vmcnt(4)
	v_mul_f32_e32 v226, v75, v151
	v_mul_f32_e32 v227, v91, v151
	v_fma_f32 v226, v91, v150, -v226
	v_fma_f32 v227, v75, v150, v227
	v_mul_f32_e32 v226, s88, v226
	v_mul_f32_e32 v227, s88, v227
	v_cvt_pk_bf16_f32 v226, v226, v227
	ds_write_b16 v207, v226 offset:2736
	ds_write_b16_d16_hi v207, v226 offset:2800
	s_waitcnt vmcnt(3)
	v_mul_f32_e32 v226, v76, v153
	v_mul_f32_e32 v227, v92, v153
	v_fma_f32 v226, v92, v152, -v226
	v_fma_f32 v227, v76, v152, v227
	v_mul_f32_e32 v226, s88, v226
	v_mul_f32_e32 v227, s88, v227
	v_cvt_pk_bf16_f32 v226, v226, v227
	ds_write_b16 v207, v226 offset:3456
	ds_write_b16_d16_hi v207, v226 offset:3520
	s_waitcnt vmcnt(2)
	v_mul_f32_e32 v226, v77, v155
	v_mul_f32_e32 v227, v93, v155
	v_fma_f32 v226, v93, v154, -v226
	v_fma_f32 v227, v77, v154, v227
	v_mul_f32_e32 v226, s88, v226
	v_mul_f32_e32 v227, s88, v227
	v_cvt_pk_bf16_f32 v226, v226, v227
	ds_write_b16 v207, v226 offset:3600
	ds_write_b16_d16_hi v207, v226 offset:3664
	s_waitcnt vmcnt(1)
	v_mul_f32_e32 v226, v78, v157
	v_mul_f32_e32 v227, v94, v157
	v_fma_f32 v226, v94, v156, -v226
	v_fma_f32 v227, v78, v156, v227
	v_mul_f32_e32 v226, s88, v226
	v_mul_f32_e32 v227, s88, v227
	v_cvt_pk_bf16_f32 v226, v226, v227
	ds_write_b16 v207, v226 offset:3744
	ds_write_b16_d16_hi v207, v226 offset:3808
	s_waitcnt vmcnt(0)
	v_mul_f32_e32 v226, v79, v159
	v_mul_f32_e32 v227, v95, v159
	v_fma_f32 v226, v95, v158, -v226
	v_fma_f32 v227, v79, v158, v227
	v_mul_f32_e32 v226, s88, v226
	v_mul_f32_e32 v227, s88, v227
	v_cvt_pk_bf16_f32 v226, v226, v227
	ds_write_b16 v207, v226 offset:3888
	ds_write_b16_d16_hi v207, v226 offset:3952
	s_branch .Lep2_01_st
.Lep2_01_mS:
	v_mul_f32_e32 v226, 0xbfb8aa3b, v80
	v_mul_f32_e32 v227, 0xbfb8aa3b, v64
	v_exp_f32_e32 v226, v226
	v_exp_f32_e32 v227, v227
	v_add_f32_e32 v226, 1.0, v226
	v_add_f32_e32 v227, 1.0, v227
	v_rcp_f32_e32 v226, v226
	v_rcp_f32_e32 v227, v227
	v_mul_f32_e32 v226, v80, v226
	v_mul_f32_e32 v227, v64, v227
	v_cvt_pk_bf16_f32 v226, v226, v227
	ds_write_b16 v207, v226
	ds_write_b16_d16_hi v207, v226 offset:64
	v_mul_f32_e32 v228, 0xbfb8aa3b, v81
	v_mul_f32_e32 v229, 0xbfb8aa3b, v65
	v_exp_f32_e32 v228, v228
	v_exp_f32_e32 v229, v229
	v_add_f32_e32 v228, 1.0, v228
	v_add_f32_e32 v229, 1.0, v229
	v_rcp_f32_e32 v228, v228
	v_rcp_f32_e32 v229, v229
	v_mul_f32_e32 v228, v81, v228
	v_mul_f32_e32 v229, v65, v229
	v_cvt_pk_bf16_f32 v228, v228, v229
	ds_write_b16 v207, v228 offset:144
	ds_write_b16_d16_hi v207, v228 offset:208
	v_mul_f32_e32 v226, 0xbfb8aa3b, v82
	v_mul_f32_e32 v227, 0xbfb8aa3b, v66
	v_exp_f32_e32 v226, v226
	v_exp_f32_e32 v227, v227
	v_add_f32_e32 v226, 1.0, v226
	v_add_f32_e32 v227, 1.0, v227
	v_rcp_f32_e32 v226, v226
	v_rcp_f32_e32 v227, v227
	v_mul_f32_e32 v226, v82, v226
	v_mul_f32_e32 v227, v66, v227
	v_cvt_pk_bf16_f32 v226, v226, v227
	ds_write_b16 v207, v226 offset:288
	ds_write_b16_d16_hi v207, v226 offset:352
	v_mul_f32_e32 v228, 0xbfb8aa3b, v83
	v_mul_f32_e32 v229, 0xbfb8aa3b, v67
	v_exp_f32_e32 v228, v228
	v_exp_f32_e32 v229, v229
	v_add_f32_e32 v228, 1.0, v228
	v_add_f32_e32 v229, 1.0, v229
	v_rcp_f32_e32 v228, v228
	v_rcp_f32_e32 v229, v229
	v_mul_f32_e32 v228, v83, v228
	v_mul_f32_e32 v229, v67, v229
	v_cvt_pk_bf16_f32 v228, v228, v229
	ds_write_b16 v207, v228 offset:432
	ds_write_b16_d16_hi v207, v228 offset:496
	v_mul_f32_e32 v226, 0xbfb8aa3b, v84
	v_mul_f32_e32 v227, 0xbfb8aa3b, v68
	v_exp_f32_e32 v226, v226
	v_exp_f32_e32 v227, v227
	v_add_f32_e32 v226, 1.0, v226
	v_add_f32_e32 v227, 1.0, v227
	v_rcp_f32_e32 v226, v226
	v_rcp_f32_e32 v227, v227
	v_mul_f32_e32 v226, v84, v226
	v_mul_f32_e32 v227, v68, v227
	v_cvt_pk_bf16_f32 v226, v226, v227
	ds_write_b16 v207, v226 offset:1152
	ds_write_b16_d16_hi v207, v226 offset:1216
	v_mul_f32_e32 v228, 0xbfb8aa3b, v85
	v_mul_f32_e32 v229, 0xbfb8aa3b, v69
	v_exp_f32_e32 v228, v228
	v_exp_f32_e32 v229, v229
	v_add_f32_e32 v228, 1.0, v228
	v_add_f32_e32 v229, 1.0, v229
	v_rcp_f32_e32 v228, v228
	v_rcp_f32_e32 v229, v229
	v_mul_f32_e32 v228, v85, v228
	v_mul_f32_e32 v229, v69, v229
	v_cvt_pk_bf16_f32 v228, v228, v229
	ds_write_b16 v207, v228 offset:1296
	ds_write_b16_d16_hi v207, v228 offset:1360
	v_mul_f32_e32 v226, 0xbfb8aa3b, v86
	v_mul_f32_e32 v227, 0xbfb8aa3b, v70
	v_exp_f32_e32 v226, v226
	v_exp_f32_e32 v227, v227
	v_add_f32_e32 v226, 1.0, v226
	v_add_f32_e32 v227, 1.0, v227
	v_rcp_f32_e32 v226, v226
	v_rcp_f32_e32 v227, v227
	v_mul_f32_e32 v226, v86, v226
	v_mul_f32_e32 v227, v70, v227
	v_cvt_pk_bf16_f32 v226, v226, v227
	ds_write_b16 v207, v226 offset:1440
	ds_write_b16_d16_hi v207, v226 offset:1504
	v_mul_f32_e32 v228, 0xbfb8aa3b, v87
	v_mul_f32_e32 v229, 0xbfb8aa3b, v71
	v_exp_f32_e32 v228, v228
	v_exp_f32_e32 v229, v229
	v_add_f32_e32 v228, 1.0, v228
	v_add_f32_e32 v229, 1.0, v229
	v_rcp_f32_e32 v228, v228
	v_rcp_f32_e32 v229, v229
	v_mul_f32_e32 v228, v87, v228
	v_mul_f32_e32 v229, v71, v229
	v_cvt_pk_bf16_f32 v228, v228, v229
	ds_write_b16 v207, v228 offset:1584
	ds_write_b16_d16_hi v207, v228 offset:1648
	v_mul_f32_e32 v226, 0xbfb8aa3b, v88
	v_mul_f32_e32 v227, 0xbfb8aa3b, v72
	v_exp_f32_e32 v226, v226
	v_exp_f32_e32 v227, v227
	v_add_f32_e32 v226, 1.0, v226
	v_add_f32_e32 v227, 1.0, v227
	v_rcp_f32_e32 v226, v226
	v_rcp_f32_e32 v227, v227
	v_mul_f32_e32 v226, v88, v226
	v_mul_f32_e32 v227, v72, v227
	v_cvt_pk_bf16_f32 v226, v226, v227
	ds_write_b16 v207, v226 offset:2304
	ds_write_b16_d16_hi v207, v226 offset:2368
	v_mul_f32_e32 v228, 0xbfb8aa3b, v89
	v_mul_f32_e32 v229, 0xbfb8aa3b, v73
	v_exp_f32_e32 v228, v228
	v_exp_f32_e32 v229, v229
	v_add_f32_e32 v228, 1.0, v228
	v_add_f32_e32 v229, 1.0, v229
	v_rcp_f32_e32 v228, v228
	v_rcp_f32_e32 v229, v229
	v_mul_f32_e32 v228, v89, v228
	v_mul_f32_e32 v229, v73, v229
	v_cvt_pk_bf16_f32 v228, v228, v229
	ds_write_b16 v207, v228 offset:2448
	ds_write_b16_d16_hi v207, v228 offset:2512
	v_mul_f32_e32 v226, 0xbfb8aa3b, v90
	v_mul_f32_e32 v227, 0xbfb8aa3b, v74
	v_exp_f32_e32 v226, v226
	v_exp_f32_e32 v227, v227
	v_add_f32_e32 v226, 1.0, v226
	v_add_f32_e32 v227, 1.0, v227
	v_rcp_f32_e32 v226, v226
	v_rcp_f32_e32 v227, v227
	v_mul_f32_e32 v226, v90, v226
	v_mul_f32_e32 v227, v74, v227
	v_cvt_pk_bf16_f32 v226, v226, v227
	ds_write_b16 v207, v226 offset:2592
	ds_write_b16_d16_hi v207, v226 offset:2656
	v_mul_f32_e32 v228, 0xbfb8aa3b, v91
	v_mul_f32_e32 v229, 0xbfb8aa3b, v75
	v_exp_f32_e32 v228, v228
	v_exp_f32_e32 v229, v229
	v_add_f32_e32 v228, 1.0, v228
	v_add_f32_e32 v229, 1.0, v229
	v_rcp_f32_e32 v228, v228
	v_rcp_f32_e32 v229, v229
	v_mul_f32_e32 v228, v91, v228
	v_mul_f32_e32 v229, v75, v229
	v_cvt_pk_bf16_f32 v228, v228, v229
	ds_write_b16 v207, v228 offset:2736
	ds_write_b16_d16_hi v207, v228 offset:2800
	v_mul_f32_e32 v226, 0xbfb8aa3b, v92
	v_mul_f32_e32 v227, 0xbfb8aa3b, v76
	v_exp_f32_e32 v226, v226
	v_exp_f32_e32 v227, v227
	v_add_f32_e32 v226, 1.0, v226
	v_add_f32_e32 v227, 1.0, v227
	v_rcp_f32_e32 v226, v226
	v_rcp_f32_e32 v227, v227
	v_mul_f32_e32 v226, v92, v226
	v_mul_f32_e32 v227, v76, v227
	v_cvt_pk_bf16_f32 v226, v226, v227
	ds_write_b16 v207, v226 offset:3456
	ds_write_b16_d16_hi v207, v226 offset:3520
	v_mul_f32_e32 v228, 0xbfb8aa3b, v93
	v_mul_f32_e32 v229, 0xbfb8aa3b, v77
	v_exp_f32_e32 v228, v228
	v_exp_f32_e32 v229, v229
	v_add_f32_e32 v228, 1.0, v228
	v_add_f32_e32 v229, 1.0, v229
	v_rcp_f32_e32 v228, v228
	v_rcp_f32_e32 v229, v229
	v_mul_f32_e32 v228, v93, v228
	v_mul_f32_e32 v229, v77, v229
	v_cvt_pk_bf16_f32 v228, v228, v229
	ds_write_b16 v207, v228 offset:3600
	ds_write_b16_d16_hi v207, v228 offset:3664
	v_mul_f32_e32 v226, 0xbfb8aa3b, v94
	v_mul_f32_e32 v227, 0xbfb8aa3b, v78
	v_exp_f32_e32 v226, v226
	v_exp_f32_e32 v227, v227
	v_add_f32_e32 v226, 1.0, v226
	v_add_f32_e32 v227, 1.0, v227
	v_rcp_f32_e32 v226, v226
	v_rcp_f32_e32 v227, v227
	v_mul_f32_e32 v226, v94, v226
	v_mul_f32_e32 v227, v78, v227
	v_cvt_pk_bf16_f32 v226, v226, v227
	ds_write_b16 v207, v226 offset:3744
	ds_write_b16_d16_hi v207, v226 offset:3808
	v_mul_f32_e32 v228, 0xbfb8aa3b, v95
	v_mul_f32_e32 v229, 0xbfb8aa3b, v79
	v_exp_f32_e32 v228, v228
	v_exp_f32_e32 v229, v229
	v_add_f32_e32 v228, 1.0, v228
	v_add_f32_e32 v229, 1.0, v229
	v_rcp_f32_e32 v228, v228
	v_rcp_f32_e32 v229, v229
	v_mul_f32_e32 v228, v95, v228
	v_mul_f32_e32 v229, v79, v229
	v_cvt_pk_bf16_f32 v228, v228, v229
	ds_write_b16 v207, v228 offset:3888
	ds_write_b16_d16_hi v207, v228 offset:3952
	s_branch .Lep2_01_st

.Lep2_10_mP:
	v_cvt_pk_bf16_f32 v226, v48, v32
	ds_write_b16 v207, v226
	ds_write_b16_d16_hi v207, v226 offset:64
	v_cvt_pk_bf16_f32 v227, v49, v33
	ds_write_b16 v207, v227 offset:144
	ds_write_b16_d16_hi v207, v227 offset:208
	v_cvt_pk_bf16_f32 v228, v50, v34
	ds_write_b16 v207, v228 offset:288
	ds_write_b16_d16_hi v207, v228 offset:352
	v_cvt_pk_bf16_f32 v229, v51, v35
	ds_write_b16 v207, v229 offset:432
	ds_write_b16_d16_hi v207, v229 offset:496
	v_cvt_pk_bf16_f32 v226, v52, v36
	ds_write_b16 v207, v226 offset:1152
	ds_write_b16_d16_hi v207, v226 offset:1216
	v_cvt_pk_bf16_f32 v227, v53, v37
	ds_write_b16 v207, v227 offset:1296
	ds_write_b16_d16_hi v207, v227 offset:1360
	v_cvt_pk_bf16_f32 v228, v54, v38
	ds_write_b16 v207, v228 offset:1440
	ds_write_b16_d16_hi v207, v228 offset:1504
	v_cvt_pk_bf16_f32 v229, v55, v39
	ds_write_b16 v207, v229 offset:1584
	ds_write_b16_d16_hi v207, v229 offset:1648
	v_cvt_pk_bf16_f32 v226, v56, v40
	ds_write_b16 v207, v226 offset:2304
	ds_write_b16_d16_hi v207, v226 offset:2368
	v_cvt_pk_bf16_f32 v227, v57, v41
	ds_write_b16 v207, v227 offset:2448
	ds_write_b16_d16_hi v207, v227 offset:2512
	v_cvt_pk_bf16_f32 v228, v58, v42
	ds_write_b16 v207, v228 offset:2592
	ds_write_b16_d16_hi v207, v228 offset:2656
	v_cvt_pk_bf16_f32 v229, v59, v43
	ds_write_b16 v207, v229 offset:2736
	ds_write_b16_d16_hi v207, v229 offset:2800
	v_cvt_pk_bf16_f32 v226, v60, v44
	ds_write_b16 v207, v226 offset:3456
	ds_write_b16_d16_hi v207, v226 offset:3520
	v_cvt_pk_bf16_f32 v227, v61, v45
	ds_write_b16 v207, v227 offset:3600
	ds_write_b16_d16_hi v207, v227 offset:3664
	v_cvt_pk_bf16_f32 v228, v62, v46
	ds_write_b16 v207, v228 offset:3744
	ds_write_b16_d16_hi v207, v228 offset:3808
	v_cvt_pk_bf16_f32 v229, v63, v47
	ds_write_b16 v207, v229 offset:3888
	ds_write_b16_d16_hi v207, v229 offset:3952
	s_branch .Lep2_10_st
.Lep2_10_mR:
	s_load_dwordx2 s[98:99], s[0:1], 0x148
	v_add_u32_e32 v226, s94, v209
	v_lshlrev_b32_e32 v226, 8, v226
	v_add_u32_e32 v232, v226, v160
	v_mov_b32_e32 v233, 0
	s_waitcnt lgkmcnt(0)
	v_lshl_add_u64 v[232:233], s[98:99], 0, v[232:233]
	global_load_dwordx2 v[128:129], v[232:233], off
	global_load_dwordx2 v[130:131], v[232:233], off offset:256
	global_load_dwordx2 v[132:133], v[232:233], off offset:512
	global_load_dwordx2 v[134:135], v[232:233], off offset:768
	global_load_dwordx2 v[136:137], v[232:233], off offset:2048
	global_load_dwordx2 v[138:139], v[232:233], off offset:2304
	global_load_dwordx2 v[140:141], v[232:233], off offset:2560
	global_load_dwordx2 v[142:143], v[232:233], off offset:2816
	v_add_co_u32_e32 v234, vcc, 0x1000, v232
	s_nop 1
	v_addc_co_u32_e32 v235, vcc, 0, v233, vcc
	global_load_dwordx2 v[144:145], v[234:235], off
	global_load_dwordx2 v[146:147], v[234:235], off offset:256
	global_load_dwordx2 v[148:149], v[234:235], off offset:512
	global_load_dwordx2 v[150:151], v[234:235], off offset:768
	global_load_dwordx2 v[152:153], v[234:235], off offset:2048
	global_load_dwordx2 v[154:155], v[234:235], off offset:2304
	global_load_dwordx2 v[156:157], v[234:235], off offset:2560
	global_load_dwordx2 v[158:159], v[234:235], off offset:2816
	s_waitcnt vmcnt(15)
	v_mul_f32_e32 v226, v32, v129
	v_mul_f32_e32 v227, v48, v129
	v_fma_f32 v226, v48, v128, -v226
	v_fma_f32 v227, v32, v128, v227
	v_mul_f32_e32 v226, s88, v226
	v_mul_f32_e32 v227, s88, v227
	v_cvt_pk_bf16_f32 v226, v226, v227
	ds_write_b16 v207, v226
	ds_write_b16_d16_hi v207, v226 offset:64
	s_waitcnt vmcnt(14)
	v_mul_f32_e32 v226, v33, v131
	v_mul_f32_e32 v227, v49, v131
	v_fma_f32 v226, v49, v130, -v226
	v_fma_f32 v227, v33, v130, v227
	v_mul_f32_e32 v226, s88, v226
	v_mul_f32_e32 v227, s88, v227
	v_cvt_pk_bf16_f32 v226, v226, v227
	ds_write_b16 v207, v226 offset:144
	ds_write_b16_d16_hi v207, v226 offset:208
	s_waitcnt vmcnt(13)
	v_mul_f32_e32 v226, v34, v133
	v_mul_f32_e32 v227, v50, v133
	v_fma_f32 v226, v50, v132, -v226
	v_fma_f32 v227, v34, v132, v227
	v_mul_f32_e32 v226, s88, v226
	v_mul_f32_e32 v227, s88, v227
	v_cvt_pk_bf16_f32 v226, v226, v227
	ds_write_b16 v207, v226 offset:288
	ds_write_b16_d16_hi v207, v226 offset:352
	s_waitcnt vmcnt(12)
	v_mul_f32_e32 v226, v35, v135
	v_mul_f32_e32 v227, v51, v135
	v_fma_f32 v226, v51, v134, -v226
	v_fma_f32 v227, v35, v134, v227
	v_mul_f32_e32 v226, s88, v226
	v_mul_f32_e32 v227, s88, v227
	v_cvt_pk_bf16_f32 v226, v226, v227
	ds_write_b16 v207, v226 offset:432
	ds_write_b16_d16_hi v207, v226 offset:496
	s_waitcnt vmcnt(11)
	v_mul_f32_e32 v226, v36, v137
	v_mul_f32_e32 v227, v52, v137
	v_fma_f32 v226, v52, v136, -v226
	v_fma_f32 v227, v36, v136, v227
	v_mul_f32_e32 v226, s88, v226
	v_mul_f32_e32 v227, s88, v227
	v_cvt_pk_bf16_f32 v226, v226, v227
	ds_write_b16 v207, v226 offset:1152
	ds_write_b16_d16_hi v207, v226 offset:1216
	s_waitcnt vmcnt(10)
	v_mul_f32_e32 v226, v37, v139
	v_mul_f32_e32 v227, v53, v139
	v_fma_f32 v226, v53, v138, -v226
	v_fma_f32 v227, v37, v138, v227
	v_mul_f32_e32 v226, s88, v226
	v_mul_f32_e32 v227, s88, v227
	v_cvt_pk_bf16_f32 v226, v226, v227
	ds_write_b16 v207, v226 offset:1296
	ds_write_b16_d16_hi v207, v226 offset:1360
	s_waitcnt vmcnt(9)
	v_mul_f32_e32 v226, v38, v141
	v_mul_f32_e32 v227, v54, v141
	v_fma_f32 v226, v54, v140, -v226
	v_fma_f32 v227, v38, v140, v227
	v_mul_f32_e32 v226, s88, v226
	v_mul_f32_e32 v227, s88, v227
	v_cvt_pk_bf16_f32 v226, v226, v227
	ds_write_b16 v207, v226 offset:1440
	ds_write_b16_d16_hi v207, v226 offset:1504
	s_waitcnt vmcnt(8)
	v_mul_f32_e32 v226, v39, v143
	v_mul_f32_e32 v227, v55, v143
	v_fma_f32 v226, v55, v142, -v226
	v_fma_f32 v227, v39, v142, v227
	v_mul_f32_e32 v226, s88, v226
	v_mul_f32_e32 v227, s88, v227
	v_cvt_pk_bf16_f32 v226, v226, v227
	ds_write_b16 v207, v226 offset:1584
	ds_write_b16_d16_hi v207, v226 offset:1648
	s_waitcnt vmcnt(7)
	v_mul_f32_e32 v226, v40, v145
	v_mul_f32_e32 v227, v56, v145
	v_fma_f32 v226, v56, v144, -v226
	v_fma_f32 v227, v40, v144, v227
	v_mul_f32_e32 v226, s88, v226
	v_mul_f32_e32 v227, s88, v227
	v_cvt_pk_bf16_f32 v226, v226, v227
	ds_write_b16 v207, v226 offset:2304
	ds_write_b16_d16_hi v207, v226 offset:2368
	s_waitcnt vmcnt(6)
	v_mul_f32_e32 v226, v41, v147
	v_mul_f32_e32 v227, v57, v147
	v_fma_f32 v226, v57, v146, -v226
	v_fma_f32 v227, v41, v146, v227
	v_mul_f32_e32 v226, s88, v226
	v_mul_f32_e32 v227, s88, v227
	v_cvt_pk_bf16_f32 v226, v226, v227
	ds_write_b16 v207, v226 offset:2448
	ds_write_b16_d16_hi v207, v226 offset:2512
	s_waitcnt vmcnt(5)
	v_mul_f32_e32 v226, v42, v149
	v_mul_f32_e32 v227, v58, v149
	v_fma_f32 v226, v58, v148, -v226
	v_fma_f32 v227, v42, v148, v227
	v_mul_f32_e32 v226, s88, v226
	v_mul_f32_e32 v227, s88, v227
	v_cvt_pk_bf16_f32 v226, v226, v227
	ds_write_b16 v207, v226 offset:2592
	ds_write_b16_d16_hi v207, v226 offset:2656
	s_waitcnt vmcnt(4)
	v_mul_f32_e32 v226, v43, v151
	v_mul_f32_e32 v227, v59, v151
	v_fma_f32 v226, v59, v150, -v226
	v_fma_f32 v227, v43, v150, v227
	v_mul_f32_e32 v226, s88, v226
	v_mul_f32_e32 v227, s88, v227
	v_cvt_pk_bf16_f32 v226, v226, v227
	ds_write_b16 v207, v226 offset:2736
	ds_write_b16_d16_hi v207, v226 offset:2800
	s_waitcnt vmcnt(3)
	v_mul_f32_e32 v226, v44, v153
	v_mul_f32_e32 v227, v60, v153
	v_fma_f32 v226, v60, v152, -v226
	v_fma_f32 v227, v44, v152, v227
	v_mul_f32_e32 v226, s88, v226
	v_mul_f32_e32 v227, s88, v227
	v_cvt_pk_bf16_f32 v226, v226, v227
	ds_write_b16 v207, v226 offset:3456
	ds_write_b16_d16_hi v207, v226 offset:3520
	s_waitcnt vmcnt(2)
	v_mul_f32_e32 v226, v45, v155
	v_mul_f32_e32 v227, v61, v155
	v_fma_f32 v226, v61, v154, -v226
	v_fma_f32 v227, v45, v154, v227
	v_mul_f32_e32 v226, s88, v226
	v_mul_f32_e32 v227, s88, v227
	v_cvt_pk_bf16_f32 v226, v226, v227
	ds_write_b16 v207, v226 offset:3600
	ds_write_b16_d16_hi v207, v226 offset:3664
	s_waitcnt vmcnt(1)
	v_mul_f32_e32 v226, v46, v157
	v_mul_f32_e32 v227, v62, v157
	v_fma_f32 v226, v62, v156, -v226
	v_fma_f32 v227, v46, v156, v227
	v_mul_f32_e32 v226, s88, v226
	v_mul_f32_e32 v227, s88, v227
	v_cvt_pk_bf16_f32 v226, v226, v227
	ds_write_b16 v207, v226 offset:3744
	ds_write_b16_d16_hi v207, v226 offset:3808
	s_waitcnt vmcnt(0)
	v_mul_f32_e32 v226, v47, v159
	v_mul_f32_e32 v227, v63, v159
	v_fma_f32 v226, v63, v158, -v226
	v_fma_f32 v227, v47, v158, v227
	v_mul_f32_e32 v226, s88, v226
	v_mul_f32_e32 v227, s88, v227
	v_cvt_pk_bf16_f32 v226, v226, v227
	ds_write_b16 v207, v226 offset:3888
	ds_write_b16_d16_hi v207, v226 offset:3952
	s_branch .Lep2_10_st
.Lep2_10_mS:
	v_mul_f32_e32 v226, 0xbfb8aa3b, v48
	v_mul_f32_e32 v227, 0xbfb8aa3b, v32
	v_exp_f32_e32 v226, v226
	v_exp_f32_e32 v227, v227
	v_add_f32_e32 v226, 1.0, v226
	v_add_f32_e32 v227, 1.0, v227
	v_rcp_f32_e32 v226, v226
	v_rcp_f32_e32 v227, v227
	v_mul_f32_e32 v226, v48, v226
	v_mul_f32_e32 v227, v32, v227
	v_cvt_pk_bf16_f32 v226, v226, v227
	ds_write_b16 v207, v226
	ds_write_b16_d16_hi v207, v226 offset:64
	v_mul_f32_e32 v228, 0xbfb8aa3b, v49
	v_mul_f32_e32 v229, 0xbfb8aa3b, v33
	v_exp_f32_e32 v228, v228
	v_exp_f32_e32 v229, v229
	v_add_f32_e32 v228, 1.0, v228
	v_add_f32_e32 v229, 1.0, v229
	v_rcp_f32_e32 v228, v228
	v_rcp_f32_e32 v229, v229
	v_mul_f32_e32 v228, v49, v228
	v_mul_f32_e32 v229, v33, v229
	v_cvt_pk_bf16_f32 v228, v228, v229
	ds_write_b16 v207, v228 offset:144
	ds_write_b16_d16_hi v207, v228 offset:208
	v_mul_f32_e32 v226, 0xbfb8aa3b, v50
	v_mul_f32_e32 v227, 0xbfb8aa3b, v34
	v_exp_f32_e32 v226, v226
	v_exp_f32_e32 v227, v227
	v_add_f32_e32 v226, 1.0, v226
	v_add_f32_e32 v227, 1.0, v227
	v_rcp_f32_e32 v226, v226
	v_rcp_f32_e32 v227, v227
	v_mul_f32_e32 v226, v50, v226
	v_mul_f32_e32 v227, v34, v227
	v_cvt_pk_bf16_f32 v226, v226, v227
	ds_write_b16 v207, v226 offset:288
	ds_write_b16_d16_hi v207, v226 offset:352
	v_mul_f32_e32 v228, 0xbfb8aa3b, v51
	v_mul_f32_e32 v229, 0xbfb8aa3b, v35
	v_exp_f32_e32 v228, v228
	v_exp_f32_e32 v229, v229
	v_add_f32_e32 v228, 1.0, v228
	v_add_f32_e32 v229, 1.0, v229
	v_rcp_f32_e32 v228, v228
	v_rcp_f32_e32 v229, v229
	v_mul_f32_e32 v228, v51, v228
	v_mul_f32_e32 v229, v35, v229
	v_cvt_pk_bf16_f32 v228, v228, v229
	ds_write_b16 v207, v228 offset:432
	ds_write_b16_d16_hi v207, v228 offset:496
	v_mul_f32_e32 v226, 0xbfb8aa3b, v52
	v_mul_f32_e32 v227, 0xbfb8aa3b, v36
	v_exp_f32_e32 v226, v226
	v_exp_f32_e32 v227, v227
	v_add_f32_e32 v226, 1.0, v226
	v_add_f32_e32 v227, 1.0, v227
	v_rcp_f32_e32 v226, v226
	v_rcp_f32_e32 v227, v227
	v_mul_f32_e32 v226, v52, v226
	v_mul_f32_e32 v227, v36, v227
	v_cvt_pk_bf16_f32 v226, v226, v227
	ds_write_b16 v207, v226 offset:1152
	ds_write_b16_d16_hi v207, v226 offset:1216
	v_mul_f32_e32 v228, 0xbfb8aa3b, v53
	v_mul_f32_e32 v229, 0xbfb8aa3b, v37
	v_exp_f32_e32 v228, v228
	v_exp_f32_e32 v229, v229
	v_add_f32_e32 v228, 1.0, v228
	v_add_f32_e32 v229, 1.0, v229
	v_rcp_f32_e32 v228, v228
	v_rcp_f32_e32 v229, v229
	v_mul_f32_e32 v228, v53, v228
	v_mul_f32_e32 v229, v37, v229
	v_cvt_pk_bf16_f32 v228, v228, v229
	ds_write_b16 v207, v228 offset:1296
	ds_write_b16_d16_hi v207, v228 offset:1360
	v_mul_f32_e32 v226, 0xbfb8aa3b, v54
	v_mul_f32_e32 v227, 0xbfb8aa3b, v38
	v_exp_f32_e32 v226, v226
	v_exp_f32_e32 v227, v227
	v_add_f32_e32 v226, 1.0, v226
	v_add_f32_e32 v227, 1.0, v227
	v_rcp_f32_e32 v226, v226
	v_rcp_f32_e32 v227, v227
	v_mul_f32_e32 v226, v54, v226
	v_mul_f32_e32 v227, v38, v227
	v_cvt_pk_bf16_f32 v226, v226, v227
	ds_write_b16 v207, v226 offset:1440
	ds_write_b16_d16_hi v207, v226 offset:1504
	v_mul_f32_e32 v228, 0xbfb8aa3b, v55
	v_mul_f32_e32 v229, 0xbfb8aa3b, v39
	v_exp_f32_e32 v228, v228
	v_exp_f32_e32 v229, v229
	v_add_f32_e32 v228, 1.0, v228
	v_add_f32_e32 v229, 1.0, v229
	v_rcp_f32_e32 v228, v228
	v_rcp_f32_e32 v229, v229
	v_mul_f32_e32 v228, v55, v228
	v_mul_f32_e32 v229, v39, v229
	v_cvt_pk_bf16_f32 v228, v228, v229
	ds_write_b16 v207, v228 offset:1584
	ds_write_b16_d16_hi v207, v228 offset:1648
	v_mul_f32_e32 v226, 0xbfb8aa3b, v56
	v_mul_f32_e32 v227, 0xbfb8aa3b, v40
	v_exp_f32_e32 v226, v226
	v_exp_f32_e32 v227, v227
	v_add_f32_e32 v226, 1.0, v226
	v_add_f32_e32 v227, 1.0, v227
	v_rcp_f32_e32 v226, v226
	v_rcp_f32_e32 v227, v227
	v_mul_f32_e32 v226, v56, v226
	v_mul_f32_e32 v227, v40, v227
	v_cvt_pk_bf16_f32 v226, v226, v227
	ds_write_b16 v207, v226 offset:2304
	ds_write_b16_d16_hi v207, v226 offset:2368
	v_mul_f32_e32 v228, 0xbfb8aa3b, v57
	v_mul_f32_e32 v229, 0xbfb8aa3b, v41
	v_exp_f32_e32 v228, v228
	v_exp_f32_e32 v229, v229
	v_add_f32_e32 v228, 1.0, v228
	v_add_f32_e32 v229, 1.0, v229
	v_rcp_f32_e32 v228, v228
	v_rcp_f32_e32 v229, v229
	v_mul_f32_e32 v228, v57, v228
	v_mul_f32_e32 v229, v41, v229
	v_cvt_pk_bf16_f32 v228, v228, v229
	ds_write_b16 v207, v228 offset:2448
	ds_write_b16_d16_hi v207, v228 offset:2512
	v_mul_f32_e32 v226, 0xbfb8aa3b, v58
	v_mul_f32_e32 v227, 0xbfb8aa3b, v42
	v_exp_f32_e32 v226, v226
	v_exp_f32_e32 v227, v227
	v_add_f32_e32 v226, 1.0, v226
	v_add_f32_e32 v227, 1.0, v227
	v_rcp_f32_e32 v226, v226
	v_rcp_f32_e32 v227, v227
	v_mul_f32_e32 v226, v58, v226
	v_mul_f32_e32 v227, v42, v227
	v_cvt_pk_bf16_f32 v226, v226, v227
	ds_write_b16 v207, v226 offset:2592
	ds_write_b16_d16_hi v207, v226 offset:2656
	v_mul_f32_e32 v228, 0xbfb8aa3b, v59
	v_mul_f32_e32 v229, 0xbfb8aa3b, v43
	v_exp_f32_e32 v228, v228
	v_exp_f32_e32 v229, v229
	v_add_f32_e32 v228, 1.0, v228
	v_add_f32_e32 v229, 1.0, v229
	v_rcp_f32_e32 v228, v228
	v_rcp_f32_e32 v229, v229
	v_mul_f32_e32 v228, v59, v228
	v_mul_f32_e32 v229, v43, v229
	v_cvt_pk_bf16_f32 v228, v228, v229
	ds_write_b16 v207, v228 offset:2736
	ds_write_b16_d16_hi v207, v228 offset:2800
	v_mul_f32_e32 v226, 0xbfb8aa3b, v60
	v_mul_f32_e32 v227, 0xbfb8aa3b, v44
	v_exp_f32_e32 v226, v226
	v_exp_f32_e32 v227, v227
	v_add_f32_e32 v226, 1.0, v226
	v_add_f32_e32 v227, 1.0, v227
	v_rcp_f32_e32 v226, v226
	v_rcp_f32_e32 v227, v227
	v_mul_f32_e32 v226, v60, v226
	v_mul_f32_e32 v227, v44, v227
	v_cvt_pk_bf16_f32 v226, v226, v227
	ds_write_b16 v207, v226 offset:3456
	ds_write_b16_d16_hi v207, v226 offset:3520
	v_mul_f32_e32 v228, 0xbfb8aa3b, v61
	v_mul_f32_e32 v229, 0xbfb8aa3b, v45
	v_exp_f32_e32 v228, v228
	v_exp_f32_e32 v229, v229
	v_add_f32_e32 v228, 1.0, v228
	v_add_f32_e32 v229, 1.0, v229
	v_rcp_f32_e32 v228, v228
	v_rcp_f32_e32 v229, v229
	v_mul_f32_e32 v228, v61, v228
	v_mul_f32_e32 v229, v45, v229
	v_cvt_pk_bf16_f32 v228, v228, v229
	ds_write_b16 v207, v228 offset:3600
	ds_write_b16_d16_hi v207, v228 offset:3664
	v_mul_f32_e32 v226, 0xbfb8aa3b, v62
	v_mul_f32_e32 v227, 0xbfb8aa3b, v46
	v_exp_f32_e32 v226, v226
	v_exp_f32_e32 v227, v227
	v_add_f32_e32 v226, 1.0, v226
	v_add_f32_e32 v227, 1.0, v227
	v_rcp_f32_e32 v226, v226
	v_rcp_f32_e32 v227, v227
	v_mul_f32_e32 v226, v62, v226
	v_mul_f32_e32 v227, v46, v227
	v_cvt_pk_bf16_f32 v226, v226, v227
	ds_write_b16 v207, v226 offset:3744
	ds_write_b16_d16_hi v207, v226 offset:3808
	v_mul_f32_e32 v228, 0xbfb8aa3b, v63
	v_mul_f32_e32 v229, 0xbfb8aa3b, v47
	v_exp_f32_e32 v228, v228
	v_exp_f32_e32 v229, v229
	v_add_f32_e32 v228, 1.0, v228
	v_add_f32_e32 v229, 1.0, v229
	v_rcp_f32_e32 v228, v228
	v_rcp_f32_e32 v229, v229
	v_mul_f32_e32 v228, v63, v228
	v_mul_f32_e32 v229, v47, v229
	v_cvt_pk_bf16_f32 v228, v228, v229
	ds_write_b16 v207, v228 offset:3888
	ds_write_b16_d16_hi v207, v228 offset:3952
	s_branch .Lep2_10_st

.Lep2_11_mP:
	v_cvt_pk_bf16_f32 v226, v16, v0
	ds_write_b16 v207, v226
	ds_write_b16_d16_hi v207, v226 offset:64
	v_cvt_pk_bf16_f32 v227, v17, v1
	ds_write_b16 v207, v227 offset:144
	ds_write_b16_d16_hi v207, v227 offset:208
	v_cvt_pk_bf16_f32 v228, v18, v2
	ds_write_b16 v207, v228 offset:288
	ds_write_b16_d16_hi v207, v228 offset:352
	v_cvt_pk_bf16_f32 v229, v19, v3
	ds_write_b16 v207, v229 offset:432
	ds_write_b16_d16_hi v207, v229 offset:496
	v_cvt_pk_bf16_f32 v226, v20, v4
	ds_write_b16 v207, v226 offset:1152
	ds_write_b16_d16_hi v207, v226 offset:1216
	v_cvt_pk_bf16_f32 v227, v21, v5
	ds_write_b16 v207, v227 offset:1296
	ds_write_b16_d16_hi v207, v227 offset:1360
	v_cvt_pk_bf16_f32 v228, v22, v6
	ds_write_b16 v207, v228 offset:1440
	ds_write_b16_d16_hi v207, v228 offset:1504
	v_cvt_pk_bf16_f32 v229, v23, v7
	ds_write_b16 v207, v229 offset:1584
	ds_write_b16_d16_hi v207, v229 offset:1648
	v_cvt_pk_bf16_f32 v226, v24, v8
	ds_write_b16 v207, v226 offset:2304
	ds_write_b16_d16_hi v207, v226 offset:2368
	v_cvt_pk_bf16_f32 v227, v25, v9
	ds_write_b16 v207, v227 offset:2448
	ds_write_b16_d16_hi v207, v227 offset:2512
	v_cvt_pk_bf16_f32 v228, v26, v10
	ds_write_b16 v207, v228 offset:2592
	ds_write_b16_d16_hi v207, v228 offset:2656
	v_cvt_pk_bf16_f32 v229, v27, v11
	ds_write_b16 v207, v229 offset:2736
	ds_write_b16_d16_hi v207, v229 offset:2800
	v_cvt_pk_bf16_f32 v226, v28, v12
	ds_write_b16 v207, v226 offset:3456
	ds_write_b16_d16_hi v207, v226 offset:3520
	v_cvt_pk_bf16_f32 v227, v29, v13
	ds_write_b16 v207, v227 offset:3600
	ds_write_b16_d16_hi v207, v227 offset:3664
	v_cvt_pk_bf16_f32 v228, v30, v14
	ds_write_b16 v207, v228 offset:3744
	ds_write_b16_d16_hi v207, v228 offset:3808
	v_cvt_pk_bf16_f32 v229, v31, v15
	ds_write_b16 v207, v229 offset:3888
	ds_write_b16_d16_hi v207, v229 offset:3952
	s_branch .Lep2_11_st
.Lep2_11_mR:
	s_load_dwordx2 s[98:99], s[0:1], 0x148
	v_add_u32_e32 v226, s94, v209
	v_lshlrev_b32_e32 v226, 8, v226
	v_add_u32_e32 v232, v226, v160
	v_mov_b32_e32 v233, 0
	s_waitcnt lgkmcnt(0)
	v_lshl_add_u64 v[232:233], s[98:99], 0, v[232:233]
	global_load_dwordx2 v[128:129], v[232:233], off
	global_load_dwordx2 v[130:131], v[232:233], off offset:256
	global_load_dwordx2 v[132:133], v[232:233], off offset:512
	global_load_dwordx2 v[134:135], v[232:233], off offset:768
	global_load_dwordx2 v[136:137], v[232:233], off offset:2048
	global_load_dwordx2 v[138:139], v[232:233], off offset:2304
	global_load_dwordx2 v[140:141], v[232:233], off offset:2560
	global_load_dwordx2 v[142:143], v[232:233], off offset:2816
	v_add_co_u32_e32 v234, vcc, 0x1000, v232
	s_nop 1
	v_addc_co_u32_e32 v235, vcc, 0, v233, vcc
	global_load_dwordx2 v[144:145], v[234:235], off
	global_load_dwordx2 v[146:147], v[234:235], off offset:256
	global_load_dwordx2 v[148:149], v[234:235], off offset:512
	global_load_dwordx2 v[150:151], v[234:235], off offset:768
	global_load_dwordx2 v[152:153], v[234:235], off offset:2048
	global_load_dwordx2 v[154:155], v[234:235], off offset:2304
	global_load_dwordx2 v[156:157], v[234:235], off offset:2560
	global_load_dwordx2 v[158:159], v[234:235], off offset:2816
	s_waitcnt vmcnt(15)
	v_mul_f32_e32 v226, v0, v129
	v_mul_f32_e32 v227, v16, v129
	v_fma_f32 v226, v16, v128, -v226
	v_fma_f32 v227, v0, v128, v227
	v_mul_f32_e32 v226, s88, v226
	v_mul_f32_e32 v227, s88, v227
	v_cvt_pk_bf16_f32 v226, v226, v227
	ds_write_b16 v207, v226
	ds_write_b16_d16_hi v207, v226 offset:64
	s_waitcnt vmcnt(14)
	v_mul_f32_e32 v226, v1, v131
	v_mul_f32_e32 v227, v17, v131
	v_fma_f32 v226, v17, v130, -v226
	v_fma_f32 v227, v1, v130, v227
	v_mul_f32_e32 v226, s88, v226
	v_mul_f32_e32 v227, s88, v227
	v_cvt_pk_bf16_f32 v226, v226, v227
	ds_write_b16 v207, v226 offset:144
	ds_write_b16_d16_hi v207, v226 offset:208
	s_waitcnt vmcnt(13)
	v_mul_f32_e32 v226, v2, v133
	v_mul_f32_e32 v227, v18, v133
	v_fma_f32 v226, v18, v132, -v226
	v_fma_f32 v227, v2, v132, v227
	v_mul_f32_e32 v226, s88, v226
	v_mul_f32_e32 v227, s88, v227
	v_cvt_pk_bf16_f32 v226, v226, v227
	ds_write_b16 v207, v226 offset:288
	ds_write_b16_d16_hi v207, v226 offset:352
	s_waitcnt vmcnt(12)
	v_mul_f32_e32 v226, v3, v135
	v_mul_f32_e32 v227, v19, v135
	v_fma_f32 v226, v19, v134, -v226
	v_fma_f32 v227, v3, v134, v227
	v_mul_f32_e32 v226, s88, v226
	v_mul_f32_e32 v227, s88, v227
	v_cvt_pk_bf16_f32 v226, v226, v227
	ds_write_b16 v207, v226 offset:432
	ds_write_b16_d16_hi v207, v226 offset:496
	s_waitcnt vmcnt(11)
	v_mul_f32_e32 v226, v4, v137
	v_mul_f32_e32 v227, v20, v137
	v_fma_f32 v226, v20, v136, -v226
	v_fma_f32 v227, v4, v136, v227
	v_mul_f32_e32 v226, s88, v226
	v_mul_f32_e32 v227, s88, v227
	v_cvt_pk_bf16_f32 v226, v226, v227
	ds_write_b16 v207, v226 offset:1152
	ds_write_b16_d16_hi v207, v226 offset:1216
	s_waitcnt vmcnt(10)
	v_mul_f32_e32 v226, v5, v139
	v_mul_f32_e32 v227, v21, v139
	v_fma_f32 v226, v21, v138, -v226
	v_fma_f32 v227, v5, v138, v227
	v_mul_f32_e32 v226, s88, v226
	v_mul_f32_e32 v227, s88, v227
	v_cvt_pk_bf16_f32 v226, v226, v227
	ds_write_b16 v207, v226 offset:1296
	ds_write_b16_d16_hi v207, v226 offset:1360
	s_waitcnt vmcnt(9)
	v_mul_f32_e32 v226, v6, v141
	v_mul_f32_e32 v227, v22, v141
	v_fma_f32 v226, v22, v140, -v226
	v_fma_f32 v227, v6, v140, v227
	v_mul_f32_e32 v226, s88, v226
	v_mul_f32_e32 v227, s88, v227
	v_cvt_pk_bf16_f32 v226, v226, v227
	ds_write_b16 v207, v226 offset:1440
	ds_write_b16_d16_hi v207, v226 offset:1504
	s_waitcnt vmcnt(8)
	v_mul_f32_e32 v226, v7, v143
	v_mul_f32_e32 v227, v23, v143
	v_fma_f32 v226, v23, v142, -v226
	v_fma_f32 v227, v7, v142, v227
	v_mul_f32_e32 v226, s88, v226
	v_mul_f32_e32 v227, s88, v227
	v_cvt_pk_bf16_f32 v226, v226, v227
	ds_write_b16 v207, v226 offset:1584
	ds_write_b16_d16_hi v207, v226 offset:1648
	s_waitcnt vmcnt(7)
	v_mul_f32_e32 v226, v8, v145
	v_mul_f32_e32 v227, v24, v145
	v_fma_f32 v226, v24, v144, -v226
	v_fma_f32 v227, v8, v144, v227
	v_mul_f32_e32 v226, s88, v226
	v_mul_f32_e32 v227, s88, v227
	v_cvt_pk_bf16_f32 v226, v226, v227
	ds_write_b16 v207, v226 offset:2304
	ds_write_b16_d16_hi v207, v226 offset:2368
	s_waitcnt vmcnt(6)
	v_mul_f32_e32 v226, v9, v147
	v_mul_f32_e32 v227, v25, v147
	v_fma_f32 v226, v25, v146, -v226
	v_fma_f32 v227, v9, v146, v227
	v_mul_f32_e32 v226, s88, v226
	v_mul_f32_e32 v227, s88, v227
	v_cvt_pk_bf16_f32 v226, v226, v227
	ds_write_b16 v207, v226 offset:2448
	ds_write_b16_d16_hi v207, v226 offset:2512
	s_waitcnt vmcnt(5)
	v_mul_f32_e32 v226, v10, v149
	v_mul_f32_e32 v227, v26, v149
	v_fma_f32 v226, v26, v148, -v226
	v_fma_f32 v227, v10, v148, v227
	v_mul_f32_e32 v226, s88, v226
	v_mul_f32_e32 v227, s88, v227
	v_cvt_pk_bf16_f32 v226, v226, v227
	ds_write_b16 v207, v226 offset:2592
	ds_write_b16_d16_hi v207, v226 offset:2656
	s_waitcnt vmcnt(4)
	v_mul_f32_e32 v226, v11, v151
	v_mul_f32_e32 v227, v27, v151
	v_fma_f32 v226, v27, v150, -v226
	v_fma_f32 v227, v11, v150, v227
	v_mul_f32_e32 v226, s88, v226
	v_mul_f32_e32 v227, s88, v227
	v_cvt_pk_bf16_f32 v226, v226, v227
	ds_write_b16 v207, v226 offset:2736
	ds_write_b16_d16_hi v207, v226 offset:2800
	s_waitcnt vmcnt(3)
	v_mul_f32_e32 v226, v12, v153
	v_mul_f32_e32 v227, v28, v153
	v_fma_f32 v226, v28, v152, -v226
	v_fma_f32 v227, v12, v152, v227
	v_mul_f32_e32 v226, s88, v226
	v_mul_f32_e32 v227, s88, v227
	v_cvt_pk_bf16_f32 v226, v226, v227
	ds_write_b16 v207, v226 offset:3456
	ds_write_b16_d16_hi v207, v226 offset:3520
	s_waitcnt vmcnt(2)
	v_mul_f32_e32 v226, v13, v155
	v_mul_f32_e32 v227, v29, v155
	v_fma_f32 v226, v29, v154, -v226
	v_fma_f32 v227, v13, v154, v227
	v_mul_f32_e32 v226, s88, v226
	v_mul_f32_e32 v227, s88, v227
	v_cvt_pk_bf16_f32 v226, v226, v227
	ds_write_b16 v207, v226 offset:3600
	ds_write_b16_d16_hi v207, v226 offset:3664
	s_waitcnt vmcnt(1)
	v_mul_f32_e32 v226, v14, v157
	v_mul_f32_e32 v227, v30, v157
	v_fma_f32 v226, v30, v156, -v226
	v_fma_f32 v227, v14, v156, v227
	v_mul_f32_e32 v226, s88, v226
	v_mul_f32_e32 v227, s88, v227
	v_cvt_pk_bf16_f32 v226, v226, v227
	ds_write_b16 v207, v226 offset:3744
	ds_write_b16_d16_hi v207, v226 offset:3808
	s_waitcnt vmcnt(0)
	v_mul_f32_e32 v226, v15, v159
	v_mul_f32_e32 v227, v31, v159
	v_fma_f32 v226, v31, v158, -v226
	v_fma_f32 v227, v15, v158, v227
	v_mul_f32_e32 v226, s88, v226
	v_mul_f32_e32 v227, s88, v227
	v_cvt_pk_bf16_f32 v226, v226, v227
	ds_write_b16 v207, v226 offset:3888
	ds_write_b16_d16_hi v207, v226 offset:3952
	s_branch .Lep2_11_st
.Lep2_11_mS:
	v_mul_f32_e32 v226, 0xbfb8aa3b, v16
	v_mul_f32_e32 v227, 0xbfb8aa3b, v0
	v_exp_f32_e32 v226, v226
	v_exp_f32_e32 v227, v227
	v_add_f32_e32 v226, 1.0, v226
	v_add_f32_e32 v227, 1.0, v227
	v_rcp_f32_e32 v226, v226
	v_rcp_f32_e32 v227, v227
	v_mul_f32_e32 v226, v16, v226
	v_mul_f32_e32 v227, v0, v227
	v_cvt_pk_bf16_f32 v226, v226, v227
	ds_write_b16 v207, v226
	ds_write_b16_d16_hi v207, v226 offset:64
	v_mul_f32_e32 v228, 0xbfb8aa3b, v17
	v_mul_f32_e32 v229, 0xbfb8aa3b, v1
	v_exp_f32_e32 v228, v228
	v_exp_f32_e32 v229, v229
	v_add_f32_e32 v228, 1.0, v228
	v_add_f32_e32 v229, 1.0, v229
	v_rcp_f32_e32 v228, v228
	v_rcp_f32_e32 v229, v229
	v_mul_f32_e32 v228, v17, v228
	v_mul_f32_e32 v229, v1, v229
	v_cvt_pk_bf16_f32 v228, v228, v229
	ds_write_b16 v207, v228 offset:144
	ds_write_b16_d16_hi v207, v228 offset:208
	v_mul_f32_e32 v226, 0xbfb8aa3b, v18
	v_mul_f32_e32 v227, 0xbfb8aa3b, v2
	v_exp_f32_e32 v226, v226
	v_exp_f32_e32 v227, v227
	v_add_f32_e32 v226, 1.0, v226
	v_add_f32_e32 v227, 1.0, v227
	v_rcp_f32_e32 v226, v226
	v_rcp_f32_e32 v227, v227
	v_mul_f32_e32 v226, v18, v226
	v_mul_f32_e32 v227, v2, v227
	v_cvt_pk_bf16_f32 v226, v226, v227
	ds_write_b16 v207, v226 offset:288
	ds_write_b16_d16_hi v207, v226 offset:352
	v_mul_f32_e32 v228, 0xbfb8aa3b, v19
	v_mul_f32_e32 v229, 0xbfb8aa3b, v3
	v_exp_f32_e32 v228, v228
	v_exp_f32_e32 v229, v229
	v_add_f32_e32 v228, 1.0, v228
	v_add_f32_e32 v229, 1.0, v229
	v_rcp_f32_e32 v228, v228
	v_rcp_f32_e32 v229, v229
	v_mul_f32_e32 v228, v19, v228
	v_mul_f32_e32 v229, v3, v229
	v_cvt_pk_bf16_f32 v228, v228, v229
	ds_write_b16 v207, v228 offset:432
	ds_write_b16_d16_hi v207, v228 offset:496
	v_mul_f32_e32 v226, 0xbfb8aa3b, v20
	v_mul_f32_e32 v227, 0xbfb8aa3b, v4
	v_exp_f32_e32 v226, v226
	v_exp_f32_e32 v227, v227
	v_add_f32_e32 v226, 1.0, v226
	v_add_f32_e32 v227, 1.0, v227
	v_rcp_f32_e32 v226, v226
	v_rcp_f32_e32 v227, v227
	v_mul_f32_e32 v226, v20, v226
	v_mul_f32_e32 v227, v4, v227
	v_cvt_pk_bf16_f32 v226, v226, v227
	ds_write_b16 v207, v226 offset:1152
	ds_write_b16_d16_hi v207, v226 offset:1216
	v_mul_f32_e32 v228, 0xbfb8aa3b, v21
	v_mul_f32_e32 v229, 0xbfb8aa3b, v5
	v_exp_f32_e32 v228, v228
	v_exp_f32_e32 v229, v229
	v_add_f32_e32 v228, 1.0, v228
	v_add_f32_e32 v229, 1.0, v229
	v_rcp_f32_e32 v228, v228
	v_rcp_f32_e32 v229, v229
	v_mul_f32_e32 v228, v21, v228
	v_mul_f32_e32 v229, v5, v229
	v_cvt_pk_bf16_f32 v228, v228, v229
	ds_write_b16 v207, v228 offset:1296
	ds_write_b16_d16_hi v207, v228 offset:1360
	v_mul_f32_e32 v226, 0xbfb8aa3b, v22
	v_mul_f32_e32 v227, 0xbfb8aa3b, v6
	v_exp_f32_e32 v226, v226
	v_exp_f32_e32 v227, v227
	v_add_f32_e32 v226, 1.0, v226
	v_add_f32_e32 v227, 1.0, v227
	v_rcp_f32_e32 v226, v226
	v_rcp_f32_e32 v227, v227
	v_mul_f32_e32 v226, v22, v226
	v_mul_f32_e32 v227, v6, v227
	v_cvt_pk_bf16_f32 v226, v226, v227
	ds_write_b16 v207, v226 offset:1440
	ds_write_b16_d16_hi v207, v226 offset:1504
	v_mul_f32_e32 v228, 0xbfb8aa3b, v23
	v_mul_f32_e32 v229, 0xbfb8aa3b, v7
	v_exp_f32_e32 v228, v228
	v_exp_f32_e32 v229, v229
	v_add_f32_e32 v228, 1.0, v228
	v_add_f32_e32 v229, 1.0, v229
	v_rcp_f32_e32 v228, v228
	v_rcp_f32_e32 v229, v229
	v_mul_f32_e32 v228, v23, v228
	v_mul_f32_e32 v229, v7, v229
	v_cvt_pk_bf16_f32 v228, v228, v229
	ds_write_b16 v207, v228 offset:1584
	ds_write_b16_d16_hi v207, v228 offset:1648
	v_mul_f32_e32 v226, 0xbfb8aa3b, v24
	v_mul_f32_e32 v227, 0xbfb8aa3b, v8
	v_exp_f32_e32 v226, v226
	v_exp_f32_e32 v227, v227
	v_add_f32_e32 v226, 1.0, v226
	v_add_f32_e32 v227, 1.0, v227
	v_rcp_f32_e32 v226, v226
	v_rcp_f32_e32 v227, v227
	v_mul_f32_e32 v226, v24, v226
	v_mul_f32_e32 v227, v8, v227
	v_cvt_pk_bf16_f32 v226, v226, v227
	ds_write_b16 v207, v226 offset:2304
	ds_write_b16_d16_hi v207, v226 offset:2368
	v_mul_f32_e32 v228, 0xbfb8aa3b, v25
	v_mul_f32_e32 v229, 0xbfb8aa3b, v9
	v_exp_f32_e32 v228, v228
	v_exp_f32_e32 v229, v229
	v_add_f32_e32 v228, 1.0, v228
	v_add_f32_e32 v229, 1.0, v229
	v_rcp_f32_e32 v228, v228
	v_rcp_f32_e32 v229, v229
	v_mul_f32_e32 v228, v25, v228
	v_mul_f32_e32 v229, v9, v229
	v_cvt_pk_bf16_f32 v228, v228, v229
	ds_write_b16 v207, v228 offset:2448
	ds_write_b16_d16_hi v207, v228 offset:2512
	v_mul_f32_e32 v226, 0xbfb8aa3b, v26
	v_mul_f32_e32 v227, 0xbfb8aa3b, v10
	v_exp_f32_e32 v226, v226
	v_exp_f32_e32 v227, v227
	v_add_f32_e32 v226, 1.0, v226
	v_add_f32_e32 v227, 1.0, v227
	v_rcp_f32_e32 v226, v226
	v_rcp_f32_e32 v227, v227
	v_mul_f32_e32 v226, v26, v226
	v_mul_f32_e32 v227, v10, v227
	v_cvt_pk_bf16_f32 v226, v226, v227
	ds_write_b16 v207, v226 offset:2592
	ds_write_b16_d16_hi v207, v226 offset:2656
	v_mul_f32_e32 v228, 0xbfb8aa3b, v27
	v_mul_f32_e32 v229, 0xbfb8aa3b, v11
	v_exp_f32_e32 v228, v228
	v_exp_f32_e32 v229, v229
	v_add_f32_e32 v228, 1.0, v228
	v_add_f32_e32 v229, 1.0, v229
	v_rcp_f32_e32 v228, v228
	v_rcp_f32_e32 v229, v229
	v_mul_f32_e32 v228, v27, v228
	v_mul_f32_e32 v229, v11, v229
	v_cvt_pk_bf16_f32 v228, v228, v229
	ds_write_b16 v207, v228 offset:2736
	ds_write_b16_d16_hi v207, v228 offset:2800
	v_mul_f32_e32 v226, 0xbfb8aa3b, v28
	v_mul_f32_e32 v227, 0xbfb8aa3b, v12
	v_exp_f32_e32 v226, v226
	v_exp_f32_e32 v227, v227
	v_add_f32_e32 v226, 1.0, v226
	v_add_f32_e32 v227, 1.0, v227
	v_rcp_f32_e32 v226, v226
	v_rcp_f32_e32 v227, v227
	v_mul_f32_e32 v226, v28, v226
	v_mul_f32_e32 v227, v12, v227
	v_cvt_pk_bf16_f32 v226, v226, v227
	ds_write_b16 v207, v226 offset:3456
	ds_write_b16_d16_hi v207, v226 offset:3520
	v_mul_f32_e32 v228, 0xbfb8aa3b, v29
	v_mul_f32_e32 v229, 0xbfb8aa3b, v13
	v_exp_f32_e32 v228, v228
	v_exp_f32_e32 v229, v229
	v_add_f32_e32 v228, 1.0, v228
	v_add_f32_e32 v229, 1.0, v229
	v_rcp_f32_e32 v228, v228
	v_rcp_f32_e32 v229, v229
	v_mul_f32_e32 v228, v29, v228
	v_mul_f32_e32 v229, v13, v229
	v_cvt_pk_bf16_f32 v228, v228, v229
	ds_write_b16 v207, v228 offset:3600
	ds_write_b16_d16_hi v207, v228 offset:3664
	v_mul_f32_e32 v226, 0xbfb8aa3b, v30
	v_mul_f32_e32 v227, 0xbfb8aa3b, v14
	v_exp_f32_e32 v226, v226
	v_exp_f32_e32 v227, v227
	v_add_f32_e32 v226, 1.0, v226
	v_add_f32_e32 v227, 1.0, v227
	v_rcp_f32_e32 v226, v226
	v_rcp_f32_e32 v227, v227
	v_mul_f32_e32 v226, v30, v226
	v_mul_f32_e32 v227, v14, v227
	v_cvt_pk_bf16_f32 v226, v226, v227
	ds_write_b16 v207, v226 offset:3744
	ds_write_b16_d16_hi v207, v226 offset:3808
	v_mul_f32_e32 v228, 0xbfb8aa3b, v31
	v_mul_f32_e32 v229, 0xbfb8aa3b, v15
	v_exp_f32_e32 v228, v228
	v_exp_f32_e32 v229, v229
	v_add_f32_e32 v228, 1.0, v228
	v_add_f32_e32 v229, 1.0, v229
	v_rcp_f32_e32 v228, v228
	v_rcp_f32_e32 v229, v229
	v_mul_f32_e32 v228, v31, v228
	v_mul_f32_e32 v229, v15, v229
	v_cvt_pk_bf16_f32 v228, v228, v229
	ds_write_b16 v207, v228 offset:3888
	ds_write_b16_d16_hi v207, v228 offset:3952
	s_branch .Lep2_11_st

.LBB0_2219:
	s_ashr_i32 s2, s54, 31
	s_lshr_b32 s2, s2, 30
	s_add_i32 s2, s54, s2
	s_ashr_i32 s2, s2, 2
	s_lshl_b32 s4, s2, 8
	v_add_u32_e32 v0, s4, v212
	v_min_i32_e32 v0, 0x7fff, v0
	v_ashrrev_i32_e32 v1, 31, v0
	s_lshl_b32 s6, s2, 10
	v_lshlrev_b64 v[0:1], 11, v[0:1]
	v_lshl_add_u64 v[160:161], v[176:177], 0, v[0:1]
	v_subrev_u32_e32 v0, s6, v220
	v_ashrrev_i32_e32 v1, 31, v0
	v_lshlrev_b64 v[0:1], 11, v[0:1]
	v_lshl_add_u64 v[180:181], v[178:179], 0, v[0:1]
	v_subrev_u32_e32 v0, s6, v221
	v_ashrrev_i32_e32 v1, 31, v0
	v_lshlrev_b64 v[0:1], 11, v[0:1]
	v_lshl_add_u64 v[182:183], v[178:179], 0, v[0:1]
	v_subrev_u32_e32 v0, s6, v222
	v_ashrrev_i32_e32 v1, 31, v0
	v_add_u32_e32 v2, s4, v213
	v_add_u32_e32 v4, s4, v171
	v_add_u32_e32 v6, s4, v215
	v_lshlrev_b64 v[0:1], 11, v[0:1]
	v_min_i32_e32 v2, 0x7fff, v2
	v_min_i32_e32 v4, 0x7fff, v4
	v_min_i32_e32 v6, 0x7fff, v6
	v_lshl_add_u64 v[184:185], v[178:179], 0, v[0:1]
	v_subrev_u32_e32 v0, s6, v223
	v_ashrrev_i32_e32 v3, 31, v2
	v_ashrrev_i32_e32 v5, 31, v4
	v_ashrrev_i32_e32 v7, 31, v6
	v_ashrrev_i32_e32 v1, 31, v0
	v_lshlrev_b64 v[2:3], 11, v[2:3]
	v_lshlrev_b64 v[4:5], 11, v[4:5]
	v_lshlrev_b64 v[6:7], 11, v[6:7]
	v_lshlrev_b64 v[0:1], 11, v[0:1]
	s_mov_b32 s5, s54
	v_lshl_add_u64 v[162:163], v[176:177], 0, v[2:3]
	v_lshl_add_u64 v[164:165], v[176:177], 0, v[4:5]
	v_lshl_add_u64 v[166:167], v[176:177], 0, v[6:7]
	v_lshl_add_u64 v[186:187], v[178:179], 0, v[0:1]
	s_mov_b64 s[2:3], 0
	s_mov_b32 s7, 0
	v_mov_b32_e32 v0, 0
	v_mov_b32_e32 v1, v169
	v_mov_b32_e32 v2, v169
	v_mov_b32_e32 v3, v169
	v_mov_b32_e32 v4, v169
	v_mov_b32_e32 v5, v169
	v_mov_b32_e32 v6, v169
	v_mov_b32_e32 v7, v169
	v_mov_b32_e32 v8, v169
	v_mov_b32_e32 v9, v169
	v_mov_b32_e32 v10, v169
	v_mov_b32_e32 v11, v169
	v_mov_b32_e32 v12, v169
	v_mov_b32_e32 v13, v169
	v_mov_b32_e32 v14, v169
	v_mov_b32_e32 v15, v169
	v_mov_b32_e32 v16, 0
	v_mov_b32_e32 v17, v169
	v_mov_b32_e32 v18, v169
	v_mov_b32_e32 v19, v169
	v_mov_b32_e32 v20, v169
	v_mov_b32_e32 v21, v169
	v_mov_b32_e32 v22, v169
	v_mov_b32_e32 v23, v169
	v_mov_b32_e32 v24, v169
	v_mov_b32_e32 v25, v169
	v_mov_b32_e32 v26, v169
	v_mov_b32_e32 v27, v169
	v_mov_b32_e32 v28, v169
	v_mov_b32_e32 v29, v169
	v_mov_b32_e32 v30, v169
	v_mov_b32_e32 v31, v169
	v_mov_b32_e32 v32, 0
	v_mov_b32_e32 v33, v169
	v_mov_b32_e32 v34, v169
	v_mov_b32_e32 v35, v169
	v_mov_b32_e32 v36, v169
	v_mov_b32_e32 v37, v169
	v_mov_b32_e32 v38, v169
	v_mov_b32_e32 v39, v169
	v_mov_b32_e32 v40, v169
	v_mov_b32_e32 v41, v169
	v_mov_b32_e32 v42, v169
	v_mov_b32_e32 v43, v169
	v_mov_b32_e32 v44, v169
	v_mov_b32_e32 v45, v169
	v_mov_b32_e32 v46, v169
	v_mov_b32_e32 v47, v169
	v_mov_b32_e32 v48, 0
	v_mov_b32_e32 v49, v169
	v_mov_b32_e32 v50, v169
	v_mov_b32_e32 v51, v169
	v_mov_b32_e32 v52, v169
	v_mov_b32_e32 v53, v169
	v_mov_b32_e32 v54, v169
	v_mov_b32_e32 v55, v169
	v_mov_b32_e32 v56, v169
	v_mov_b32_e32 v57, v169
	v_mov_b32_e32 v58, v169
	v_mov_b32_e32 v59, v169
	v_mov_b32_e32 v60, v169
	v_mov_b32_e32 v61, v169
	v_mov_b32_e32 v62, v169
	v_mov_b32_e32 v63, v169
	v_mov_b32_e32 v64, 0
	v_mov_b32_e32 v65, v169
	v_mov_b32_e32 v66, v169
	v_mov_b32_e32 v67, v169
	v_mov_b32_e32 v68, v169
	v_mov_b32_e32 v69, v169
	v_mov_b32_e32 v70, v169
	v_mov_b32_e32 v71, v169
	v_mov_b32_e32 v72, v169
	v_mov_b32_e32 v73, v169
	v_mov_b32_e32 v74, v169
	v_mov_b32_e32 v75, v169
	v_mov_b32_e32 v76, v169
	v_mov_b32_e32 v77, v169
	v_mov_b32_e32 v78, v169
	v_mov_b32_e32 v79, v169
	v_mov_b32_e32 v80, 0
	v_mov_b32_e32 v81, v169
	v_mov_b32_e32 v82, v169
	v_mov_b32_e32 v83, v169
	v_mov_b32_e32 v84, v169
	v_mov_b32_e32 v85, v169
	v_mov_b32_e32 v86, v169
	v_mov_b32_e32 v87, v169
	v_mov_b32_e32 v88, v169
	v_mov_b32_e32 v89, v169
	v_mov_b32_e32 v90, v169
	v_mov_b32_e32 v91, v169
	v_mov_b32_e32 v92, v169
	v_mov_b32_e32 v93, v169
	v_mov_b32_e32 v94, v169
	v_mov_b32_e32 v95, v169
	v_mov_b32_e32 v96, 0
	v_mov_b32_e32 v97, v169
	v_mov_b32_e32 v98, v169
	v_mov_b32_e32 v99, v169
	v_mov_b32_e32 v100, v169
	v_mov_b32_e32 v101, v169
	v_mov_b32_e32 v102, v169
	v_mov_b32_e32 v103, v169
	v_mov_b32_e32 v104, v169
	v_mov_b32_e32 v105, v169
	v_mov_b32_e32 v106, v169
	v_mov_b32_e32 v107, v169
	v_mov_b32_e32 v108, v169
	v_mov_b32_e32 v109, v169
	v_mov_b32_e32 v110, v169
	v_mov_b32_e32 v111, v169
	v_mov_b32_e32 v112, 0
	v_mov_b32_e32 v113, v169
	v_mov_b32_e32 v114, v169
	v_mov_b32_e32 v115, v169
	v_mov_b32_e32 v116, v169
	v_mov_b32_e32 v117, v169
	v_mov_b32_e32 v118, v169
	v_mov_b32_e32 v119, v169
	v_mov_b32_e32 v120, v169
	v_mov_b32_e32 v121, v169
	v_mov_b32_e32 v122, v169
	v_mov_b32_e32 v123, v169
	v_mov_b32_e32 v124, v169
	v_mov_b32_e32 v125, v169
	v_mov_b32_e32 v126, v169
	v_mov_b32_e32 v127, v169
	v_mbcnt_hi_u32_b32 v128, -1, v210
	s_and_b32 s90, s70, 0x40
	v_and_b32_e32 v159, 48, v128
	v_or_b32_e32 v159, s90, v159
	v_and_b32_e32 v129, 31, v128
	v_lshrrev_b32_e32 v130, 5, v128
	v_bfe_u32 v131, v128, 1, 3
	v_lshlrev_b32_e32 v132, 7, v129
	s_lshr_b32 s91, s70, 7
	s_lshl_b32 s91, s91, 13
	s_lshl_b32 s90, s90, 8
	s_add_u32 s90, s90, 0x8000
	s_lshl_b32 s88, s70, 4
	s_mov_b32 s89, 0x10000
	s_lshl_b32 s92, s22, 4
	s_and_b32 s92, s92, 0x780
	s_mov_b32 s93, 0
	s_load_dwordx2 s[96:97], s[0:1], 0x158
	s_load_dwordx2 s[98:99], s[0:1], 0x108
	s_waitcnt lgkmcnt(0)
	v_subrev_u32_e32 v152, s96, v160
	v_xor_b32_e32 v152, v159, v152
	v_subrev_u32_e32 v153, s98, v180
	v_xor_b32_e32 v153, v159, v153
	v_subrev_u32_e32 v154, s96, v162
	v_xor_b32_e32 v154, v159, v154
	v_subrev_u32_e32 v155, s98, v182
	v_xor_b32_e32 v155, v159, v155
	v_subrev_u32_e32 v156, s96, v164
	v_xor_b32_e32 v156, v159, v156
	v_subrev_u32_e32 v157, s98, v184
	v_xor_b32_e32 v157, v159, v157
	v_subrev_u32_e32 v158, s96, v166
	v_xor_b32_e32 v158, v159, v158
	v_subrev_u32_e32 v168, s98, v186
	v_xor_b32_e32 v168, v159, v168
	v_xor_b32_e32 v133, v130, v131
	v_lshl_add_u32 v133, v133, 4, v132
	v_add_u32_e32 v230, s91, v133
	v_add_u32_e32 v234, s90, v133
	v_add_u32_e32 v208, 0x10000, v230
	v_add_u32_e32 v241, 0x10000, v234
	v_or_b32_e32 v133, 2, v130
	v_xor_b32_e32 v133, v133, v131
	v_lshl_add_u32 v133, v133, 4, v132
	v_add_u32_e32 v231, s91, v133
	v_add_u32_e32 v235, s90, v133
	v_add_u32_e32 v238, 0x10000, v231
	v_add_u32_e32 v253, 0x10000, v235
	v_or_b32_e32 v133, 4, v130
	v_xor_b32_e32 v133, v133, v131
	v_lshl_add_u32 v133, v133, 4, v132
	v_add_u32_e32 v232, s91, v133
	v_add_u32_e32 v236, s90, v133
	v_add_u32_e32 v239, 0x10000, v232
	v_add_u32_e32 v254, 0x10000, v236
	v_or_b32_e32 v133, 6, v130
	v_xor_b32_e32 v133, v133, v131
	v_lshl_add_u32 v133, v133, 4, v132
	v_add_u32_e32 v233, s91, v133
	v_add_u32_e32 v237, s90, v133
	v_add_u32_e32 v240, 0x10000, v233
	v_add_u32_e32 v255, 0x10000, v237
	s_barrier
	ds_read_b128 v[188:191], v230
	ds_read_b128 v[196:199], v234
	ds_read_b128 v[192:195], v230 offset:4096
	ds_read_b128 v[200:203], v234 offset:4096
	ds_read_b128 v[204:207], v234 offset:8192
	ds_read_b128 v[226:229], v234 offset:12288
	s_add_u32 s94, s2, s92
	s_add_u32 s94, s94, 0x80
	s_and_b32 s94, s94, 0x780
	s_sub_u32 s94, s94, 0x80
	s_subb_u32 s95, 0, 0
	s_add_u32 s100, s96, s94
	s_addc_u32 s101, s97, s95
	s_add_u32 s94, s98, s94
	s_addc_u32 s95, s99, s95
	s_add_u32 s90, s88, s89
	s_add_u32 m0, s90, 0
	s_nop 0
	global_load_lds_dwordx4 v152, s[100:101]
	s_add_u32 m0, s90, 32768
	s_nop 0
	global_load_lds_dwordx4 v153, s[94:95]
	s_add_u32 m0, s90, 8192
	s_nop 0
	global_load_lds_dwordx4 v154, s[100:101]
	s_add_u32 m0, s90, 40960
	s_nop 0
	global_load_lds_dwordx4 v155, s[94:95]
	s_add_u32 m0, s90, 16384
	s_nop 0
	global_load_lds_dwordx4 v156, s[100:101]
	s_add_u32 m0, s90, 49152
	s_nop 0
	global_load_lds_dwordx4 v157, s[94:95]
	s_add_u32 m0, s90, 24576
	s_nop 0
	global_load_lds_dwordx4 v158, s[100:101]
	s_add_u32 m0, s90, 57344
	s_nop 0
	global_load_lds_dwordx4 v168, s[94:95]
	s_xor_b32 s89, s89, 0x10000

.LBB0_2223:
	ds_read_b128 v[128:131], v238
	ds_read_b128 v[136:139], v253
	ds_read_b128 v[132:135], v238 offset:4096
	ds_read_b128 v[140:143], v253 offset:4096
	ds_read_b128 v[144:147], v253 offset:8192
	ds_read_b128 v[148:151], v253 offset:12288
	s_waitcnt lgkmcnt(6)
	v_mfma_f32_32x32x16_bf16 v[112:127], v[188:191], v[196:199], v[112:127]
	v_mfma_f32_32x32x16_bf16 v[48:63], v[192:195], v[196:199], v[48:63]
	v_mfma_f32_32x32x16_bf16 v[96:111], v[188:191], v[200:203], v[96:111]
	v_mfma_f32_32x32x16_bf16 v[32:47], v[192:195], v[200:203], v[32:47]
	v_mfma_f32_32x32x16_bf16 v[80:95], v[188:191], v[204:207], v[80:95]
	v_mfma_f32_32x32x16_bf16 v[16:31], v[192:195], v[204:207], v[16:31]
	v_mfma_f32_32x32x16_bf16 v[64:79], v[188:191], v[226:229], v[64:79]
	v_mfma_f32_32x32x16_bf16 v[0:15], v[192:195], v[226:229], v[0:15]
	ds_read_b128 v[188:191], v239
	ds_read_b128 v[196:199], v254
	ds_read_b128 v[192:195], v239 offset:4096
	ds_read_b128 v[200:203], v254 offset:4096
	ds_read_b128 v[204:207], v254 offset:8192
	ds_read_b128 v[226:229], v254 offset:12288
	s_waitcnt lgkmcnt(6)
	v_mfma_f32_32x32x16_bf16 v[112:127], v[128:131], v[136:139], v[112:127]
	v_mfma_f32_32x32x16_bf16 v[48:63], v[132:135], v[136:139], v[48:63]
	v_mfma_f32_32x32x16_bf16 v[96:111], v[128:131], v[140:143], v[96:111]
	v_mfma_f32_32x32x16_bf16 v[32:47], v[132:135], v[140:143], v[32:47]
	v_mfma_f32_32x32x16_bf16 v[80:95], v[128:131], v[144:147], v[80:95]
	v_mfma_f32_32x32x16_bf16 v[16:31], v[132:135], v[144:147], v[16:31]
	v_mfma_f32_32x32x16_bf16 v[64:79], v[128:131], v[148:151], v[64:79]
	v_mfma_f32_32x32x16_bf16 v[0:15], v[132:135], v[148:151], v[0:15]
	ds_read_b128 v[128:131], v240
	ds_read_b128 v[136:139], v255
	ds_read_b128 v[132:135], v240 offset:4096
	ds_read_b128 v[140:143], v255 offset:4096
	ds_read_b128 v[144:147], v255 offset:8192
	ds_read_b128 v[148:151], v255 offset:12288
	s_waitcnt lgkmcnt(6)
	v_mfma_f32_32x32x16_bf16 v[112:127], v[188:191], v[196:199], v[112:127]
	v_mfma_f32_32x32x16_bf16 v[48:63], v[192:195], v[196:199], v[48:63]
	v_mfma_f32_32x32x16_bf16 v[96:111], v[188:191], v[200:203], v[96:111]
	v_mfma_f32_32x32x16_bf16 v[32:47], v[192:195], v[200:203], v[32:47]
	v_mfma_f32_32x32x16_bf16 v[80:95], v[188:191], v[204:207], v[80:95]
	v_mfma_f32_32x32x16_bf16 v[16:31], v[192:195], v[204:207], v[16:31]
	v_mfma_f32_32x32x16_bf16 v[64:79], v[188:191], v[226:229], v[64:79]
	v_mfma_f32_32x32x16_bf16 v[0:15], v[192:195], v[226:229], v[0:15]
	s_waitcnt vmcnt(0) lgkmcnt(0)
	s_barrier
	v_mfma_f32_32x32x16_bf16 v[112:127], v[128:131], v[136:139], v[112:127]
	v_mfma_f32_32x32x16_bf16 v[48:63], v[132:135], v[136:139], v[48:63]
	v_mfma_f32_32x32x16_bf16 v[96:111], v[128:131], v[140:143], v[96:111]
	v_mfma_f32_32x32x16_bf16 v[32:47], v[132:135], v[140:143], v[32:47]
	v_mfma_f32_32x32x16_bf16 v[80:95], v[128:131], v[144:147], v[80:95]
	v_mfma_f32_32x32x16_bf16 v[16:31], v[132:135], v[144:147], v[16:31]
	v_mfma_f32_32x32x16_bf16 v[64:79], v[128:131], v[148:151], v[64:79]
	v_mfma_f32_32x32x16_bf16 v[0:15], v[132:135], v[148:151], v[0:15]
	s_lshl_b32 s2, s5, 8
	s_sub_i32 s2, s2, s6
	v_mov_b32_e32 v168, v214
	s_add_i32 s55, s4, s30
	s_or_b32 s26, s2, s31
	s_ashr_i32 s27, s26, 31
	s_load_dwordx2 s[24:25], s[0:1], 0x140
	v_ashrrev_i32_e32 v180, 3, v168
	v_and_b32_e32 v183, -4, v180
	v_add_u32_e32 v225, s55, v183
	v_add_u32_e32 v190, 8, v225
	v_min_i32_e32 v190, 0x7fff, v190
	v_ashrrev_i32_e32 v190, 12, v190
	v_add_u32_e32 v190, 8, v190
	v_mul_hi_i32_i24_e32 v191, 0x3000, v190
	v_mul_i32_i24_e32 v190, 0x3000, v190
	v_min_i32_e32 v184, 0x7fff, v225
	v_ashrrev_i32_e32 v184, 12, v184
	v_and_b32_e32 v182, 31, v168
	v_add_u32_e32 v184, 8, v184
	v_or_b32_e32 v180, s26, v182
	v_mul_hi_i32_i24_e32 v185, 0x3000, v184
	v_mul_i32_i24_e32 v184, 0x3000, v184
	v_ashrrev_i32_e32 v181, 31, v180
	s_waitcnt lgkmcnt(0)
	v_lshl_add_u64 v[184:185], s[24:25], 0, v[184:185]
	v_lshl_add_u64 v[184:185], v[184:185], 0, s[18:19]
	v_lshlrev_b64 v[180:181], 2, v[180:181]
	v_lshl_add_u64 v[196:197], v[184:185], 0, v[180:181]
	v_lshl_add_u64 v[186:187], s[24:25], 0, v[190:191]
	v_add_u32_e32 v188, 9, v225
	v_add_u32_e32 v190, 10, v225
	v_min_i32_e32 v188, 0x7fff, v188
	v_min_i32_e32 v190, 0x7fff, v190
	v_ashrrev_i32_e32 v188, 12, v188
	v_ashrrev_i32_e32 v190, 12, v190
	v_add_u32_e32 v188, 8, v188
	v_add_u32_e32 v190, 8, v190
	v_mul_hi_i32_i24_e32 v189, 0x3000, v188
	v_mul_i32_i24_e32 v188, 0x3000, v188
	v_mul_hi_i32_i24_e32 v191, 0x3000, v190
	v_mul_i32_i24_e32 v190, 0x3000, v190
	v_lshl_add_u64 v[188:189], s[24:25], 0, v[188:189]
	v_lshl_add_u64 v[190:191], s[24:25], 0, v[190:191]
	v_lshl_add_u64 v[186:187], v[186:187], 0, s[18:19]
	v_lshl_add_u64 v[188:189], v[188:189], 0, s[18:19]
	v_lshl_add_u64 v[190:191], v[190:191], 0, s[18:19]
	v_lshl_add_u64 v[206:207], v[186:187], 0, v[180:181]
	v_add_u32_e32 v208, 18, v225
	v_min_i32_e32 v208, 0x7fff, v208
	v_ashrrev_i32_e32 v208, 12, v208
	v_add_u32_e32 v208, 8, v208
	v_mul_hi_i32_i24_e32 v209, 0x3000, v208
	v_mul_i32_i24_e32 v208, 0x3000, v208
	v_lshl_add_u64 v[208:209], s[24:25], 0, v[208:209]
	v_lshl_add_u64 v[202:203], v[188:189], 0, v[180:181]
	v_lshl_add_u64 v[204:205], v[190:191], 0, v[180:181]
	global_load_dword v232, v[196:197], off
	global_load_dword v233, v[196:197], off offset:128
	global_load_dword v242, v[206:207], off
	global_load_dword v243, v[206:207], off offset:128
	global_load_dword v244, v[202:203], off
	global_load_dword v245, v[202:203], off offset:128
	global_load_dword v246, v[204:205], off
	global_load_dword v247, v[204:205], off offset:128
	v_add_u32_e32 v196, 17, v225
	v_min_i32_e32 v196, 0x7fff, v196
	v_ashrrev_i32_e32 v196, 12, v196
	v_add_u32_e32 v196, 8, v196
	v_mul_hi_i32_i24_e32 v197, 0x3000, v196
	v_mul_i32_i24_e32 v196, 0x3000, v196
	v_lshl_add_u64 v[196:197], s[24:25], 0, v[196:197]
	v_lshl_add_u64 v[196:197], v[196:197], 0, s[18:19]
	v_lshl_add_u64 v[206:207], v[196:197], 0, v[180:181]
	s_waitcnt vmcnt(7)
	s_nop 5
	v_mul_f32_e32 v112, v112, v232
	v_add_u32_e32 v192, 11, v225
	v_add_u32_e32 v194, 16, v225
	v_min_i32_e32 v192, 0x7fff, v192
	v_min_i32_e32 v194, 0x7fff, v194
	v_ashrrev_i32_e32 v192, 12, v192
	v_ashrrev_i32_e32 v194, 12, v194
	v_add_u32_e32 v192, 8, v192
	v_add_u32_e32 v194, 8, v194
	v_mul_hi_i32_i24_e32 v193, 0x3000, v192
	v_mul_i32_i24_e32 v192, 0x3000, v192
	v_mul_hi_i32_i24_e32 v195, 0x3000, v194
	v_mul_i32_i24_e32 v194, 0x3000, v194
	v_lshl_add_u64 v[192:193], s[24:25], 0, v[192:193]
	v_lshl_add_u64 v[194:195], s[24:25], 0, v[194:195]
	v_lshl_add_u64 v[192:193], v[192:193], 0, s[18:19]
	v_lshl_add_u64 v[194:195], v[194:195], 0, s[18:19]
	v_lshl_add_u64 v[202:203], v[192:193], 0, v[180:181]
	v_lshl_add_u64 v[204:205], v[194:195], 0, v[180:181]
	s_waitcnt vmcnt(6)
	s_nop 5
	v_mul_f32_e32 v96, v96, v233
	v_mul_f32_e32 v97, v97, v233
	v_lshl_add_u64 v[198:199], v[208:209], 0, s[18:19]
	v_lshl_add_u64 v[200:201], v[198:199], 0, v[180:181]
	global_load_dword v234, v[202:203], off
	global_load_dword v235, v[202:203], off offset:128
	global_load_dword v236, v[204:205], off
	global_load_dword v237, v[204:205], off offset:128
	global_load_dword v238, v[206:207], off
	global_load_dword v239, v[206:207], off offset:128
	global_load_dword v240, v[200:201], off
	global_load_dword v241, v[200:201], off offset:128
	v_add_u32_e32 v200, 19, v225
	v_add_u32_e32 v204, 25, v225
	v_add_u32_e32 v206, 26, v225
	v_min_i32_e32 v200, 0x7fff, v200
	v_add_u32_e32 v202, 24, v225
	v_min_i32_e32 v204, 0x7fff, v204
	v_min_i32_e32 v206, 0x7fff, v206
	v_ashrrev_i32_e32 v200, 12, v200
	v_min_i32_e32 v202, 0x7fff, v202
	v_ashrrev_i32_e32 v204, 12, v204
	v_ashrrev_i32_e32 v206, 12, v206
	v_add_u32_e32 v200, 8, v200
	v_ashrrev_i32_e32 v202, 12, v202
	v_add_u32_e32 v204, 8, v204
	v_add_u32_e32 v206, 8, v206
	v_mul_hi_i32_i24_e32 v201, 0x3000, v200
	v_mul_i32_i24_e32 v200, 0x3000, v200
	v_add_u32_e32 v202, 8, v202
	v_mul_hi_i32_i24_e32 v205, 0x3000, v204
	v_mul_i32_i24_e32 v204, 0x3000, v204
	v_mul_hi_i32_i24_e32 v207, 0x3000, v206
	v_mul_i32_i24_e32 v206, 0x3000, v206
	v_lshl_add_u64 v[200:201], s[24:25], 0, v[200:201]
	v_mul_hi_i32_i24_e32 v203, 0x3000, v202
	v_mul_i32_i24_e32 v202, 0x3000, v202
	v_lshl_add_u64 v[204:205], s[24:25], 0, v[204:205]
	v_lshl_add_u64 v[206:207], s[24:25], 0, v[206:207]
	v_lshl_add_u64 v[200:201], v[200:201], 0, s[18:19]
	v_lshl_add_u64 v[202:203], s[24:25], 0, v[202:203]
	v_lshl_add_u64 v[204:205], v[204:205], 0, s[18:19]
	v_lshl_add_u64 v[206:207], v[206:207], 0, s[18:19]
	v_lshl_add_u64 v[208:209], v[200:201], 0, v[180:181]
	v_lshl_add_u64 v[202:203], v[202:203], 0, s[18:19]
	v_lshl_add_u64 v[228:229], v[204:205], 0, v[180:181]
	v_lshl_add_u64 v[230:231], v[206:207], 0, v[180:181]
	v_lshl_add_u64 v[226:227], v[202:203], 0, v[180:181]
	global_load_dword v248, v[208:209], off
	global_load_dword v249, v[208:209], off offset:128
	global_load_dword v250, v[226:227], off
	global_load_dword v251, v[226:227], off offset:128
	global_load_dword v252, v[228:229], off
	s_nop 0
	global_load_dword v228, v[228:229], off offset:128
	s_nop 0
	global_load_dword v229, v[230:231], off
	s_nop 0
	global_load_dword v230, v[230:231], off offset:128
	v_add_u32_e32 v208, 27, v225
	v_min_i32_e32 v208, 0x7fff, v208
	v_ashrrev_i32_e32 v208, 12, v208
	v_add_u32_e32 v208, 8, v208
	v_mul_hi_i32_i24_e32 v209, 0x3000, v208
	v_mul_i32_i24_e32 v208, 0x3000, v208
	v_lshl_add_u64 v[208:209], s[24:25], 0, v[208:209]
	v_lshl_add_u64 v[208:209], v[208:209], 0, s[18:19]
	v_lshl_add_u64 v[226:227], v[208:209], 0, v[180:181]
	global_load_dword v225, v[226:227], off
	s_nop 0
	global_load_dword v226, v[226:227], off offset:128
	v_mad_u64_u32 v[160:161], s[2:3], v183, s36, v[182:183]
	v_lshl_add_u32 v162, v160, 2, s34
	ds_write2_b32 v162, v112, v96 offset1:32
	v_mul_f32_e32 v96, v113, v232
	ds_write2_b32 v162, v96, v97 offset0:68 offset1:100
	v_mul_f32_e32 v96, v114, v232
	v_mul_f32_e32 v97, v98, v233
	ds_write2_b32 v162, v96, v97 offset0:136 offset1:168
	v_mul_f32_e32 v96, v115, v232
	v_mul_f32_e32 v97, v99, v233
	ds_write2_b32 v162, v96, v97 offset0:204 offset1:236
	s_waitcnt vmcnt(23)
	v_mul_f32_e32 v96, v116, v242
	s_waitcnt vmcnt(22)
	v_mul_f32_e32 v97, v100, v243
	v_add_u32_e32 v115, 0x800, v162
	ds_write2_b32 v115, v96, v97 offset0:32 offset1:64
	s_waitcnt vmcnt(21)
	v_mul_f32_e32 v96, v117, v244
	s_waitcnt vmcnt(20)
	v_mul_f32_e32 v97, v101, v245
	ds_write2_b32 v115, v96, v97 offset0:100 offset1:132
	s_waitcnt vmcnt(19)
	v_mul_f32_e32 v96, v118, v246
	s_waitcnt vmcnt(18)
	v_mul_f32_e32 v97, v102, v247
	ds_write2_b32 v115, v96, v97 offset0:168 offset1:200
	v_add_u32_e32 v116, 0xa00, v162
	v_add_u32_e32 v117, 0x1000, v162
	s_waitcnt vmcnt(17)
	v_mul_f32_e32 v96, v119, v234
	s_waitcnt vmcnt(16)
	v_mul_f32_e32 v97, v103, v235
	ds_write2_b32 v116, v96, v97 offset0:108 offset1:140
	s_waitcnt vmcnt(15)
	v_mul_f32_e32 v96, v120, v236
	s_waitcnt vmcnt(14)
	v_mul_f32_e32 v97, v104, v237
	ds_write2_b32 v117, v96, v97 offset0:64 offset1:96
	s_waitcnt vmcnt(13)
	v_mul_f32_e32 v96, v121, v238
	s_waitcnt vmcnt(12)
	v_mul_f32_e32 v97, v105, v239
	ds_write2_b32 v117, v96, v97 offset0:132 offset1:164
	s_waitcnt vmcnt(11)
	v_mul_f32_e32 v96, v122, v240
	s_waitcnt vmcnt(10)
	v_mul_f32_e32 v97, v106, v241
	ds_write2_b32 v117, v96, v97 offset0:200 offset1:232
	v_add_u32_e32 v118, 0x1400, v162
	v_add_u32_e32 v119, 0x1800, v162
	v_ashrrev_i32_e32 v163, 4, v168
	v_and_b32_e32 v160, 15, v168
	v_add_u32_e32 v120, 0x1a00, v162
	v_mul_lo_u32 v164, v163, s37
	v_lshl_add_u32 v165, v160, 4, s34
	v_lshlrev_b32_e32 v168, 2, v160
	v_add_u32_e32 v160, s55, v163
	v_add_u32_e32 v121, 0x1c00, v162
	v_cmp_gt_i32_e32 vcc, s38, v160
	v_ashrrev_i32_e32 v161, 31, v160
	v_add_u32_e32 v114, v165, v164
	s_waitcnt vmcnt(9)
	v_mul_f32_e32 v96, v123, v248
	s_waitcnt vmcnt(8)
	v_mul_f32_e32 v97, v107, v249
	ds_write2_b32 v118, v96, v97 offset0:12 offset1:44
	s_waitcnt vmcnt(7)
	v_mul_f32_e32 v96, v124, v250
	s_waitcnt vmcnt(6)
	v_mul_f32_e32 v97, v108, v251
	ds_write2_b32 v119, v96, v97 offset0:96 offset1:128
	s_waitcnt vmcnt(5)
	v_mul_f32_e32 v96, v125, v252
	s_waitcnt vmcnt(4)
	v_mul_f32_e32 v97, v109, v228
	ds_write2_b32 v119, v96, v97 offset0:164 offset1:196
	s_waitcnt vmcnt(3)
	v_mul_f32_e32 v96, v126, v229
	s_waitcnt vmcnt(2)
	v_mul_f32_e32 v97, v110, v230
	ds_write2_b32 v120, v96, v97 offset0:104 offset1:136
	s_waitcnt vmcnt(1)
	v_mul_f32_e32 v96, v127, v225
	s_waitcnt vmcnt(0)
	v_mul_f32_e32 v97, v111, v226
	ds_write2_b32 v121, v96, v97 offset0:44 offset1:76
	v_or_b32_e32 v96, s26, v168
	v_mov_b32_e32 v97, s27
	v_add_u32_e32 v128, 0, v160
	v_ashrrev_i32_e32 v129, 31, v128
	v_lshlrev_b64 v[128:129], 12, v[128:129]
	v_lshl_add_u64 v[128:129], s[16:17], 0, v[128:129]
	v_lshl_add_u64 v[128:129], v[96:97], 2, v[128:129]
	global_load_dwordx4 v[128:131], v[128:129], off
	v_add_u32_e32 v132, 4, v160
	v_ashrrev_i32_e32 v133, 31, v132
	v_lshlrev_b64 v[132:133], 12, v[132:133]
	v_lshl_add_u64 v[132:133], s[16:17], 0, v[132:133]
	v_lshl_add_u64 v[132:133], v[96:97], 2, v[132:133]
	global_load_dwordx4 v[132:135], v[132:133], off
	v_add_u32_e32 v136, 8, v160
	v_ashrrev_i32_e32 v137, 31, v136
	v_lshlrev_b64 v[136:137], 12, v[136:137]
	v_lshl_add_u64 v[136:137], s[16:17], 0, v[136:137]
	v_lshl_add_u64 v[136:137], v[96:97], 2, v[136:137]
	global_load_dwordx4 v[136:139], v[136:137], off
	v_add_u32_e32 v140, 12, v160
	v_ashrrev_i32_e32 v141, 31, v140
	v_lshlrev_b64 v[140:141], 12, v[140:141]
	v_lshl_add_u64 v[140:141], s[16:17], 0, v[140:141]
	v_lshl_add_u64 v[140:141], v[96:97], 2, v[140:141]
	global_load_dwordx4 v[140:143], v[140:141], off
	v_add_u32_e32 v144, 16, v160
	v_ashrrev_i32_e32 v145, 31, v144
	v_lshlrev_b64 v[144:145], 12, v[144:145]
	v_lshl_add_u64 v[144:145], s[16:17], 0, v[144:145]
	v_lshl_add_u64 v[144:145], v[96:97], 2, v[144:145]
	global_load_dwordx4 v[144:147], v[144:145], off
	v_add_u32_e32 v148, 20, v160
	v_ashrrev_i32_e32 v149, 31, v148
	v_lshlrev_b64 v[148:149], 12, v[148:149]
	v_lshl_add_u64 v[148:149], s[16:17], 0, v[148:149]
	v_lshl_add_u64 v[148:149], v[96:97], 2, v[148:149]
	global_load_dwordx4 v[148:151], v[148:149], off
	v_add_u32_e32 v152, 24, v160
	v_ashrrev_i32_e32 v153, 31, v152
	v_lshlrev_b64 v[152:153], 12, v[152:153]
	v_lshl_add_u64 v[152:153], s[16:17], 0, v[152:153]
	v_lshl_add_u64 v[152:153], v[96:97], 2, v[152:153]
	global_load_dwordx4 v[152:155], v[152:153], off
	v_add_u32_e32 v156, 28, v160
	v_ashrrev_i32_e32 v157, 31, v156
	v_lshlrev_b64 v[156:157], 12, v[156:157]
	v_lshl_add_u64 v[156:157], s[16:17], 0, v[156:157]
	v_lshl_add_u64 v[156:157], v[96:97], 2, v[156:157]
	global_load_dwordx4 v[156:159], v[156:157], off
	s_and_saveexec_b64 s[2:3], vcc
	s_cbranch_execz .LBB0_2225
	v_lshlrev_b64 v[98:99], 12, v[160:161]
	v_lshl_add_u64 v[98:99], s[16:17], 0, v[98:99]
	v_lshl_add_u64 v[106:107], v[96:97], 2, v[98:99]
	ds_read_b128 v[102:105], v114
	s_waitcnt vmcnt(7) lgkmcnt(0)
	v_pk_add_f32 v[100:101], v[104:105], v[130:131]
	v_pk_add_f32 v[98:99], v[102:103], v[128:129]
	global_store_dwordx4 v[106:107], v[98:101], off

.LBB0_4478:
	s_ashr_i32 s2, s54, 31
	s_lshr_b32 s2, s2, 30
	s_add_i32 s2, s54, s2
	s_ashr_i32 s2, s2, 2
	s_lshl_b32 s4, s2, 8
	v_add_u32_e32 v0, s4, v212
	v_min_i32_e32 v0, 0x7fff, v0
	v_ashrrev_i32_e32 v1, 31, v0
	s_lshl_b32 s6, s2, 10
	v_lshlrev_b64 v[0:1], 11, v[0:1]
	v_lshl_add_u64 v[160:161], v[176:177], 0, v[0:1]
	v_subrev_u32_e32 v0, s6, v220
	v_ashrrev_i32_e32 v1, 31, v0
	v_lshlrev_b64 v[0:1], 11, v[0:1]
	v_lshl_add_u64 v[180:181], v[178:179], 0, v[0:1]
	v_subrev_u32_e32 v0, s6, v221
	v_ashrrev_i32_e32 v1, 31, v0
	v_lshlrev_b64 v[0:1], 11, v[0:1]
	v_lshl_add_u64 v[182:183], v[178:179], 0, v[0:1]
	v_subrev_u32_e32 v0, s6, v222
	v_ashrrev_i32_e32 v1, 31, v0
	v_add_u32_e32 v2, s4, v213
	v_add_u32_e32 v4, s4, v171
	v_add_u32_e32 v6, s4, v215
	v_lshlrev_b64 v[0:1], 11, v[0:1]
	v_min_i32_e32 v2, 0x7fff, v2
	v_min_i32_e32 v4, 0x7fff, v4
	v_min_i32_e32 v6, 0x7fff, v6
	v_lshl_add_u64 v[184:185], v[178:179], 0, v[0:1]
	v_subrev_u32_e32 v0, s6, v223
	v_ashrrev_i32_e32 v3, 31, v2
	v_ashrrev_i32_e32 v5, 31, v4
	v_ashrrev_i32_e32 v7, 31, v6
	v_ashrrev_i32_e32 v1, 31, v0
	v_lshlrev_b64 v[2:3], 11, v[2:3]
	v_lshlrev_b64 v[4:5], 11, v[4:5]
	v_lshlrev_b64 v[6:7], 11, v[6:7]
	v_lshlrev_b64 v[0:1], 11, v[0:1]
	s_mov_b32 s5, s54
	v_lshl_add_u64 v[162:163], v[176:177], 0, v[2:3]
	v_lshl_add_u64 v[164:165], v[176:177], 0, v[4:5]
	v_lshl_add_u64 v[166:167], v[176:177], 0, v[6:7]
	v_lshl_add_u64 v[186:187], v[178:179], 0, v[0:1]
	s_mov_b64 s[2:3], 0
	s_mov_b32 s7, 0
	v_mov_b32_e32 v0, 0
	v_mov_b32_e32 v1, v169
	v_mov_b32_e32 v2, v169
	v_mov_b32_e32 v3, v169
	v_mov_b32_e32 v4, v169
	v_mov_b32_e32 v5, v169
	v_mov_b32_e32 v6, v169
	v_mov_b32_e32 v7, v169
	v_mov_b32_e32 v8, v169
	v_mov_b32_e32 v9, v169
	v_mov_b32_e32 v10, v169
	v_mov_b32_e32 v11, v169
	v_mov_b32_e32 v12, v169
	v_mov_b32_e32 v13, v169
	v_mov_b32_e32 v14, v169
	v_mov_b32_e32 v15, v169
	v_mov_b32_e32 v16, 0
	v_mov_b32_e32 v17, v169
	v_mov_b32_e32 v18, v169
	v_mov_b32_e32 v19, v169
	v_mov_b32_e32 v20, v169
	v_mov_b32_e32 v21, v169
	v_mov_b32_e32 v22, v169
	v_mov_b32_e32 v23, v169
	v_mov_b32_e32 v24, v169
	v_mov_b32_e32 v25, v169
	v_mov_b32_e32 v26, v169
	v_mov_b32_e32 v27, v169
	v_mov_b32_e32 v28, v169
	v_mov_b32_e32 v29, v169
	v_mov_b32_e32 v30, v169
	v_mov_b32_e32 v31, v169
	v_mov_b32_e32 v32, 0
	v_mov_b32_e32 v33, v169
	v_mov_b32_e32 v34, v169
	v_mov_b32_e32 v35, v169
	v_mov_b32_e32 v36, v169
	v_mov_b32_e32 v37, v169
	v_mov_b32_e32 v38, v169
	v_mov_b32_e32 v39, v169
	v_mov_b32_e32 v40, v169
	v_mov_b32_e32 v41, v169
	v_mov_b32_e32 v42, v169
	v_mov_b32_e32 v43, v169
	v_mov_b32_e32 v44, v169
	v_mov_b32_e32 v45, v169
	v_mov_b32_e32 v46, v169
	v_mov_b32_e32 v47, v169
	v_mov_b32_e32 v48, 0
	v_mov_b32_e32 v49, v169
	v_mov_b32_e32 v50, v169
	v_mov_b32_e32 v51, v169
	v_mov_b32_e32 v52, v169
	v_mov_b32_e32 v53, v169
	v_mov_b32_e32 v54, v169
	v_mov_b32_e32 v55, v169
	v_mov_b32_e32 v56, v169
	v_mov_b32_e32 v57, v169
	v_mov_b32_e32 v58, v169
	v_mov_b32_e32 v59, v169
	v_mov_b32_e32 v60, v169
	v_mov_b32_e32 v61, v169
	v_mov_b32_e32 v62, v169
	v_mov_b32_e32 v63, v169
	v_mov_b32_e32 v64, 0
	v_mov_b32_e32 v65, v169
	v_mov_b32_e32 v66, v169
	v_mov_b32_e32 v67, v169
	v_mov_b32_e32 v68, v169
	v_mov_b32_e32 v69, v169
	v_mov_b32_e32 v70, v169
	v_mov_b32_e32 v71, v169
	v_mov_b32_e32 v72, v169
	v_mov_b32_e32 v73, v169
	v_mov_b32_e32 v74, v169
	v_mov_b32_e32 v75, v169
	v_mov_b32_e32 v76, v169
	v_mov_b32_e32 v77, v169
	v_mov_b32_e32 v78, v169
	v_mov_b32_e32 v79, v169
	v_mov_b32_e32 v80, 0
	v_mov_b32_e32 v81, v169
	v_mov_b32_e32 v82, v169
	v_mov_b32_e32 v83, v169
	v_mov_b32_e32 v84, v169
	v_mov_b32_e32 v85, v169
	v_mov_b32_e32 v86, v169
	v_mov_b32_e32 v87, v169
	v_mov_b32_e32 v88, v169
	v_mov_b32_e32 v89, v169
	v_mov_b32_e32 v90, v169
	v_mov_b32_e32 v91, v169
	v_mov_b32_e32 v92, v169
	v_mov_b32_e32 v93, v169
	v_mov_b32_e32 v94, v169
	v_mov_b32_e32 v95, v169
	s_waitcnt vmcnt(7)
	v_mov_b32_e32 v96, 0
	v_mov_b32_e32 v97, v169
	v_mov_b32_e32 v98, v169
	v_mov_b32_e32 v99, v169
	s_waitcnt vmcnt(6)
	v_mov_b32_e32 v100, v169
	v_mov_b32_e32 v101, v169
	v_mov_b32_e32 v102, v169
	v_mov_b32_e32 v103, v169
	s_waitcnt vmcnt(5)
	v_mov_b32_e32 v104, v169
	v_mov_b32_e32 v105, v169
	v_mov_b32_e32 v106, v169
	v_mov_b32_e32 v107, v169
	s_waitcnt vmcnt(4)
	v_mov_b32_e32 v108, v169
	v_mov_b32_e32 v109, v169
	v_mov_b32_e32 v110, v169
	v_mov_b32_e32 v111, v169
	s_waitcnt vmcnt(3)
	v_mov_b32_e32 v112, 0
	v_mov_b32_e32 v113, v169
	v_mov_b32_e32 v114, v169
	v_mov_b32_e32 v115, v169
	s_waitcnt vmcnt(2)
	v_mov_b32_e32 v116, v169
	v_mov_b32_e32 v117, v169
	v_mov_b32_e32 v118, v169
	v_mov_b32_e32 v119, v169
	s_waitcnt vmcnt(1)
	v_mov_b32_e32 v120, v169
	v_mov_b32_e32 v121, v169
	v_mov_b32_e32 v122, v169
	v_mov_b32_e32 v123, v169
	s_waitcnt vmcnt(0)
	v_mov_b32_e32 v124, v169
	v_mov_b32_e32 v125, v169
	v_mov_b32_e32 v126, v169
	v_mov_b32_e32 v127, v169
	v_mbcnt_hi_u32_b32 v128, -1, v210
	s_and_b32 s90, s70, 0x40
	v_and_b32_e32 v159, 48, v128
	v_or_b32_e32 v159, s90, v159
	v_and_b32_e32 v129, 31, v128
	v_lshrrev_b32_e32 v130, 5, v128
	v_bfe_u32 v131, v128, 1, 3
	v_lshlrev_b32_e32 v132, 7, v129
	s_lshr_b32 s91, s70, 7
	s_lshl_b32 s91, s91, 13
	s_lshl_b32 s90, s90, 8
	s_add_u32 s90, s90, 0x8000
	s_lshl_b32 s88, s70, 4
	s_mov_b32 s89, 0x10000
	s_lshl_b32 s92, s22, 4
	s_and_b32 s92, s92, 0x780
	s_mov_b32 s93, 0
	s_load_dwordx2 s[96:97], s[0:1], 0x158
	s_load_dwordx2 s[98:99], s[0:1], 0x138
	s_waitcnt lgkmcnt(0)
	v_subrev_u32_e32 v152, s96, v160
	v_xor_b32_e32 v152, v159, v152
	v_subrev_u32_e32 v153, s98, v180
	v_xor_b32_e32 v153, v159, v153
	v_subrev_u32_e32 v154, s96, v162
	v_xor_b32_e32 v154, v159, v154
	v_subrev_u32_e32 v155, s98, v182
	v_xor_b32_e32 v155, v159, v155
	v_subrev_u32_e32 v156, s96, v164
	v_xor_b32_e32 v156, v159, v156
	v_subrev_u32_e32 v157, s98, v184
	v_xor_b32_e32 v157, v159, v157
	v_subrev_u32_e32 v158, s96, v166
	v_xor_b32_e32 v158, v159, v158
	v_subrev_u32_e32 v168, s98, v186
	v_xor_b32_e32 v168, v159, v168
	v_xor_b32_e32 v133, v130, v131
	v_lshl_add_u32 v133, v133, 4, v132
	v_add_u32_e32 v230, s91, v133
	v_add_u32_e32 v234, s90, v133
	v_add_u32_e32 v208, 0x10000, v230
	v_add_u32_e32 v241, 0x10000, v234
	v_or_b32_e32 v133, 2, v130
	v_xor_b32_e32 v133, v133, v131
	v_lshl_add_u32 v133, v133, 4, v132
	v_add_u32_e32 v231, s91, v133
	v_add_u32_e32 v235, s90, v133
	v_add_u32_e32 v238, 0x10000, v231
	v_add_u32_e32 v253, 0x10000, v235
	v_or_b32_e32 v133, 4, v130
	v_xor_b32_e32 v133, v133, v131
	v_lshl_add_u32 v133, v133, 4, v132
	v_add_u32_e32 v232, s91, v133
	v_add_u32_e32 v236, s90, v133
	v_add_u32_e32 v239, 0x10000, v232
	v_add_u32_e32 v254, 0x10000, v236
	v_or_b32_e32 v133, 6, v130
	v_xor_b32_e32 v133, v133, v131
	v_lshl_add_u32 v133, v133, 4, v132
	v_add_u32_e32 v233, s91, v133
	v_add_u32_e32 v237, s90, v133
	v_add_u32_e32 v240, 0x10000, v233
	v_add_u32_e32 v255, 0x10000, v237
	s_barrier
	ds_read_b128 v[188:191], v230
	ds_read_b128 v[196:199], v234
	ds_read_b128 v[192:195], v230 offset:4096
	ds_read_b128 v[200:203], v234 offset:4096
	ds_read_b128 v[204:207], v234 offset:8192
	ds_read_b128 v[226:229], v234 offset:12288
	s_add_u32 s94, s2, s92
	s_add_u32 s94, s94, 0x80
	s_and_b32 s94, s94, 0x780
	s_sub_u32 s94, s94, 0x80
	s_subb_u32 s95, 0, 0
	s_add_u32 s100, s96, s94
	s_addc_u32 s101, s97, s95
	s_add_u32 s94, s98, s94
	s_addc_u32 s95, s99, s95
	s_add_u32 s90, s88, s89
	s_add_u32 m0, s90, 0
	s_nop 0
	global_load_lds_dwordx4 v152, s[100:101]
	s_add_u32 m0, s90, 32768
	s_nop 0
	global_load_lds_dwordx4 v153, s[94:95]
	s_add_u32 m0, s90, 8192
	s_nop 0
	global_load_lds_dwordx4 v154, s[100:101]
	s_add_u32 m0, s90, 40960
	s_nop 0
	global_load_lds_dwordx4 v155, s[94:95]
	s_add_u32 m0, s90, 16384
	s_nop 0
	global_load_lds_dwordx4 v156, s[100:101]
	s_add_u32 m0, s90, 49152
	s_nop 0
	global_load_lds_dwordx4 v157, s[94:95]
	s_add_u32 m0, s90, 24576
	s_nop 0
	global_load_lds_dwordx4 v158, s[100:101]
	s_add_u32 m0, s90, 57344
	s_nop 0
	global_load_lds_dwordx4 v168, s[94:95]
	s_xor_b32 s89, s89, 0x10000

.LBB0_4482:
	ds_read_b128 v[128:131], v238
	ds_read_b128 v[136:139], v253
	ds_read_b128 v[132:135], v238 offset:4096
	ds_read_b128 v[140:143], v253 offset:4096
	ds_read_b128 v[144:147], v253 offset:8192
	ds_read_b128 v[148:151], v253 offset:12288
	s_waitcnt lgkmcnt(6)
	v_mfma_f32_32x32x16_bf16 v[112:127], v[188:191], v[196:199], v[112:127]
	v_mfma_f32_32x32x16_bf16 v[48:63], v[192:195], v[196:199], v[48:63]
	v_mfma_f32_32x32x16_bf16 v[96:111], v[188:191], v[200:203], v[96:111]
	v_mfma_f32_32x32x16_bf16 v[32:47], v[192:195], v[200:203], v[32:47]
	v_mfma_f32_32x32x16_bf16 v[80:95], v[188:191], v[204:207], v[80:95]
	v_mfma_f32_32x32x16_bf16 v[16:31], v[192:195], v[204:207], v[16:31]
	v_mfma_f32_32x32x16_bf16 v[64:79], v[188:191], v[226:229], v[64:79]
	v_mfma_f32_32x32x16_bf16 v[0:15], v[192:195], v[226:229], v[0:15]
	ds_read_b128 v[188:191], v239
	ds_read_b128 v[196:199], v254
	ds_read_b128 v[192:195], v239 offset:4096
	ds_read_b128 v[200:203], v254 offset:4096
	ds_read_b128 v[204:207], v254 offset:8192
	ds_read_b128 v[226:229], v254 offset:12288
	s_waitcnt lgkmcnt(6)
	v_mfma_f32_32x32x16_bf16 v[112:127], v[128:131], v[136:139], v[112:127]
	v_mfma_f32_32x32x16_bf16 v[48:63], v[132:135], v[136:139], v[48:63]
	v_mfma_f32_32x32x16_bf16 v[96:111], v[128:131], v[140:143], v[96:111]
	v_mfma_f32_32x32x16_bf16 v[32:47], v[132:135], v[140:143], v[32:47]
	v_mfma_f32_32x32x16_bf16 v[80:95], v[128:131], v[144:147], v[80:95]
	v_mfma_f32_32x32x16_bf16 v[16:31], v[132:135], v[144:147], v[16:31]
	v_mfma_f32_32x32x16_bf16 v[64:79], v[128:131], v[148:151], v[64:79]
	v_mfma_f32_32x32x16_bf16 v[0:15], v[132:135], v[148:151], v[0:15]
	ds_read_b128 v[128:131], v240
	ds_read_b128 v[136:139], v255
	ds_read_b128 v[132:135], v240 offset:4096
	ds_read_b128 v[140:143], v255 offset:4096
	ds_read_b128 v[144:147], v255 offset:8192
	ds_read_b128 v[148:151], v255 offset:12288
	s_waitcnt lgkmcnt(6)
	v_mfma_f32_32x32x16_bf16 v[112:127], v[188:191], v[196:199], v[112:127]
	v_mfma_f32_32x32x16_bf16 v[48:63], v[192:195], v[196:199], v[48:63]
	v_mfma_f32_32x32x16_bf16 v[96:111], v[188:191], v[200:203], v[96:111]
	v_mfma_f32_32x32x16_bf16 v[32:47], v[192:195], v[200:203], v[32:47]
	v_mfma_f32_32x32x16_bf16 v[80:95], v[188:191], v[204:207], v[80:95]
	v_mfma_f32_32x32x16_bf16 v[16:31], v[192:195], v[204:207], v[16:31]
	v_mfma_f32_32x32x16_bf16 v[64:79], v[188:191], v[226:229], v[64:79]
	v_mfma_f32_32x32x16_bf16 v[0:15], v[192:195], v[226:229], v[0:15]
	s_waitcnt vmcnt(0) lgkmcnt(0)
	s_barrier
	v_mfma_f32_32x32x16_bf16 v[112:127], v[128:131], v[136:139], v[112:127]
	v_mfma_f32_32x32x16_bf16 v[48:63], v[132:135], v[136:139], v[48:63]
	v_mfma_f32_32x32x16_bf16 v[96:111], v[128:131], v[140:143], v[96:111]
	v_mfma_f32_32x32x16_bf16 v[32:47], v[132:135], v[140:143], v[32:47]
	v_mfma_f32_32x32x16_bf16 v[80:95], v[128:131], v[144:147], v[80:95]
	v_mfma_f32_32x32x16_bf16 v[16:31], v[132:135], v[144:147], v[16:31]
	v_mfma_f32_32x32x16_bf16 v[64:79], v[128:131], v[148:151], v[64:79]
	v_mfma_f32_32x32x16_bf16 v[0:15], v[132:135], v[148:151], v[0:15]
	s_lshl_b32 s2, s5, 8
	s_sub_i32 s2, s2, s6
	v_mov_b32_e32 v168, v214
	s_add_i32 s55, s4, s30
	s_or_b32 s26, s2, s31
	s_ashr_i32 s27, s26, 31
	s_load_dwordx2 s[24:25], s[0:1], 0x140
	v_ashrrev_i32_e32 v180, 3, v168
	v_and_b32_e32 v183, -4, v180
	v_add_u32_e32 v225, s55, v183
	v_add_u32_e32 v190, 8, v225
	v_min_i32_e32 v190, 0x7fff, v190
	v_ashrrev_i32_e32 v190, 12, v190
	v_add_u32_e32 v190, 16, v190
	v_mul_hi_i32_i24_e32 v191, 0x3000, v190
	v_mul_i32_i24_e32 v190, 0x3000, v190
	v_min_i32_e32 v184, 0x7fff, v225
	v_ashrrev_i32_e32 v184, 12, v184
	v_and_b32_e32 v182, 31, v168
	v_add_u32_e32 v184, 16, v184
	v_or_b32_e32 v180, s26, v182
	v_mul_hi_i32_i24_e32 v185, 0x3000, v184
	v_mul_i32_i24_e32 v184, 0x3000, v184
	v_ashrrev_i32_e32 v181, 31, v180
	s_waitcnt lgkmcnt(0)
	v_lshl_add_u64 v[184:185], s[24:25], 0, v[184:185]
	v_lshl_add_u64 v[184:185], v[184:185], 0, s[18:19]
	v_lshlrev_b64 v[180:181], 2, v[180:181]
	v_lshl_add_u64 v[196:197], v[184:185], 0, v[180:181]
	v_lshl_add_u64 v[186:187], s[24:25], 0, v[190:191]
	v_add_u32_e32 v188, 9, v225
	v_add_u32_e32 v190, 10, v225
	v_min_i32_e32 v188, 0x7fff, v188
	v_min_i32_e32 v190, 0x7fff, v190
	v_ashrrev_i32_e32 v188, 12, v188
	v_ashrrev_i32_e32 v190, 12, v190
	v_add_u32_e32 v188, 16, v188
	v_add_u32_e32 v190, 16, v190
	v_mul_hi_i32_i24_e32 v189, 0x3000, v188
	v_mul_i32_i24_e32 v188, 0x3000, v188
	v_mul_hi_i32_i24_e32 v191, 0x3000, v190
	v_mul_i32_i24_e32 v190, 0x3000, v190
	v_lshl_add_u64 v[188:189], s[24:25], 0, v[188:189]
	v_lshl_add_u64 v[190:191], s[24:25], 0, v[190:191]
	v_lshl_add_u64 v[186:187], v[186:187], 0, s[18:19]
	v_lshl_add_u64 v[188:189], v[188:189], 0, s[18:19]
	v_lshl_add_u64 v[190:191], v[190:191], 0, s[18:19]
	v_lshl_add_u64 v[206:207], v[186:187], 0, v[180:181]
	v_add_u32_e32 v208, 18, v225
	v_min_i32_e32 v208, 0x7fff, v208
	v_ashrrev_i32_e32 v208, 12, v208
	v_add_u32_e32 v208, 16, v208
	v_mul_hi_i32_i24_e32 v209, 0x3000, v208
	v_mul_i32_i24_e32 v208, 0x3000, v208
	v_lshl_add_u64 v[208:209], s[24:25], 0, v[208:209]
	v_lshl_add_u64 v[202:203], v[188:189], 0, v[180:181]
	v_lshl_add_u64 v[204:205], v[190:191], 0, v[180:181]
	global_load_dword v232, v[196:197], off
	global_load_dword v233, v[196:197], off offset:128
	global_load_dword v242, v[206:207], off
	global_load_dword v243, v[206:207], off offset:128
	global_load_dword v244, v[202:203], off
	global_load_dword v245, v[202:203], off offset:128
	global_load_dword v246, v[204:205], off
	global_load_dword v247, v[204:205], off offset:128
	v_add_u32_e32 v196, 17, v225
	v_min_i32_e32 v196, 0x7fff, v196
	v_ashrrev_i32_e32 v196, 12, v196
	v_add_u32_e32 v196, 16, v196
	v_mul_hi_i32_i24_e32 v197, 0x3000, v196
	v_mul_i32_i24_e32 v196, 0x3000, v196
	v_lshl_add_u64 v[196:197], s[24:25], 0, v[196:197]
	v_lshl_add_u64 v[196:197], v[196:197], 0, s[18:19]
	v_lshl_add_u64 v[206:207], v[196:197], 0, v[180:181]
	s_waitcnt vmcnt(7)
	s_nop 5
	v_mul_f32_e32 v112, v112, v232
	v_add_u32_e32 v192, 11, v225
	v_add_u32_e32 v194, 16, v225
	v_min_i32_e32 v192, 0x7fff, v192
	v_min_i32_e32 v194, 0x7fff, v194
	v_ashrrev_i32_e32 v192, 12, v192
	v_ashrrev_i32_e32 v194, 12, v194
	v_add_u32_e32 v192, 16, v192
	v_add_u32_e32 v194, 16, v194
	v_mul_hi_i32_i24_e32 v193, 0x3000, v192
	v_mul_i32_i24_e32 v192, 0x3000, v192
	v_mul_hi_i32_i24_e32 v195, 0x3000, v194
	v_mul_i32_i24_e32 v194, 0x3000, v194
	v_lshl_add_u64 v[192:193], s[24:25], 0, v[192:193]
	v_lshl_add_u64 v[194:195], s[24:25], 0, v[194:195]
	v_lshl_add_u64 v[192:193], v[192:193], 0, s[18:19]
	v_lshl_add_u64 v[194:195], v[194:195], 0, s[18:19]
	v_lshl_add_u64 v[202:203], v[192:193], 0, v[180:181]
	v_lshl_add_u64 v[204:205], v[194:195], 0, v[180:181]
	s_waitcnt vmcnt(6)
	s_nop 5
	v_mul_f32_e32 v96, v96, v233
	v_mul_f32_e32 v97, v97, v233
	v_lshl_add_u64 v[198:199], v[208:209], 0, s[18:19]
	v_lshl_add_u64 v[200:201], v[198:199], 0, v[180:181]
	global_load_dword v234, v[202:203], off
	global_load_dword v235, v[202:203], off offset:128
	global_load_dword v236, v[204:205], off
	global_load_dword v237, v[204:205], off offset:128
	global_load_dword v238, v[206:207], off
	global_load_dword v239, v[206:207], off offset:128
	global_load_dword v240, v[200:201], off
	global_load_dword v241, v[200:201], off offset:128
	v_add_u32_e32 v200, 19, v225
	v_add_u32_e32 v204, 25, v225
	v_add_u32_e32 v206, 26, v225
	v_min_i32_e32 v200, 0x7fff, v200
	v_add_u32_e32 v202, 24, v225
	v_min_i32_e32 v204, 0x7fff, v204
	v_min_i32_e32 v206, 0x7fff, v206
	v_ashrrev_i32_e32 v200, 12, v200
	v_min_i32_e32 v202, 0x7fff, v202
	v_ashrrev_i32_e32 v204, 12, v204
	v_ashrrev_i32_e32 v206, 12, v206
	v_add_u32_e32 v200, 16, v200
	v_ashrrev_i32_e32 v202, 12, v202
	v_add_u32_e32 v204, 16, v204
	v_add_u32_e32 v206, 16, v206
	v_mul_hi_i32_i24_e32 v201, 0x3000, v200
	v_mul_i32_i24_e32 v200, 0x3000, v200
	v_add_u32_e32 v202, 16, v202
	v_mul_hi_i32_i24_e32 v205, 0x3000, v204
	v_mul_i32_i24_e32 v204, 0x3000, v204
	v_mul_hi_i32_i24_e32 v207, 0x3000, v206
	v_mul_i32_i24_e32 v206, 0x3000, v206
	v_lshl_add_u64 v[200:201], s[24:25], 0, v[200:201]
	v_mul_hi_i32_i24_e32 v203, 0x3000, v202
	v_mul_i32_i24_e32 v202, 0x3000, v202
	v_lshl_add_u64 v[204:205], s[24:25], 0, v[204:205]
	v_lshl_add_u64 v[206:207], s[24:25], 0, v[206:207]
	v_lshl_add_u64 v[200:201], v[200:201], 0, s[18:19]
	v_lshl_add_u64 v[202:203], s[24:25], 0, v[202:203]
	v_lshl_add_u64 v[204:205], v[204:205], 0, s[18:19]
	v_lshl_add_u64 v[206:207], v[206:207], 0, s[18:19]
	v_lshl_add_u64 v[208:209], v[200:201], 0, v[180:181]
	v_lshl_add_u64 v[202:203], v[202:203], 0, s[18:19]
	v_lshl_add_u64 v[228:229], v[204:205], 0, v[180:181]
	v_lshl_add_u64 v[230:231], v[206:207], 0, v[180:181]
	v_lshl_add_u64 v[226:227], v[202:203], 0, v[180:181]
	global_load_dword v248, v[208:209], off
	global_load_dword v249, v[208:209], off offset:128
	global_load_dword v250, v[226:227], off
	global_load_dword v251, v[226:227], off offset:128
	global_load_dword v252, v[228:229], off
	s_nop 0
	global_load_dword v228, v[228:229], off offset:128
	s_nop 0
	global_load_dword v229, v[230:231], off
	s_nop 0
	global_load_dword v230, v[230:231], off offset:128
	v_add_u32_e32 v208, 27, v225
	v_min_i32_e32 v208, 0x7fff, v208
	v_ashrrev_i32_e32 v208, 12, v208
	v_add_u32_e32 v208, 16, v208
	v_mul_hi_i32_i24_e32 v209, 0x3000, v208
	v_mul_i32_i24_e32 v208, 0x3000, v208
	v_lshl_add_u64 v[208:209], s[24:25], 0, v[208:209]
	v_lshl_add_u64 v[208:209], v[208:209], 0, s[18:19]
	v_lshl_add_u64 v[226:227], v[208:209], 0, v[180:181]
	global_load_dword v225, v[226:227], off
	s_nop 0
	global_load_dword v226, v[226:227], off offset:128
	v_mad_u64_u32 v[160:161], s[2:3], v183, s36, v[182:183]
	v_lshl_add_u32 v162, v160, 2, s34
	ds_write2_b32 v162, v112, v96 offset1:32
	v_mul_f32_e32 v96, v113, v232
	ds_write2_b32 v162, v96, v97 offset0:68 offset1:100
	v_mul_f32_e32 v96, v114, v232
	v_mul_f32_e32 v97, v98, v233
	ds_write2_b32 v162, v96, v97 offset0:136 offset1:168
	v_mul_f32_e32 v96, v115, v232
	v_mul_f32_e32 v97, v99, v233
	ds_write2_b32 v162, v96, v97 offset0:204 offset1:236
	s_waitcnt vmcnt(23)
	v_mul_f32_e32 v96, v116, v242
	s_waitcnt vmcnt(22)
	v_mul_f32_e32 v97, v100, v243
	v_add_u32_e32 v115, 0x800, v162
	ds_write2_b32 v115, v96, v97 offset0:32 offset1:64
	s_waitcnt vmcnt(21)
	v_mul_f32_e32 v96, v117, v244
	s_waitcnt vmcnt(20)
	v_mul_f32_e32 v97, v101, v245
	ds_write2_b32 v115, v96, v97 offset0:100 offset1:132
	s_waitcnt vmcnt(19)
	v_mul_f32_e32 v96, v118, v246
	s_waitcnt vmcnt(18)
	v_mul_f32_e32 v97, v102, v247
	ds_write2_b32 v115, v96, v97 offset0:168 offset1:200
	v_add_u32_e32 v116, 0xa00, v162
	v_add_u32_e32 v117, 0x1000, v162
	s_waitcnt vmcnt(17)
	v_mul_f32_e32 v96, v119, v234
	s_waitcnt vmcnt(16)
	v_mul_f32_e32 v97, v103, v235
	ds_write2_b32 v116, v96, v97 offset0:108 offset1:140
	s_waitcnt vmcnt(15)
	v_mul_f32_e32 v96, v120, v236
	s_waitcnt vmcnt(14)
	v_mul_f32_e32 v97, v104, v237
	ds_write2_b32 v117, v96, v97 offset0:64 offset1:96
	s_waitcnt vmcnt(13)
	v_mul_f32_e32 v96, v121, v238
	s_waitcnt vmcnt(12)
	v_mul_f32_e32 v97, v105, v239
	ds_write2_b32 v117, v96, v97 offset0:132 offset1:164
	s_waitcnt vmcnt(11)
	v_mul_f32_e32 v96, v122, v240
	s_waitcnt vmcnt(10)
	v_mul_f32_e32 v97, v106, v241
	ds_write2_b32 v117, v96, v97 offset0:200 offset1:232
	v_add_u32_e32 v118, 0x1400, v162
	v_add_u32_e32 v119, 0x1800, v162
	v_ashrrev_i32_e32 v163, 4, v168
	v_and_b32_e32 v160, 15, v168
	v_add_u32_e32 v120, 0x1a00, v162
	v_mul_lo_u32 v164, v163, s37
	v_lshl_add_u32 v165, v160, 4, s34
	v_lshlrev_b32_e32 v168, 2, v160
	v_add_u32_e32 v160, s55, v163
	v_add_u32_e32 v121, 0x1c00, v162
	v_cmp_gt_i32_e32 vcc, s38, v160
	v_ashrrev_i32_e32 v161, 31, v160
	v_add_u32_e32 v114, v165, v164
	s_waitcnt vmcnt(9)
	v_mul_f32_e32 v96, v123, v248
	s_waitcnt vmcnt(8)
	v_mul_f32_e32 v97, v107, v249
	ds_write2_b32 v118, v96, v97 offset0:12 offset1:44
	s_waitcnt vmcnt(7)
	v_mul_f32_e32 v96, v124, v250
	s_waitcnt vmcnt(6)
	v_mul_f32_e32 v97, v108, v251
	ds_write2_b32 v119, v96, v97 offset0:96 offset1:128
	s_waitcnt vmcnt(5)
	v_mul_f32_e32 v96, v125, v252
	s_waitcnt vmcnt(4)
	v_mul_f32_e32 v97, v109, v228
	ds_write2_b32 v119, v96, v97 offset0:164 offset1:196
	s_waitcnt vmcnt(3)
	v_mul_f32_e32 v96, v126, v229
	s_waitcnt vmcnt(2)
	v_mul_f32_e32 v97, v110, v230
	ds_write2_b32 v120, v96, v97 offset0:104 offset1:136
	s_waitcnt vmcnt(1)
	v_mul_f32_e32 v96, v127, v225
	s_waitcnt vmcnt(0)
	v_mul_f32_e32 v97, v111, v226
	ds_write2_b32 v121, v96, v97 offset0:44 offset1:76
	v_or_b32_e32 v96, s26, v168
	v_mov_b32_e32 v97, s27
	v_add_u32_e32 v128, 0, v160
	v_ashrrev_i32_e32 v129, 31, v128
	v_lshlrev_b64 v[128:129], 12, v[128:129]
	v_lshl_add_u64 v[128:129], s[16:17], 0, v[128:129]
	v_lshl_add_u64 v[128:129], v[96:97], 2, v[128:129]
	global_load_dwordx4 v[128:131], v[128:129], off
	v_add_u32_e32 v132, 4, v160
	v_ashrrev_i32_e32 v133, 31, v132
	v_lshlrev_b64 v[132:133], 12, v[132:133]
	v_lshl_add_u64 v[132:133], s[16:17], 0, v[132:133]
	v_lshl_add_u64 v[132:133], v[96:97], 2, v[132:133]
	global_load_dwordx4 v[132:135], v[132:133], off
	v_add_u32_e32 v136, 8, v160
	v_ashrrev_i32_e32 v137, 31, v136
	v_lshlrev_b64 v[136:137], 12, v[136:137]
	v_lshl_add_u64 v[136:137], s[16:17], 0, v[136:137]
	v_lshl_add_u64 v[136:137], v[96:97], 2, v[136:137]
	global_load_dwordx4 v[136:139], v[136:137], off
	v_add_u32_e32 v140, 12, v160
	v_ashrrev_i32_e32 v141, 31, v140
	v_lshlrev_b64 v[140:141], 12, v[140:141]
	v_lshl_add_u64 v[140:141], s[16:17], 0, v[140:141]
	v_lshl_add_u64 v[140:141], v[96:97], 2, v[140:141]
	global_load_dwordx4 v[140:143], v[140:141], off
	v_add_u32_e32 v144, 16, v160
	v_ashrrev_i32_e32 v145, 31, v144
	v_lshlrev_b64 v[144:145], 12, v[144:145]
	v_lshl_add_u64 v[144:145], s[16:17], 0, v[144:145]
	v_lshl_add_u64 v[144:145], v[96:97], 2, v[144:145]
	global_load_dwordx4 v[144:147], v[144:145], off
	v_add_u32_e32 v148, 20, v160
	v_ashrrev_i32_e32 v149, 31, v148
	v_lshlrev_b64 v[148:149], 12, v[148:149]
	v_lshl_add_u64 v[148:149], s[16:17], 0, v[148:149]
	v_lshl_add_u64 v[148:149], v[96:97], 2, v[148:149]
	global_load_dwordx4 v[148:151], v[148:149], off
	v_add_u32_e32 v152, 24, v160
	v_ashrrev_i32_e32 v153, 31, v152
	v_lshlrev_b64 v[152:153], 12, v[152:153]
	v_lshl_add_u64 v[152:153], s[16:17], 0, v[152:153]
	v_lshl_add_u64 v[152:153], v[96:97], 2, v[152:153]
	global_load_dwordx4 v[152:155], v[152:153], off
	v_add_u32_e32 v156, 28, v160
	v_ashrrev_i32_e32 v157, 31, v156
	v_lshlrev_b64 v[156:157], 12, v[156:157]
	v_lshl_add_u64 v[156:157], s[16:17], 0, v[156:157]
	v_lshl_add_u64 v[156:157], v[96:97], 2, v[156:157]
	global_load_dwordx4 v[156:159], v[156:157], off
	s_and_saveexec_b64 s[2:3], vcc
	s_cbranch_execz .LBB0_4484
	v_lshlrev_b64 v[98:99], 12, v[160:161]
	v_lshl_add_u64 v[98:99], s[16:17], 0, v[98:99]
	v_lshl_add_u64 v[106:107], v[96:97], 2, v[98:99]
	ds_read_b128 v[102:105], v114
	s_waitcnt vmcnt(7) lgkmcnt(0)
	v_pk_add_f32 v[100:101], v[104:105], v[130:131]
	v_pk_add_f32 v[98:99], v[102:103], v[128:129]
	global_store_dwordx4 v[106:107], v[98:101], off

.LBB0_4668:
	s_mul_hi_i32 s5, s68, 0x2aaaaaab
	s_lshr_b32 s2, s5, 31
	s_add_i32 s5, s5, s2
	s_lshl_b32 s69, s5, 8
	s_waitcnt lgkmcnt(0)
	v_add_u32_e32 v0, s69, v189
	v_min_i32_e32 v0, 0x7fff, v0
	v_ashrrev_i32_e32 v1, 31, v0
	v_lshlrev_b64 v[0:1], 11, v[0:1]
	s_mul_i32 s2, s5, 0x600
	v_lshl_add_u64 v[172:173], v[168:169], 0, v[0:1]
	v_subrev_u32_e32 v0, s2, v200
	v_ashrrev_i32_e32 v1, 31, v0
	v_lshlrev_b64 v[0:1], 11, v[0:1]
	v_lshl_add_u64 v[180:181], v[170:171], 0, v[0:1]
	v_subrev_u32_e32 v0, s2, v201
	v_ashrrev_i32_e32 v1, 31, v0
	v_lshlrev_b64 v[0:1], 11, v[0:1]
	v_lshl_add_u64 v[182:183], v[170:171], 0, v[0:1]
	v_subrev_u32_e32 v0, s2, v202
	v_ashrrev_i32_e32 v1, 31, v0
	v_add_u32_e32 v2, s69, v190
	v_add_u32_e32 v4, s69, v163
	v_add_u32_e32 v6, s69, v192
	v_lshlrev_b64 v[0:1], 11, v[0:1]
	v_min_i32_e32 v2, 0x7fff, v2
	v_min_i32_e32 v4, 0x7fff, v4
	v_min_i32_e32 v6, 0x7fff, v6
	v_lshl_add_u64 v[184:185], v[170:171], 0, v[0:1]
	v_subrev_u32_e32 v0, s2, v203
	v_ashrrev_i32_e32 v3, 31, v2
	v_ashrrev_i32_e32 v5, 31, v4
	v_ashrrev_i32_e32 v7, 31, v6
	v_ashrrev_i32_e32 v1, 31, v0
	v_lshlrev_b64 v[2:3], 11, v[2:3]
	v_lshlrev_b64 v[4:5], 11, v[4:5]
	v_lshlrev_b64 v[6:7], 11, v[6:7]
	v_lshlrev_b64 v[0:1], 11, v[0:1]
	s_mov_b32 s4, s68
	v_lshl_add_u64 v[174:175], v[168:169], 0, v[2:3]
	v_lshl_add_u64 v[176:177], v[168:169], 0, v[4:5]
	v_lshl_add_u64 v[178:179], v[168:169], 0, v[6:7]
	v_lshl_add_u64 v[186:187], v[170:171], 0, v[0:1]
	s_mov_b64 s[2:3], 0
	s_mov_b32 s6, s25
	v_mov_b32_e32 v0, v161
	v_mov_b32_e32 v1, v161
	v_mov_b32_e32 v2, v161
	v_mov_b32_e32 v3, v161
	v_mov_b32_e32 v4, v161
	v_mov_b32_e32 v5, v161
	v_mov_b32_e32 v6, v161
	v_mov_b32_e32 v7, v161
	v_mov_b32_e32 v8, v161
	v_mov_b32_e32 v9, v161
	v_mov_b32_e32 v10, v161
	v_mov_b32_e32 v11, v161
	v_mov_b32_e32 v12, v161
	v_mov_b32_e32 v13, v161
	v_mov_b32_e32 v14, v161
	v_mov_b32_e32 v15, v161
	v_mov_b32_e32 v16, v161
	v_mov_b32_e32 v17, v161
	v_mov_b32_e32 v18, v161
	v_mov_b32_e32 v19, v161
	v_mov_b32_e32 v20, v161
	v_mov_b32_e32 v21, v161
	v_mov_b32_e32 v22, v161
	v_mov_b32_e32 v23, v161
	v_mov_b32_e32 v24, v161
	v_mov_b32_e32 v25, v161
	v_mov_b32_e32 v26, v161
	v_mov_b32_e32 v27, v161
	v_mov_b32_e32 v28, v161
	v_mov_b32_e32 v29, v161
	v_mov_b32_e32 v30, v161
	v_mov_b32_e32 v31, v161
	v_mov_b32_e32 v32, v161
	v_mov_b32_e32 v33, v161
	v_mov_b32_e32 v34, v161
	v_mov_b32_e32 v35, v161
	v_mov_b32_e32 v36, v161
	v_mov_b32_e32 v37, v161
	v_mov_b32_e32 v38, v161
	v_mov_b32_e32 v39, v161
	v_mov_b32_e32 v40, v161
	v_mov_b32_e32 v41, v161
	v_mov_b32_e32 v42, v161
	v_mov_b32_e32 v43, v161
	v_mov_b32_e32 v44, v161
	v_mov_b32_e32 v45, v161
	v_mov_b32_e32 v46, v161
	v_mov_b32_e32 v47, v161
	v_mov_b32_e32 v48, v161
	v_mov_b32_e32 v49, v161
	v_mov_b32_e32 v50, v161
	v_mov_b32_e32 v51, v161
	v_mov_b32_e32 v52, v161
	v_mov_b32_e32 v53, v161
	v_mov_b32_e32 v54, v161
	v_mov_b32_e32 v55, v161
	v_mov_b32_e32 v56, v161
	v_mov_b32_e32 v57, v161
	v_mov_b32_e32 v58, v161
	v_mov_b32_e32 v59, v161
	v_mov_b32_e32 v60, v161
	v_mov_b32_e32 v61, v161
	v_mov_b32_e32 v62, v161
	v_mov_b32_e32 v63, v161
	v_mov_b32_e32 v64, v161
	v_mov_b32_e32 v65, v161
	v_mov_b32_e32 v66, v161
	v_mov_b32_e32 v67, v161
	v_mov_b32_e32 v68, v161
	v_mov_b32_e32 v69, v161
	v_mov_b32_e32 v70, v161
	v_mov_b32_e32 v71, v161
	v_mov_b32_e32 v72, v161
	v_mov_b32_e32 v73, v161
	v_mov_b32_e32 v74, v161
	v_mov_b32_e32 v75, v161
	v_mov_b32_e32 v76, v161
	v_mov_b32_e32 v77, v161
	v_mov_b32_e32 v78, v161
	v_mov_b32_e32 v79, v161
	v_mov_b32_e32 v80, v161
	v_mov_b32_e32 v81, v161
	v_mov_b32_e32 v82, v161
	v_mov_b32_e32 v83, v161
	v_mov_b32_e32 v84, v161
	v_mov_b32_e32 v85, v161
	v_mov_b32_e32 v86, v161
	v_mov_b32_e32 v87, v161
	v_mov_b32_e32 v88, v161
	v_mov_b32_e32 v89, v161
	v_mov_b32_e32 v90, v161
	v_mov_b32_e32 v91, v161
	v_mov_b32_e32 v92, v161
	v_mov_b32_e32 v93, v161
	v_mov_b32_e32 v94, v161
	v_mov_b32_e32 v95, v161
	s_waitcnt vmcnt(7)
	v_mov_b32_e32 v96, v161
	v_mov_b32_e32 v97, v161
	v_mov_b32_e32 v98, v161
	v_mov_b32_e32 v99, v161
	s_waitcnt vmcnt(6)
	v_mov_b32_e32 v100, v161
	v_mov_b32_e32 v101, v161
	v_mov_b32_e32 v102, v161
	v_mov_b32_e32 v103, v161
	s_waitcnt vmcnt(5)
	v_mov_b32_e32 v104, v161
	v_mov_b32_e32 v105, v161
	v_mov_b32_e32 v106, v161
	v_mov_b32_e32 v107, v161
	s_waitcnt vmcnt(4)
	v_mov_b32_e32 v108, v161
	v_mov_b32_e32 v109, v161
	v_mov_b32_e32 v110, v161
	v_mov_b32_e32 v111, v161
	s_waitcnt vmcnt(3)
	v_mov_b32_e32 v112, v161
	v_mov_b32_e32 v113, v161
	v_mov_b32_e32 v114, v161
	v_mov_b32_e32 v115, v161
	s_waitcnt vmcnt(2)
	v_mov_b32_e32 v116, v161
	v_mov_b32_e32 v117, v161
	v_mov_b32_e32 v118, v161
	v_mov_b32_e32 v119, v161
	s_waitcnt vmcnt(1)
	v_mov_b32_e32 v120, v161
	v_mov_b32_e32 v121, v161
	v_mov_b32_e32 v122, v161
	v_mov_b32_e32 v123, v161
	s_waitcnt vmcnt(0)
	v_mov_b32_e32 v124, v161
	v_mov_b32_e32 v125, v161
	v_mov_b32_e32 v126, v161
	v_mov_b32_e32 v127, v161
	v_mbcnt_hi_u32_b32 v128, -1, v210
	s_and_b32 s90, s70, 0x40
	v_and_b32_e32 v159, 48, v128
	v_or_b32_e32 v159, s90, v159
	v_and_b32_e32 v129, 31, v128
	v_lshrrev_b32_e32 v130, 5, v128
	v_bfe_u32 v131, v128, 1, 3
	v_lshlrev_b32_e32 v132, 7, v129
	s_lshr_b32 s91, s70, 7
	s_lshl_b32 s91, s91, 13
	s_lshl_b32 s90, s90, 8
	s_add_u32 s90, s90, 0x8000
	s_lshl_b32 s88, s70, 4
	s_mov_b32 s89, 0x10000
	s_lshl_b32 s92, s22, 4
	s_and_b32 s92, s92, 0x780
	s_mov_b32 s93, 0
	s_load_dwordx2 s[96:97], s[0:1], 0x158
	s_load_dwordx2 s[98:99], s[0:1], 0xc8
	s_waitcnt lgkmcnt(0)
	v_subrev_u32_e32 v152, s96, v172
	v_xor_b32_e32 v152, v159, v152
	v_subrev_u32_e32 v153, s98, v180
	v_xor_b32_e32 v153, v159, v153
	v_subrev_u32_e32 v154, s96, v174
	v_xor_b32_e32 v154, v159, v154
	v_subrev_u32_e32 v155, s98, v182
	v_xor_b32_e32 v155, v159, v155
	v_subrev_u32_e32 v156, s96, v176
	v_xor_b32_e32 v156, v159, v156
	v_subrev_u32_e32 v157, s98, v184
	v_xor_b32_e32 v157, v159, v157
	v_subrev_u32_e32 v158, s96, v178
	v_xor_b32_e32 v158, v159, v158
	v_subrev_u32_e32 v160, s98, v186
	v_xor_b32_e32 v160, v159, v160
	v_xor_b32_e32 v133, v130, v131
	v_lshl_add_u32 v133, v133, 4, v132
	v_add_u32_e32 v232, s91, v133
	v_add_u32_e32 v236, s90, v133
	v_add_u32_e32 v205, 0x10000, v232
	v_add_u32_e32 v243, 0x10000, v236
	v_or_b32_e32 v133, 2, v130
	v_xor_b32_e32 v133, v133, v131
	v_lshl_add_u32 v133, v133, 4, v132
	v_add_u32_e32 v233, s91, v133
	v_add_u32_e32 v237, s90, v133
	v_add_u32_e32 v240, 0x10000, v233
	v_add_u32_e32 v253, 0x10000, v237
	v_or_b32_e32 v133, 4, v130
	v_xor_b32_e32 v133, v133, v131
	v_lshl_add_u32 v133, v133, 4, v132
	v_add_u32_e32 v234, s91, v133
	v_add_u32_e32 v238, s90, v133
	v_add_u32_e32 v241, 0x10000, v234
	v_add_u32_e32 v254, 0x10000, v238
	v_or_b32_e32 v133, 6, v130
	v_xor_b32_e32 v133, v133, v131
	v_lshl_add_u32 v133, v133, 4, v132
	v_add_u32_e32 v235, s91, v133
	v_add_u32_e32 v239, s90, v133
	v_add_u32_e32 v242, 0x10000, v235
	v_add_u32_e32 v255, 0x10000, v239
	s_barrier
	ds_read_b128 v[206:209], v232
	ds_read_b128 v[216:219], v236
	ds_read_b128 v[212:215], v232 offset:4096
	ds_read_b128 v[220:223], v236 offset:4096
	ds_read_b128 v[224:227], v236 offset:8192
	ds_read_b128 v[228:231], v236 offset:12288
	s_add_u32 s94, s2, s92
	s_add_u32 s94, s94, 0x80
	s_and_b32 s94, s94, 0x780
	s_sub_u32 s94, s94, 0x80
	s_subb_u32 s95, 0, 0
	s_add_u32 s100, s96, s94
	s_addc_u32 s101, s97, s95
	s_add_u32 s94, s98, s94
	s_addc_u32 s95, s99, s95
	s_add_u32 s90, s88, s89
	s_add_u32 m0, s90, 0
	s_nop 0
	global_load_lds_dwordx4 v152, s[100:101]
	s_add_u32 m0, s90, 32768
	s_nop 0
	global_load_lds_dwordx4 v153, s[94:95]
	s_add_u32 m0, s90, 8192
	s_nop 0
	global_load_lds_dwordx4 v154, s[100:101]
	s_add_u32 m0, s90, 40960
	s_nop 0
	global_load_lds_dwordx4 v155, s[94:95]
	s_add_u32 m0, s90, 16384
	s_nop 0
	global_load_lds_dwordx4 v156, s[100:101]
	s_add_u32 m0, s90, 49152
	s_nop 0
	global_load_lds_dwordx4 v157, s[94:95]
	s_add_u32 m0, s90, 24576
	s_nop 0
	global_load_lds_dwordx4 v158, s[100:101]
	s_add_u32 m0, s90, 57344
	s_nop 0
	global_load_lds_dwordx4 v160, s[94:95]
	s_xor_b32 s89, s89, 0x10000

.LBB0_5640:
	s_ashr_i32 s2, s54, 31
	s_lshr_b32 s2, s2, 30
	s_add_i32 s2, s54, s2
	s_ashr_i32 s2, s2, 2
	s_lshl_b32 s4, s2, 8
	v_add_u32_e32 v0, s4, v212
	v_min_i32_e32 v0, 0x7fff, v0
	v_ashrrev_i32_e32 v1, 31, v0
	s_lshl_b32 s6, s2, 10
	v_lshlrev_b64 v[0:1], 11, v[0:1]
	v_lshl_add_u64 v[160:161], v[176:177], 0, v[0:1]
	v_subrev_u32_e32 v0, s6, v220
	v_ashrrev_i32_e32 v1, 31, v0
	v_lshlrev_b64 v[0:1], 11, v[0:1]
	v_lshl_add_u64 v[180:181], v[178:179], 0, v[0:1]
	v_subrev_u32_e32 v0, s6, v221
	v_ashrrev_i32_e32 v1, 31, v0
	v_lshlrev_b64 v[0:1], 11, v[0:1]
	v_lshl_add_u64 v[182:183], v[178:179], 0, v[0:1]
	v_subrev_u32_e32 v0, s6, v222
	v_ashrrev_i32_e32 v1, 31, v0
	v_add_u32_e32 v2, s4, v213
	v_add_u32_e32 v4, s4, v171
	v_add_u32_e32 v6, s4, v215
	v_lshlrev_b64 v[0:1], 11, v[0:1]
	v_min_i32_e32 v2, 0x7fff, v2
	v_min_i32_e32 v4, 0x7fff, v4
	v_min_i32_e32 v6, 0x7fff, v6
	v_lshl_add_u64 v[184:185], v[178:179], 0, v[0:1]
	v_subrev_u32_e32 v0, s6, v223
	v_ashrrev_i32_e32 v3, 31, v2
	v_ashrrev_i32_e32 v5, 31, v4
	v_ashrrev_i32_e32 v7, 31, v6
	v_ashrrev_i32_e32 v1, 31, v0
	v_lshlrev_b64 v[2:3], 11, v[2:3]
	v_lshlrev_b64 v[4:5], 11, v[4:5]
	v_lshlrev_b64 v[6:7], 11, v[6:7]
	v_lshlrev_b64 v[0:1], 11, v[0:1]
	s_mov_b32 s5, s54
	v_lshl_add_u64 v[162:163], v[176:177], 0, v[2:3]
	v_lshl_add_u64 v[164:165], v[176:177], 0, v[4:5]
	v_lshl_add_u64 v[166:167], v[176:177], 0, v[6:7]
	v_lshl_add_u64 v[186:187], v[178:179], 0, v[0:1]
	s_mov_b64 s[2:3], 0
	s_mov_b32 s7, 0
	v_mov_b32_e32 v0, 0
	v_mov_b32_e32 v1, v169
	v_mov_b32_e32 v2, v169
	v_mov_b32_e32 v3, v169
	v_mov_b32_e32 v4, v169
	v_mov_b32_e32 v5, v169
	v_mov_b32_e32 v6, v169
	v_mov_b32_e32 v7, v169
	v_mov_b32_e32 v8, v169
	v_mov_b32_e32 v9, v169
	v_mov_b32_e32 v10, v169
	v_mov_b32_e32 v11, v169
	v_mov_b32_e32 v12, v169
	v_mov_b32_e32 v13, v169
	v_mov_b32_e32 v14, v169
	v_mov_b32_e32 v15, v169
	v_mov_b32_e32 v16, 0
	v_mov_b32_e32 v17, v169
	v_mov_b32_e32 v18, v169
	v_mov_b32_e32 v19, v169
	v_mov_b32_e32 v20, v169
	v_mov_b32_e32 v21, v169
	v_mov_b32_e32 v22, v169
	v_mov_b32_e32 v23, v169
	v_mov_b32_e32 v24, v169
	v_mov_b32_e32 v25, v169
	v_mov_b32_e32 v26, v169
	v_mov_b32_e32 v27, v169
	v_mov_b32_e32 v28, v169
	v_mov_b32_e32 v29, v169
	v_mov_b32_e32 v30, v169
	v_mov_b32_e32 v31, v169
	v_mov_b32_e32 v32, 0
	v_mov_b32_e32 v33, v169
	v_mov_b32_e32 v34, v169
	v_mov_b32_e32 v35, v169
	v_mov_b32_e32 v36, v169
	v_mov_b32_e32 v37, v169
	v_mov_b32_e32 v38, v169
	v_mov_b32_e32 v39, v169
	v_mov_b32_e32 v40, v169
	v_mov_b32_e32 v41, v169
	v_mov_b32_e32 v42, v169
	v_mov_b32_e32 v43, v169
	v_mov_b32_e32 v44, v169
	v_mov_b32_e32 v45, v169
	v_mov_b32_e32 v46, v169
	v_mov_b32_e32 v47, v169
	v_mov_b32_e32 v48, 0
	v_mov_b32_e32 v49, v169
	v_mov_b32_e32 v50, v169
	v_mov_b32_e32 v51, v169
	v_mov_b32_e32 v52, v169
	v_mov_b32_e32 v53, v169
	v_mov_b32_e32 v54, v169
	v_mov_b32_e32 v55, v169
	v_mov_b32_e32 v56, v169
	v_mov_b32_e32 v57, v169
	v_mov_b32_e32 v58, v169
	v_mov_b32_e32 v59, v169
	v_mov_b32_e32 v60, v169
	v_mov_b32_e32 v61, v169
	v_mov_b32_e32 v62, v169
	v_mov_b32_e32 v63, v169
	v_mov_b32_e32 v64, 0
	v_mov_b32_e32 v65, v169
	v_mov_b32_e32 v66, v169
	v_mov_b32_e32 v67, v169
	v_mov_b32_e32 v68, v169
	v_mov_b32_e32 v69, v169
	v_mov_b32_e32 v70, v169
	v_mov_b32_e32 v71, v169
	v_mov_b32_e32 v72, v169
	v_mov_b32_e32 v73, v169
	v_mov_b32_e32 v74, v169
	v_mov_b32_e32 v75, v169
	v_mov_b32_e32 v76, v169
	v_mov_b32_e32 v77, v169
	v_mov_b32_e32 v78, v169
	v_mov_b32_e32 v79, v169
	v_mov_b32_e32 v80, 0
	v_mov_b32_e32 v81, v169
	v_mov_b32_e32 v82, v169
	v_mov_b32_e32 v83, v169
	v_mov_b32_e32 v84, v169
	v_mov_b32_e32 v85, v169
	v_mov_b32_e32 v86, v169
	v_mov_b32_e32 v87, v169
	v_mov_b32_e32 v88, v169
	v_mov_b32_e32 v89, v169
	v_mov_b32_e32 v90, v169
	v_mov_b32_e32 v91, v169
	v_mov_b32_e32 v92, v169
	v_mov_b32_e32 v93, v169
	v_mov_b32_e32 v94, v169
	v_mov_b32_e32 v95, v169
	s_waitcnt vmcnt(7)
	v_mov_b32_e32 v96, 0
	v_mov_b32_e32 v97, v169
	v_mov_b32_e32 v98, v169
	v_mov_b32_e32 v99, v169
	s_waitcnt vmcnt(6)
	v_mov_b32_e32 v100, v169
	v_mov_b32_e32 v101, v169
	v_mov_b32_e32 v102, v169
	v_mov_b32_e32 v103, v169
	s_waitcnt vmcnt(5)
	v_mov_b32_e32 v104, v169
	v_mov_b32_e32 v105, v169
	v_mov_b32_e32 v106, v169
	v_mov_b32_e32 v107, v169
	s_waitcnt vmcnt(4)
	v_mov_b32_e32 v108, v169
	v_mov_b32_e32 v109, v169
	v_mov_b32_e32 v110, v169
	v_mov_b32_e32 v111, v169
	s_waitcnt vmcnt(3)
	v_mov_b32_e32 v112, 0
	v_mov_b32_e32 v113, v169
	v_mov_b32_e32 v114, v169
	v_mov_b32_e32 v115, v169
	s_waitcnt vmcnt(2)
	v_mov_b32_e32 v116, v169
	v_mov_b32_e32 v117, v169
	v_mov_b32_e32 v118, v169
	v_mov_b32_e32 v119, v169
	s_waitcnt vmcnt(1)
	v_mov_b32_e32 v120, v169
	v_mov_b32_e32 v121, v169
	v_mov_b32_e32 v122, v169
	v_mov_b32_e32 v123, v169
	s_waitcnt vmcnt(0)
	v_mov_b32_e32 v124, v169
	v_mov_b32_e32 v125, v169
	v_mov_b32_e32 v126, v169
	v_mov_b32_e32 v127, v169
	v_mbcnt_hi_u32_b32 v128, -1, v210
	s_and_b32 s90, s70, 0x40
	v_and_b32_e32 v159, 48, v128
	v_or_b32_e32 v159, s90, v159
	v_and_b32_e32 v129, 31, v128
	v_lshrrev_b32_e32 v130, 5, v128
	v_bfe_u32 v131, v128, 1, 3
	v_lshlrev_b32_e32 v132, 7, v129
	s_lshr_b32 s91, s70, 7
	s_lshl_b32 s91, s91, 13
	s_lshl_b32 s90, s90, 8
	s_add_u32 s90, s90, 0x8000
	s_lshl_b32 s88, s70, 4
	s_mov_b32 s89, 0x10000
	s_lshl_b32 s92, s22, 4
	s_and_b32 s92, s92, 0x780
	s_mov_b32 s93, 0
	s_load_dwordx2 s[96:97], s[0:1], 0x158
	s_load_dwordx2 s[98:99], s[0:1], 0xf8
	s_waitcnt lgkmcnt(0)
	v_subrev_u32_e32 v152, s96, v160
	v_xor_b32_e32 v152, v159, v152
	v_subrev_u32_e32 v153, s98, v180
	v_xor_b32_e32 v153, v159, v153
	v_subrev_u32_e32 v154, s96, v162
	v_xor_b32_e32 v154, v159, v154
	v_subrev_u32_e32 v155, s98, v182
	v_xor_b32_e32 v155, v159, v155
	v_subrev_u32_e32 v156, s96, v164
	v_xor_b32_e32 v156, v159, v156
	v_subrev_u32_e32 v157, s98, v184
	v_xor_b32_e32 v157, v159, v157
	v_subrev_u32_e32 v158, s96, v166
	v_xor_b32_e32 v158, v159, v158
	v_subrev_u32_e32 v168, s98, v186
	v_xor_b32_e32 v168, v159, v168
	v_xor_b32_e32 v133, v130, v131
	v_lshl_add_u32 v133, v133, 4, v132
	v_add_u32_e32 v230, s91, v133
	v_add_u32_e32 v234, s90, v133
	v_add_u32_e32 v208, 0x10000, v230
	v_add_u32_e32 v241, 0x10000, v234
	v_or_b32_e32 v133, 2, v130
	v_xor_b32_e32 v133, v133, v131
	v_lshl_add_u32 v133, v133, 4, v132
	v_add_u32_e32 v231, s91, v133
	v_add_u32_e32 v235, s90, v133
	v_add_u32_e32 v238, 0x10000, v231
	v_add_u32_e32 v253, 0x10000, v235
	v_or_b32_e32 v133, 4, v130
	v_xor_b32_e32 v133, v133, v131
	v_lshl_add_u32 v133, v133, 4, v132
	v_add_u32_e32 v232, s91, v133
	v_add_u32_e32 v236, s90, v133
	v_add_u32_e32 v239, 0x10000, v232
	v_add_u32_e32 v254, 0x10000, v236
	v_or_b32_e32 v133, 6, v130
	v_xor_b32_e32 v133, v133, v131
	v_lshl_add_u32 v133, v133, 4, v132
	v_add_u32_e32 v233, s91, v133
	v_add_u32_e32 v237, s90, v133
	v_add_u32_e32 v240, 0x10000, v233
	v_add_u32_e32 v255, 0x10000, v237
	s_barrier
	ds_read_b128 v[188:191], v230
	ds_read_b128 v[196:199], v234
	ds_read_b128 v[192:195], v230 offset:4096
	ds_read_b128 v[200:203], v234 offset:4096
	ds_read_b128 v[204:207], v234 offset:8192
	ds_read_b128 v[226:229], v234 offset:12288
	s_add_u32 s94, s2, s92
	s_add_u32 s94, s94, 0x80
	s_and_b32 s94, s94, 0x780
	s_sub_u32 s94, s94, 0x80
	s_subb_u32 s95, 0, 0
	s_add_u32 s100, s96, s94
	s_addc_u32 s101, s97, s95
	s_add_u32 s94, s98, s94
	s_addc_u32 s95, s99, s95
	s_add_u32 s90, s88, s89
	s_add_u32 m0, s90, 0
	s_nop 0
	global_load_lds_dwordx4 v152, s[100:101]
	s_add_u32 m0, s90, 32768
	s_nop 0
	global_load_lds_dwordx4 v153, s[94:95]
	s_add_u32 m0, s90, 8192
	s_nop 0
	global_load_lds_dwordx4 v154, s[100:101]
	s_add_u32 m0, s90, 40960
	s_nop 0
	global_load_lds_dwordx4 v155, s[94:95]
	s_add_u32 m0, s90, 16384
	s_nop 0
	global_load_lds_dwordx4 v156, s[100:101]
	s_add_u32 m0, s90, 49152
	s_nop 0
	global_load_lds_dwordx4 v157, s[94:95]
	s_add_u32 m0, s90, 24576
	s_nop 0
	global_load_lds_dwordx4 v158, s[100:101]
	s_add_u32 m0, s90, 57344
	s_nop 0
	global_load_lds_dwordx4 v168, s[94:95]
	s_xor_b32 s89, s89, 0x10000

.LBB0_5644:
	ds_read_b128 v[128:131], v238
	ds_read_b128 v[136:139], v253
	ds_read_b128 v[132:135], v238 offset:4096
	ds_read_b128 v[140:143], v253 offset:4096
	ds_read_b128 v[144:147], v253 offset:8192
	ds_read_b128 v[148:151], v253 offset:12288
	s_waitcnt lgkmcnt(6)
	v_mfma_f32_32x32x16_bf16 v[112:127], v[188:191], v[196:199], v[112:127]
	v_mfma_f32_32x32x16_bf16 v[48:63], v[192:195], v[196:199], v[48:63]
	v_mfma_f32_32x32x16_bf16 v[96:111], v[188:191], v[200:203], v[96:111]
	v_mfma_f32_32x32x16_bf16 v[32:47], v[192:195], v[200:203], v[32:47]
	v_mfma_f32_32x32x16_bf16 v[80:95], v[188:191], v[204:207], v[80:95]
	v_mfma_f32_32x32x16_bf16 v[16:31], v[192:195], v[204:207], v[16:31]
	v_mfma_f32_32x32x16_bf16 v[64:79], v[188:191], v[226:229], v[64:79]
	v_mfma_f32_32x32x16_bf16 v[0:15], v[192:195], v[226:229], v[0:15]
	ds_read_b128 v[188:191], v239
	ds_read_b128 v[196:199], v254
	ds_read_b128 v[192:195], v239 offset:4096
	ds_read_b128 v[200:203], v254 offset:4096
	ds_read_b128 v[204:207], v254 offset:8192
	ds_read_b128 v[226:229], v254 offset:12288
	s_waitcnt lgkmcnt(6)
	v_mfma_f32_32x32x16_bf16 v[112:127], v[128:131], v[136:139], v[112:127]
	v_mfma_f32_32x32x16_bf16 v[48:63], v[132:135], v[136:139], v[48:63]
	v_mfma_f32_32x32x16_bf16 v[96:111], v[128:131], v[140:143], v[96:111]
	v_mfma_f32_32x32x16_bf16 v[32:47], v[132:135], v[140:143], v[32:47]
	v_mfma_f32_32x32x16_bf16 v[80:95], v[128:131], v[144:147], v[80:95]
	v_mfma_f32_32x32x16_bf16 v[16:31], v[132:135], v[144:147], v[16:31]
	v_mfma_f32_32x32x16_bf16 v[64:79], v[128:131], v[148:151], v[64:79]
	v_mfma_f32_32x32x16_bf16 v[0:15], v[132:135], v[148:151], v[0:15]
	ds_read_b128 v[128:131], v240
	ds_read_b128 v[136:139], v255
	ds_read_b128 v[132:135], v240 offset:4096
	ds_read_b128 v[140:143], v255 offset:4096
	ds_read_b128 v[144:147], v255 offset:8192
	ds_read_b128 v[148:151], v255 offset:12288
	s_waitcnt lgkmcnt(6)
	v_mfma_f32_32x32x16_bf16 v[112:127], v[188:191], v[196:199], v[112:127]
	v_mfma_f32_32x32x16_bf16 v[48:63], v[192:195], v[196:199], v[48:63]
	v_mfma_f32_32x32x16_bf16 v[96:111], v[188:191], v[200:203], v[96:111]
	v_mfma_f32_32x32x16_bf16 v[32:47], v[192:195], v[200:203], v[32:47]
	v_mfma_f32_32x32x16_bf16 v[80:95], v[188:191], v[204:207], v[80:95]
	v_mfma_f32_32x32x16_bf16 v[16:31], v[192:195], v[204:207], v[16:31]
	v_mfma_f32_32x32x16_bf16 v[64:79], v[188:191], v[226:229], v[64:79]
	v_mfma_f32_32x32x16_bf16 v[0:15], v[192:195], v[226:229], v[0:15]
	s_waitcnt vmcnt(0) lgkmcnt(0)
	s_barrier
	v_mfma_f32_32x32x16_bf16 v[112:127], v[128:131], v[136:139], v[112:127]
	v_mfma_f32_32x32x16_bf16 v[48:63], v[132:135], v[136:139], v[48:63]
	v_mfma_f32_32x32x16_bf16 v[96:111], v[128:131], v[140:143], v[96:111]
	v_mfma_f32_32x32x16_bf16 v[32:47], v[132:135], v[140:143], v[32:47]
	v_mfma_f32_32x32x16_bf16 v[80:95], v[128:131], v[144:147], v[80:95]
	v_mfma_f32_32x32x16_bf16 v[16:31], v[132:135], v[144:147], v[16:31]
	v_mfma_f32_32x32x16_bf16 v[64:79], v[128:131], v[148:151], v[64:79]
	v_mfma_f32_32x32x16_bf16 v[0:15], v[132:135], v[148:151], v[0:15]
	s_lshl_b32 s2, s5, 8
	s_sub_i32 s2, s2, s6
	v_mov_b32_e32 v168, v214
	s_add_i32 s55, s4, s30
	s_or_b32 s26, s2, s31
	s_ashr_i32 s27, s26, 31
	s_load_dwordx2 s[24:25], s[0:1], 0x140
	v_ashrrev_i32_e32 v180, 3, v168
	v_and_b32_e32 v183, -4, v180
	v_add_u32_e32 v225, s55, v183
	v_add_u32_e32 v190, 8, v225
	v_min_i32_e32 v190, 0x7fff, v190
	v_ashrrev_i32_e32 v190, 12, v190
	v_add_u32_e32 v190, 24, v190
	v_mul_hi_i32_i24_e32 v191, 0x3000, v190
	v_mul_i32_i24_e32 v190, 0x3000, v190
	v_min_i32_e32 v184, 0x7fff, v225
	v_ashrrev_i32_e32 v184, 12, v184
	v_and_b32_e32 v182, 31, v168
	v_add_u32_e32 v184, 24, v184
	v_or_b32_e32 v180, s26, v182
	v_mul_hi_i32_i24_e32 v185, 0x3000, v184
	v_mul_i32_i24_e32 v184, 0x3000, v184
	v_ashrrev_i32_e32 v181, 31, v180
	s_waitcnt lgkmcnt(0)
	v_lshl_add_u64 v[184:185], s[24:25], 0, v[184:185]
	v_lshl_add_u64 v[184:185], v[184:185], 0, s[18:19]
	v_lshlrev_b64 v[180:181], 2, v[180:181]
	v_lshl_add_u64 v[196:197], v[184:185], 0, v[180:181]
	v_lshl_add_u64 v[186:187], s[24:25], 0, v[190:191]
	v_add_u32_e32 v188, 9, v225
	v_add_u32_e32 v190, 10, v225
	v_min_i32_e32 v188, 0x7fff, v188
	v_min_i32_e32 v190, 0x7fff, v190
	v_ashrrev_i32_e32 v188, 12, v188
	v_ashrrev_i32_e32 v190, 12, v190
	v_add_u32_e32 v188, 24, v188
	v_add_u32_e32 v190, 24, v190
	v_mul_hi_i32_i24_e32 v189, 0x3000, v188
	v_mul_i32_i24_e32 v188, 0x3000, v188
	v_mul_hi_i32_i24_e32 v191, 0x3000, v190
	v_mul_i32_i24_e32 v190, 0x3000, v190
	v_lshl_add_u64 v[188:189], s[24:25], 0, v[188:189]
	v_lshl_add_u64 v[190:191], s[24:25], 0, v[190:191]
	v_lshl_add_u64 v[186:187], v[186:187], 0, s[18:19]
	v_lshl_add_u64 v[188:189], v[188:189], 0, s[18:19]
	v_lshl_add_u64 v[190:191], v[190:191], 0, s[18:19]
	v_lshl_add_u64 v[206:207], v[186:187], 0, v[180:181]
	v_add_u32_e32 v208, 18, v225
	v_min_i32_e32 v208, 0x7fff, v208
	v_ashrrev_i32_e32 v208, 12, v208
	v_add_u32_e32 v208, 24, v208
	v_mul_hi_i32_i24_e32 v209, 0x3000, v208
	v_mul_i32_i24_e32 v208, 0x3000, v208
	v_lshl_add_u64 v[208:209], s[24:25], 0, v[208:209]
	v_lshl_add_u64 v[202:203], v[188:189], 0, v[180:181]
	v_lshl_add_u64 v[204:205], v[190:191], 0, v[180:181]
	global_load_dword v232, v[196:197], off
	global_load_dword v233, v[196:197], off offset:128
	global_load_dword v242, v[206:207], off
	global_load_dword v243, v[206:207], off offset:128
	global_load_dword v244, v[202:203], off
	global_load_dword v245, v[202:203], off offset:128
	global_load_dword v246, v[204:205], off
	global_load_dword v247, v[204:205], off offset:128
	v_add_u32_e32 v196, 17, v225
	v_min_i32_e32 v196, 0x7fff, v196
	v_ashrrev_i32_e32 v196, 12, v196
	v_add_u32_e32 v196, 24, v196
	v_mul_hi_i32_i24_e32 v197, 0x3000, v196
	v_mul_i32_i24_e32 v196, 0x3000, v196
	v_lshl_add_u64 v[196:197], s[24:25], 0, v[196:197]
	v_lshl_add_u64 v[196:197], v[196:197], 0, s[18:19]
	v_lshl_add_u64 v[206:207], v[196:197], 0, v[180:181]
	s_waitcnt vmcnt(7)
	s_nop 5
	v_mul_f32_e32 v112, v112, v232
	v_add_u32_e32 v192, 11, v225
	v_add_u32_e32 v194, 16, v225
	v_min_i32_e32 v192, 0x7fff, v192
	v_min_i32_e32 v194, 0x7fff, v194
	v_ashrrev_i32_e32 v192, 12, v192
	v_ashrrev_i32_e32 v194, 12, v194
	v_add_u32_e32 v192, 24, v192
	v_add_u32_e32 v194, 24, v194
	v_mul_hi_i32_i24_e32 v193, 0x3000, v192
	v_mul_i32_i24_e32 v192, 0x3000, v192
	v_mul_hi_i32_i24_e32 v195, 0x3000, v194
	v_mul_i32_i24_e32 v194, 0x3000, v194
	v_lshl_add_u64 v[192:193], s[24:25], 0, v[192:193]
	v_lshl_add_u64 v[194:195], s[24:25], 0, v[194:195]
	v_lshl_add_u64 v[192:193], v[192:193], 0, s[18:19]
	v_lshl_add_u64 v[194:195], v[194:195], 0, s[18:19]
	v_lshl_add_u64 v[202:203], v[192:193], 0, v[180:181]
	v_lshl_add_u64 v[204:205], v[194:195], 0, v[180:181]
	s_waitcnt vmcnt(6)
	s_nop 5
	v_mul_f32_e32 v96, v96, v233
	v_mul_f32_e32 v97, v97, v233
	v_lshl_add_u64 v[198:199], v[208:209], 0, s[18:19]
	v_lshl_add_u64 v[200:201], v[198:199], 0, v[180:181]
	global_load_dword v234, v[202:203], off
	global_load_dword v235, v[202:203], off offset:128
	global_load_dword v236, v[204:205], off
	global_load_dword v237, v[204:205], off offset:128
	global_load_dword v238, v[206:207], off
	global_load_dword v239, v[206:207], off offset:128
	global_load_dword v240, v[200:201], off
	global_load_dword v241, v[200:201], off offset:128
	v_add_u32_e32 v200, 19, v225
	v_add_u32_e32 v204, 25, v225
	v_add_u32_e32 v206, 26, v225
	v_min_i32_e32 v200, 0x7fff, v200
	v_add_u32_e32 v202, 24, v225
	v_min_i32_e32 v204, 0x7fff, v204
	v_min_i32_e32 v206, 0x7fff, v206
	v_ashrrev_i32_e32 v200, 12, v200
	v_min_i32_e32 v202, 0x7fff, v202
	v_ashrrev_i32_e32 v204, 12, v204
	v_ashrrev_i32_e32 v206, 12, v206
	v_add_u32_e32 v200, 24, v200
	v_ashrrev_i32_e32 v202, 12, v202
	v_add_u32_e32 v204, 24, v204
	v_add_u32_e32 v206, 24, v206
	v_mul_hi_i32_i24_e32 v201, 0x3000, v200
	v_mul_i32_i24_e32 v200, 0x3000, v200
	v_add_u32_e32 v202, 24, v202
	v_mul_hi_i32_i24_e32 v205, 0x3000, v204
	v_mul_i32_i24_e32 v204, 0x3000, v204
	v_mul_hi_i32_i24_e32 v207, 0x3000, v206
	v_mul_i32_i24_e32 v206, 0x3000, v206
	v_lshl_add_u64 v[200:201], s[24:25], 0, v[200:201]
	v_mul_hi_i32_i24_e32 v203, 0x3000, v202
	v_mul_i32_i24_e32 v202, 0x3000, v202
	v_lshl_add_u64 v[204:205], s[24:25], 0, v[204:205]
	v_lshl_add_u64 v[206:207], s[24:25], 0, v[206:207]
	v_lshl_add_u64 v[200:201], v[200:201], 0, s[18:19]
	v_lshl_add_u64 v[202:203], s[24:25], 0, v[202:203]
	v_lshl_add_u64 v[204:205], v[204:205], 0, s[18:19]
	v_lshl_add_u64 v[206:207], v[206:207], 0, s[18:19]
	v_lshl_add_u64 v[208:209], v[200:201], 0, v[180:181]
	v_lshl_add_u64 v[202:203], v[202:203], 0, s[18:19]
	v_lshl_add_u64 v[228:229], v[204:205], 0, v[180:181]
	v_lshl_add_u64 v[230:231], v[206:207], 0, v[180:181]
	v_lshl_add_u64 v[226:227], v[202:203], 0, v[180:181]
	global_load_dword v248, v[208:209], off
	global_load_dword v249, v[208:209], off offset:128
	global_load_dword v250, v[226:227], off
	global_load_dword v251, v[226:227], off offset:128
	global_load_dword v252, v[228:229], off
	s_nop 0
	global_load_dword v228, v[228:229], off offset:128
	s_nop 0
	global_load_dword v229, v[230:231], off
	s_nop 0
	global_load_dword v230, v[230:231], off offset:128
	v_add_u32_e32 v208, 27, v225
	v_min_i32_e32 v208, 0x7fff, v208
	v_ashrrev_i32_e32 v208, 12, v208
	v_add_u32_e32 v208, 24, v208
	v_mul_hi_i32_i24_e32 v209, 0x3000, v208
	v_mul_i32_i24_e32 v208, 0x3000, v208
	v_lshl_add_u64 v[208:209], s[24:25], 0, v[208:209]
	v_lshl_add_u64 v[208:209], v[208:209], 0, s[18:19]
	v_lshl_add_u64 v[226:227], v[208:209], 0, v[180:181]
	global_load_dword v225, v[226:227], off
	s_nop 0
	global_load_dword v226, v[226:227], off offset:128
	v_mad_u64_u32 v[160:161], s[2:3], v183, s36, v[182:183]
	v_lshl_add_u32 v162, v160, 2, s34
	ds_write2_b32 v162, v112, v96 offset1:32
	v_mul_f32_e32 v96, v113, v232
	ds_write2_b32 v162, v96, v97 offset0:68 offset1:100
	v_mul_f32_e32 v96, v114, v232
	v_mul_f32_e32 v97, v98, v233
	ds_write2_b32 v162, v96, v97 offset0:136 offset1:168
	v_mul_f32_e32 v96, v115, v232
	v_mul_f32_e32 v97, v99, v233
	ds_write2_b32 v162, v96, v97 offset0:204 offset1:236
	s_waitcnt vmcnt(23)
	v_mul_f32_e32 v96, v116, v242
	s_waitcnt vmcnt(22)
	v_mul_f32_e32 v97, v100, v243
	v_add_u32_e32 v115, 0x800, v162
	ds_write2_b32 v115, v96, v97 offset0:32 offset1:64
	s_waitcnt vmcnt(21)
	v_mul_f32_e32 v96, v117, v244
	s_waitcnt vmcnt(20)
	v_mul_f32_e32 v97, v101, v245
	ds_write2_b32 v115, v96, v97 offset0:100 offset1:132
	s_waitcnt vmcnt(19)
	v_mul_f32_e32 v96, v118, v246
	s_waitcnt vmcnt(18)
	v_mul_f32_e32 v97, v102, v247
	ds_write2_b32 v115, v96, v97 offset0:168 offset1:200
	v_add_u32_e32 v116, 0xa00, v162
	v_add_u32_e32 v117, 0x1000, v162
	s_waitcnt vmcnt(17)
	v_mul_f32_e32 v96, v119, v234
	s_waitcnt vmcnt(16)
	v_mul_f32_e32 v97, v103, v235
	ds_write2_b32 v116, v96, v97 offset0:108 offset1:140
	s_waitcnt vmcnt(15)
	v_mul_f32_e32 v96, v120, v236
	s_waitcnt vmcnt(14)
	v_mul_f32_e32 v97, v104, v237
	ds_write2_b32 v117, v96, v97 offset0:64 offset1:96
	s_waitcnt vmcnt(13)
	v_mul_f32_e32 v96, v121, v238
	s_waitcnt vmcnt(12)
	v_mul_f32_e32 v97, v105, v239
	ds_write2_b32 v117, v96, v97 offset0:132 offset1:164
	s_waitcnt vmcnt(11)
	v_mul_f32_e32 v96, v122, v240
	s_waitcnt vmcnt(10)
	v_mul_f32_e32 v97, v106, v241
	ds_write2_b32 v117, v96, v97 offset0:200 offset1:232
	v_add_u32_e32 v118, 0x1400, v162
	v_add_u32_e32 v119, 0x1800, v162
	v_ashrrev_i32_e32 v163, 4, v168
	v_and_b32_e32 v160, 15, v168
	v_add_u32_e32 v120, 0x1a00, v162
	v_mul_lo_u32 v164, v163, s37
	v_lshl_add_u32 v165, v160, 4, s34
	v_lshlrev_b32_e32 v168, 2, v160
	v_add_u32_e32 v160, s55, v163
	v_add_u32_e32 v121, 0x1c00, v162
	v_cmp_gt_i32_e32 vcc, s38, v160
	v_ashrrev_i32_e32 v161, 31, v160
	v_add_u32_e32 v114, v165, v164
	s_waitcnt vmcnt(9)
	v_mul_f32_e32 v96, v123, v248
	s_waitcnt vmcnt(8)
	v_mul_f32_e32 v97, v107, v249
	ds_write2_b32 v118, v96, v97 offset0:12 offset1:44
	s_waitcnt vmcnt(7)
	v_mul_f32_e32 v96, v124, v250
	s_waitcnt vmcnt(6)
	v_mul_f32_e32 v97, v108, v251
	ds_write2_b32 v119, v96, v97 offset0:96 offset1:128
	s_waitcnt vmcnt(5)
	v_mul_f32_e32 v96, v125, v252
	s_waitcnt vmcnt(4)
	v_mul_f32_e32 v97, v109, v228
	ds_write2_b32 v119, v96, v97 offset0:164 offset1:196
	s_waitcnt vmcnt(3)
	v_mul_f32_e32 v96, v126, v229
	s_waitcnt vmcnt(2)
	v_mul_f32_e32 v97, v110, v230
	ds_write2_b32 v120, v96, v97 offset0:104 offset1:136
	s_waitcnt vmcnt(1)
	v_mul_f32_e32 v96, v127, v225
	s_waitcnt vmcnt(0)
	v_mul_f32_e32 v97, v111, v226
	ds_write2_b32 v121, v96, v97 offset0:44 offset1:76
	v_or_b32_e32 v96, s26, v168
	v_mov_b32_e32 v97, s27
	v_add_u32_e32 v128, 0, v160
	v_ashrrev_i32_e32 v129, 31, v128
	v_lshlrev_b64 v[128:129], 12, v[128:129]
	v_lshl_add_u64 v[128:129], s[16:17], 0, v[128:129]
	v_lshl_add_u64 v[128:129], v[96:97], 2, v[128:129]
	global_load_dwordx4 v[128:131], v[128:129], off
	v_add_u32_e32 v132, 4, v160
	v_ashrrev_i32_e32 v133, 31, v132
	v_lshlrev_b64 v[132:133], 12, v[132:133]
	v_lshl_add_u64 v[132:133], s[16:17], 0, v[132:133]
	v_lshl_add_u64 v[132:133], v[96:97], 2, v[132:133]
	global_load_dwordx4 v[132:135], v[132:133], off
	v_add_u32_e32 v136, 8, v160
	v_ashrrev_i32_e32 v137, 31, v136
	v_lshlrev_b64 v[136:137], 12, v[136:137]
	v_lshl_add_u64 v[136:137], s[16:17], 0, v[136:137]
	v_lshl_add_u64 v[136:137], v[96:97], 2, v[136:137]
	global_load_dwordx4 v[136:139], v[136:137], off
	v_add_u32_e32 v140, 12, v160
	v_ashrrev_i32_e32 v141, 31, v140
	v_lshlrev_b64 v[140:141], 12, v[140:141]
	v_lshl_add_u64 v[140:141], s[16:17], 0, v[140:141]
	v_lshl_add_u64 v[140:141], v[96:97], 2, v[140:141]
	global_load_dwordx4 v[140:143], v[140:141], off
	v_add_u32_e32 v144, 16, v160
	v_ashrrev_i32_e32 v145, 31, v144
	v_lshlrev_b64 v[144:145], 12, v[144:145]
	v_lshl_add_u64 v[144:145], s[16:17], 0, v[144:145]
	v_lshl_add_u64 v[144:145], v[96:97], 2, v[144:145]
	global_load_dwordx4 v[144:147], v[144:145], off
	v_add_u32_e32 v148, 20, v160
	v_ashrrev_i32_e32 v149, 31, v148
	v_lshlrev_b64 v[148:149], 12, v[148:149]
	v_lshl_add_u64 v[148:149], s[16:17], 0, v[148:149]
	v_lshl_add_u64 v[148:149], v[96:97], 2, v[148:149]
	global_load_dwordx4 v[148:151], v[148:149], off
	v_add_u32_e32 v152, 24, v160
	v_ashrrev_i32_e32 v153, 31, v152
	v_lshlrev_b64 v[152:153], 12, v[152:153]
	v_lshl_add_u64 v[152:153], s[16:17], 0, v[152:153]
	v_lshl_add_u64 v[152:153], v[96:97], 2, v[152:153]
	global_load_dwordx4 v[152:155], v[152:153], off
	v_add_u32_e32 v156, 28, v160
	v_ashrrev_i32_e32 v157, 31, v156
	v_lshlrev_b64 v[156:157], 12, v[156:157]
	v_lshl_add_u64 v[156:157], s[16:17], 0, v[156:157]
	v_lshl_add_u64 v[156:157], v[96:97], 2, v[156:157]
	global_load_dwordx4 v[156:159], v[156:157], off
	s_and_saveexec_b64 s[2:3], vcc
	s_cbranch_execz .LBB0_5646
	v_lshlrev_b64 v[98:99], 12, v[160:161]
	v_lshl_add_u64 v[98:99], s[16:17], 0, v[98:99]
	v_lshl_add_u64 v[106:107], v[96:97], 2, v[98:99]
	ds_read_b128 v[102:105], v114
	s_waitcnt vmcnt(7) lgkmcnt(0)
	v_pk_add_f32 v[100:101], v[104:105], v[130:131]
	v_pk_add_f32 v[98:99], v[102:103], v[128:129]
	global_store_dwordx4 v[106:107], v[98:101], off
